# K-loop rebalance part 2 (branch-free): 4th segment's last 2 LDS-DMA pieces issued at loop bottom after its MFMA block; waits 8/6/8/6
# speedup vs baseline: 1.0047x; 1.0019x over previous
.LBB0_410:
	ds_read_b128 v[154:157], v149
	ds_read_b128 v[158:161], v149 offset:1024
	ds_read_b128 v[162:165], v149 offset:2048
	ds_read_b128 v[166:169], v149 offset:3072
	ds_read_b128 v[170:173], v150
	ds_read_b128 v[174:177], v150 offset:1024
	ds_read_b128 v[178:181], v150 offset:2048
	ds_read_b128 v[182:185], v150 offset:3072
	s_add_u32 s30, s28, 0xfffc0080
	s_addc_u32 s31, s29, -1
	s_cmp_eq_u32 s71, 12
	s_cselect_b32 s35, s21, s31
	s_cselect_b32 s34, s61, s30
	s_cselect_b32 s31, s19, s70
	s_cselect_b32 s30, s62, s63
	v_lshl_add_u64 v[144:145], s[28:29], 0, v[136:137]
	s_add_i32 m0, s27, 0xc000
	ds_read_b128 v[186:189], v151
	ds_read_b128 v[190:193], v151 offset:1024
	ds_read_b128 v[196:199], v151 offset:2048
	ds_read_b128 v[200:203], v151 offset:3072
	ds_read_b128 v[204:207], v151 offset:4096
	ds_read_b128 v[208:211], v151 offset:5120
	ds_read_b128 v[212:215], v151 offset:6144
	ds_read_b128 v[216:219], v151 offset:7168
	global_load_lds_dwordx4 v[144:145], off
	v_lshl_add_u64 v[144:145], s[28:29], 0, v[138:139]
	s_add_i32 m0, s27, 0xe000
	s_nop 0
	global_load_lds_dwordx4 v[144:145], off
	s_waitcnt vmcnt(8)
	s_waitcnt lgkmcnt(0)
	s_barrier
	s_setprio 1
	s_waitcnt lgkmcnt(0)
	v_mfma_f32_16x16x32_bf16 v[116:119], v[154:157], v[186:189], v[116:119]
	v_mfma_f32_16x16x32_bf16 v[112:115], v[162:165], v[186:189], v[112:115]
	v_mfma_f32_16x16x32_bf16 v[100:103], v[154:157], v[196:199], v[100:103]
	v_mfma_f32_16x16x32_bf16 v[96:99], v[162:165], v[196:199], v[96:99]
	v_mfma_f32_16x16x32_bf16 v[84:87], v[154:157], v[204:207], v[84:87]
	v_mfma_f32_16x16x32_bf16 v[80:83], v[162:165], v[204:207], v[80:83]
	v_mfma_f32_16x16x32_bf16 v[68:71], v[154:157], v[212:215], v[68:71]
	v_mfma_f32_16x16x32_bf16 v[64:67], v[162:165], v[212:215], v[64:67]
	v_mfma_f32_16x16x32_bf16 v[116:119], v[158:161], v[190:193], v[116:119]
	v_mfma_f32_16x16x32_bf16 v[112:115], v[166:169], v[190:193], v[112:115]
	v_mfma_f32_16x16x32_bf16 v[100:103], v[158:161], v[200:203], v[100:103]
	v_mfma_f32_16x16x32_bf16 v[96:99], v[166:169], v[200:203], v[96:99]
	v_mfma_f32_16x16x32_bf16 v[84:87], v[158:161], v[208:211], v[84:87]
	v_mfma_f32_16x16x32_bf16 v[80:83], v[166:169], v[208:211], v[80:83]
	v_mfma_f32_16x16x32_bf16 v[68:71], v[158:161], v[216:219], v[68:71]
	v_mfma_f32_16x16x32_bf16 v[64:67], v[166:169], v[216:219], v[64:67]
	s_setprio 0
	s_setprio 1
	v_mfma_f32_16x16x32_bf16 v[124:127], v[170:173], v[186:189], v[124:127]
	v_mfma_f32_16x16x32_bf16 v[120:123], v[178:181], v[186:189], v[120:123]
	v_mfma_f32_16x16x32_bf16 v[108:111], v[170:173], v[196:199], v[108:111]
	v_mfma_f32_16x16x32_bf16 v[104:107], v[178:181], v[196:199], v[104:107]
	v_mfma_f32_16x16x32_bf16 v[92:95], v[170:173], v[204:207], v[92:95]
	v_mfma_f32_16x16x32_bf16 v[88:91], v[178:181], v[204:207], v[88:91]
	v_mfma_f32_16x16x32_bf16 v[76:79], v[170:173], v[212:215], v[76:79]
	v_mfma_f32_16x16x32_bf16 v[72:75], v[178:181], v[212:215], v[72:75]
	v_mfma_f32_16x16x32_bf16 v[124:127], v[174:177], v[190:193], v[124:127]
	v_mfma_f32_16x16x32_bf16 v[120:123], v[182:185], v[190:193], v[120:123]
	v_mfma_f32_16x16x32_bf16 v[108:111], v[174:177], v[200:203], v[108:111]
	v_mfma_f32_16x16x32_bf16 v[104:107], v[182:185], v[200:203], v[104:107]
	v_mfma_f32_16x16x32_bf16 v[92:95], v[174:177], v[208:211], v[92:95]
	v_mfma_f32_16x16x32_bf16 v[88:91], v[182:185], v[208:211], v[88:91]
	v_mfma_f32_16x16x32_bf16 v[76:79], v[174:177], v[216:219], v[76:79]
	v_mfma_f32_16x16x32_bf16 v[72:75], v[182:185], v[216:219], v[72:75]
	s_setprio 0
	s_barrier
	s_add_i32 s72, s54, s41
	v_lshl_add_u64 v[144:145], s[30:31], 0, v[132:133]
	s_mov_b32 m0, s72
	ds_read_b128 v[186:189], v151 offset:16384
	ds_read_b128 v[190:193], v151 offset:17408
	ds_read_b128 v[196:199], v151 offset:18432
	ds_read_b128 v[200:203], v151 offset:19456
	ds_read_b128 v[204:207], v151 offset:20480
	ds_read_b128 v[208:211], v151 offset:21504
	ds_read_b128 v[212:215], v151 offset:22528
	ds_read_b128 v[216:219], v151 offset:23552
	global_load_lds_dwordx4 v[144:145], off
	s_add_i32 m0, s72, 0x2000
	s_add_u32 s72, s30, 0x40000
	v_lshl_add_u64 v[220:221], s[30:31], 0, v[128:129]
	s_addc_u32 s73, s31, 0
	s_add_i32 s77, s55, s41
	global_load_lds_dwordx4 v[220:221], off
	v_lshl_add_u64 v[222:223], s[72:73], 0, v[132:133]
	s_mov_b32 m0, s77
	v_lshl_add_u64 v[224:225], s[34:35], 0, v[130:131]
	global_load_lds_dwordx4 v[222:223], off
	v_lshl_add_u64 v[222:223], s[72:73], 0, v[128:129]
	s_add_i32 m0, s77, 0x2000
	s_nop 0
	global_load_lds_dwordx4 v[222:223], off
	v_lshl_add_u64 v[222:223], s[34:35], 0, v[134:135]
	s_waitcnt vmcnt(6)
	s_waitcnt lgkmcnt(0)
	s_barrier
	s_setprio 1
	s_waitcnt lgkmcnt(0)
	v_mfma_f32_16x16x32_bf16 v[52:55], v[154:157], v[186:189], v[52:55]
	v_mfma_f32_16x16x32_bf16 v[48:51], v[162:165], v[186:189], v[48:51]
	v_mfma_f32_16x16x32_bf16 v[36:39], v[154:157], v[196:199], v[36:39]
	v_mfma_f32_16x16x32_bf16 v[32:35], v[162:165], v[196:199], v[32:35]
	v_mfma_f32_16x16x32_bf16 v[20:23], v[154:157], v[204:207], v[20:23]
	v_mfma_f32_16x16x32_bf16 v[16:19], v[162:165], v[204:207], v[16:19]
	v_mfma_f32_16x16x32_bf16 v[4:7], v[154:157], v[212:215], v[4:7]
	v_mfma_f32_16x16x32_bf16 v[0:3], v[162:165], v[212:215], v[0:3]
	v_mfma_f32_16x16x32_bf16 v[52:55], v[158:161], v[190:193], v[52:55]
	v_mfma_f32_16x16x32_bf16 v[48:51], v[166:169], v[190:193], v[48:51]
	v_mfma_f32_16x16x32_bf16 v[36:39], v[158:161], v[200:203], v[36:39]
	v_mfma_f32_16x16x32_bf16 v[32:35], v[166:169], v[200:203], v[32:35]
	v_mfma_f32_16x16x32_bf16 v[20:23], v[158:161], v[208:211], v[20:23]
	v_mfma_f32_16x16x32_bf16 v[16:19], v[166:169], v[208:211], v[16:19]
	v_mfma_f32_16x16x32_bf16 v[4:7], v[158:161], v[216:219], v[4:7]
	v_mfma_f32_16x16x32_bf16 v[0:3], v[166:169], v[216:219], v[0:3]
	s_setprio 0
	s_setprio 1
	v_mfma_f32_16x16x32_bf16 v[60:63], v[170:173], v[186:189], v[60:63]
	v_mfma_f32_16x16x32_bf16 v[56:59], v[178:181], v[186:189], v[56:59]
	v_mfma_f32_16x16x32_bf16 v[44:47], v[170:173], v[196:199], v[44:47]
	v_mfma_f32_16x16x32_bf16 v[40:43], v[178:181], v[196:199], v[40:43]
	v_mfma_f32_16x16x32_bf16 v[28:31], v[170:173], v[204:207], v[28:31]
	v_mfma_f32_16x16x32_bf16 v[24:27], v[178:181], v[204:207], v[24:27]
	v_mfma_f32_16x16x32_bf16 v[12:15], v[170:173], v[212:215], v[12:15]
	v_mfma_f32_16x16x32_bf16 v[8:11], v[178:181], v[212:215], v[8:11]
	v_mfma_f32_16x16x32_bf16 v[60:63], v[174:177], v[190:193], v[60:63]
	v_mfma_f32_16x16x32_bf16 v[56:59], v[182:185], v[190:193], v[56:59]
	v_mfma_f32_16x16x32_bf16 v[44:47], v[174:177], v[200:203], v[44:47]
	v_mfma_f32_16x16x32_bf16 v[40:43], v[182:185], v[200:203], v[40:43]
	v_mfma_f32_16x16x32_bf16 v[28:31], v[174:177], v[208:211], v[28:31]
	v_mfma_f32_16x16x32_bf16 v[24:27], v[182:185], v[208:211], v[24:27]
	v_mfma_f32_16x16x32_bf16 v[12:15], v[174:177], v[216:219], v[12:15]
	v_mfma_f32_16x16x32_bf16 v[8:11], v[182:185], v[216:219], v[8:11]
	s_setprio 0
	s_barrier
	s_add_i32 s72, 0, 0x18000
	v_add_u32_e32 v153, s72, v147
	s_add_i32 s73, 0, 0x1c000
	ds_read_b128 v[154:157], v153
	ds_read_b128 v[158:161], v153 offset:1024
	ds_read_b128 v[162:165], v153 offset:2048
	ds_read_b128 v[166:169], v153 offset:3072
	v_add_u32_e32 v153, s73, v147
	ds_read_b128 v[170:173], v153
	ds_read_b128 v[174:177], v153 offset:1024
	ds_read_b128 v[178:181], v153 offset:2048
	ds_read_b128 v[182:185], v153 offset:3072
	s_add_u32 s34, s34, 0x40000
	s_addc_u32 s35, s35, 0
	v_lshl_add_u64 v[226:227], s[34:35], 0, v[134:135]
	ds_read_b128 v[186:189], v151 offset:32768
	ds_read_b128 v[190:193], v151 offset:33792
	ds_read_b128 v[196:199], v151 offset:34816
	ds_read_b128 v[200:203], v151 offset:35840
	ds_read_b128 v[204:207], v151 offset:36864
	ds_read_b128 v[208:211], v151 offset:37888
	ds_read_b128 v[212:215], v151 offset:38912
	ds_read_b128 v[216:219], v151 offset:39936
	s_mov_b32 m0, s27
	s_nop 0
	global_load_lds_dwordx4 v[222:223], off
	s_mov_b32 m0, s43
	s_nop 0
	global_load_lds_dwordx4 v[224:225], off
	s_mov_b32 m0, s44
	s_nop 0
	global_load_lds_dwordx4 v[226:227], off
	v_lshl_add_u64 v[226:227], s[34:35], 0, v[130:131]
	s_mov_b32 m0, s45
	s_nop 0
	global_load_lds_dwordx4 v[226:227], off
	s_waitcnt vmcnt(8)
	s_waitcnt lgkmcnt(0)
	s_barrier
	s_setprio 1
	s_waitcnt lgkmcnt(0)
	v_mfma_f32_16x16x32_bf16 v[116:119], v[154:157], v[186:189], v[116:119]
	v_mfma_f32_16x16x32_bf16 v[112:115], v[162:165], v[186:189], v[112:115]
	v_mfma_f32_16x16x32_bf16 v[100:103], v[154:157], v[196:199], v[100:103]
	v_mfma_f32_16x16x32_bf16 v[96:99], v[162:165], v[196:199], v[96:99]
	v_mfma_f32_16x16x32_bf16 v[84:87], v[154:157], v[204:207], v[84:87]
	v_mfma_f32_16x16x32_bf16 v[80:83], v[162:165], v[204:207], v[80:83]
	v_mfma_f32_16x16x32_bf16 v[68:71], v[154:157], v[212:215], v[68:71]
	v_mfma_f32_16x16x32_bf16 v[64:67], v[162:165], v[212:215], v[64:67]
	v_mfma_f32_16x16x32_bf16 v[116:119], v[158:161], v[190:193], v[116:119]
	v_mfma_f32_16x16x32_bf16 v[112:115], v[166:169], v[190:193], v[112:115]
	v_mfma_f32_16x16x32_bf16 v[100:103], v[158:161], v[200:203], v[100:103]
	v_mfma_f32_16x16x32_bf16 v[96:99], v[166:169], v[200:203], v[96:99]
	v_mfma_f32_16x16x32_bf16 v[84:87], v[158:161], v[208:211], v[84:87]
	v_mfma_f32_16x16x32_bf16 v[80:83], v[166:169], v[208:211], v[80:83]
	v_mfma_f32_16x16x32_bf16 v[68:71], v[158:161], v[216:219], v[68:71]
	v_mfma_f32_16x16x32_bf16 v[64:67], v[166:169], v[216:219], v[64:67]
	s_setprio 0
	s_setprio 1
	v_mfma_f32_16x16x32_bf16 v[124:127], v[170:173], v[186:189], v[124:127]
	v_mfma_f32_16x16x32_bf16 v[120:123], v[178:181], v[186:189], v[120:123]
	v_mfma_f32_16x16x32_bf16 v[108:111], v[170:173], v[196:199], v[108:111]
	v_mfma_f32_16x16x32_bf16 v[104:107], v[178:181], v[196:199], v[104:107]
	v_mfma_f32_16x16x32_bf16 v[92:95], v[170:173], v[204:207], v[92:95]
	v_mfma_f32_16x16x32_bf16 v[88:91], v[178:181], v[204:207], v[88:91]
	v_mfma_f32_16x16x32_bf16 v[76:79], v[170:173], v[212:215], v[76:79]
	v_mfma_f32_16x16x32_bf16 v[72:75], v[178:181], v[212:215], v[72:75]
	v_mfma_f32_16x16x32_bf16 v[124:127], v[174:177], v[190:193], v[124:127]
	v_mfma_f32_16x16x32_bf16 v[120:123], v[182:185], v[190:193], v[120:123]
	v_mfma_f32_16x16x32_bf16 v[108:111], v[174:177], v[200:203], v[108:111]
	v_mfma_f32_16x16x32_bf16 v[104:107], v[182:185], v[200:203], v[104:107]
	v_mfma_f32_16x16x32_bf16 v[92:95], v[174:177], v[208:211], v[92:95]
	v_mfma_f32_16x16x32_bf16 v[88:91], v[182:185], v[208:211], v[88:91]
	v_mfma_f32_16x16x32_bf16 v[76:79], v[174:177], v[216:219], v[76:79]
	v_mfma_f32_16x16x32_bf16 v[72:75], v[182:185], v[216:219], v[72:75]
	s_setprio 0
	s_barrier
	s_add_i32 s34, s72, s41
	v_lshl_add_u64 v[144:145], v[144:145], 0, s[12:13]
	s_mov_b32 m0, s34
	ds_read_b128 v[186:189], v151 offset:49152
	ds_read_b128 v[190:193], v151 offset:50176
	ds_read_b128 v[196:199], v151 offset:51200
	ds_read_b128 v[200:203], v151 offset:52224
	ds_read_b128 v[204:207], v151 offset:53248
	ds_read_b128 v[208:211], v151 offset:54272
	ds_read_b128 v[212:215], v151 offset:55296
	ds_read_b128 v[216:219], v151 offset:56320
	global_load_lds_dwordx4 v[144:145], off
	s_add_i32 m0, s34, 0x2000
	s_add_u32 s30, s30, 0x40080
	v_lshl_add_u64 v[144:145], v[220:221], 0, s[12:13]
	s_addc_u32 s31, s31, 0
	s_add_i32 s34, s73, s41
	global_load_lds_dwordx4 v[144:145], off
	v_lshl_add_u64 v[144:145], s[30:31], 0, v[132:133]
	s_mov_b32 m0, s34
	s_nop 0
	global_load_lds_dwordx4 v[144:145], off
	v_lshl_add_u64 v[144:145], s[30:31], 0, v[128:129]
	s_add_i32 m0, s34, 0x2000
	s_nop 0
	global_load_lds_dwordx4 v[144:145], off
	s_waitcnt vmcnt(6)
	s_waitcnt lgkmcnt(0)
	s_barrier
	s_setprio 1
	s_waitcnt lgkmcnt(0)
	v_mfma_f32_16x16x32_bf16 v[52:55], v[154:157], v[186:189], v[52:55]
	v_mfma_f32_16x16x32_bf16 v[48:51], v[162:165], v[186:189], v[48:51]
	v_mfma_f32_16x16x32_bf16 v[36:39], v[154:157], v[196:199], v[36:39]
	v_mfma_f32_16x16x32_bf16 v[32:35], v[162:165], v[196:199], v[32:35]
	v_mfma_f32_16x16x32_bf16 v[20:23], v[154:157], v[204:207], v[20:23]
	v_mfma_f32_16x16x32_bf16 v[16:19], v[162:165], v[204:207], v[16:19]
	v_mfma_f32_16x16x32_bf16 v[4:7], v[154:157], v[212:215], v[4:7]
	v_mfma_f32_16x16x32_bf16 v[0:3], v[162:165], v[212:215], v[0:3]
	v_mfma_f32_16x16x32_bf16 v[52:55], v[158:161], v[190:193], v[52:55]
	v_mfma_f32_16x16x32_bf16 v[48:51], v[166:169], v[190:193], v[48:51]
	v_mfma_f32_16x16x32_bf16 v[36:39], v[158:161], v[200:203], v[36:39]
	v_mfma_f32_16x16x32_bf16 v[32:35], v[166:169], v[200:203], v[32:35]
	v_mfma_f32_16x16x32_bf16 v[20:23], v[158:161], v[208:211], v[20:23]
	v_mfma_f32_16x16x32_bf16 v[16:19], v[166:169], v[208:211], v[16:19]
	v_mfma_f32_16x16x32_bf16 v[4:7], v[158:161], v[216:219], v[4:7]
	v_mfma_f32_16x16x32_bf16 v[0:3], v[166:169], v[216:219], v[0:3]
	s_setprio 0
	s_setprio 1
	v_mfma_f32_16x16x32_bf16 v[60:63], v[170:173], v[186:189], v[60:63]
	v_mfma_f32_16x16x32_bf16 v[56:59], v[178:181], v[186:189], v[56:59]
	v_mfma_f32_16x16x32_bf16 v[44:47], v[170:173], v[196:199], v[44:47]
	v_mfma_f32_16x16x32_bf16 v[40:43], v[178:181], v[196:199], v[40:43]
	v_mfma_f32_16x16x32_bf16 v[28:31], v[170:173], v[204:207], v[28:31]
	v_mfma_f32_16x16x32_bf16 v[24:27], v[178:181], v[204:207], v[24:27]
	v_mfma_f32_16x16x32_bf16 v[12:15], v[170:173], v[212:215], v[12:15]
	v_mfma_f32_16x16x32_bf16 v[8:11], v[178:181], v[212:215], v[8:11]
	v_mfma_f32_16x16x32_bf16 v[60:63], v[174:177], v[190:193], v[60:63]
	v_mfma_f32_16x16x32_bf16 v[56:59], v[182:185], v[190:193], v[56:59]
	v_mfma_f32_16x16x32_bf16 v[44:47], v[174:177], v[200:203], v[44:47]
	v_mfma_f32_16x16x32_bf16 v[40:43], v[182:185], v[200:203], v[40:43]
	v_mfma_f32_16x16x32_bf16 v[28:31], v[174:177], v[208:211], v[28:31]
	v_mfma_f32_16x16x32_bf16 v[24:27], v[182:185], v[208:211], v[24:27]
	v_mfma_f32_16x16x32_bf16 v[12:15], v[174:177], v[216:219], v[12:15]
	v_mfma_f32_16x16x32_bf16 v[8:11], v[182:185], v[216:219], v[8:11]
	s_setprio 0
	s_barrier
	v_lshl_add_u64 v[222:223], v[222:223], 0, s[12:13]
	s_mov_b32 m0, s51
	s_nop 0
	global_load_lds_dwordx4 v[222:223], off
	v_lshl_add_u64 v[224:225], v[224:225], 0, s[12:13]
	s_mov_b32 m0, s52
	s_nop 0
	global_load_lds_dwordx4 v[224:225], off
	s_add_i32 s71, s71, 2
	s_add_u32 s28, s28, 0x100
	s_addc_u32 s29, s29, 0
	s_add_u32 s63, s63, 0x100
	s_addc_u32 s70, s70, 0
	s_cmp_gt_u32 s71, 13
	s_cbranch_scc0 .LBB0_410
	s_and_b64 vcc, exec, s[16:17]
	s_cbranch_vccz .LBB0_413
	s_barrier

.LBB0_532:
	ds_read_b128 v[146:149], v155
	ds_read_b128 v[160:163], v155 offset:1024
	ds_read_b128 v[164:167], v155 offset:2048
	ds_read_b128 v[168:171], v155 offset:3072
	ds_read_b128 v[172:175], v156
	ds_read_b128 v[176:179], v156 offset:1024
	ds_read_b128 v[180:183], v156 offset:2048
	ds_read_b128 v[184:187], v156 offset:3072
	s_add_u32 s30, s28, 0x100
	s_addc_u32 s31, s29, 0
	s_cmp_eq_u32 s77, 40
	s_cselect_b32 s37, s1, s31
	s_cselect_b32 s36, s0, s30
	s_cselect_b32 s35, s27, s73
	s_cselect_b32 s34, s26, s72
	v_lshl_add_u64 v[150:151], s[28:29], 0, v[138:139]
	s_add_i32 m0, s44, 0xc000
	ds_read_b128 v[188:191], v157
	ds_read_b128 v[196:199], v157 offset:1024
	ds_read_b128 v[200:203], v157 offset:2048
	ds_read_b128 v[204:207], v157 offset:3072
	ds_read_b128 v[208:211], v157 offset:4096
	ds_read_b128 v[212:215], v157 offset:5120
	ds_read_b128 v[216:219], v157 offset:6144
	ds_read_b128 v[220:223], v157 offset:7168
	global_load_lds_dwordx4 v[150:151], off
	v_lshl_add_u64 v[150:151], s[28:29], 0, v[140:141]
	s_add_i32 m0, s44, 0xe000
	s_nop 0
	global_load_lds_dwordx4 v[150:151], off
	s_waitcnt vmcnt(8)
	s_waitcnt lgkmcnt(0)
	s_barrier
	s_setprio 1
	s_waitcnt lgkmcnt(0)
	v_mfma_f32_16x16x32_bf16 v[124:127], v[146:149], v[188:191], v[124:127]
	v_mfma_f32_16x16x32_bf16 v[120:123], v[164:167], v[188:191], v[120:123]
	v_mfma_f32_16x16x32_bf16 v[108:111], v[146:149], v[200:203], v[108:111]
	v_mfma_f32_16x16x32_bf16 v[104:107], v[164:167], v[200:203], v[104:107]
	v_mfma_f32_16x16x32_bf16 v[92:95], v[146:149], v[208:211], v[92:95]
	v_mfma_f32_16x16x32_bf16 v[88:91], v[164:167], v[208:211], v[88:91]
	v_mfma_f32_16x16x32_bf16 v[76:79], v[146:149], v[216:219], v[76:79]
	v_mfma_f32_16x16x32_bf16 v[72:75], v[164:167], v[216:219], v[72:75]
	v_mfma_f32_16x16x32_bf16 v[124:127], v[160:163], v[196:199], v[124:127]
	v_mfma_f32_16x16x32_bf16 v[120:123], v[168:171], v[196:199], v[120:123]
	v_mfma_f32_16x16x32_bf16 v[108:111], v[160:163], v[204:207], v[108:111]
	v_mfma_f32_16x16x32_bf16 v[104:107], v[168:171], v[204:207], v[104:107]
	v_mfma_f32_16x16x32_bf16 v[92:95], v[160:163], v[212:215], v[92:95]
	v_mfma_f32_16x16x32_bf16 v[88:91], v[168:171], v[212:215], v[88:91]
	v_mfma_f32_16x16x32_bf16 v[76:79], v[160:163], v[220:223], v[76:79]
	v_mfma_f32_16x16x32_bf16 v[72:75], v[168:171], v[220:223], v[72:75]
	s_setprio 0
	s_setprio 1
	v_mfma_f32_16x16x32_bf16 v[116:119], v[172:175], v[188:191], v[116:119]
	v_mfma_f32_16x16x32_bf16 v[112:115], v[180:183], v[188:191], v[112:115]
	v_mfma_f32_16x16x32_bf16 v[100:103], v[172:175], v[200:203], v[100:103]
	v_mfma_f32_16x16x32_bf16 v[96:99], v[180:183], v[200:203], v[96:99]
	v_mfma_f32_16x16x32_bf16 v[84:87], v[172:175], v[208:211], v[84:87]
	v_mfma_f32_16x16x32_bf16 v[80:83], v[180:183], v[208:211], v[80:83]
	v_mfma_f32_16x16x32_bf16 v[68:71], v[172:175], v[216:219], v[68:71]
	v_mfma_f32_16x16x32_bf16 v[64:67], v[180:183], v[216:219], v[64:67]
	v_mfma_f32_16x16x32_bf16 v[116:119], v[176:179], v[196:199], v[116:119]
	v_mfma_f32_16x16x32_bf16 v[112:115], v[184:187], v[196:199], v[112:115]
	v_mfma_f32_16x16x32_bf16 v[100:103], v[176:179], v[204:207], v[100:103]
	v_mfma_f32_16x16x32_bf16 v[96:99], v[184:187], v[204:207], v[96:99]
	v_mfma_f32_16x16x32_bf16 v[84:87], v[176:179], v[212:215], v[84:87]
	v_mfma_f32_16x16x32_bf16 v[80:83], v[184:187], v[212:215], v[80:83]
	v_mfma_f32_16x16x32_bf16 v[68:71], v[176:179], v[220:223], v[68:71]
	v_mfma_f32_16x16x32_bf16 v[64:67], v[184:187], v[220:223], v[64:67]
	s_setprio 0
	s_barrier
	s_add_i32 s28, s60, s43
	v_lshl_add_u64 v[150:151], s[34:35], 0, v[132:133]
	s_mov_b32 m0, s28
	ds_read_b128 v[188:191], v157 offset:16384
	ds_read_b128 v[196:199], v157 offset:17408
	ds_read_b128 v[200:203], v157 offset:18432
	ds_read_b128 v[204:207], v157 offset:19456
	ds_read_b128 v[208:211], v157 offset:20480
	ds_read_b128 v[212:215], v157 offset:21504
	ds_read_b128 v[216:219], v157 offset:22528
	ds_read_b128 v[220:223], v157 offset:23552
	global_load_lds_dwordx4 v[150:151], off
	s_add_i32 m0, s28, 0x2000
	s_add_u32 s28, s34, 0xb0000
	v_lshl_add_u64 v[192:193], s[34:35], 0, v[136:137]
	s_addc_u32 s29, s35, 0
	s_add_i32 s78, s61, s43
	global_load_lds_dwordx4 v[192:193], off
	v_lshl_add_u64 v[224:225], s[28:29], 0, v[132:133]
	s_mov_b32 m0, s78
	v_lshl_add_u64 v[226:227], s[36:37], 0, v[134:135]
	global_load_lds_dwordx4 v[224:225], off
	v_lshl_add_u64 v[224:225], s[28:29], 0, v[136:137]
	s_add_i32 m0, s78, 0x2000
	s_nop 0
	global_load_lds_dwordx4 v[224:225], off
	v_lshl_add_u64 v[224:225], s[36:37], 0, v[130:131]
	s_waitcnt vmcnt(6)
	s_waitcnt lgkmcnt(0)
	s_barrier
	s_setprio 1
	s_waitcnt lgkmcnt(0)
	v_mfma_f32_16x16x32_bf16 v[60:63], v[146:149], v[188:191], v[60:63]
	v_mfma_f32_16x16x32_bf16 v[56:59], v[164:167], v[188:191], v[56:59]
	v_mfma_f32_16x16x32_bf16 v[44:47], v[146:149], v[200:203], v[44:47]
	v_mfma_f32_16x16x32_bf16 v[40:43], v[164:167], v[200:203], v[40:43]
	v_mfma_f32_16x16x32_bf16 v[28:31], v[146:149], v[208:211], v[28:31]
	v_mfma_f32_16x16x32_bf16 v[24:27], v[164:167], v[208:211], v[24:27]
	v_mfma_f32_16x16x32_bf16 v[12:15], v[146:149], v[216:219], v[12:15]
	v_mfma_f32_16x16x32_bf16 v[8:11], v[164:167], v[216:219], v[8:11]
	v_mfma_f32_16x16x32_bf16 v[60:63], v[160:163], v[196:199], v[60:63]
	v_mfma_f32_16x16x32_bf16 v[56:59], v[168:171], v[196:199], v[56:59]
	v_mfma_f32_16x16x32_bf16 v[44:47], v[160:163], v[204:207], v[44:47]
	v_mfma_f32_16x16x32_bf16 v[40:43], v[168:171], v[204:207], v[40:43]
	v_mfma_f32_16x16x32_bf16 v[28:31], v[160:163], v[212:215], v[28:31]
	v_mfma_f32_16x16x32_bf16 v[24:27], v[168:171], v[212:215], v[24:27]
	v_mfma_f32_16x16x32_bf16 v[12:15], v[160:163], v[220:223], v[12:15]
	v_mfma_f32_16x16x32_bf16 v[8:11], v[168:171], v[220:223], v[8:11]
	s_setprio 0
	s_setprio 1
	v_mfma_f32_16x16x32_bf16 v[52:55], v[172:175], v[188:191], v[52:55]
	v_mfma_f32_16x16x32_bf16 v[48:51], v[180:183], v[188:191], v[48:51]
	v_mfma_f32_16x16x32_bf16 v[36:39], v[172:175], v[200:203], v[36:39]
	v_mfma_f32_16x16x32_bf16 v[32:35], v[180:183], v[200:203], v[32:35]
	v_mfma_f32_16x16x32_bf16 v[20:23], v[172:175], v[208:211], v[20:23]
	v_mfma_f32_16x16x32_bf16 v[16:19], v[180:183], v[208:211], v[16:19]
	v_mfma_f32_16x16x32_bf16 v[4:7], v[172:175], v[216:219], v[4:7]
	v_mfma_f32_16x16x32_bf16 v[0:3], v[180:183], v[216:219], v[0:3]
	v_mfma_f32_16x16x32_bf16 v[52:55], v[176:179], v[196:199], v[52:55]
	v_mfma_f32_16x16x32_bf16 v[48:51], v[184:187], v[196:199], v[48:51]
	v_mfma_f32_16x16x32_bf16 v[36:39], v[176:179], v[204:207], v[36:39]
	v_mfma_f32_16x16x32_bf16 v[32:35], v[184:187], v[204:207], v[32:35]
	v_mfma_f32_16x16x32_bf16 v[20:23], v[176:179], v[212:215], v[20:23]
	v_mfma_f32_16x16x32_bf16 v[16:19], v[184:187], v[212:215], v[16:19]
	v_mfma_f32_16x16x32_bf16 v[4:7], v[176:179], v[220:223], v[4:7]
	v_mfma_f32_16x16x32_bf16 v[0:3], v[184:187], v[220:223], v[0:3]
	s_setprio 0
	s_barrier
	s_add_i32 s78, 0, 0x18000
	v_add_u32_e32 v159, s78, v153
	s_add_i32 s79, 0, 0x1c000
	ds_read_b128 v[146:149], v159
	ds_read_b128 v[160:163], v159 offset:1024
	ds_read_b128 v[164:167], v159 offset:2048
	ds_read_b128 v[168:171], v159 offset:3072
	v_add_u32_e32 v159, s79, v153
	ds_read_b128 v[172:175], v159
	ds_read_b128 v[176:179], v159 offset:1024
	ds_read_b128 v[180:183], v159 offset:2048
	ds_read_b128 v[184:187], v159 offset:3072
	s_add_u32 s28, s36, 0xb0000
	s_addc_u32 s29, s37, 0
	v_lshl_add_u64 v[228:229], s[28:29], 0, v[130:131]
	ds_read_b128 v[188:191], v157 offset:32768
	ds_read_b128 v[196:199], v157 offset:33792
	ds_read_b128 v[200:203], v157 offset:34816
	ds_read_b128 v[204:207], v157 offset:35840
	ds_read_b128 v[208:211], v157 offset:36864
	ds_read_b128 v[212:215], v157 offset:37888
	ds_read_b128 v[216:219], v157 offset:38912
	ds_read_b128 v[220:223], v157 offset:39936
	s_mov_b32 m0, s44
	s_nop 0
	global_load_lds_dwordx4 v[224:225], off
	s_mov_b32 m0, s45
	s_nop 0
	global_load_lds_dwordx4 v[226:227], off
	s_mov_b32 m0, s50
	s_nop 0
	global_load_lds_dwordx4 v[228:229], off
	v_lshl_add_u64 v[228:229], s[28:29], 0, v[134:135]
	s_mov_b32 m0, s51
	s_nop 0
	global_load_lds_dwordx4 v[228:229], off
	s_waitcnt vmcnt(8)
	s_waitcnt lgkmcnt(0)
	s_barrier
	s_setprio 1
	s_waitcnt lgkmcnt(0)
	v_mfma_f32_16x16x32_bf16 v[124:127], v[146:149], v[188:191], v[124:127]
	v_mfma_f32_16x16x32_bf16 v[120:123], v[164:167], v[188:191], v[120:123]
	v_mfma_f32_16x16x32_bf16 v[108:111], v[146:149], v[200:203], v[108:111]
	v_mfma_f32_16x16x32_bf16 v[104:107], v[164:167], v[200:203], v[104:107]
	v_mfma_f32_16x16x32_bf16 v[92:95], v[146:149], v[208:211], v[92:95]
	v_mfma_f32_16x16x32_bf16 v[88:91], v[164:167], v[208:211], v[88:91]
	v_mfma_f32_16x16x32_bf16 v[76:79], v[146:149], v[216:219], v[76:79]
	v_mfma_f32_16x16x32_bf16 v[72:75], v[164:167], v[216:219], v[72:75]
	v_mfma_f32_16x16x32_bf16 v[124:127], v[160:163], v[196:199], v[124:127]
	v_mfma_f32_16x16x32_bf16 v[120:123], v[168:171], v[196:199], v[120:123]
	v_mfma_f32_16x16x32_bf16 v[108:111], v[160:163], v[204:207], v[108:111]
	v_mfma_f32_16x16x32_bf16 v[104:107], v[168:171], v[204:207], v[104:107]
	v_mfma_f32_16x16x32_bf16 v[92:95], v[160:163], v[212:215], v[92:95]
	v_mfma_f32_16x16x32_bf16 v[88:91], v[168:171], v[212:215], v[88:91]
	v_mfma_f32_16x16x32_bf16 v[76:79], v[160:163], v[220:223], v[76:79]
	v_mfma_f32_16x16x32_bf16 v[72:75], v[168:171], v[220:223], v[72:75]
	s_setprio 0
	s_setprio 1
	v_mfma_f32_16x16x32_bf16 v[116:119], v[172:175], v[188:191], v[116:119]
	v_mfma_f32_16x16x32_bf16 v[112:115], v[180:183], v[188:191], v[112:115]
	v_mfma_f32_16x16x32_bf16 v[100:103], v[172:175], v[200:203], v[100:103]
	v_mfma_f32_16x16x32_bf16 v[96:99], v[180:183], v[200:203], v[96:99]
	v_mfma_f32_16x16x32_bf16 v[84:87], v[172:175], v[208:211], v[84:87]
	v_mfma_f32_16x16x32_bf16 v[80:83], v[180:183], v[208:211], v[80:83]
	v_mfma_f32_16x16x32_bf16 v[68:71], v[172:175], v[216:219], v[68:71]
	v_mfma_f32_16x16x32_bf16 v[64:67], v[180:183], v[216:219], v[64:67]
	v_mfma_f32_16x16x32_bf16 v[116:119], v[176:179], v[196:199], v[116:119]
	v_mfma_f32_16x16x32_bf16 v[112:115], v[184:187], v[196:199], v[112:115]
	v_mfma_f32_16x16x32_bf16 v[100:103], v[176:179], v[204:207], v[100:103]
	v_mfma_f32_16x16x32_bf16 v[96:99], v[184:187], v[204:207], v[96:99]
	v_mfma_f32_16x16x32_bf16 v[84:87], v[176:179], v[212:215], v[84:87]
	v_mfma_f32_16x16x32_bf16 v[80:83], v[184:187], v[212:215], v[80:83]
	v_mfma_f32_16x16x32_bf16 v[68:71], v[176:179], v[220:223], v[68:71]
	v_mfma_f32_16x16x32_bf16 v[64:67], v[184:187], v[220:223], v[64:67]
	s_setprio 0
	s_barrier
	s_add_i32 s28, s78, s43
	v_lshl_add_u64 v[150:151], v[150:151], 0, s[22:23]
	s_mov_b32 m0, s28
	ds_read_b128 v[188:191], v157 offset:49152
	ds_read_b128 v[196:199], v157 offset:50176
	ds_read_b128 v[200:203], v157 offset:51200
	ds_read_b128 v[204:207], v157 offset:52224
	ds_read_b128 v[208:211], v157 offset:53248
	ds_read_b128 v[212:215], v157 offset:54272
	ds_read_b128 v[216:219], v157 offset:55296
	ds_read_b128 v[220:223], v157 offset:56320
	global_load_lds_dwordx4 v[150:151], off
	s_add_i32 m0, s28, 0x2000
	s_add_u32 s28, s34, 0xb0080
	v_lshl_add_u64 v[150:151], v[192:193], 0, s[22:23]
	s_addc_u32 s29, s35, 0
	s_add_i32 s34, s79, s43
	global_load_lds_dwordx4 v[150:151], off
	v_lshl_add_u64 v[150:151], s[28:29], 0, v[132:133]
	s_mov_b32 m0, s34
	s_nop 0
	global_load_lds_dwordx4 v[150:151], off
	v_lshl_add_u64 v[150:151], s[28:29], 0, v[136:137]
	s_add_i32 m0, s34, 0x2000
	s_nop 0
	global_load_lds_dwordx4 v[150:151], off
	s_waitcnt vmcnt(6)
	s_waitcnt lgkmcnt(0)
	s_barrier
	s_setprio 1
	s_waitcnt lgkmcnt(0)
	v_mfma_f32_16x16x32_bf16 v[60:63], v[146:149], v[188:191], v[60:63]
	v_mfma_f32_16x16x32_bf16 v[56:59], v[164:167], v[188:191], v[56:59]
	v_mfma_f32_16x16x32_bf16 v[44:47], v[146:149], v[200:203], v[44:47]
	v_mfma_f32_16x16x32_bf16 v[40:43], v[164:167], v[200:203], v[40:43]
	v_mfma_f32_16x16x32_bf16 v[28:31], v[146:149], v[208:211], v[28:31]
	v_mfma_f32_16x16x32_bf16 v[24:27], v[164:167], v[208:211], v[24:27]
	v_mfma_f32_16x16x32_bf16 v[12:15], v[146:149], v[216:219], v[12:15]
	v_mfma_f32_16x16x32_bf16 v[8:11], v[164:167], v[216:219], v[8:11]
	v_mfma_f32_16x16x32_bf16 v[60:63], v[160:163], v[196:199], v[60:63]
	v_mfma_f32_16x16x32_bf16 v[56:59], v[168:171], v[196:199], v[56:59]
	v_mfma_f32_16x16x32_bf16 v[44:47], v[160:163], v[204:207], v[44:47]
	v_mfma_f32_16x16x32_bf16 v[40:43], v[168:171], v[204:207], v[40:43]
	v_mfma_f32_16x16x32_bf16 v[28:31], v[160:163], v[212:215], v[28:31]
	v_mfma_f32_16x16x32_bf16 v[24:27], v[168:171], v[212:215], v[24:27]
	v_mfma_f32_16x16x32_bf16 v[12:15], v[160:163], v[220:223], v[12:15]
	v_mfma_f32_16x16x32_bf16 v[8:11], v[168:171], v[220:223], v[8:11]
	s_setprio 0
	s_setprio 1
	v_mfma_f32_16x16x32_bf16 v[52:55], v[172:175], v[188:191], v[52:55]
	v_mfma_f32_16x16x32_bf16 v[48:51], v[180:183], v[188:191], v[48:51]
	v_mfma_f32_16x16x32_bf16 v[36:39], v[172:175], v[200:203], v[36:39]
	v_mfma_f32_16x16x32_bf16 v[32:35], v[180:183], v[200:203], v[32:35]
	v_mfma_f32_16x16x32_bf16 v[20:23], v[172:175], v[208:211], v[20:23]
	v_mfma_f32_16x16x32_bf16 v[16:19], v[180:183], v[208:211], v[16:19]
	v_mfma_f32_16x16x32_bf16 v[4:7], v[172:175], v[216:219], v[4:7]
	v_mfma_f32_16x16x32_bf16 v[0:3], v[180:183], v[216:219], v[0:3]
	v_mfma_f32_16x16x32_bf16 v[52:55], v[176:179], v[196:199], v[52:55]
	v_mfma_f32_16x16x32_bf16 v[48:51], v[184:187], v[196:199], v[48:51]
	v_mfma_f32_16x16x32_bf16 v[36:39], v[176:179], v[204:207], v[36:39]
	v_mfma_f32_16x16x32_bf16 v[32:35], v[184:187], v[204:207], v[32:35]
	v_mfma_f32_16x16x32_bf16 v[20:23], v[176:179], v[212:215], v[20:23]
	v_mfma_f32_16x16x32_bf16 v[16:19], v[184:187], v[212:215], v[16:19]
	v_mfma_f32_16x16x32_bf16 v[4:7], v[176:179], v[220:223], v[4:7]
	v_mfma_f32_16x16x32_bf16 v[0:3], v[184:187], v[220:223], v[0:3]
	s_setprio 0
	s_barrier
	v_lshl_add_u64 v[224:225], v[224:225], 0, s[22:23]
	s_mov_b32 m0, s55
	s_nop 0
	global_load_lds_dwordx4 v[224:225], off
	v_lshl_add_u64 v[226:227], v[226:227], 0, s[22:23]
	s_mov_b32 m0, s58
	s_nop 0
	global_load_lds_dwordx4 v[226:227], off
	s_add_i32 s77, s77, 2
	s_add_u32 s72, s72, 0x100
	s_addc_u32 s73, s73, 0
	s_cmp_gt_u32 s77, 41
	s_mov_b64 s[28:29], s[30:31]
	s_cbranch_scc0 .LBB0_532
	s_and_b64 vcc, exec, s[24:25]
	s_cbranch_vccz .LBB0_535
	s_barrier

.LBB0_626:
	ds_read_b128 v[152:155], v157
	ds_read_b128 v[162:165], v157 offset:1024
	ds_read_b128 v[166:169], v157 offset:2048
	ds_read_b128 v[170:173], v157 offset:3072
	ds_read_b128 v[174:177], v158
	ds_read_b128 v[178:181], v158 offset:1024
	ds_read_b128 v[182:185], v158 offset:2048
	ds_read_b128 v[186:189], v158 offset:3072
	s_add_u32 s40, s38, 0xfffc0080
	s_addc_u32 s41, s39, -1
	s_cmp_eq_u32 s86, 12
	s_cselect_b32 s43, s1, s41
	s_cselect_b32 s42, s11, s40
	s_cselect_b32 s41, s12, s85
	s_cselect_b32 s40, s29, s31
	v_lshl_add_u64 v[224:225], s[38:39], 0, v[144:145]
	s_add_i32 m0, s58, 0xc000
	ds_read_b128 v[190:193], v159
	ds_read_b128 v[196:199], v159 offset:1024
	ds_read_b128 v[200:203], v159 offset:2048
	ds_read_b128 v[204:207], v159 offset:3072
	ds_read_b128 v[208:211], v159 offset:4096
	ds_read_b128 v[212:215], v159 offset:5120
	ds_read_b128 v[216:219], v159 offset:6144
	ds_read_b128 v[220:223], v159 offset:7168
	global_load_lds_dwordx4 v[224:225], off
	v_lshl_add_u64 v[224:225], s[38:39], 0, v[146:147]
	s_add_i32 m0, s58, 0xe000
	s_nop 0
	global_load_lds_dwordx4 v[224:225], off
	s_waitcnt vmcnt(8)
	s_waitcnt lgkmcnt(0)
	s_barrier
	s_setprio 1
	s_waitcnt lgkmcnt(0)
	v_mfma_f32_16x16x32_bf16 v[124:127], v[152:155], v[190:193], v[124:127]
	v_mfma_f32_16x16x32_bf16 v[120:123], v[166:169], v[190:193], v[120:123]
	v_mfma_f32_16x16x32_bf16 v[108:111], v[152:155], v[200:203], v[108:111]
	v_mfma_f32_16x16x32_bf16 v[104:107], v[166:169], v[200:203], v[104:107]
	v_mfma_f32_16x16x32_bf16 v[92:95], v[152:155], v[208:211], v[92:95]
	v_mfma_f32_16x16x32_bf16 v[88:91], v[166:169], v[208:211], v[88:91]
	v_mfma_f32_16x16x32_bf16 v[76:79], v[152:155], v[216:219], v[76:79]
	v_mfma_f32_16x16x32_bf16 v[72:75], v[166:169], v[216:219], v[72:75]
	v_mfma_f32_16x16x32_bf16 v[124:127], v[162:165], v[196:199], v[124:127]
	v_mfma_f32_16x16x32_bf16 v[120:123], v[170:173], v[196:199], v[120:123]
	v_mfma_f32_16x16x32_bf16 v[108:111], v[162:165], v[204:207], v[108:111]
	v_mfma_f32_16x16x32_bf16 v[104:107], v[170:173], v[204:207], v[104:107]
	v_mfma_f32_16x16x32_bf16 v[92:95], v[162:165], v[212:215], v[92:95]
	v_mfma_f32_16x16x32_bf16 v[88:91], v[170:173], v[212:215], v[88:91]
	v_mfma_f32_16x16x32_bf16 v[76:79], v[162:165], v[220:223], v[76:79]
	v_mfma_f32_16x16x32_bf16 v[72:75], v[170:173], v[220:223], v[72:75]
	s_setprio 0
	s_setprio 1
	v_mfma_f32_16x16x32_bf16 v[116:119], v[174:177], v[190:193], v[116:119]
	v_mfma_f32_16x16x32_bf16 v[112:115], v[182:185], v[190:193], v[112:115]
	v_mfma_f32_16x16x32_bf16 v[100:103], v[174:177], v[200:203], v[100:103]
	v_mfma_f32_16x16x32_bf16 v[96:99], v[182:185], v[200:203], v[96:99]
	v_mfma_f32_16x16x32_bf16 v[84:87], v[174:177], v[208:211], v[84:87]
	v_mfma_f32_16x16x32_bf16 v[80:83], v[182:185], v[208:211], v[80:83]
	v_mfma_f32_16x16x32_bf16 v[68:71], v[174:177], v[216:219], v[68:71]
	v_mfma_f32_16x16x32_bf16 v[64:67], v[182:185], v[216:219], v[64:67]
	v_mfma_f32_16x16x32_bf16 v[116:119], v[178:181], v[196:199], v[116:119]
	v_mfma_f32_16x16x32_bf16 v[112:115], v[186:189], v[196:199], v[112:115]
	v_mfma_f32_16x16x32_bf16 v[100:103], v[178:181], v[204:207], v[100:103]
	v_mfma_f32_16x16x32_bf16 v[96:99], v[186:189], v[204:207], v[96:99]
	v_mfma_f32_16x16x32_bf16 v[84:87], v[178:181], v[212:215], v[84:87]
	v_mfma_f32_16x16x32_bf16 v[80:83], v[186:189], v[212:215], v[80:83]
	v_mfma_f32_16x16x32_bf16 v[68:71], v[178:181], v[220:223], v[68:71]
	v_mfma_f32_16x16x32_bf16 v[64:67], v[186:189], v[220:223], v[64:67]
	s_setprio 0
	s_barrier
	s_add_i32 s87, s73, s55
	v_lshl_add_u64 v[224:225], s[40:41], 0, v[130:131]
	s_mov_b32 m0, s87
	ds_read_b128 v[190:193], v159 offset:16384
	ds_read_b128 v[196:199], v159 offset:17408
	ds_read_b128 v[200:203], v159 offset:18432
	ds_read_b128 v[204:207], v159 offset:19456
	ds_read_b128 v[208:211], v159 offset:20480
	ds_read_b128 v[212:215], v159 offset:21504
	ds_read_b128 v[216:219], v159 offset:22528
	ds_read_b128 v[220:223], v159 offset:23552
	global_load_lds_dwordx4 v[224:225], off
	s_add_i32 m0, s87, 0x2000
	s_add_u32 s88, s40, 0x40000
	v_lshl_add_u64 v[226:227], s[40:41], 0, v[134:135]
	s_addc_u32 s89, s41, 0
	s_add_i32 s87, s77, s55
	global_load_lds_dwordx4 v[226:227], off
	v_lshl_add_u64 v[228:229], s[88:89], 0, v[130:131]
	s_mov_b32 m0, s87
	v_lshl_add_u64 v[230:231], s[42:43], 0, v[132:133]
	global_load_lds_dwordx4 v[228:229], off
	v_lshl_add_u64 v[228:229], s[88:89], 0, v[134:135]
	s_add_i32 m0, s87, 0x2000
	s_nop 0
	global_load_lds_dwordx4 v[228:229], off
	v_lshl_add_u64 v[228:229], s[42:43], 0, v[128:129]
	s_waitcnt vmcnt(6)
	s_waitcnt lgkmcnt(0)
	s_barrier
	s_setprio 1
	s_waitcnt lgkmcnt(0)
	v_mfma_f32_16x16x32_bf16 v[60:63], v[152:155], v[190:193], v[60:63]
	v_mfma_f32_16x16x32_bf16 v[56:59], v[166:169], v[190:193], v[56:59]
	v_mfma_f32_16x16x32_bf16 v[44:47], v[152:155], v[200:203], v[44:47]
	v_mfma_f32_16x16x32_bf16 v[40:43], v[166:169], v[200:203], v[40:43]
	v_mfma_f32_16x16x32_bf16 v[28:31], v[152:155], v[208:211], v[28:31]
	v_mfma_f32_16x16x32_bf16 v[24:27], v[166:169], v[208:211], v[24:27]
	v_mfma_f32_16x16x32_bf16 v[12:15], v[152:155], v[216:219], v[12:15]
	v_mfma_f32_16x16x32_bf16 v[8:11], v[166:169], v[216:219], v[8:11]
	v_mfma_f32_16x16x32_bf16 v[60:63], v[162:165], v[196:199], v[60:63]
	v_mfma_f32_16x16x32_bf16 v[56:59], v[170:173], v[196:199], v[56:59]
	v_mfma_f32_16x16x32_bf16 v[44:47], v[162:165], v[204:207], v[44:47]
	v_mfma_f32_16x16x32_bf16 v[40:43], v[170:173], v[204:207], v[40:43]
	v_mfma_f32_16x16x32_bf16 v[28:31], v[162:165], v[212:215], v[28:31]
	v_mfma_f32_16x16x32_bf16 v[24:27], v[170:173], v[212:215], v[24:27]
	v_mfma_f32_16x16x32_bf16 v[12:15], v[162:165], v[220:223], v[12:15]
	v_mfma_f32_16x16x32_bf16 v[8:11], v[170:173], v[220:223], v[8:11]
	s_setprio 0
	s_setprio 1
	v_mfma_f32_16x16x32_bf16 v[52:55], v[174:177], v[190:193], v[52:55]
	v_mfma_f32_16x16x32_bf16 v[48:51], v[182:185], v[190:193], v[48:51]
	v_mfma_f32_16x16x32_bf16 v[36:39], v[174:177], v[200:203], v[36:39]
	v_mfma_f32_16x16x32_bf16 v[32:35], v[182:185], v[200:203], v[32:35]
	v_mfma_f32_16x16x32_bf16 v[20:23], v[174:177], v[208:211], v[20:23]
	v_mfma_f32_16x16x32_bf16 v[16:19], v[182:185], v[208:211], v[16:19]
	v_mfma_f32_16x16x32_bf16 v[4:7], v[174:177], v[216:219], v[4:7]
	v_mfma_f32_16x16x32_bf16 v[0:3], v[182:185], v[216:219], v[0:3]
	v_mfma_f32_16x16x32_bf16 v[52:55], v[178:181], v[196:199], v[52:55]
	v_mfma_f32_16x16x32_bf16 v[48:51], v[186:189], v[196:199], v[48:51]
	v_mfma_f32_16x16x32_bf16 v[36:39], v[178:181], v[204:207], v[36:39]
	v_mfma_f32_16x16x32_bf16 v[32:35], v[186:189], v[204:207], v[32:35]
	v_mfma_f32_16x16x32_bf16 v[20:23], v[178:181], v[212:215], v[20:23]
	v_mfma_f32_16x16x32_bf16 v[16:19], v[186:189], v[212:215], v[16:19]
	v_mfma_f32_16x16x32_bf16 v[4:7], v[178:181], v[220:223], v[4:7]
	v_mfma_f32_16x16x32_bf16 v[0:3], v[186:189], v[220:223], v[0:3]
	s_setprio 0
	s_barrier
	s_add_i32 s87, 0, 0x18000
	v_add_u32_e32 v136, s87, v141
	s_add_i32 s88, 0, 0x1c000
	ds_read_b128 v[152:155], v136
	ds_read_b128 v[162:165], v136 offset:1024
	ds_read_b128 v[166:169], v136 offset:2048
	ds_read_b128 v[170:173], v136 offset:3072
	v_add_u32_e32 v136, s88, v141
	ds_read_b128 v[174:177], v136
	ds_read_b128 v[178:181], v136 offset:1024
	ds_read_b128 v[182:185], v136 offset:2048
	ds_read_b128 v[186:189], v136 offset:3072
	s_add_u32 s42, s42, 0x40000
	s_addc_u32 s43, s43, 0
	v_lshl_add_u64 v[232:233], s[42:43], 0, v[128:129]
	ds_read_b128 v[190:193], v159 offset:32768
	ds_read_b128 v[196:199], v159 offset:33792
	ds_read_b128 v[200:203], v159 offset:34816
	ds_read_b128 v[204:207], v159 offset:35840
	ds_read_b128 v[208:211], v159 offset:36864
	ds_read_b128 v[212:215], v159 offset:37888
	ds_read_b128 v[216:219], v159 offset:38912
	ds_read_b128 v[220:223], v159 offset:39936
	s_mov_b32 m0, s58
	s_nop 0
	global_load_lds_dwordx4 v[228:229], off
	s_mov_b32 m0, s59
	s_nop 0
	global_load_lds_dwordx4 v[230:231], off
	s_mov_b32 m0, s60
	s_nop 0
	global_load_lds_dwordx4 v[232:233], off
	v_lshl_add_u64 v[232:233], s[42:43], 0, v[132:133]
	s_mov_b32 m0, s61
	s_nop 0
	global_load_lds_dwordx4 v[232:233], off
	s_waitcnt vmcnt(8)
	s_waitcnt lgkmcnt(0)
	s_barrier
	s_setprio 1
	s_waitcnt lgkmcnt(0)
	v_mfma_f32_16x16x32_bf16 v[124:127], v[152:155], v[190:193], v[124:127]
	v_mfma_f32_16x16x32_bf16 v[120:123], v[166:169], v[190:193], v[120:123]
	v_mfma_f32_16x16x32_bf16 v[108:111], v[152:155], v[200:203], v[108:111]
	v_mfma_f32_16x16x32_bf16 v[104:107], v[166:169], v[200:203], v[104:107]
	v_mfma_f32_16x16x32_bf16 v[92:95], v[152:155], v[208:211], v[92:95]
	v_mfma_f32_16x16x32_bf16 v[88:91], v[166:169], v[208:211], v[88:91]
	v_mfma_f32_16x16x32_bf16 v[76:79], v[152:155], v[216:219], v[76:79]
	v_mfma_f32_16x16x32_bf16 v[72:75], v[166:169], v[216:219], v[72:75]
	v_mfma_f32_16x16x32_bf16 v[124:127], v[162:165], v[196:199], v[124:127]
	v_mfma_f32_16x16x32_bf16 v[120:123], v[170:173], v[196:199], v[120:123]
	v_mfma_f32_16x16x32_bf16 v[108:111], v[162:165], v[204:207], v[108:111]
	v_mfma_f32_16x16x32_bf16 v[104:107], v[170:173], v[204:207], v[104:107]
	v_mfma_f32_16x16x32_bf16 v[92:95], v[162:165], v[212:215], v[92:95]
	v_mfma_f32_16x16x32_bf16 v[88:91], v[170:173], v[212:215], v[88:91]
	v_mfma_f32_16x16x32_bf16 v[76:79], v[162:165], v[220:223], v[76:79]
	v_mfma_f32_16x16x32_bf16 v[72:75], v[170:173], v[220:223], v[72:75]
	s_setprio 0
	s_setprio 1
	v_mfma_f32_16x16x32_bf16 v[116:119], v[174:177], v[190:193], v[116:119]
	v_mfma_f32_16x16x32_bf16 v[112:115], v[182:185], v[190:193], v[112:115]
	v_mfma_f32_16x16x32_bf16 v[100:103], v[174:177], v[200:203], v[100:103]
	v_mfma_f32_16x16x32_bf16 v[96:99], v[182:185], v[200:203], v[96:99]
	v_mfma_f32_16x16x32_bf16 v[84:87], v[174:177], v[208:211], v[84:87]
	v_mfma_f32_16x16x32_bf16 v[80:83], v[182:185], v[208:211], v[80:83]
	v_mfma_f32_16x16x32_bf16 v[68:71], v[174:177], v[216:219], v[68:71]
	v_mfma_f32_16x16x32_bf16 v[64:67], v[182:185], v[216:219], v[64:67]
	v_mfma_f32_16x16x32_bf16 v[116:119], v[178:181], v[196:199], v[116:119]
	v_mfma_f32_16x16x32_bf16 v[112:115], v[186:189], v[196:199], v[112:115]
	v_mfma_f32_16x16x32_bf16 v[100:103], v[178:181], v[204:207], v[100:103]
	v_mfma_f32_16x16x32_bf16 v[96:99], v[186:189], v[204:207], v[96:99]
	v_mfma_f32_16x16x32_bf16 v[84:87], v[178:181], v[212:215], v[84:87]
	v_mfma_f32_16x16x32_bf16 v[80:83], v[186:189], v[212:215], v[80:83]
	v_mfma_f32_16x16x32_bf16 v[68:71], v[178:181], v[220:223], v[68:71]
	v_mfma_f32_16x16x32_bf16 v[64:67], v[186:189], v[220:223], v[64:67]
	s_setprio 0
	s_barrier
	s_add_i32 s42, s87, s55
	v_lshl_add_u64 v[224:225], v[224:225], 0, s[24:25]
	s_mov_b32 m0, s42
	ds_read_b128 v[190:193], v159 offset:49152
	ds_read_b128 v[196:199], v159 offset:50176
	ds_read_b128 v[200:203], v159 offset:51200
	ds_read_b128 v[204:207], v159 offset:52224
	ds_read_b128 v[208:211], v159 offset:53248
	ds_read_b128 v[212:215], v159 offset:54272
	ds_read_b128 v[216:219], v159 offset:55296
	ds_read_b128 v[220:223], v159 offset:56320
	global_load_lds_dwordx4 v[224:225], off
	s_add_i32 m0, s42, 0x2000
	s_add_u32 s40, s40, 0x40080
	v_lshl_add_u64 v[224:225], v[226:227], 0, s[24:25]
	s_addc_u32 s41, s41, 0
	s_add_i32 s42, s88, s55
	global_load_lds_dwordx4 v[224:225], off
	v_lshl_add_u64 v[224:225], s[40:41], 0, v[130:131]
	s_mov_b32 m0, s42
	s_nop 0
	global_load_lds_dwordx4 v[224:225], off
	v_lshl_add_u64 v[224:225], s[40:41], 0, v[134:135]
	s_add_i32 m0, s42, 0x2000
	s_nop 0
	global_load_lds_dwordx4 v[224:225], off
	s_waitcnt vmcnt(6)
	s_waitcnt lgkmcnt(0)
	s_barrier
	s_setprio 1
	s_waitcnt lgkmcnt(0)
	v_mfma_f32_16x16x32_bf16 v[60:63], v[152:155], v[190:193], v[60:63]
	v_mfma_f32_16x16x32_bf16 v[56:59], v[166:169], v[190:193], v[56:59]
	v_mfma_f32_16x16x32_bf16 v[44:47], v[152:155], v[200:203], v[44:47]
	v_mfma_f32_16x16x32_bf16 v[40:43], v[166:169], v[200:203], v[40:43]
	v_mfma_f32_16x16x32_bf16 v[28:31], v[152:155], v[208:211], v[28:31]
	v_mfma_f32_16x16x32_bf16 v[24:27], v[166:169], v[208:211], v[24:27]
	v_mfma_f32_16x16x32_bf16 v[12:15], v[152:155], v[216:219], v[12:15]
	v_mfma_f32_16x16x32_bf16 v[8:11], v[166:169], v[216:219], v[8:11]
	v_mfma_f32_16x16x32_bf16 v[60:63], v[162:165], v[196:199], v[60:63]
	v_mfma_f32_16x16x32_bf16 v[56:59], v[170:173], v[196:199], v[56:59]
	v_mfma_f32_16x16x32_bf16 v[44:47], v[162:165], v[204:207], v[44:47]
	v_mfma_f32_16x16x32_bf16 v[40:43], v[170:173], v[204:207], v[40:43]
	v_mfma_f32_16x16x32_bf16 v[28:31], v[162:165], v[212:215], v[28:31]
	v_mfma_f32_16x16x32_bf16 v[24:27], v[170:173], v[212:215], v[24:27]
	v_mfma_f32_16x16x32_bf16 v[12:15], v[162:165], v[220:223], v[12:15]
	v_mfma_f32_16x16x32_bf16 v[8:11], v[170:173], v[220:223], v[8:11]
	s_setprio 0
	s_setprio 1
	v_mfma_f32_16x16x32_bf16 v[52:55], v[174:177], v[190:193], v[52:55]
	v_mfma_f32_16x16x32_bf16 v[48:51], v[182:185], v[190:193], v[48:51]
	v_mfma_f32_16x16x32_bf16 v[36:39], v[174:177], v[200:203], v[36:39]
	v_mfma_f32_16x16x32_bf16 v[32:35], v[182:185], v[200:203], v[32:35]
	v_mfma_f32_16x16x32_bf16 v[20:23], v[174:177], v[208:211], v[20:23]
	v_mfma_f32_16x16x32_bf16 v[16:19], v[182:185], v[208:211], v[16:19]
	v_mfma_f32_16x16x32_bf16 v[4:7], v[174:177], v[216:219], v[4:7]
	v_mfma_f32_16x16x32_bf16 v[0:3], v[182:185], v[216:219], v[0:3]
	v_mfma_f32_16x16x32_bf16 v[52:55], v[178:181], v[196:199], v[52:55]
	v_mfma_f32_16x16x32_bf16 v[48:51], v[186:189], v[196:199], v[48:51]
	v_mfma_f32_16x16x32_bf16 v[36:39], v[178:181], v[204:207], v[36:39]
	v_mfma_f32_16x16x32_bf16 v[32:35], v[186:189], v[204:207], v[32:35]
	v_mfma_f32_16x16x32_bf16 v[20:23], v[178:181], v[212:215], v[20:23]
	v_mfma_f32_16x16x32_bf16 v[16:19], v[186:189], v[212:215], v[16:19]
	v_mfma_f32_16x16x32_bf16 v[4:7], v[178:181], v[220:223], v[4:7]
	v_mfma_f32_16x16x32_bf16 v[0:3], v[186:189], v[220:223], v[0:3]
	s_setprio 0
	s_barrier
	v_lshl_add_u64 v[228:229], v[228:229], 0, s[24:25]
	s_mov_b32 m0, s70
	s_nop 0
	global_load_lds_dwordx4 v[228:229], off
	v_lshl_add_u64 v[230:231], v[230:231], 0, s[24:25]
	s_mov_b32 m0, s71
	s_nop 0
	global_load_lds_dwordx4 v[230:231], off
	s_add_i32 s86, s86, 2
	s_add_u32 s38, s38, 0x100
	s_addc_u32 s39, s39, 0
	s_add_u32 s31, s31, 0x100
	s_addc_u32 s85, s85, 0
	s_cmp_gt_u32 s86, 13
	s_cbranch_scc0 .LBB0_626
	s_and_b64 vcc, exec, s[26:27]
	s_cbranch_vccz .LBB0_629
	s_barrier

.LBB0_760:
	ds_read_b128 v[148:151], v144
	ds_read_b128 v[152:155], v144 offset:1024
	ds_read_b128 v[156:159], v144 offset:2048
	ds_read_b128 v[160:163], v144 offset:3072
	ds_read_b128 v[164:167], v145
	ds_read_b128 v[168:171], v145 offset:1024
	ds_read_b128 v[172:175], v145 offset:2048
	ds_read_b128 v[176:179], v145 offset:3072
	s_add_u32 s36, s34, 0x100
	s_addc_u32 s37, s35, 0
	s_cmp_eq_u32 s83, 4
	s_cselect_b32 s41, s29, s37
	s_cselect_b32 s40, s28, s36
	s_cselect_b32 s39, s31, s25
	s_cselect_b32 s38, s30, s13
	v_lshl_add_u64 v[192:193], s[34:35], 0, v[138:139]
	s_add_i32 m0, s58, 0xc000
	ds_read_b128 v[180:183], v146
	ds_read_b128 v[184:187], v146 offset:1024
	ds_read_b128 v[188:191], v146 offset:2048
	ds_read_b128 v[196:199], v146 offset:3072
	ds_read_b128 v[200:203], v146 offset:4096
	ds_read_b128 v[204:207], v146 offset:5120
	ds_read_b128 v[208:211], v146 offset:6144
	ds_read_b128 v[212:215], v146 offset:7168
	global_load_lds_dwordx4 v[192:193], off
	v_lshl_add_u64 v[192:193], s[34:35], 0, v[140:141]
	s_add_i32 m0, s58, 0xe000
	s_nop 0
	global_load_lds_dwordx4 v[192:193], off
	s_waitcnt vmcnt(8)
	s_waitcnt lgkmcnt(0)
	s_barrier
	s_setprio 1
	s_waitcnt lgkmcnt(0)
	v_mfma_f32_16x16x32_bf16 v[124:127], v[148:151], v[180:183], v[124:127]
	v_mfma_f32_16x16x32_bf16 v[120:123], v[156:159], v[180:183], v[120:123]
	v_mfma_f32_16x16x32_bf16 v[116:119], v[148:151], v[188:191], v[116:119]
	v_mfma_f32_16x16x32_bf16 v[112:115], v[156:159], v[188:191], v[112:115]
	v_mfma_f32_16x16x32_bf16 v[104:107], v[148:151], v[200:203], v[104:107]
	v_mfma_f32_16x16x32_bf16 v[96:99], v[156:159], v[200:203], v[96:99]
	v_mfma_f32_16x16x32_bf16 v[88:91], v[148:151], v[208:211], v[88:91]
	v_mfma_f32_16x16x32_bf16 v[80:83], v[156:159], v[208:211], v[80:83]
	v_mfma_f32_16x16x32_bf16 v[124:127], v[152:155], v[184:187], v[124:127]
	v_mfma_f32_16x16x32_bf16 v[120:123], v[160:163], v[184:187], v[120:123]
	v_mfma_f32_16x16x32_bf16 v[116:119], v[152:155], v[196:199], v[116:119]
	v_mfma_f32_16x16x32_bf16 v[112:115], v[160:163], v[196:199], v[112:115]
	v_mfma_f32_16x16x32_bf16 v[104:107], v[152:155], v[204:207], v[104:107]
	v_mfma_f32_16x16x32_bf16 v[96:99], v[160:163], v[204:207], v[96:99]
	v_mfma_f32_16x16x32_bf16 v[88:91], v[152:155], v[212:215], v[88:91]
	v_mfma_f32_16x16x32_bf16 v[80:83], v[160:163], v[212:215], v[80:83]
	s_setprio 0
	s_setprio 1
	v_mfma_f32_16x16x32_bf16 v[108:111], v[164:167], v[180:183], v[108:111]
	v_mfma_f32_16x16x32_bf16 v[100:103], v[172:175], v[180:183], v[100:103]
	v_mfma_f32_16x16x32_bf16 v[92:95], v[164:167], v[188:191], v[92:95]
	v_mfma_f32_16x16x32_bf16 v[84:87], v[172:175], v[188:191], v[84:87]
	v_mfma_f32_16x16x32_bf16 v[76:79], v[164:167], v[200:203], v[76:79]
	v_mfma_f32_16x16x32_bf16 v[72:75], v[172:175], v[200:203], v[72:75]
	v_mfma_f32_16x16x32_bf16 v[68:71], v[164:167], v[208:211], v[68:71]
	v_mfma_f32_16x16x32_bf16 v[64:67], v[172:175], v[208:211], v[64:67]
	v_mfma_f32_16x16x32_bf16 v[108:111], v[168:171], v[184:187], v[108:111]
	v_mfma_f32_16x16x32_bf16 v[100:103], v[176:179], v[184:187], v[100:103]
	v_mfma_f32_16x16x32_bf16 v[92:95], v[168:171], v[196:199], v[92:95]
	v_mfma_f32_16x16x32_bf16 v[84:87], v[176:179], v[196:199], v[84:87]
	v_mfma_f32_16x16x32_bf16 v[76:79], v[168:171], v[204:207], v[76:79]
	v_mfma_f32_16x16x32_bf16 v[72:75], v[176:179], v[204:207], v[72:75]
	v_mfma_f32_16x16x32_bf16 v[68:71], v[168:171], v[212:215], v[68:71]
	v_mfma_f32_16x16x32_bf16 v[64:67], v[176:179], v[212:215], v[64:67]
	s_setprio 0
	s_barrier
	s_add_i32 s34, s77, s51
	v_lshl_add_u64 v[192:193], s[38:39], 0, v[132:133]
	s_mov_b32 m0, s34
	ds_read_b128 v[180:183], v146 offset:16384
	ds_read_b128 v[184:187], v146 offset:17408
	ds_read_b128 v[188:191], v146 offset:18432
	ds_read_b128 v[196:199], v146 offset:19456
	ds_read_b128 v[200:203], v146 offset:20480
	ds_read_b128 v[204:207], v146 offset:21504
	ds_read_b128 v[208:211], v146 offset:22528
	ds_read_b128 v[212:215], v146 offset:23552
	global_load_lds_dwordx4 v[192:193], off
	s_add_i32 m0, s34, 0x2000
	s_add_u32 s34, s38, 0x20000
	v_lshl_add_u64 v[216:217], s[38:39], 0, v[128:129]
	s_addc_u32 s35, s39, 0
	s_add_i32 s84, s78, s51
	global_load_lds_dwordx4 v[216:217], off
	v_lshl_add_u64 v[218:219], s[34:35], 0, v[132:133]
	s_mov_b32 m0, s84
	v_lshl_add_u64 v[220:221], s[40:41], 0, v[130:131]
	global_load_lds_dwordx4 v[218:219], off
	v_lshl_add_u64 v[218:219], s[34:35], 0, v[128:129]
	s_add_i32 m0, s84, 0x2000
	s_nop 0
	global_load_lds_dwordx4 v[218:219], off
	v_lshl_add_u64 v[218:219], s[40:41], 0, v[134:135]
	s_waitcnt vmcnt(6)
	s_waitcnt lgkmcnt(0)
	s_barrier
	s_setprio 1
	s_waitcnt lgkmcnt(0)
	v_mfma_f32_16x16x32_bf16 v[60:63], v[148:151], v[180:183], v[60:63]
	v_mfma_f32_16x16x32_bf16 v[56:59], v[156:159], v[180:183], v[56:59]
	v_mfma_f32_16x16x32_bf16 v[52:55], v[148:151], v[188:191], v[52:55]
	v_mfma_f32_16x16x32_bf16 v[48:51], v[156:159], v[188:191], v[48:51]
	v_mfma_f32_16x16x32_bf16 v[40:43], v[148:151], v[200:203], v[40:43]
	v_mfma_f32_16x16x32_bf16 v[32:35], v[156:159], v[200:203], v[32:35]
	v_mfma_f32_16x16x32_bf16 v[24:27], v[148:151], v[208:211], v[24:27]
	v_mfma_f32_16x16x32_bf16 v[16:19], v[156:159], v[208:211], v[16:19]
	v_mfma_f32_16x16x32_bf16 v[60:63], v[152:155], v[184:187], v[60:63]
	v_mfma_f32_16x16x32_bf16 v[56:59], v[160:163], v[184:187], v[56:59]
	v_mfma_f32_16x16x32_bf16 v[52:55], v[152:155], v[196:199], v[52:55]
	v_mfma_f32_16x16x32_bf16 v[48:51], v[160:163], v[196:199], v[48:51]
	v_mfma_f32_16x16x32_bf16 v[40:43], v[152:155], v[204:207], v[40:43]
	v_mfma_f32_16x16x32_bf16 v[32:35], v[160:163], v[204:207], v[32:35]
	v_mfma_f32_16x16x32_bf16 v[24:27], v[152:155], v[212:215], v[24:27]
	v_mfma_f32_16x16x32_bf16 v[16:19], v[160:163], v[212:215], v[16:19]
	s_setprio 0
	s_setprio 1
	v_mfma_f32_16x16x32_bf16 v[44:47], v[164:167], v[180:183], v[44:47]
	v_mfma_f32_16x16x32_bf16 v[36:39], v[172:175], v[180:183], v[36:39]
	v_mfma_f32_16x16x32_bf16 v[28:31], v[164:167], v[188:191], v[28:31]
	v_mfma_f32_16x16x32_bf16 v[20:23], v[172:175], v[188:191], v[20:23]
	v_mfma_f32_16x16x32_bf16 v[12:15], v[164:167], v[200:203], v[12:15]
	v_mfma_f32_16x16x32_bf16 v[8:11], v[172:175], v[200:203], v[8:11]
	v_mfma_f32_16x16x32_bf16 v[4:7], v[164:167], v[208:211], v[4:7]
	v_mfma_f32_16x16x32_bf16 v[0:3], v[172:175], v[208:211], v[0:3]
	v_mfma_f32_16x16x32_bf16 v[44:47], v[168:171], v[184:187], v[44:47]
	v_mfma_f32_16x16x32_bf16 v[36:39], v[176:179], v[184:187], v[36:39]
	v_mfma_f32_16x16x32_bf16 v[28:31], v[168:171], v[196:199], v[28:31]
	v_mfma_f32_16x16x32_bf16 v[20:23], v[176:179], v[196:199], v[20:23]
	v_mfma_f32_16x16x32_bf16 v[12:15], v[168:171], v[204:207], v[12:15]
	v_mfma_f32_16x16x32_bf16 v[8:11], v[176:179], v[204:207], v[8:11]
	v_mfma_f32_16x16x32_bf16 v[4:7], v[168:171], v[212:215], v[4:7]
	v_mfma_f32_16x16x32_bf16 v[0:3], v[176:179], v[212:215], v[0:3]
	s_setprio 0
	s_barrier
	s_add_i32 s84, 0, 0x18000
	v_add_u32_e32 v147, s84, v143
	s_add_i32 s85, 0, 0x1c000
	ds_read_b128 v[148:151], v147
	ds_read_b128 v[152:155], v147 offset:1024
	ds_read_b128 v[156:159], v147 offset:2048
	ds_read_b128 v[160:163], v147 offset:3072
	v_add_u32_e32 v147, s85, v143
	ds_read_b128 v[164:167], v147
	ds_read_b128 v[168:171], v147 offset:1024
	ds_read_b128 v[172:175], v147 offset:2048
	ds_read_b128 v[176:179], v147 offset:3072
	s_add_u32 s34, s40, 0x30000
	s_addc_u32 s35, s41, 0
	v_lshl_add_u64 v[222:223], s[34:35], 0, v[134:135]
	ds_read_b128 v[180:183], v146 offset:32768
	ds_read_b128 v[184:187], v146 offset:33792
	ds_read_b128 v[188:191], v146 offset:34816
	ds_read_b128 v[196:199], v146 offset:35840
	ds_read_b128 v[200:203], v146 offset:36864
	ds_read_b128 v[204:207], v146 offset:37888
	ds_read_b128 v[208:211], v146 offset:38912
	ds_read_b128 v[212:215], v146 offset:39936
	s_mov_b32 m0, s58
	s_nop 0
	global_load_lds_dwordx4 v[218:219], off
	s_mov_b32 m0, s59
	s_nop 0
	global_load_lds_dwordx4 v[220:221], off
	s_mov_b32 m0, s60
	s_nop 0
	global_load_lds_dwordx4 v[222:223], off
	v_lshl_add_u64 v[222:223], s[34:35], 0, v[130:131]
	s_mov_b32 m0, s61
	s_nop 0
	global_load_lds_dwordx4 v[222:223], off
	s_waitcnt vmcnt(8)
	s_waitcnt lgkmcnt(0)
	s_barrier
	s_setprio 1
	s_waitcnt lgkmcnt(0)
	v_mfma_f32_16x16x32_bf16 v[124:127], v[148:151], v[180:183], v[124:127]
	v_mfma_f32_16x16x32_bf16 v[120:123], v[156:159], v[180:183], v[120:123]
	v_mfma_f32_16x16x32_bf16 v[116:119], v[148:151], v[188:191], v[116:119]
	v_mfma_f32_16x16x32_bf16 v[112:115], v[156:159], v[188:191], v[112:115]
	v_mfma_f32_16x16x32_bf16 v[104:107], v[148:151], v[200:203], v[104:107]
	v_mfma_f32_16x16x32_bf16 v[96:99], v[156:159], v[200:203], v[96:99]
	v_mfma_f32_16x16x32_bf16 v[88:91], v[148:151], v[208:211], v[88:91]
	v_mfma_f32_16x16x32_bf16 v[80:83], v[156:159], v[208:211], v[80:83]
	v_mfma_f32_16x16x32_bf16 v[124:127], v[152:155], v[184:187], v[124:127]
	v_mfma_f32_16x16x32_bf16 v[120:123], v[160:163], v[184:187], v[120:123]
	v_mfma_f32_16x16x32_bf16 v[116:119], v[152:155], v[196:199], v[116:119]
	v_mfma_f32_16x16x32_bf16 v[112:115], v[160:163], v[196:199], v[112:115]
	v_mfma_f32_16x16x32_bf16 v[104:107], v[152:155], v[204:207], v[104:107]
	v_mfma_f32_16x16x32_bf16 v[96:99], v[160:163], v[204:207], v[96:99]
	v_mfma_f32_16x16x32_bf16 v[88:91], v[152:155], v[212:215], v[88:91]
	v_mfma_f32_16x16x32_bf16 v[80:83], v[160:163], v[212:215], v[80:83]
	s_setprio 0
	s_setprio 1
	v_mfma_f32_16x16x32_bf16 v[108:111], v[164:167], v[180:183], v[108:111]
	v_mfma_f32_16x16x32_bf16 v[100:103], v[172:175], v[180:183], v[100:103]
	v_mfma_f32_16x16x32_bf16 v[92:95], v[164:167], v[188:191], v[92:95]
	v_mfma_f32_16x16x32_bf16 v[84:87], v[172:175], v[188:191], v[84:87]
	v_mfma_f32_16x16x32_bf16 v[76:79], v[164:167], v[200:203], v[76:79]
	v_mfma_f32_16x16x32_bf16 v[72:75], v[172:175], v[200:203], v[72:75]
	v_mfma_f32_16x16x32_bf16 v[68:71], v[164:167], v[208:211], v[68:71]
	v_mfma_f32_16x16x32_bf16 v[64:67], v[172:175], v[208:211], v[64:67]
	v_mfma_f32_16x16x32_bf16 v[108:111], v[168:171], v[184:187], v[108:111]
	v_mfma_f32_16x16x32_bf16 v[100:103], v[176:179], v[184:187], v[100:103]
	v_mfma_f32_16x16x32_bf16 v[92:95], v[168:171], v[196:199], v[92:95]
	v_mfma_f32_16x16x32_bf16 v[84:87], v[176:179], v[196:199], v[84:87]
	v_mfma_f32_16x16x32_bf16 v[76:79], v[168:171], v[204:207], v[76:79]
	v_mfma_f32_16x16x32_bf16 v[72:75], v[176:179], v[204:207], v[72:75]
	v_mfma_f32_16x16x32_bf16 v[68:71], v[168:171], v[212:215], v[68:71]
	v_mfma_f32_16x16x32_bf16 v[64:67], v[176:179], v[212:215], v[64:67]
	s_setprio 0
	s_barrier
	s_add_i32 s34, s84, s51
	v_lshl_add_u64 v[192:193], v[192:193], 0, s[10:11]
	s_mov_b32 m0, s34
	ds_read_b128 v[180:183], v146 offset:49152
	ds_read_b128 v[184:187], v146 offset:50176
	ds_read_b128 v[188:191], v146 offset:51200
	ds_read_b128 v[196:199], v146 offset:52224
	ds_read_b128 v[200:203], v146 offset:53248
	ds_read_b128 v[204:207], v146 offset:54272
	ds_read_b128 v[208:211], v146 offset:55296
	ds_read_b128 v[212:215], v146 offset:56320
	global_load_lds_dwordx4 v[192:193], off
	s_add_i32 m0, s34, 0x2000
	s_add_u32 s34, s38, 0x20080
	v_lshl_add_u64 v[192:193], v[216:217], 0, s[10:11]
	s_addc_u32 s35, s39, 0
	s_add_i32 s38, s85, s51
	global_load_lds_dwordx4 v[192:193], off
	v_lshl_add_u64 v[192:193], s[34:35], 0, v[132:133]
	s_mov_b32 m0, s38
	s_nop 0
	global_load_lds_dwordx4 v[192:193], off
	v_lshl_add_u64 v[192:193], s[34:35], 0, v[128:129]
	s_add_i32 m0, s38, 0x2000
	s_nop 0
	global_load_lds_dwordx4 v[192:193], off
	s_waitcnt vmcnt(6)
	s_waitcnt lgkmcnt(0)
	s_barrier
	s_setprio 1
	s_waitcnt lgkmcnt(0)
	v_mfma_f32_16x16x32_bf16 v[60:63], v[148:151], v[180:183], v[60:63]
	v_mfma_f32_16x16x32_bf16 v[56:59], v[156:159], v[180:183], v[56:59]
	v_mfma_f32_16x16x32_bf16 v[52:55], v[148:151], v[188:191], v[52:55]
	v_mfma_f32_16x16x32_bf16 v[48:51], v[156:159], v[188:191], v[48:51]
	v_mfma_f32_16x16x32_bf16 v[40:43], v[148:151], v[200:203], v[40:43]
	v_mfma_f32_16x16x32_bf16 v[32:35], v[156:159], v[200:203], v[32:35]
	v_mfma_f32_16x16x32_bf16 v[24:27], v[148:151], v[208:211], v[24:27]
	v_mfma_f32_16x16x32_bf16 v[16:19], v[156:159], v[208:211], v[16:19]
	v_mfma_f32_16x16x32_bf16 v[60:63], v[152:155], v[184:187], v[60:63]
	v_mfma_f32_16x16x32_bf16 v[56:59], v[160:163], v[184:187], v[56:59]
	v_mfma_f32_16x16x32_bf16 v[52:55], v[152:155], v[196:199], v[52:55]
	v_mfma_f32_16x16x32_bf16 v[48:51], v[160:163], v[196:199], v[48:51]
	v_mfma_f32_16x16x32_bf16 v[40:43], v[152:155], v[204:207], v[40:43]
	v_mfma_f32_16x16x32_bf16 v[32:35], v[160:163], v[204:207], v[32:35]
	v_mfma_f32_16x16x32_bf16 v[24:27], v[152:155], v[212:215], v[24:27]
	v_mfma_f32_16x16x32_bf16 v[16:19], v[160:163], v[212:215], v[16:19]
	s_setprio 0
	s_setprio 1
	v_mfma_f32_16x16x32_bf16 v[44:47], v[164:167], v[180:183], v[44:47]
	v_mfma_f32_16x16x32_bf16 v[36:39], v[172:175], v[180:183], v[36:39]
	v_mfma_f32_16x16x32_bf16 v[28:31], v[164:167], v[188:191], v[28:31]
	v_mfma_f32_16x16x32_bf16 v[20:23], v[172:175], v[188:191], v[20:23]
	v_mfma_f32_16x16x32_bf16 v[12:15], v[164:167], v[200:203], v[12:15]
	v_mfma_f32_16x16x32_bf16 v[8:11], v[172:175], v[200:203], v[8:11]
	v_mfma_f32_16x16x32_bf16 v[4:7], v[164:167], v[208:211], v[4:7]
	v_mfma_f32_16x16x32_bf16 v[0:3], v[172:175], v[208:211], v[0:3]
	v_mfma_f32_16x16x32_bf16 v[44:47], v[168:171], v[184:187], v[44:47]
	v_mfma_f32_16x16x32_bf16 v[36:39], v[176:179], v[184:187], v[36:39]
	v_mfma_f32_16x16x32_bf16 v[28:31], v[168:171], v[196:199], v[28:31]
	v_mfma_f32_16x16x32_bf16 v[20:23], v[176:179], v[196:199], v[20:23]
	v_mfma_f32_16x16x32_bf16 v[12:15], v[168:171], v[204:207], v[12:15]
	v_mfma_f32_16x16x32_bf16 v[8:11], v[176:179], v[204:207], v[8:11]
	v_mfma_f32_16x16x32_bf16 v[4:7], v[168:171], v[212:215], v[4:7]
	v_mfma_f32_16x16x32_bf16 v[0:3], v[176:179], v[212:215], v[0:3]
	s_setprio 0
	s_barrier
	v_lshl_add_u64 v[218:219], v[218:219], 0, s[10:11]
	s_mov_b32 m0, s71
	s_nop 0
	global_load_lds_dwordx4 v[218:219], off
	v_lshl_add_u64 v[220:221], v[220:221], 0, s[10:11]
	s_mov_b32 m0, s72
	s_nop 0
	global_load_lds_dwordx4 v[220:221], off
	s_add_i32 s83, s83, 2
	s_add_u32 s13, s13, 0x100
	s_addc_u32 s25, s25, 0
	s_cmp_gt_u32 s83, 5
	s_mov_b64 s[34:35], s[36:37]
	s_cbranch_scc0 .LBB0_760
	s_and_b64 vcc, exec, s[16:17]
	s_cbranch_vccz .LBB0_763
	s_barrier

.LBB0_786:
	ds_read_b128 v[144:147], v153
	ds_read_b128 v[158:161], v153 offset:1024
	ds_read_b128 v[162:165], v153 offset:2048
	ds_read_b128 v[166:169], v153 offset:3072
	ds_read_b128 v[170:173], v154
	ds_read_b128 v[174:177], v154 offset:1024
	ds_read_b128 v[178:181], v154 offset:2048
	ds_read_b128 v[182:185], v154 offset:3072
	s_add_u32 s34, s30, 0xfffc0080
	s_addc_u32 s35, s31, -1
	s_cmp_eq_u32 s82, 12
	s_cselect_b32 s37, s25, s35
	s_cselect_b32 s36, s78, s34
	s_cselect_b32 s35, s23, s81
	s_cselect_b32 s34, s79, s80
	v_lshl_add_u64 v[148:149], s[30:31], 0, v[136:137]
	s_add_i32 m0, s50, 0xc000
	ds_read_b128 v[186:189], v155
	ds_read_b128 v[190:193], v155 offset:1024
	ds_read_b128 v[196:199], v155 offset:2048
	ds_read_b128 v[200:203], v155 offset:3072
	ds_read_b128 v[204:207], v155 offset:4096
	ds_read_b128 v[208:211], v155 offset:5120
	ds_read_b128 v[212:215], v155 offset:6144
	ds_read_b128 v[216:219], v155 offset:7168
	global_load_lds_dwordx4 v[148:149], off
	v_lshl_add_u64 v[148:149], s[30:31], 0, v[138:139]
	s_add_i32 m0, s50, 0xe000
	s_nop 0
	global_load_lds_dwordx4 v[148:149], off
	s_waitcnt vmcnt(8)
	s_waitcnt lgkmcnt(0)
	s_barrier
	s_setprio 1
	s_waitcnt lgkmcnt(0)
	v_mfma_f32_16x16x32_bf16 v[124:127], v[144:147], v[186:189], v[124:127]
	v_mfma_f32_16x16x32_bf16 v[120:123], v[162:165], v[186:189], v[120:123]
	v_mfma_f32_16x16x32_bf16 v[108:111], v[144:147], v[196:199], v[108:111]
	v_mfma_f32_16x16x32_bf16 v[104:107], v[162:165], v[196:199], v[104:107]
	v_mfma_f32_16x16x32_bf16 v[92:95], v[144:147], v[204:207], v[92:95]
	v_mfma_f32_16x16x32_bf16 v[88:91], v[162:165], v[204:207], v[88:91]
	v_mfma_f32_16x16x32_bf16 v[76:79], v[144:147], v[212:215], v[76:79]
	v_mfma_f32_16x16x32_bf16 v[72:75], v[162:165], v[212:215], v[72:75]
	v_mfma_f32_16x16x32_bf16 v[124:127], v[158:161], v[190:193], v[124:127]
	v_mfma_f32_16x16x32_bf16 v[120:123], v[166:169], v[190:193], v[120:123]
	v_mfma_f32_16x16x32_bf16 v[108:111], v[158:161], v[200:203], v[108:111]
	v_mfma_f32_16x16x32_bf16 v[104:107], v[166:169], v[200:203], v[104:107]
	v_mfma_f32_16x16x32_bf16 v[92:95], v[158:161], v[208:211], v[92:95]
	v_mfma_f32_16x16x32_bf16 v[88:91], v[166:169], v[208:211], v[88:91]
	v_mfma_f32_16x16x32_bf16 v[76:79], v[158:161], v[216:219], v[76:79]
	v_mfma_f32_16x16x32_bf16 v[72:75], v[166:169], v[216:219], v[72:75]
	s_setprio 0
	s_setprio 1
	v_mfma_f32_16x16x32_bf16 v[116:119], v[170:173], v[186:189], v[116:119]
	v_mfma_f32_16x16x32_bf16 v[112:115], v[178:181], v[186:189], v[112:115]
	v_mfma_f32_16x16x32_bf16 v[100:103], v[170:173], v[196:199], v[100:103]
	v_mfma_f32_16x16x32_bf16 v[96:99], v[178:181], v[196:199], v[96:99]
	v_mfma_f32_16x16x32_bf16 v[84:87], v[170:173], v[204:207], v[84:87]
	v_mfma_f32_16x16x32_bf16 v[80:83], v[178:181], v[204:207], v[80:83]
	v_mfma_f32_16x16x32_bf16 v[68:71], v[170:173], v[212:215], v[68:71]
	v_mfma_f32_16x16x32_bf16 v[64:67], v[178:181], v[212:215], v[64:67]
	v_mfma_f32_16x16x32_bf16 v[116:119], v[174:177], v[190:193], v[116:119]
	v_mfma_f32_16x16x32_bf16 v[112:115], v[182:185], v[190:193], v[112:115]
	v_mfma_f32_16x16x32_bf16 v[100:103], v[174:177], v[200:203], v[100:103]
	v_mfma_f32_16x16x32_bf16 v[96:99], v[182:185], v[200:203], v[96:99]
	v_mfma_f32_16x16x32_bf16 v[84:87], v[174:177], v[208:211], v[84:87]
	v_mfma_f32_16x16x32_bf16 v[80:83], v[182:185], v[208:211], v[80:83]
	v_mfma_f32_16x16x32_bf16 v[68:71], v[174:177], v[216:219], v[68:71]
	v_mfma_f32_16x16x32_bf16 v[64:67], v[182:185], v[216:219], v[64:67]
	s_setprio 0
	s_barrier
	s_add_i32 s83, s70, s45
	v_lshl_add_u64 v[148:149], s[34:35], 0, v[130:131]
	s_mov_b32 m0, s83
	ds_read_b128 v[186:189], v155 offset:16384
	ds_read_b128 v[190:193], v155 offset:17408
	ds_read_b128 v[196:199], v155 offset:18432
	ds_read_b128 v[200:203], v155 offset:19456
	ds_read_b128 v[204:207], v155 offset:20480
	ds_read_b128 v[208:211], v155 offset:21504
	ds_read_b128 v[212:215], v155 offset:22528
	ds_read_b128 v[216:219], v155 offset:23552
	global_load_lds_dwordx4 v[148:149], off
	s_add_i32 m0, s83, 0x2000
	s_add_u32 s84, s34, 0x40000
	v_lshl_add_u64 v[220:221], s[34:35], 0, v[134:135]
	s_addc_u32 s85, s35, 0
	s_add_i32 s83, s71, s45
	global_load_lds_dwordx4 v[220:221], off
	v_lshl_add_u64 v[222:223], s[84:85], 0, v[130:131]
	s_mov_b32 m0, s83
	v_lshl_add_u64 v[224:225], s[36:37], 0, v[132:133]
	global_load_lds_dwordx4 v[222:223], off
	v_lshl_add_u64 v[222:223], s[84:85], 0, v[134:135]
	s_add_i32 m0, s83, 0x2000
	s_nop 0
	global_load_lds_dwordx4 v[222:223], off
	v_lshl_add_u64 v[222:223], s[36:37], 0, v[128:129]
	s_waitcnt vmcnt(6)
	s_waitcnt lgkmcnt(0)
	s_barrier
	s_setprio 1
	s_waitcnt lgkmcnt(0)
	v_mfma_f32_16x16x32_bf16 v[60:63], v[144:147], v[186:189], v[60:63]
	v_mfma_f32_16x16x32_bf16 v[56:59], v[162:165], v[186:189], v[56:59]
	v_mfma_f32_16x16x32_bf16 v[44:47], v[144:147], v[196:199], v[44:47]
	v_mfma_f32_16x16x32_bf16 v[40:43], v[162:165], v[196:199], v[40:43]
	v_mfma_f32_16x16x32_bf16 v[28:31], v[144:147], v[204:207], v[28:31]
	v_mfma_f32_16x16x32_bf16 v[24:27], v[162:165], v[204:207], v[24:27]
	v_mfma_f32_16x16x32_bf16 v[12:15], v[144:147], v[212:215], v[12:15]
	v_mfma_f32_16x16x32_bf16 v[8:11], v[162:165], v[212:215], v[8:11]
	v_mfma_f32_16x16x32_bf16 v[60:63], v[158:161], v[190:193], v[60:63]
	v_mfma_f32_16x16x32_bf16 v[56:59], v[166:169], v[190:193], v[56:59]
	v_mfma_f32_16x16x32_bf16 v[44:47], v[158:161], v[200:203], v[44:47]
	v_mfma_f32_16x16x32_bf16 v[40:43], v[166:169], v[200:203], v[40:43]
	v_mfma_f32_16x16x32_bf16 v[28:31], v[158:161], v[208:211], v[28:31]
	v_mfma_f32_16x16x32_bf16 v[24:27], v[166:169], v[208:211], v[24:27]
	v_mfma_f32_16x16x32_bf16 v[12:15], v[158:161], v[216:219], v[12:15]
	v_mfma_f32_16x16x32_bf16 v[8:11], v[166:169], v[216:219], v[8:11]
	s_setprio 0
	s_setprio 1
	v_mfma_f32_16x16x32_bf16 v[52:55], v[170:173], v[186:189], v[52:55]
	v_mfma_f32_16x16x32_bf16 v[48:51], v[178:181], v[186:189], v[48:51]
	v_mfma_f32_16x16x32_bf16 v[36:39], v[170:173], v[196:199], v[36:39]
	v_mfma_f32_16x16x32_bf16 v[32:35], v[178:181], v[196:199], v[32:35]
	v_mfma_f32_16x16x32_bf16 v[20:23], v[170:173], v[204:207], v[20:23]
	v_mfma_f32_16x16x32_bf16 v[16:19], v[178:181], v[204:207], v[16:19]
	v_mfma_f32_16x16x32_bf16 v[4:7], v[170:173], v[212:215], v[4:7]
	v_mfma_f32_16x16x32_bf16 v[0:3], v[178:181], v[212:215], v[0:3]
	v_mfma_f32_16x16x32_bf16 v[52:55], v[174:177], v[190:193], v[52:55]
	v_mfma_f32_16x16x32_bf16 v[48:51], v[182:185], v[190:193], v[48:51]
	v_mfma_f32_16x16x32_bf16 v[36:39], v[174:177], v[200:203], v[36:39]
	v_mfma_f32_16x16x32_bf16 v[32:35], v[182:185], v[200:203], v[32:35]
	v_mfma_f32_16x16x32_bf16 v[20:23], v[174:177], v[208:211], v[20:23]
	v_mfma_f32_16x16x32_bf16 v[16:19], v[182:185], v[208:211], v[16:19]
	v_mfma_f32_16x16x32_bf16 v[4:7], v[174:177], v[216:219], v[4:7]
	v_mfma_f32_16x16x32_bf16 v[0:3], v[182:185], v[216:219], v[0:3]
	s_setprio 0
	s_barrier
	s_add_i32 s83, 0, 0x18000
	v_add_u32_e32 v157, s83, v151
	s_add_i32 s84, 0, 0x1c000
	ds_read_b128 v[144:147], v157
	ds_read_b128 v[158:161], v157 offset:1024
	ds_read_b128 v[162:165], v157 offset:2048
	ds_read_b128 v[166:169], v157 offset:3072
	v_add_u32_e32 v157, s84, v151
	ds_read_b128 v[170:173], v157
	ds_read_b128 v[174:177], v157 offset:1024
	ds_read_b128 v[178:181], v157 offset:2048
	ds_read_b128 v[182:185], v157 offset:3072
	s_add_u32 s36, s36, 0x40000
	s_addc_u32 s37, s37, 0
	v_lshl_add_u64 v[226:227], s[36:37], 0, v[128:129]
	ds_read_b128 v[186:189], v155 offset:32768
	ds_read_b128 v[190:193], v155 offset:33792
	ds_read_b128 v[196:199], v155 offset:34816
	ds_read_b128 v[200:203], v155 offset:35840
	ds_read_b128 v[204:207], v155 offset:36864
	ds_read_b128 v[208:211], v155 offset:37888
	ds_read_b128 v[212:215], v155 offset:38912
	ds_read_b128 v[216:219], v155 offset:39936
	s_mov_b32 m0, s50
	s_nop 0
	global_load_lds_dwordx4 v[222:223], off
	s_mov_b32 m0, s51
	s_nop 0
	global_load_lds_dwordx4 v[224:225], off
	s_mov_b32 m0, s58
	s_nop 0
	global_load_lds_dwordx4 v[226:227], off
	v_lshl_add_u64 v[226:227], s[36:37], 0, v[132:133]
	s_mov_b32 m0, s59
	s_nop 0
	global_load_lds_dwordx4 v[226:227], off
	s_waitcnt vmcnt(8)
	s_waitcnt lgkmcnt(0)
	s_barrier
	s_setprio 1
	s_waitcnt lgkmcnt(0)
	v_mfma_f32_16x16x32_bf16 v[124:127], v[144:147], v[186:189], v[124:127]
	v_mfma_f32_16x16x32_bf16 v[120:123], v[162:165], v[186:189], v[120:123]
	v_mfma_f32_16x16x32_bf16 v[108:111], v[144:147], v[196:199], v[108:111]
	v_mfma_f32_16x16x32_bf16 v[104:107], v[162:165], v[196:199], v[104:107]
	v_mfma_f32_16x16x32_bf16 v[92:95], v[144:147], v[204:207], v[92:95]
	v_mfma_f32_16x16x32_bf16 v[88:91], v[162:165], v[204:207], v[88:91]
	v_mfma_f32_16x16x32_bf16 v[76:79], v[144:147], v[212:215], v[76:79]
	v_mfma_f32_16x16x32_bf16 v[72:75], v[162:165], v[212:215], v[72:75]
	v_mfma_f32_16x16x32_bf16 v[124:127], v[158:161], v[190:193], v[124:127]
	v_mfma_f32_16x16x32_bf16 v[120:123], v[166:169], v[190:193], v[120:123]
	v_mfma_f32_16x16x32_bf16 v[108:111], v[158:161], v[200:203], v[108:111]
	v_mfma_f32_16x16x32_bf16 v[104:107], v[166:169], v[200:203], v[104:107]
	v_mfma_f32_16x16x32_bf16 v[92:95], v[158:161], v[208:211], v[92:95]
	v_mfma_f32_16x16x32_bf16 v[88:91], v[166:169], v[208:211], v[88:91]
	v_mfma_f32_16x16x32_bf16 v[76:79], v[158:161], v[216:219], v[76:79]
	v_mfma_f32_16x16x32_bf16 v[72:75], v[166:169], v[216:219], v[72:75]
	s_setprio 0
	s_setprio 1
	v_mfma_f32_16x16x32_bf16 v[116:119], v[170:173], v[186:189], v[116:119]
	v_mfma_f32_16x16x32_bf16 v[112:115], v[178:181], v[186:189], v[112:115]
	v_mfma_f32_16x16x32_bf16 v[100:103], v[170:173], v[196:199], v[100:103]
	v_mfma_f32_16x16x32_bf16 v[96:99], v[178:181], v[196:199], v[96:99]
	v_mfma_f32_16x16x32_bf16 v[84:87], v[170:173], v[204:207], v[84:87]
	v_mfma_f32_16x16x32_bf16 v[80:83], v[178:181], v[204:207], v[80:83]
	v_mfma_f32_16x16x32_bf16 v[68:71], v[170:173], v[212:215], v[68:71]
	v_mfma_f32_16x16x32_bf16 v[64:67], v[178:181], v[212:215], v[64:67]
	v_mfma_f32_16x16x32_bf16 v[116:119], v[174:177], v[190:193], v[116:119]
	v_mfma_f32_16x16x32_bf16 v[112:115], v[182:185], v[190:193], v[112:115]
	v_mfma_f32_16x16x32_bf16 v[100:103], v[174:177], v[200:203], v[100:103]
	v_mfma_f32_16x16x32_bf16 v[96:99], v[182:185], v[200:203], v[96:99]
	v_mfma_f32_16x16x32_bf16 v[84:87], v[174:177], v[208:211], v[84:87]
	v_mfma_f32_16x16x32_bf16 v[80:83], v[182:185], v[208:211], v[80:83]
	v_mfma_f32_16x16x32_bf16 v[68:71], v[174:177], v[216:219], v[68:71]
	v_mfma_f32_16x16x32_bf16 v[64:67], v[182:185], v[216:219], v[64:67]
	s_setprio 0
	s_barrier
	s_add_i32 s36, s83, s45
	v_lshl_add_u64 v[148:149], v[148:149], 0, s[18:19]
	s_mov_b32 m0, s36
	ds_read_b128 v[186:189], v155 offset:49152
	ds_read_b128 v[190:193], v155 offset:50176
	ds_read_b128 v[196:199], v155 offset:51200
	ds_read_b128 v[200:203], v155 offset:52224
	ds_read_b128 v[204:207], v155 offset:53248
	ds_read_b128 v[208:211], v155 offset:54272
	ds_read_b128 v[212:215], v155 offset:55296
	ds_read_b128 v[216:219], v155 offset:56320
	global_load_lds_dwordx4 v[148:149], off
	s_add_i32 m0, s36, 0x2000
	s_add_u32 s34, s34, 0x40080
	v_lshl_add_u64 v[148:149], v[220:221], 0, s[18:19]
	s_addc_u32 s35, s35, 0
	s_add_i32 s36, s84, s45
	global_load_lds_dwordx4 v[148:149], off
	v_lshl_add_u64 v[148:149], s[34:35], 0, v[130:131]
	s_mov_b32 m0, s36
	s_nop 0
	global_load_lds_dwordx4 v[148:149], off
	v_lshl_add_u64 v[148:149], s[34:35], 0, v[134:135]
	s_add_i32 m0, s36, 0x2000
	s_nop 0
	global_load_lds_dwordx4 v[148:149], off
	s_waitcnt vmcnt(6)
	s_waitcnt lgkmcnt(0)
	s_barrier
	s_setprio 1
	s_waitcnt lgkmcnt(0)
	v_mfma_f32_16x16x32_bf16 v[60:63], v[144:147], v[186:189], v[60:63]
	v_mfma_f32_16x16x32_bf16 v[56:59], v[162:165], v[186:189], v[56:59]
	v_mfma_f32_16x16x32_bf16 v[44:47], v[144:147], v[196:199], v[44:47]
	v_mfma_f32_16x16x32_bf16 v[40:43], v[162:165], v[196:199], v[40:43]
	v_mfma_f32_16x16x32_bf16 v[28:31], v[144:147], v[204:207], v[28:31]
	v_mfma_f32_16x16x32_bf16 v[24:27], v[162:165], v[204:207], v[24:27]
	v_mfma_f32_16x16x32_bf16 v[12:15], v[144:147], v[212:215], v[12:15]
	v_mfma_f32_16x16x32_bf16 v[8:11], v[162:165], v[212:215], v[8:11]
	v_mfma_f32_16x16x32_bf16 v[60:63], v[158:161], v[190:193], v[60:63]
	v_mfma_f32_16x16x32_bf16 v[56:59], v[166:169], v[190:193], v[56:59]
	v_mfma_f32_16x16x32_bf16 v[44:47], v[158:161], v[200:203], v[44:47]
	v_mfma_f32_16x16x32_bf16 v[40:43], v[166:169], v[200:203], v[40:43]
	v_mfma_f32_16x16x32_bf16 v[28:31], v[158:161], v[208:211], v[28:31]
	v_mfma_f32_16x16x32_bf16 v[24:27], v[166:169], v[208:211], v[24:27]
	v_mfma_f32_16x16x32_bf16 v[12:15], v[158:161], v[216:219], v[12:15]
	v_mfma_f32_16x16x32_bf16 v[8:11], v[166:169], v[216:219], v[8:11]
	s_setprio 0
	s_setprio 1
	v_mfma_f32_16x16x32_bf16 v[52:55], v[170:173], v[186:189], v[52:55]
	v_mfma_f32_16x16x32_bf16 v[48:51], v[178:181], v[186:189], v[48:51]
	v_mfma_f32_16x16x32_bf16 v[36:39], v[170:173], v[196:199], v[36:39]
	v_mfma_f32_16x16x32_bf16 v[32:35], v[178:181], v[196:199], v[32:35]
	v_mfma_f32_16x16x32_bf16 v[20:23], v[170:173], v[204:207], v[20:23]
	v_mfma_f32_16x16x32_bf16 v[16:19], v[178:181], v[204:207], v[16:19]
	v_mfma_f32_16x16x32_bf16 v[4:7], v[170:173], v[212:215], v[4:7]
	v_mfma_f32_16x16x32_bf16 v[0:3], v[178:181], v[212:215], v[0:3]
	v_mfma_f32_16x16x32_bf16 v[52:55], v[174:177], v[190:193], v[52:55]
	v_mfma_f32_16x16x32_bf16 v[48:51], v[182:185], v[190:193], v[48:51]
	v_mfma_f32_16x16x32_bf16 v[36:39], v[174:177], v[200:203], v[36:39]
	v_mfma_f32_16x16x32_bf16 v[32:35], v[182:185], v[200:203], v[32:35]
	v_mfma_f32_16x16x32_bf16 v[20:23], v[174:177], v[208:211], v[20:23]
	v_mfma_f32_16x16x32_bf16 v[16:19], v[182:185], v[208:211], v[16:19]
	v_mfma_f32_16x16x32_bf16 v[4:7], v[174:177], v[216:219], v[4:7]
	v_mfma_f32_16x16x32_bf16 v[0:3], v[182:185], v[216:219], v[0:3]
	s_setprio 0
	s_barrier
	v_lshl_add_u64 v[222:223], v[222:223], 0, s[18:19]
	s_mov_b32 m0, s61
	s_nop 0
	global_load_lds_dwordx4 v[222:223], off
	v_lshl_add_u64 v[224:225], v[224:225], 0, s[18:19]
	s_mov_b32 m0, s62
	s_nop 0
	global_load_lds_dwordx4 v[224:225], off
	s_add_i32 s82, s82, 2
	s_add_u32 s30, s30, 0x100
	s_addc_u32 s31, s31, 0
	s_add_u32 s80, s80, 0x100
	s_addc_u32 s81, s81, 0
	s_cmp_gt_u32 s82, 13
	s_cbranch_scc0 .LBB0_786
	s_and_b64 vcc, exec, s[20:21]
	s_cbranch_vccz .LBB0_789
	s_barrier

.LBB0_923:
	ds_read_b128 v[152:155], v148
	ds_read_b128 v[156:159], v148 offset:1024
	ds_read_b128 v[160:163], v148 offset:2048
	ds_read_b128 v[164:167], v148 offset:3072
	ds_read_b128 v[168:171], v149
	ds_read_b128 v[172:175], v149 offset:1024
	ds_read_b128 v[176:179], v149 offset:2048
	ds_read_b128 v[180:183], v149 offset:3072
	s_add_u32 s26, s24, 0x100
	s_addc_u32 s27, s25, 0
	s_cmp_eq_u32 s79, 8
	s_cselect_b32 s31, s21, s27
	s_cselect_b32 s30, s20, s26
	s_cselect_b32 s29, s23, s78
	s_cselect_b32 s28, s22, s73
	s_mov_b32 m0, s60
	v_lshl_add_u64 v[192:193], s[24:25], 0, v[138:139]
	ds_read_b128 v[184:187], v150
	ds_read_b128 v[188:191], v150 offset:1024
	ds_read_b128 v[196:199], v150 offset:2048
	ds_read_b128 v[200:203], v150 offset:3072
	ds_read_b128 v[204:207], v150 offset:4096
	ds_read_b128 v[208:211], v150 offset:5120
	ds_read_b128 v[212:215], v150 offset:6144
	ds_read_b128 v[216:219], v150 offset:7168
	global_load_lds_dwordx4 v[192:193], off
	v_lshl_add_u64 v[192:193], s[24:25], 0, v[140:141]
	s_add_i32 m0, s40, 0xe000
	s_nop 0
	global_load_lds_dwordx4 v[192:193], off
	s_waitcnt vmcnt(8)
	s_waitcnt lgkmcnt(0)
	s_barrier
	s_setprio 1
	s_waitcnt lgkmcnt(0)
	v_mfma_f32_16x16x32_bf16 v[124:127], v[152:155], v[184:187], v[124:127]
	v_mfma_f32_16x16x32_bf16 v[120:123], v[160:163], v[184:187], v[120:123]
	v_mfma_f32_16x16x32_bf16 v[108:111], v[152:155], v[196:199], v[108:111]
	v_mfma_f32_16x16x32_bf16 v[104:107], v[160:163], v[196:199], v[104:107]
	v_mfma_f32_16x16x32_bf16 v[92:95], v[152:155], v[204:207], v[92:95]
	v_mfma_f32_16x16x32_bf16 v[88:91], v[160:163], v[204:207], v[88:91]
	v_mfma_f32_16x16x32_bf16 v[76:79], v[152:155], v[212:215], v[76:79]
	v_mfma_f32_16x16x32_bf16 v[72:75], v[160:163], v[212:215], v[72:75]
	v_mfma_f32_16x16x32_bf16 v[124:127], v[156:159], v[188:191], v[124:127]
	v_mfma_f32_16x16x32_bf16 v[120:123], v[164:167], v[188:191], v[120:123]
	v_mfma_f32_16x16x32_bf16 v[108:111], v[156:159], v[200:203], v[108:111]
	v_mfma_f32_16x16x32_bf16 v[104:107], v[164:167], v[200:203], v[104:107]
	v_mfma_f32_16x16x32_bf16 v[92:95], v[156:159], v[208:211], v[92:95]
	v_mfma_f32_16x16x32_bf16 v[88:91], v[164:167], v[208:211], v[88:91]
	v_mfma_f32_16x16x32_bf16 v[76:79], v[156:159], v[216:219], v[76:79]
	v_mfma_f32_16x16x32_bf16 v[72:75], v[164:167], v[216:219], v[72:75]
	s_setprio 0
	s_setprio 1
	v_mfma_f32_16x16x32_bf16 v[116:119], v[168:171], v[184:187], v[116:119]
	v_mfma_f32_16x16x32_bf16 v[112:115], v[176:179], v[184:187], v[112:115]
	v_mfma_f32_16x16x32_bf16 v[100:103], v[168:171], v[196:199], v[100:103]
	v_mfma_f32_16x16x32_bf16 v[96:99], v[176:179], v[196:199], v[96:99]
	v_mfma_f32_16x16x32_bf16 v[84:87], v[168:171], v[204:207], v[84:87]
	v_mfma_f32_16x16x32_bf16 v[80:83], v[176:179], v[204:207], v[80:83]
	v_mfma_f32_16x16x32_bf16 v[68:71], v[168:171], v[212:215], v[68:71]
	v_mfma_f32_16x16x32_bf16 v[64:67], v[176:179], v[212:215], v[64:67]
	v_mfma_f32_16x16x32_bf16 v[116:119], v[172:175], v[188:191], v[116:119]
	v_mfma_f32_16x16x32_bf16 v[112:115], v[180:183], v[188:191], v[112:115]
	v_mfma_f32_16x16x32_bf16 v[100:103], v[172:175], v[200:203], v[100:103]
	v_mfma_f32_16x16x32_bf16 v[96:99], v[180:183], v[200:203], v[96:99]
	v_mfma_f32_16x16x32_bf16 v[84:87], v[172:175], v[208:211], v[84:87]
	v_mfma_f32_16x16x32_bf16 v[80:83], v[180:183], v[208:211], v[80:83]
	v_mfma_f32_16x16x32_bf16 v[68:71], v[172:175], v[216:219], v[68:71]
	v_mfma_f32_16x16x32_bf16 v[64:67], v[180:183], v[216:219], v[64:67]
	s_setprio 0
	s_barrier
	s_add_i32 s24, s58, s39
	v_lshl_add_u64 v[192:193], s[28:29], 0, v[132:133]
	s_mov_b32 m0, s24
	ds_read_b128 v[184:187], v150 offset:16384
	ds_read_b128 v[188:191], v150 offset:17408
	ds_read_b128 v[196:199], v150 offset:18432
	ds_read_b128 v[200:203], v150 offset:19456
	ds_read_b128 v[204:207], v150 offset:20480
	ds_read_b128 v[208:211], v150 offset:21504
	ds_read_b128 v[212:215], v150 offset:22528
	ds_read_b128 v[216:219], v150 offset:23552
	global_load_lds_dwordx4 v[192:193], off
	s_add_i32 m0, s24, 0x2000
	s_add_u32 s24, s28, 0x30000
	v_lshl_add_u64 v[220:221], s[28:29], 0, v[128:129]
	s_addc_u32 s25, s29, 0
	s_add_i32 s80, s59, s39
	global_load_lds_dwordx4 v[220:221], off
	v_lshl_add_u64 v[222:223], s[24:25], 0, v[132:133]
	s_mov_b32 m0, s80
	v_lshl_add_u64 v[224:225], s[30:31], 0, v[130:131]
	global_load_lds_dwordx4 v[222:223], off
	v_lshl_add_u64 v[222:223], s[24:25], 0, v[128:129]
	s_add_i32 m0, s80, 0x2000
	s_nop 0
	global_load_lds_dwordx4 v[222:223], off
	v_lshl_add_u64 v[222:223], s[30:31], 0, v[134:135]
	s_waitcnt vmcnt(6)
	s_waitcnt lgkmcnt(0)
	s_barrier
	s_setprio 1
	s_waitcnt lgkmcnt(0)
	v_mfma_f32_16x16x32_bf16 v[60:63], v[152:155], v[184:187], v[60:63]
	v_mfma_f32_16x16x32_bf16 v[56:59], v[160:163], v[184:187], v[56:59]
	v_mfma_f32_16x16x32_bf16 v[44:47], v[152:155], v[196:199], v[44:47]
	v_mfma_f32_16x16x32_bf16 v[40:43], v[160:163], v[196:199], v[40:43]
	v_mfma_f32_16x16x32_bf16 v[28:31], v[152:155], v[204:207], v[28:31]
	v_mfma_f32_16x16x32_bf16 v[24:27], v[160:163], v[204:207], v[24:27]
	v_mfma_f32_16x16x32_bf16 v[12:15], v[152:155], v[212:215], v[12:15]
	v_mfma_f32_16x16x32_bf16 v[8:11], v[160:163], v[212:215], v[8:11]
	v_mfma_f32_16x16x32_bf16 v[60:63], v[156:159], v[188:191], v[60:63]
	v_mfma_f32_16x16x32_bf16 v[56:59], v[164:167], v[188:191], v[56:59]
	v_mfma_f32_16x16x32_bf16 v[44:47], v[156:159], v[200:203], v[44:47]
	v_mfma_f32_16x16x32_bf16 v[40:43], v[164:167], v[200:203], v[40:43]
	v_mfma_f32_16x16x32_bf16 v[28:31], v[156:159], v[208:211], v[28:31]
	v_mfma_f32_16x16x32_bf16 v[24:27], v[164:167], v[208:211], v[24:27]
	v_mfma_f32_16x16x32_bf16 v[12:15], v[156:159], v[216:219], v[12:15]
	v_mfma_f32_16x16x32_bf16 v[8:11], v[164:167], v[216:219], v[8:11]
	s_setprio 0
	s_setprio 1
	v_mfma_f32_16x16x32_bf16 v[52:55], v[168:171], v[184:187], v[52:55]
	v_mfma_f32_16x16x32_bf16 v[48:51], v[176:179], v[184:187], v[48:51]
	v_mfma_f32_16x16x32_bf16 v[36:39], v[168:171], v[196:199], v[36:39]
	v_mfma_f32_16x16x32_bf16 v[32:35], v[176:179], v[196:199], v[32:35]
	v_mfma_f32_16x16x32_bf16 v[20:23], v[168:171], v[204:207], v[20:23]
	v_mfma_f32_16x16x32_bf16 v[16:19], v[176:179], v[204:207], v[16:19]
	v_mfma_f32_16x16x32_bf16 v[4:7], v[168:171], v[212:215], v[4:7]
	v_mfma_f32_16x16x32_bf16 v[0:3], v[176:179], v[212:215], v[0:3]
	v_mfma_f32_16x16x32_bf16 v[52:55], v[172:175], v[188:191], v[52:55]
	v_mfma_f32_16x16x32_bf16 v[48:51], v[180:183], v[188:191], v[48:51]
	v_mfma_f32_16x16x32_bf16 v[36:39], v[172:175], v[200:203], v[36:39]
	v_mfma_f32_16x16x32_bf16 v[32:35], v[180:183], v[200:203], v[32:35]
	v_mfma_f32_16x16x32_bf16 v[20:23], v[172:175], v[208:211], v[20:23]
	v_mfma_f32_16x16x32_bf16 v[16:19], v[180:183], v[208:211], v[16:19]
	v_mfma_f32_16x16x32_bf16 v[4:7], v[172:175], v[216:219], v[4:7]
	v_mfma_f32_16x16x32_bf16 v[0:3], v[180:183], v[216:219], v[0:3]
	s_setprio 0
	s_barrier
	s_add_i32 s80, 0, 0x18000
	v_add_u32_e32 v151, s80, v142
	s_add_i32 s81, 0, 0x1c000
	ds_read_b128 v[152:155], v151
	ds_read_b128 v[156:159], v151 offset:1024
	ds_read_b128 v[160:163], v151 offset:2048
	ds_read_b128 v[164:167], v151 offset:3072
	v_add_u32_e32 v151, s81, v142
	ds_read_b128 v[168:171], v151
	ds_read_b128 v[172:175], v151 offset:1024
	ds_read_b128 v[176:179], v151 offset:2048
	ds_read_b128 v[180:183], v151 offset:3072
	s_add_u32 s24, s30, 0x30000
	s_addc_u32 s25, s31, 0
	v_lshl_add_u64 v[226:227], s[24:25], 0, v[134:135]
	ds_read_b128 v[184:187], v150 offset:32768
	ds_read_b128 v[188:191], v150 offset:33792
	ds_read_b128 v[196:199], v150 offset:34816
	ds_read_b128 v[200:203], v150 offset:35840
	ds_read_b128 v[204:207], v150 offset:36864
	ds_read_b128 v[208:211], v150 offset:37888
	ds_read_b128 v[212:215], v150 offset:38912
	ds_read_b128 v[216:219], v150 offset:39936
	s_mov_b32 m0, s40
	s_nop 0
	global_load_lds_dwordx4 v[222:223], off
	s_mov_b32 m0, s41
	s_nop 0
	global_load_lds_dwordx4 v[224:225], off
	s_mov_b32 m0, s42
	s_nop 0
	global_load_lds_dwordx4 v[226:227], off
	v_lshl_add_u64 v[226:227], s[24:25], 0, v[130:131]
	s_mov_b32 m0, s43
	s_nop 0
	global_load_lds_dwordx4 v[226:227], off
	s_waitcnt vmcnt(8)
	s_waitcnt lgkmcnt(0)
	s_barrier
	s_setprio 1
	s_waitcnt lgkmcnt(0)
	v_mfma_f32_16x16x32_bf16 v[124:127], v[152:155], v[184:187], v[124:127]
	v_mfma_f32_16x16x32_bf16 v[120:123], v[160:163], v[184:187], v[120:123]
	v_mfma_f32_16x16x32_bf16 v[108:111], v[152:155], v[196:199], v[108:111]
	v_mfma_f32_16x16x32_bf16 v[104:107], v[160:163], v[196:199], v[104:107]
	v_mfma_f32_16x16x32_bf16 v[92:95], v[152:155], v[204:207], v[92:95]
	v_mfma_f32_16x16x32_bf16 v[88:91], v[160:163], v[204:207], v[88:91]
	v_mfma_f32_16x16x32_bf16 v[76:79], v[152:155], v[212:215], v[76:79]
	v_mfma_f32_16x16x32_bf16 v[72:75], v[160:163], v[212:215], v[72:75]
	v_mfma_f32_16x16x32_bf16 v[124:127], v[156:159], v[188:191], v[124:127]
	v_mfma_f32_16x16x32_bf16 v[120:123], v[164:167], v[188:191], v[120:123]
	v_mfma_f32_16x16x32_bf16 v[108:111], v[156:159], v[200:203], v[108:111]
	v_mfma_f32_16x16x32_bf16 v[104:107], v[164:167], v[200:203], v[104:107]
	v_mfma_f32_16x16x32_bf16 v[92:95], v[156:159], v[208:211], v[92:95]
	v_mfma_f32_16x16x32_bf16 v[88:91], v[164:167], v[208:211], v[88:91]
	v_mfma_f32_16x16x32_bf16 v[76:79], v[156:159], v[216:219], v[76:79]
	v_mfma_f32_16x16x32_bf16 v[72:75], v[164:167], v[216:219], v[72:75]
	s_setprio 0
	s_setprio 1
	v_mfma_f32_16x16x32_bf16 v[116:119], v[168:171], v[184:187], v[116:119]
	v_mfma_f32_16x16x32_bf16 v[112:115], v[176:179], v[184:187], v[112:115]
	v_mfma_f32_16x16x32_bf16 v[100:103], v[168:171], v[196:199], v[100:103]
	v_mfma_f32_16x16x32_bf16 v[96:99], v[176:179], v[196:199], v[96:99]
	v_mfma_f32_16x16x32_bf16 v[84:87], v[168:171], v[204:207], v[84:87]
	v_mfma_f32_16x16x32_bf16 v[80:83], v[176:179], v[204:207], v[80:83]
	v_mfma_f32_16x16x32_bf16 v[68:71], v[168:171], v[212:215], v[68:71]
	v_mfma_f32_16x16x32_bf16 v[64:67], v[176:179], v[212:215], v[64:67]
	v_mfma_f32_16x16x32_bf16 v[116:119], v[172:175], v[188:191], v[116:119]
	v_mfma_f32_16x16x32_bf16 v[112:115], v[180:183], v[188:191], v[112:115]
	v_mfma_f32_16x16x32_bf16 v[100:103], v[172:175], v[200:203], v[100:103]
	v_mfma_f32_16x16x32_bf16 v[96:99], v[180:183], v[200:203], v[96:99]
	v_mfma_f32_16x16x32_bf16 v[84:87], v[172:175], v[208:211], v[84:87]
	v_mfma_f32_16x16x32_bf16 v[80:83], v[180:183], v[208:211], v[80:83]
	v_mfma_f32_16x16x32_bf16 v[68:71], v[172:175], v[216:219], v[68:71]
	v_mfma_f32_16x16x32_bf16 v[64:67], v[180:183], v[216:219], v[64:67]
	s_setprio 0
	s_barrier
	s_add_i32 s24, s80, s39
	v_lshl_add_u64 v[192:193], v[192:193], 0, s[16:17]
	s_mov_b32 m0, s24
	ds_read_b128 v[184:187], v150 offset:49152
	ds_read_b128 v[188:191], v150 offset:50176
	ds_read_b128 v[196:199], v150 offset:51200
	ds_read_b128 v[200:203], v150 offset:52224
	ds_read_b128 v[204:207], v150 offset:53248
	ds_read_b128 v[208:211], v150 offset:54272
	ds_read_b128 v[212:215], v150 offset:55296
	ds_read_b128 v[216:219], v150 offset:56320
	global_load_lds_dwordx4 v[192:193], off
	s_add_i32 m0, s24, 0x2000
	s_add_u32 s24, s28, 0x30080
	v_lshl_add_u64 v[192:193], v[220:221], 0, s[16:17]
	s_addc_u32 s25, s29, 0
	s_add_i32 s28, s81, s39
	global_load_lds_dwordx4 v[192:193], off
	v_lshl_add_u64 v[192:193], s[24:25], 0, v[132:133]
	s_mov_b32 m0, s28
	s_nop 0
	global_load_lds_dwordx4 v[192:193], off
	v_lshl_add_u64 v[192:193], s[24:25], 0, v[128:129]
	s_add_i32 m0, s28, 0x2000
	s_nop 0
	global_load_lds_dwordx4 v[192:193], off
	s_waitcnt vmcnt(6)
	s_waitcnt lgkmcnt(0)
	s_barrier
	s_setprio 1
	s_waitcnt lgkmcnt(0)
	v_mfma_f32_16x16x32_bf16 v[60:63], v[152:155], v[184:187], v[60:63]
	v_mfma_f32_16x16x32_bf16 v[56:59], v[160:163], v[184:187], v[56:59]
	v_mfma_f32_16x16x32_bf16 v[44:47], v[152:155], v[196:199], v[44:47]
	v_mfma_f32_16x16x32_bf16 v[40:43], v[160:163], v[196:199], v[40:43]
	v_mfma_f32_16x16x32_bf16 v[28:31], v[152:155], v[204:207], v[28:31]
	v_mfma_f32_16x16x32_bf16 v[24:27], v[160:163], v[204:207], v[24:27]
	v_mfma_f32_16x16x32_bf16 v[12:15], v[152:155], v[212:215], v[12:15]
	v_mfma_f32_16x16x32_bf16 v[8:11], v[160:163], v[212:215], v[8:11]
	v_mfma_f32_16x16x32_bf16 v[60:63], v[156:159], v[188:191], v[60:63]
	v_mfma_f32_16x16x32_bf16 v[56:59], v[164:167], v[188:191], v[56:59]
	v_mfma_f32_16x16x32_bf16 v[44:47], v[156:159], v[200:203], v[44:47]
	v_mfma_f32_16x16x32_bf16 v[40:43], v[164:167], v[200:203], v[40:43]
	v_mfma_f32_16x16x32_bf16 v[28:31], v[156:159], v[208:211], v[28:31]
	v_mfma_f32_16x16x32_bf16 v[24:27], v[164:167], v[208:211], v[24:27]
	v_mfma_f32_16x16x32_bf16 v[12:15], v[156:159], v[216:219], v[12:15]
	v_mfma_f32_16x16x32_bf16 v[8:11], v[164:167], v[216:219], v[8:11]
	s_setprio 0
	s_setprio 1
	v_mfma_f32_16x16x32_bf16 v[52:55], v[168:171], v[184:187], v[52:55]
	v_mfma_f32_16x16x32_bf16 v[48:51], v[176:179], v[184:187], v[48:51]
	v_mfma_f32_16x16x32_bf16 v[36:39], v[168:171], v[196:199], v[36:39]
	v_mfma_f32_16x16x32_bf16 v[32:35], v[176:179], v[196:199], v[32:35]
	v_mfma_f32_16x16x32_bf16 v[20:23], v[168:171], v[204:207], v[20:23]
	v_mfma_f32_16x16x32_bf16 v[16:19], v[176:179], v[204:207], v[16:19]
	v_mfma_f32_16x16x32_bf16 v[4:7], v[168:171], v[212:215], v[4:7]
	v_mfma_f32_16x16x32_bf16 v[0:3], v[176:179], v[212:215], v[0:3]
	v_mfma_f32_16x16x32_bf16 v[52:55], v[172:175], v[188:191], v[52:55]
	v_mfma_f32_16x16x32_bf16 v[48:51], v[180:183], v[188:191], v[48:51]
	v_mfma_f32_16x16x32_bf16 v[36:39], v[172:175], v[200:203], v[36:39]
	v_mfma_f32_16x16x32_bf16 v[32:35], v[180:183], v[200:203], v[32:35]
	v_mfma_f32_16x16x32_bf16 v[20:23], v[172:175], v[208:211], v[20:23]
	v_mfma_f32_16x16x32_bf16 v[16:19], v[180:183], v[208:211], v[16:19]
	v_mfma_f32_16x16x32_bf16 v[4:7], v[172:175], v[216:219], v[4:7]
	v_mfma_f32_16x16x32_bf16 v[0:3], v[180:183], v[216:219], v[0:3]
	s_setprio 0
	s_barrier
	v_lshl_add_u64 v[222:223], v[222:223], 0, s[16:17]
	s_mov_b32 m0, s45
	s_nop 0
	global_load_lds_dwordx4 v[222:223], off
	v_lshl_add_u64 v[224:225], v[224:225], 0, s[16:17]
	s_mov_b32 m0, s50
	s_nop 0
	global_load_lds_dwordx4 v[224:225], off
	s_add_i32 s79, s79, 2
	s_add_u32 s73, s73, 0x100
	s_addc_u32 s78, s78, 0
	s_cmp_gt_u32 s79, 9
	s_mov_b64 s[24:25], s[26:27]
	s_cbranch_scc0 .LBB0_923
	s_and_b64 vcc, exec, s[18:19]
	s_cbranch_vccz .LBB0_926
	s_barrier

.LBB0_947:
	ds_read_b128 v[144:147], v153
	ds_read_b128 v[158:161], v153 offset:1024
	ds_read_b128 v[162:165], v153 offset:2048
	ds_read_b128 v[166:169], v153 offset:3072
	ds_read_b128 v[170:173], v154
	ds_read_b128 v[174:177], v154 offset:1024
	ds_read_b128 v[178:181], v154 offset:2048
	ds_read_b128 v[182:185], v154 offset:3072
	s_add_u32 s36, s34, 0xfffc0080
	s_addc_u32 s37, s35, -1
	s_cmp_eq_u32 s85, 12
	s_cselect_b32 s39, s27, s37
	s_cselect_b32 s38, s81, s36
	s_cselect_b32 s37, s25, s84
	s_cselect_b32 s36, s82, s83
	v_lshl_add_u64 v[148:149], s[34:35], 0, v[136:137]
	s_add_i32 m0, s59, 0xc000
	ds_read_b128 v[186:189], v155
	ds_read_b128 v[190:193], v155 offset:1024
	ds_read_b128 v[196:199], v155 offset:2048
	ds_read_b128 v[200:203], v155 offset:3072
	ds_read_b128 v[204:207], v155 offset:4096
	ds_read_b128 v[208:211], v155 offset:5120
	ds_read_b128 v[212:215], v155 offset:6144
	ds_read_b128 v[216:219], v155 offset:7168
	global_load_lds_dwordx4 v[148:149], off
	v_lshl_add_u64 v[148:149], s[34:35], 0, v[138:139]
	s_add_i32 m0, s59, 0xe000
	s_nop 0
	global_load_lds_dwordx4 v[148:149], off
	s_waitcnt vmcnt(8)
	s_waitcnt lgkmcnt(0)
	s_barrier
	s_setprio 1
	s_waitcnt lgkmcnt(0)
	v_mfma_f32_16x16x32_bf16 v[124:127], v[144:147], v[186:189], v[124:127]
	v_mfma_f32_16x16x32_bf16 v[120:123], v[162:165], v[186:189], v[120:123]
	v_mfma_f32_16x16x32_bf16 v[108:111], v[144:147], v[196:199], v[108:111]
	v_mfma_f32_16x16x32_bf16 v[104:107], v[162:165], v[196:199], v[104:107]
	v_mfma_f32_16x16x32_bf16 v[92:95], v[144:147], v[204:207], v[92:95]
	v_mfma_f32_16x16x32_bf16 v[88:91], v[162:165], v[204:207], v[88:91]
	v_mfma_f32_16x16x32_bf16 v[76:79], v[144:147], v[212:215], v[76:79]
	v_mfma_f32_16x16x32_bf16 v[72:75], v[162:165], v[212:215], v[72:75]
	v_mfma_f32_16x16x32_bf16 v[124:127], v[158:161], v[190:193], v[124:127]
	v_mfma_f32_16x16x32_bf16 v[120:123], v[166:169], v[190:193], v[120:123]
	v_mfma_f32_16x16x32_bf16 v[108:111], v[158:161], v[200:203], v[108:111]
	v_mfma_f32_16x16x32_bf16 v[104:107], v[166:169], v[200:203], v[104:107]
	v_mfma_f32_16x16x32_bf16 v[92:95], v[158:161], v[208:211], v[92:95]
	v_mfma_f32_16x16x32_bf16 v[88:91], v[166:169], v[208:211], v[88:91]
	v_mfma_f32_16x16x32_bf16 v[76:79], v[158:161], v[216:219], v[76:79]
	v_mfma_f32_16x16x32_bf16 v[72:75], v[166:169], v[216:219], v[72:75]
	s_setprio 0
	s_setprio 1
	v_mfma_f32_16x16x32_bf16 v[116:119], v[170:173], v[186:189], v[116:119]
	v_mfma_f32_16x16x32_bf16 v[112:115], v[178:181], v[186:189], v[112:115]
	v_mfma_f32_16x16x32_bf16 v[100:103], v[170:173], v[196:199], v[100:103]
	v_mfma_f32_16x16x32_bf16 v[96:99], v[178:181], v[196:199], v[96:99]
	v_mfma_f32_16x16x32_bf16 v[84:87], v[170:173], v[204:207], v[84:87]
	v_mfma_f32_16x16x32_bf16 v[80:83], v[178:181], v[204:207], v[80:83]
	v_mfma_f32_16x16x32_bf16 v[68:71], v[170:173], v[212:215], v[68:71]
	v_mfma_f32_16x16x32_bf16 v[64:67], v[178:181], v[212:215], v[64:67]
	v_mfma_f32_16x16x32_bf16 v[116:119], v[174:177], v[190:193], v[116:119]
	v_mfma_f32_16x16x32_bf16 v[112:115], v[182:185], v[190:193], v[112:115]
	v_mfma_f32_16x16x32_bf16 v[100:103], v[174:177], v[200:203], v[100:103]
	v_mfma_f32_16x16x32_bf16 v[96:99], v[182:185], v[200:203], v[96:99]
	v_mfma_f32_16x16x32_bf16 v[84:87], v[174:177], v[208:211], v[84:87]
	v_mfma_f32_16x16x32_bf16 v[80:83], v[182:185], v[208:211], v[80:83]
	v_mfma_f32_16x16x32_bf16 v[68:71], v[174:177], v[216:219], v[68:71]
	v_mfma_f32_16x16x32_bf16 v[64:67], v[182:185], v[216:219], v[64:67]
	s_setprio 0
	s_barrier
	s_add_i32 s86, s73, s58
	v_lshl_add_u64 v[148:149], s[36:37], 0, v[130:131]
	s_mov_b32 m0, s86
	ds_read_b128 v[186:189], v155 offset:16384
	ds_read_b128 v[190:193], v155 offset:17408
	ds_read_b128 v[196:199], v155 offset:18432
	ds_read_b128 v[200:203], v155 offset:19456
	ds_read_b128 v[204:207], v155 offset:20480
	ds_read_b128 v[208:211], v155 offset:21504
	ds_read_b128 v[212:215], v155 offset:22528
	ds_read_b128 v[216:219], v155 offset:23552
	global_load_lds_dwordx4 v[148:149], off
	s_add_i32 m0, s86, 0x2000
	s_add_u32 s86, s36, 0x40000
	v_lshl_add_u64 v[220:221], s[36:37], 0, v[134:135]
	s_addc_u32 s87, s37, 0
	s_add_i32 s88, s78, s58
	global_load_lds_dwordx4 v[220:221], off
	v_lshl_add_u64 v[222:223], s[86:87], 0, v[130:131]
	s_mov_b32 m0, s88
	v_lshl_add_u64 v[224:225], s[38:39], 0, v[132:133]
	global_load_lds_dwordx4 v[222:223], off
	v_lshl_add_u64 v[222:223], s[86:87], 0, v[134:135]
	s_add_i32 m0, s88, 0x2000
	s_nop 0
	global_load_lds_dwordx4 v[222:223], off
	v_lshl_add_u64 v[222:223], s[38:39], 0, v[128:129]
	s_waitcnt vmcnt(6)
	s_waitcnt lgkmcnt(0)
	s_barrier
	s_setprio 1
	s_waitcnt lgkmcnt(0)
	v_mfma_f32_16x16x32_bf16 v[60:63], v[144:147], v[186:189], v[60:63]
	v_mfma_f32_16x16x32_bf16 v[56:59], v[162:165], v[186:189], v[56:59]
	v_mfma_f32_16x16x32_bf16 v[44:47], v[144:147], v[196:199], v[44:47]
	v_mfma_f32_16x16x32_bf16 v[40:43], v[162:165], v[196:199], v[40:43]
	v_mfma_f32_16x16x32_bf16 v[28:31], v[144:147], v[204:207], v[28:31]
	v_mfma_f32_16x16x32_bf16 v[24:27], v[162:165], v[204:207], v[24:27]
	v_mfma_f32_16x16x32_bf16 v[12:15], v[144:147], v[212:215], v[12:15]
	v_mfma_f32_16x16x32_bf16 v[8:11], v[162:165], v[212:215], v[8:11]
	v_mfma_f32_16x16x32_bf16 v[60:63], v[158:161], v[190:193], v[60:63]
	v_mfma_f32_16x16x32_bf16 v[56:59], v[166:169], v[190:193], v[56:59]
	v_mfma_f32_16x16x32_bf16 v[44:47], v[158:161], v[200:203], v[44:47]
	v_mfma_f32_16x16x32_bf16 v[40:43], v[166:169], v[200:203], v[40:43]
	v_mfma_f32_16x16x32_bf16 v[28:31], v[158:161], v[208:211], v[28:31]
	v_mfma_f32_16x16x32_bf16 v[24:27], v[166:169], v[208:211], v[24:27]
	v_mfma_f32_16x16x32_bf16 v[12:15], v[158:161], v[216:219], v[12:15]
	v_mfma_f32_16x16x32_bf16 v[8:11], v[166:169], v[216:219], v[8:11]
	s_setprio 0
	s_setprio 1
	v_mfma_f32_16x16x32_bf16 v[52:55], v[170:173], v[186:189], v[52:55]
	v_mfma_f32_16x16x32_bf16 v[48:51], v[178:181], v[186:189], v[48:51]
	v_mfma_f32_16x16x32_bf16 v[36:39], v[170:173], v[196:199], v[36:39]
	v_mfma_f32_16x16x32_bf16 v[32:35], v[178:181], v[196:199], v[32:35]
	v_mfma_f32_16x16x32_bf16 v[20:23], v[170:173], v[204:207], v[20:23]
	v_mfma_f32_16x16x32_bf16 v[16:19], v[178:181], v[204:207], v[16:19]
	v_mfma_f32_16x16x32_bf16 v[4:7], v[170:173], v[212:215], v[4:7]
	v_mfma_f32_16x16x32_bf16 v[0:3], v[178:181], v[212:215], v[0:3]
	v_mfma_f32_16x16x32_bf16 v[52:55], v[174:177], v[190:193], v[52:55]
	v_mfma_f32_16x16x32_bf16 v[48:51], v[182:185], v[190:193], v[48:51]
	v_mfma_f32_16x16x32_bf16 v[36:39], v[174:177], v[200:203], v[36:39]
	v_mfma_f32_16x16x32_bf16 v[32:35], v[182:185], v[200:203], v[32:35]
	v_mfma_f32_16x16x32_bf16 v[20:23], v[174:177], v[208:211], v[20:23]
	v_mfma_f32_16x16x32_bf16 v[16:19], v[182:185], v[208:211], v[16:19]
	v_mfma_f32_16x16x32_bf16 v[4:7], v[174:177], v[216:219], v[4:7]
	v_mfma_f32_16x16x32_bf16 v[0:3], v[182:185], v[216:219], v[0:3]
	s_setprio 0
	s_barrier
	s_add_i32 s86, 0, 0x18000
	v_add_u32_e32 v157, s86, v151
	s_add_i32 s87, 0, 0x1c000
	ds_read_b128 v[144:147], v157
	ds_read_b128 v[158:161], v157 offset:1024
	ds_read_b128 v[162:165], v157 offset:2048
	ds_read_b128 v[166:169], v157 offset:3072
	v_add_u32_e32 v157, s87, v151
	ds_read_b128 v[170:173], v157
	ds_read_b128 v[174:177], v157 offset:1024
	ds_read_b128 v[178:181], v157 offset:2048
	ds_read_b128 v[182:185], v157 offset:3072
	s_add_u32 s38, s38, 0x40000
	s_addc_u32 s39, s39, 0
	v_lshl_add_u64 v[226:227], s[38:39], 0, v[128:129]
	ds_read_b128 v[186:189], v155 offset:32768
	ds_read_b128 v[190:193], v155 offset:33792
	ds_read_b128 v[196:199], v155 offset:34816
	ds_read_b128 v[200:203], v155 offset:35840
	ds_read_b128 v[204:207], v155 offset:36864
	ds_read_b128 v[208:211], v155 offset:37888
	ds_read_b128 v[212:215], v155 offset:38912
	ds_read_b128 v[216:219], v155 offset:39936
	s_mov_b32 m0, s59
	s_nop 0
	global_load_lds_dwordx4 v[222:223], off
	s_mov_b32 m0, s60
	s_nop 0
	global_load_lds_dwordx4 v[224:225], off
	s_mov_b32 m0, s61
	s_nop 0
	global_load_lds_dwordx4 v[226:227], off
	v_lshl_add_u64 v[226:227], s[38:39], 0, v[132:133]
	s_mov_b32 m0, s62
	s_nop 0
	global_load_lds_dwordx4 v[226:227], off
	s_waitcnt vmcnt(8)
	s_waitcnt lgkmcnt(0)
	s_barrier
	s_setprio 1
	s_waitcnt lgkmcnt(0)
	v_mfma_f32_16x16x32_bf16 v[124:127], v[144:147], v[186:189], v[124:127]
	v_mfma_f32_16x16x32_bf16 v[120:123], v[162:165], v[186:189], v[120:123]
	v_mfma_f32_16x16x32_bf16 v[108:111], v[144:147], v[196:199], v[108:111]
	v_mfma_f32_16x16x32_bf16 v[104:107], v[162:165], v[196:199], v[104:107]
	v_mfma_f32_16x16x32_bf16 v[92:95], v[144:147], v[204:207], v[92:95]
	v_mfma_f32_16x16x32_bf16 v[88:91], v[162:165], v[204:207], v[88:91]
	v_mfma_f32_16x16x32_bf16 v[76:79], v[144:147], v[212:215], v[76:79]
	v_mfma_f32_16x16x32_bf16 v[72:75], v[162:165], v[212:215], v[72:75]
	v_mfma_f32_16x16x32_bf16 v[124:127], v[158:161], v[190:193], v[124:127]
	v_mfma_f32_16x16x32_bf16 v[120:123], v[166:169], v[190:193], v[120:123]
	v_mfma_f32_16x16x32_bf16 v[108:111], v[158:161], v[200:203], v[108:111]
	v_mfma_f32_16x16x32_bf16 v[104:107], v[166:169], v[200:203], v[104:107]
	v_mfma_f32_16x16x32_bf16 v[92:95], v[158:161], v[208:211], v[92:95]
	v_mfma_f32_16x16x32_bf16 v[88:91], v[166:169], v[208:211], v[88:91]
	v_mfma_f32_16x16x32_bf16 v[76:79], v[158:161], v[216:219], v[76:79]
	v_mfma_f32_16x16x32_bf16 v[72:75], v[166:169], v[216:219], v[72:75]
	s_setprio 0
	s_setprio 1
	v_mfma_f32_16x16x32_bf16 v[116:119], v[170:173], v[186:189], v[116:119]
	v_mfma_f32_16x16x32_bf16 v[112:115], v[178:181], v[186:189], v[112:115]
	v_mfma_f32_16x16x32_bf16 v[100:103], v[170:173], v[196:199], v[100:103]
	v_mfma_f32_16x16x32_bf16 v[96:99], v[178:181], v[196:199], v[96:99]
	v_mfma_f32_16x16x32_bf16 v[84:87], v[170:173], v[204:207], v[84:87]
	v_mfma_f32_16x16x32_bf16 v[80:83], v[178:181], v[204:207], v[80:83]
	v_mfma_f32_16x16x32_bf16 v[68:71], v[170:173], v[212:215], v[68:71]
	v_mfma_f32_16x16x32_bf16 v[64:67], v[178:181], v[212:215], v[64:67]
	v_mfma_f32_16x16x32_bf16 v[116:119], v[174:177], v[190:193], v[116:119]
	v_mfma_f32_16x16x32_bf16 v[112:115], v[182:185], v[190:193], v[112:115]
	v_mfma_f32_16x16x32_bf16 v[100:103], v[174:177], v[200:203], v[100:103]
	v_mfma_f32_16x16x32_bf16 v[96:99], v[182:185], v[200:203], v[96:99]
	v_mfma_f32_16x16x32_bf16 v[84:87], v[174:177], v[208:211], v[84:87]
	v_mfma_f32_16x16x32_bf16 v[80:83], v[182:185], v[208:211], v[80:83]
	v_mfma_f32_16x16x32_bf16 v[68:71], v[174:177], v[216:219], v[68:71]
	v_mfma_f32_16x16x32_bf16 v[64:67], v[182:185], v[216:219], v[64:67]
	s_setprio 0
	s_barrier
	s_add_i32 s38, s86, s58
	v_lshl_add_u64 v[148:149], v[148:149], 0, s[20:21]
	s_mov_b32 m0, s38
	ds_read_b128 v[186:189], v155 offset:49152
	ds_read_b128 v[190:193], v155 offset:50176
	ds_read_b128 v[196:199], v155 offset:51200
	ds_read_b128 v[200:203], v155 offset:52224
	ds_read_b128 v[204:207], v155 offset:53248
	ds_read_b128 v[208:211], v155 offset:54272
	ds_read_b128 v[212:215], v155 offset:55296
	ds_read_b128 v[216:219], v155 offset:56320
	global_load_lds_dwordx4 v[148:149], off
	s_add_i32 m0, s38, 0x2000
	s_add_u32 s36, s36, 0x40080
	v_lshl_add_u64 v[148:149], v[220:221], 0, s[20:21]
	s_addc_u32 s37, s37, 0
	s_add_i32 s38, s87, s58
	global_load_lds_dwordx4 v[148:149], off
	v_lshl_add_u64 v[148:149], s[36:37], 0, v[130:131]
	s_mov_b32 m0, s38
	s_nop 0
	global_load_lds_dwordx4 v[148:149], off
	v_lshl_add_u64 v[148:149], s[36:37], 0, v[134:135]
	s_add_i32 m0, s38, 0x2000
	s_nop 0
	global_load_lds_dwordx4 v[148:149], off
	s_waitcnt vmcnt(6)
	s_waitcnt lgkmcnt(0)
	s_barrier
	s_setprio 1
	s_waitcnt lgkmcnt(0)
	v_mfma_f32_16x16x32_bf16 v[60:63], v[144:147], v[186:189], v[60:63]
	v_mfma_f32_16x16x32_bf16 v[56:59], v[162:165], v[186:189], v[56:59]
	v_mfma_f32_16x16x32_bf16 v[44:47], v[144:147], v[196:199], v[44:47]
	v_mfma_f32_16x16x32_bf16 v[40:43], v[162:165], v[196:199], v[40:43]
	v_mfma_f32_16x16x32_bf16 v[28:31], v[144:147], v[204:207], v[28:31]
	v_mfma_f32_16x16x32_bf16 v[24:27], v[162:165], v[204:207], v[24:27]
	v_mfma_f32_16x16x32_bf16 v[12:15], v[144:147], v[212:215], v[12:15]
	v_mfma_f32_16x16x32_bf16 v[8:11], v[162:165], v[212:215], v[8:11]
	v_mfma_f32_16x16x32_bf16 v[60:63], v[158:161], v[190:193], v[60:63]
	v_mfma_f32_16x16x32_bf16 v[56:59], v[166:169], v[190:193], v[56:59]
	v_mfma_f32_16x16x32_bf16 v[44:47], v[158:161], v[200:203], v[44:47]
	v_mfma_f32_16x16x32_bf16 v[40:43], v[166:169], v[200:203], v[40:43]
	v_mfma_f32_16x16x32_bf16 v[28:31], v[158:161], v[208:211], v[28:31]
	v_mfma_f32_16x16x32_bf16 v[24:27], v[166:169], v[208:211], v[24:27]
	v_mfma_f32_16x16x32_bf16 v[12:15], v[158:161], v[216:219], v[12:15]
	v_mfma_f32_16x16x32_bf16 v[8:11], v[166:169], v[216:219], v[8:11]
	s_setprio 0
	s_setprio 1
	v_mfma_f32_16x16x32_bf16 v[52:55], v[170:173], v[186:189], v[52:55]
	v_mfma_f32_16x16x32_bf16 v[48:51], v[178:181], v[186:189], v[48:51]
	v_mfma_f32_16x16x32_bf16 v[36:39], v[170:173], v[196:199], v[36:39]
	v_mfma_f32_16x16x32_bf16 v[32:35], v[178:181], v[196:199], v[32:35]
	v_mfma_f32_16x16x32_bf16 v[20:23], v[170:173], v[204:207], v[20:23]
	v_mfma_f32_16x16x32_bf16 v[16:19], v[178:181], v[204:207], v[16:19]
	v_mfma_f32_16x16x32_bf16 v[4:7], v[170:173], v[212:215], v[4:7]
	v_mfma_f32_16x16x32_bf16 v[0:3], v[178:181], v[212:215], v[0:3]
	v_mfma_f32_16x16x32_bf16 v[52:55], v[174:177], v[190:193], v[52:55]
	v_mfma_f32_16x16x32_bf16 v[48:51], v[182:185], v[190:193], v[48:51]
	v_mfma_f32_16x16x32_bf16 v[36:39], v[174:177], v[200:203], v[36:39]
	v_mfma_f32_16x16x32_bf16 v[32:35], v[182:185], v[200:203], v[32:35]
	v_mfma_f32_16x16x32_bf16 v[20:23], v[174:177], v[208:211], v[20:23]
	v_mfma_f32_16x16x32_bf16 v[16:19], v[182:185], v[208:211], v[16:19]
	v_mfma_f32_16x16x32_bf16 v[4:7], v[174:177], v[216:219], v[4:7]
	v_mfma_f32_16x16x32_bf16 v[0:3], v[182:185], v[216:219], v[0:3]
	s_setprio 0
	s_barrier
	v_lshl_add_u64 v[222:223], v[222:223], 0, s[20:21]
	s_mov_b32 m0, s70
	s_nop 0
	global_load_lds_dwordx4 v[222:223], off
	v_lshl_add_u64 v[224:225], v[224:225], 0, s[20:21]
	s_mov_b32 m0, s71
	s_nop 0
	global_load_lds_dwordx4 v[224:225], off
	s_add_i32 s85, s85, 2
	s_add_u32 s34, s34, 0x100
	s_addc_u32 s35, s35, 0
	s_add_u32 s83, s83, 0x100
	s_addc_u32 s84, s84, 0
	s_cmp_gt_u32 s85, 13
	s_cbranch_scc0 .LBB0_947
	s_and_b64 vcc, exec, s[22:23]
	s_cbranch_vccz .LBB0_950
	s_barrier

.LBB0_1023:
	ds_read_b128 v[144:147], v153
	ds_read_b128 v[156:159], v153 offset:1024
	ds_read_b128 v[160:163], v153 offset:2048
	ds_read_b128 v[164:167], v153 offset:3072
	ds_read_b128 v[168:171], v154
	ds_read_b128 v[172:175], v154 offset:1024
	ds_read_b128 v[176:179], v154 offset:2048
	ds_read_b128 v[180:183], v154 offset:3072
	s_add_u32 s44, s42, 0xfffe0080
	s_addc_u32 s45, s43, -1
	s_cmp_eq_u32 s87, 4
	s_cselect_b32 s59, s35, s45
	s_cselect_b32 s58, s83, s44
	s_cselect_b32 s45, s31, s86
	s_cselect_b32 s44, s84, s85
	v_lshl_add_u64 v[148:149], s[42:43], 0, v[136:137]
	s_add_i32 m0, s41, 0xc000
	ds_read_b128 v[184:187], v155
	ds_read_b128 v[188:191], v155 offset:1024
	ds_read_b128 v[196:199], v155 offset:2048
	ds_read_b128 v[200:203], v155 offset:3072
	ds_read_b128 v[204:207], v155 offset:4096
	ds_read_b128 v[208:211], v155 offset:5120
	ds_read_b128 v[212:215], v155 offset:6144
	ds_read_b128 v[216:219], v155 offset:7168
	global_load_lds_dwordx4 v[148:149], off
	v_lshl_add_u64 v[148:149], s[42:43], 0, v[138:139]
	s_add_i32 m0, s41, 0xe000
	s_nop 0
	global_load_lds_dwordx4 v[148:149], off
	s_waitcnt vmcnt(8)
	s_waitcnt lgkmcnt(0)
	s_barrier
	s_setprio 1
	s_waitcnt lgkmcnt(0)
	v_mfma_f32_16x16x32_bf16 v[124:127], v[144:147], v[184:187], v[124:127]
	v_mfma_f32_16x16x32_bf16 v[120:123], v[160:163], v[184:187], v[120:123]
	v_mfma_f32_16x16x32_bf16 v[108:111], v[144:147], v[196:199], v[108:111]
	v_mfma_f32_16x16x32_bf16 v[104:107], v[160:163], v[196:199], v[104:107]
	v_mfma_f32_16x16x32_bf16 v[92:95], v[144:147], v[204:207], v[92:95]
	v_mfma_f32_16x16x32_bf16 v[88:91], v[160:163], v[204:207], v[88:91]
	v_mfma_f32_16x16x32_bf16 v[76:79], v[144:147], v[212:215], v[76:79]
	v_mfma_f32_16x16x32_bf16 v[72:75], v[160:163], v[212:215], v[72:75]
	v_mfma_f32_16x16x32_bf16 v[124:127], v[156:159], v[188:191], v[124:127]
	v_mfma_f32_16x16x32_bf16 v[120:123], v[164:167], v[188:191], v[120:123]
	v_mfma_f32_16x16x32_bf16 v[108:111], v[156:159], v[200:203], v[108:111]
	v_mfma_f32_16x16x32_bf16 v[104:107], v[164:167], v[200:203], v[104:107]
	v_mfma_f32_16x16x32_bf16 v[92:95], v[156:159], v[208:211], v[92:95]
	v_mfma_f32_16x16x32_bf16 v[88:91], v[164:167], v[208:211], v[88:91]
	v_mfma_f32_16x16x32_bf16 v[76:79], v[156:159], v[216:219], v[76:79]
	v_mfma_f32_16x16x32_bf16 v[72:75], v[164:167], v[216:219], v[72:75]
	s_setprio 0
	s_setprio 1
	v_mfma_f32_16x16x32_bf16 v[116:119], v[168:171], v[184:187], v[116:119]
	v_mfma_f32_16x16x32_bf16 v[112:115], v[176:179], v[184:187], v[112:115]
	v_mfma_f32_16x16x32_bf16 v[100:103], v[168:171], v[196:199], v[100:103]
	v_mfma_f32_16x16x32_bf16 v[96:99], v[176:179], v[196:199], v[96:99]
	v_mfma_f32_16x16x32_bf16 v[84:87], v[168:171], v[204:207], v[84:87]
	v_mfma_f32_16x16x32_bf16 v[80:83], v[176:179], v[204:207], v[80:83]
	v_mfma_f32_16x16x32_bf16 v[68:71], v[168:171], v[212:215], v[68:71]
	v_mfma_f32_16x16x32_bf16 v[64:67], v[176:179], v[212:215], v[64:67]
	v_mfma_f32_16x16x32_bf16 v[116:119], v[172:175], v[188:191], v[116:119]
	v_mfma_f32_16x16x32_bf16 v[112:115], v[180:183], v[188:191], v[112:115]
	v_mfma_f32_16x16x32_bf16 v[100:103], v[172:175], v[200:203], v[100:103]
	v_mfma_f32_16x16x32_bf16 v[96:99], v[180:183], v[200:203], v[96:99]
	v_mfma_f32_16x16x32_bf16 v[84:87], v[172:175], v[208:211], v[84:87]
	v_mfma_f32_16x16x32_bf16 v[80:83], v[180:183], v[208:211], v[80:83]
	v_mfma_f32_16x16x32_bf16 v[68:71], v[172:175], v[216:219], v[68:71]
	v_mfma_f32_16x16x32_bf16 v[64:67], v[180:183], v[216:219], v[64:67]
	s_setprio 0
	s_barrier
	s_add_i32 s88, s80, s62
	v_lshl_add_u64 v[148:149], s[44:45], 0, v[130:131]
	s_mov_b32 m0, s88
	ds_read_b128 v[184:187], v155 offset:16384
	ds_read_b128 v[188:191], v155 offset:17408
	ds_read_b128 v[196:199], v155 offset:18432
	ds_read_b128 v[200:203], v155 offset:19456
	ds_read_b128 v[204:207], v155 offset:20480
	ds_read_b128 v[208:211], v155 offset:21504
	ds_read_b128 v[212:215], v155 offset:22528
	ds_read_b128 v[216:219], v155 offset:23552
	global_load_lds_dwordx4 v[148:149], off
	s_add_i32 m0, s88, 0x2000
	s_add_u32 s88, s44, 0x20000
	v_lshl_add_u64 v[192:193], s[44:45], 0, v[134:135]
	s_addc_u32 s89, s45, 0
	s_add_i32 s90, s81, s62
	global_load_lds_dwordx4 v[192:193], off
	v_lshl_add_u64 v[220:221], s[88:89], 0, v[130:131]
	s_mov_b32 m0, s90
	v_lshl_add_u64 v[222:223], s[58:59], 0, v[132:133]
	global_load_lds_dwordx4 v[220:221], off
	v_lshl_add_u64 v[220:221], s[88:89], 0, v[134:135]
	s_add_i32 m0, s90, 0x2000
	s_nop 0
	global_load_lds_dwordx4 v[220:221], off
	v_lshl_add_u64 v[220:221], s[58:59], 0, v[128:129]
	s_waitcnt vmcnt(6)
	s_waitcnt lgkmcnt(0)
	s_barrier
	s_setprio 1
	s_waitcnt lgkmcnt(0)
	v_mfma_f32_16x16x32_bf16 v[60:63], v[144:147], v[184:187], v[60:63]
	v_mfma_f32_16x16x32_bf16 v[56:59], v[160:163], v[184:187], v[56:59]
	v_mfma_f32_16x16x32_bf16 v[44:47], v[144:147], v[196:199], v[44:47]
	v_mfma_f32_16x16x32_bf16 v[40:43], v[160:163], v[196:199], v[40:43]
	v_mfma_f32_16x16x32_bf16 v[28:31], v[144:147], v[204:207], v[28:31]
	v_mfma_f32_16x16x32_bf16 v[24:27], v[160:163], v[204:207], v[24:27]
	v_mfma_f32_16x16x32_bf16 v[12:15], v[144:147], v[212:215], v[12:15]
	v_mfma_f32_16x16x32_bf16 v[8:11], v[160:163], v[212:215], v[8:11]
	v_mfma_f32_16x16x32_bf16 v[60:63], v[156:159], v[188:191], v[60:63]
	v_mfma_f32_16x16x32_bf16 v[56:59], v[164:167], v[188:191], v[56:59]
	v_mfma_f32_16x16x32_bf16 v[44:47], v[156:159], v[200:203], v[44:47]
	v_mfma_f32_16x16x32_bf16 v[40:43], v[164:167], v[200:203], v[40:43]
	v_mfma_f32_16x16x32_bf16 v[28:31], v[156:159], v[208:211], v[28:31]
	v_mfma_f32_16x16x32_bf16 v[24:27], v[164:167], v[208:211], v[24:27]
	v_mfma_f32_16x16x32_bf16 v[12:15], v[156:159], v[216:219], v[12:15]
	v_mfma_f32_16x16x32_bf16 v[8:11], v[164:167], v[216:219], v[8:11]
	s_setprio 0
	s_setprio 1
	v_mfma_f32_16x16x32_bf16 v[52:55], v[168:171], v[184:187], v[52:55]
	v_mfma_f32_16x16x32_bf16 v[48:51], v[176:179], v[184:187], v[48:51]
	v_mfma_f32_16x16x32_bf16 v[36:39], v[168:171], v[196:199], v[36:39]
	v_mfma_f32_16x16x32_bf16 v[32:35], v[176:179], v[196:199], v[32:35]
	v_mfma_f32_16x16x32_bf16 v[20:23], v[168:171], v[204:207], v[20:23]
	v_mfma_f32_16x16x32_bf16 v[16:19], v[176:179], v[204:207], v[16:19]
	v_mfma_f32_16x16x32_bf16 v[4:7], v[168:171], v[212:215], v[4:7]
	v_mfma_f32_16x16x32_bf16 v[0:3], v[176:179], v[212:215], v[0:3]
	v_mfma_f32_16x16x32_bf16 v[52:55], v[172:175], v[188:191], v[52:55]
	v_mfma_f32_16x16x32_bf16 v[48:51], v[180:183], v[188:191], v[48:51]
	v_mfma_f32_16x16x32_bf16 v[36:39], v[172:175], v[200:203], v[36:39]
	v_mfma_f32_16x16x32_bf16 v[32:35], v[180:183], v[200:203], v[32:35]
	v_mfma_f32_16x16x32_bf16 v[20:23], v[172:175], v[208:211], v[20:23]
	v_mfma_f32_16x16x32_bf16 v[16:19], v[180:183], v[208:211], v[16:19]
	v_mfma_f32_16x16x32_bf16 v[4:7], v[172:175], v[216:219], v[4:7]
	v_mfma_f32_16x16x32_bf16 v[0:3], v[180:183], v[216:219], v[0:3]
	s_setprio 0
	s_barrier
	s_add_i32 s88, 0, 0x18000
	s_add_i32 s89, 0, 0x1c000
	v_add_u32_e32 v164, s88, v151
	v_add_u32_e32 v180, s89, v151
	ds_read_b128 v[144:147], v164
	ds_read_b128 v[156:159], v164 offset:1024
	ds_read_b128 v[160:163], v164 offset:2048
	ds_read_b128 v[164:167], v164 offset:3072
	ds_read_b128 v[168:171], v180
	ds_read_b128 v[172:175], v180 offset:1024
	ds_read_b128 v[176:179], v180 offset:2048
	ds_read_b128 v[180:183], v180 offset:3072
	s_add_u32 s58, s58, 0x20000
	s_addc_u32 s59, s59, 0
	v_lshl_add_u64 v[224:225], s[58:59], 0, v[128:129]
	ds_read_b128 v[184:187], v155 offset:32768
	ds_read_b128 v[188:191], v155 offset:33792
	ds_read_b128 v[196:199], v155 offset:34816
	ds_read_b128 v[200:203], v155 offset:35840
	ds_read_b128 v[204:207], v155 offset:36864
	ds_read_b128 v[208:211], v155 offset:37888
	ds_read_b128 v[212:215], v155 offset:38912
	ds_read_b128 v[216:219], v155 offset:39936
	s_mov_b32 m0, s41
	s_nop 0
	global_load_lds_dwordx4 v[220:221], off
	s_mov_b32 m0, s63
	s_nop 0
	global_load_lds_dwordx4 v[222:223], off
	s_mov_b32 m0, s70
	s_nop 0
	global_load_lds_dwordx4 v[224:225], off
	v_lshl_add_u64 v[224:225], s[58:59], 0, v[132:133]
	s_mov_b32 m0, s71
	s_nop 0
	global_load_lds_dwordx4 v[224:225], off
	s_waitcnt vmcnt(8)
	s_waitcnt lgkmcnt(0)
	s_barrier
	s_setprio 1
	s_waitcnt lgkmcnt(0)
	v_mfma_f32_16x16x32_bf16 v[124:127], v[144:147], v[184:187], v[124:127]
	v_mfma_f32_16x16x32_bf16 v[120:123], v[160:163], v[184:187], v[120:123]
	v_mfma_f32_16x16x32_bf16 v[108:111], v[144:147], v[196:199], v[108:111]
	v_mfma_f32_16x16x32_bf16 v[104:107], v[160:163], v[196:199], v[104:107]
	v_mfma_f32_16x16x32_bf16 v[92:95], v[144:147], v[204:207], v[92:95]
	v_mfma_f32_16x16x32_bf16 v[88:91], v[160:163], v[204:207], v[88:91]
	v_mfma_f32_16x16x32_bf16 v[76:79], v[144:147], v[212:215], v[76:79]
	v_mfma_f32_16x16x32_bf16 v[72:75], v[160:163], v[212:215], v[72:75]
	v_mfma_f32_16x16x32_bf16 v[124:127], v[156:159], v[188:191], v[124:127]
	v_mfma_f32_16x16x32_bf16 v[120:123], v[164:167], v[188:191], v[120:123]
	v_mfma_f32_16x16x32_bf16 v[108:111], v[156:159], v[200:203], v[108:111]
	v_mfma_f32_16x16x32_bf16 v[104:107], v[164:167], v[200:203], v[104:107]
	v_mfma_f32_16x16x32_bf16 v[92:95], v[156:159], v[208:211], v[92:95]
	v_mfma_f32_16x16x32_bf16 v[88:91], v[164:167], v[208:211], v[88:91]
	v_mfma_f32_16x16x32_bf16 v[76:79], v[156:159], v[216:219], v[76:79]
	v_mfma_f32_16x16x32_bf16 v[72:75], v[164:167], v[216:219], v[72:75]
	s_setprio 0
	s_setprio 1
	v_mfma_f32_16x16x32_bf16 v[116:119], v[168:171], v[184:187], v[116:119]
	v_mfma_f32_16x16x32_bf16 v[112:115], v[176:179], v[184:187], v[112:115]
	v_mfma_f32_16x16x32_bf16 v[100:103], v[168:171], v[196:199], v[100:103]
	v_mfma_f32_16x16x32_bf16 v[96:99], v[176:179], v[196:199], v[96:99]
	v_mfma_f32_16x16x32_bf16 v[84:87], v[168:171], v[204:207], v[84:87]
	v_mfma_f32_16x16x32_bf16 v[80:83], v[176:179], v[204:207], v[80:83]
	v_mfma_f32_16x16x32_bf16 v[68:71], v[168:171], v[212:215], v[68:71]
	v_mfma_f32_16x16x32_bf16 v[64:67], v[176:179], v[212:215], v[64:67]
	v_mfma_f32_16x16x32_bf16 v[116:119], v[172:175], v[188:191], v[116:119]
	v_mfma_f32_16x16x32_bf16 v[112:115], v[180:183], v[188:191], v[112:115]
	v_mfma_f32_16x16x32_bf16 v[100:103], v[172:175], v[200:203], v[100:103]
	v_mfma_f32_16x16x32_bf16 v[96:99], v[180:183], v[200:203], v[96:99]
	v_mfma_f32_16x16x32_bf16 v[84:87], v[172:175], v[208:211], v[84:87]
	v_mfma_f32_16x16x32_bf16 v[80:83], v[180:183], v[208:211], v[80:83]
	v_mfma_f32_16x16x32_bf16 v[68:71], v[172:175], v[216:219], v[68:71]
	v_mfma_f32_16x16x32_bf16 v[64:67], v[180:183], v[216:219], v[64:67]
	s_setprio 0
	s_barrier
	s_add_i32 s58, s88, s62
	v_lshl_add_u64 v[148:149], v[148:149], 0, s[20:21]
	s_mov_b32 m0, s58
	ds_read_b128 v[184:187], v155 offset:49152
	ds_read_b128 v[188:191], v155 offset:50176
	ds_read_b128 v[196:199], v155 offset:51200
	ds_read_b128 v[200:203], v155 offset:52224
	ds_read_b128 v[204:207], v155 offset:53248
	ds_read_b128 v[208:211], v155 offset:54272
	ds_read_b128 v[212:215], v155 offset:55296
	ds_read_b128 v[216:219], v155 offset:56320
	global_load_lds_dwordx4 v[148:149], off
	s_add_i32 m0, s58, 0x2000
	s_add_u32 s44, s44, 0x20080
	v_lshl_add_u64 v[148:149], v[192:193], 0, s[20:21]
	s_addc_u32 s45, s45, 0
	s_add_i32 s58, s89, s62
	global_load_lds_dwordx4 v[148:149], off
	v_lshl_add_u64 v[148:149], s[44:45], 0, v[130:131]
	s_mov_b32 m0, s58
	s_nop 0
	global_load_lds_dwordx4 v[148:149], off
	v_lshl_add_u64 v[148:149], s[44:45], 0, v[134:135]
	s_add_i32 m0, s58, 0x2000
	s_nop 0
	global_load_lds_dwordx4 v[148:149], off
	s_waitcnt vmcnt(6)
	s_waitcnt lgkmcnt(0)
	s_barrier
	s_setprio 1
	s_waitcnt lgkmcnt(0)
	v_mfma_f32_16x16x32_bf16 v[60:63], v[144:147], v[184:187], v[60:63]
	v_mfma_f32_16x16x32_bf16 v[56:59], v[160:163], v[184:187], v[56:59]
	v_mfma_f32_16x16x32_bf16 v[44:47], v[144:147], v[196:199], v[44:47]
	v_mfma_f32_16x16x32_bf16 v[40:43], v[160:163], v[196:199], v[40:43]
	v_mfma_f32_16x16x32_bf16 v[28:31], v[144:147], v[204:207], v[28:31]
	v_mfma_f32_16x16x32_bf16 v[24:27], v[160:163], v[204:207], v[24:27]
	v_mfma_f32_16x16x32_bf16 v[12:15], v[144:147], v[212:215], v[12:15]
	v_mfma_f32_16x16x32_bf16 v[8:11], v[160:163], v[212:215], v[8:11]
	v_mfma_f32_16x16x32_bf16 v[60:63], v[156:159], v[188:191], v[60:63]
	v_mfma_f32_16x16x32_bf16 v[56:59], v[164:167], v[188:191], v[56:59]
	v_mfma_f32_16x16x32_bf16 v[44:47], v[156:159], v[200:203], v[44:47]
	v_mfma_f32_16x16x32_bf16 v[40:43], v[164:167], v[200:203], v[40:43]
	v_mfma_f32_16x16x32_bf16 v[28:31], v[156:159], v[208:211], v[28:31]
	v_mfma_f32_16x16x32_bf16 v[24:27], v[164:167], v[208:211], v[24:27]
	v_mfma_f32_16x16x32_bf16 v[12:15], v[156:159], v[216:219], v[12:15]
	v_mfma_f32_16x16x32_bf16 v[8:11], v[164:167], v[216:219], v[8:11]
	s_setprio 0
	s_setprio 1
	v_mfma_f32_16x16x32_bf16 v[52:55], v[168:171], v[184:187], v[52:55]
	v_mfma_f32_16x16x32_bf16 v[48:51], v[176:179], v[184:187], v[48:51]
	v_mfma_f32_16x16x32_bf16 v[36:39], v[168:171], v[196:199], v[36:39]
	v_mfma_f32_16x16x32_bf16 v[32:35], v[176:179], v[196:199], v[32:35]
	v_mfma_f32_16x16x32_bf16 v[20:23], v[168:171], v[204:207], v[20:23]
	v_mfma_f32_16x16x32_bf16 v[16:19], v[176:179], v[204:207], v[16:19]
	v_mfma_f32_16x16x32_bf16 v[4:7], v[168:171], v[212:215], v[4:7]
	v_mfma_f32_16x16x32_bf16 v[0:3], v[176:179], v[212:215], v[0:3]
	v_mfma_f32_16x16x32_bf16 v[52:55], v[172:175], v[188:191], v[52:55]
	v_mfma_f32_16x16x32_bf16 v[48:51], v[180:183], v[188:191], v[48:51]
	v_mfma_f32_16x16x32_bf16 v[36:39], v[172:175], v[200:203], v[36:39]
	v_mfma_f32_16x16x32_bf16 v[32:35], v[180:183], v[200:203], v[32:35]
	v_mfma_f32_16x16x32_bf16 v[20:23], v[172:175], v[208:211], v[20:23]
	v_mfma_f32_16x16x32_bf16 v[16:19], v[180:183], v[208:211], v[16:19]
	v_mfma_f32_16x16x32_bf16 v[4:7], v[172:175], v[216:219], v[4:7]
	v_mfma_f32_16x16x32_bf16 v[0:3], v[180:183], v[216:219], v[0:3]
	s_setprio 0
	s_barrier
	v_lshl_add_u64 v[220:221], v[220:221], 0, s[20:21]
	s_mov_b32 m0, s73
	s_nop 0
	global_load_lds_dwordx4 v[220:221], off
	v_lshl_add_u64 v[222:223], v[222:223], 0, s[20:21]
	s_mov_b32 m0, s78
	s_nop 0
	global_load_lds_dwordx4 v[222:223], off
	s_add_i32 s87, s87, 2
	s_add_u32 s42, s42, 0x100
	s_addc_u32 s43, s43, 0
	s_add_u32 s85, s85, 0x100
	s_addc_u32 s86, s86, 0
	s_cmp_gt_u32 s87, 5
	s_cbranch_scc0 .LBB0_1023
	s_and_b64 vcc, exec, s[22:23]
	s_cbranch_vccz .LBB0_1026
	s_barrier

.LBB0_1421:
	ds_read_b128 v[146:149], v155
	ds_read_b128 v[160:163], v155 offset:1024
	ds_read_b128 v[164:167], v155 offset:2048
	ds_read_b128 v[168:171], v155 offset:3072
	ds_read_b128 v[172:175], v156
	ds_read_b128 v[176:179], v156 offset:1024
	ds_read_b128 v[180:183], v156 offset:2048
	ds_read_b128 v[184:187], v156 offset:3072
	s_add_u32 s40, s0, 0xfffc0080
	s_addc_u32 s41, s1, -1
	s_cmp_eq_u32 s83, 12
	s_cselect_b32 s43, s25, s41
	s_cselect_b32 s42, s27, s40
	s_cselect_b32 s41, s31, s82
	s_cselect_b32 s40, s30, s29
	v_lshl_add_u64 v[150:151], s[0:1], 0, v[138:139]
	s_add_i32 m0, s39, 0xc000
	ds_read_b128 v[188:191], v157
	ds_read_b128 v[196:199], v157 offset:1024
	ds_read_b128 v[200:203], v157 offset:2048
	ds_read_b128 v[204:207], v157 offset:3072
	ds_read_b128 v[208:211], v157 offset:4096
	ds_read_b128 v[212:215], v157 offset:5120
	ds_read_b128 v[216:219], v157 offset:6144
	ds_read_b128 v[220:223], v157 offset:7168
	global_load_lds_dwordx4 v[150:151], off
	v_lshl_add_u64 v[150:151], s[0:1], 0, v[140:141]
	s_add_i32 m0, s39, 0xe000
	s_nop 0
	global_load_lds_dwordx4 v[150:151], off
	s_waitcnt vmcnt(8)
	s_waitcnt lgkmcnt(0)
	s_barrier
	s_setprio 1
	s_waitcnt lgkmcnt(0)
	v_mfma_f32_16x16x32_bf16 v[124:127], v[146:149], v[188:191], v[124:127]
	v_mfma_f32_16x16x32_bf16 v[120:123], v[164:167], v[188:191], v[120:123]
	v_mfma_f32_16x16x32_bf16 v[108:111], v[146:149], v[200:203], v[108:111]
	v_mfma_f32_16x16x32_bf16 v[104:107], v[164:167], v[200:203], v[104:107]
	v_mfma_f32_16x16x32_bf16 v[92:95], v[146:149], v[208:211], v[92:95]
	v_mfma_f32_16x16x32_bf16 v[88:91], v[164:167], v[208:211], v[88:91]
	v_mfma_f32_16x16x32_bf16 v[76:79], v[146:149], v[216:219], v[76:79]
	v_mfma_f32_16x16x32_bf16 v[72:75], v[164:167], v[216:219], v[72:75]
	v_mfma_f32_16x16x32_bf16 v[124:127], v[160:163], v[196:199], v[124:127]
	v_mfma_f32_16x16x32_bf16 v[120:123], v[168:171], v[196:199], v[120:123]
	v_mfma_f32_16x16x32_bf16 v[108:111], v[160:163], v[204:207], v[108:111]
	v_mfma_f32_16x16x32_bf16 v[104:107], v[168:171], v[204:207], v[104:107]
	v_mfma_f32_16x16x32_bf16 v[92:95], v[160:163], v[212:215], v[92:95]
	v_mfma_f32_16x16x32_bf16 v[88:91], v[168:171], v[212:215], v[88:91]
	v_mfma_f32_16x16x32_bf16 v[76:79], v[160:163], v[220:223], v[76:79]
	v_mfma_f32_16x16x32_bf16 v[72:75], v[168:171], v[220:223], v[72:75]
	s_setprio 0
	s_setprio 1
	v_mfma_f32_16x16x32_bf16 v[116:119], v[172:175], v[188:191], v[116:119]
	v_mfma_f32_16x16x32_bf16 v[112:115], v[180:183], v[188:191], v[112:115]
	v_mfma_f32_16x16x32_bf16 v[100:103], v[172:175], v[200:203], v[100:103]
	v_mfma_f32_16x16x32_bf16 v[96:99], v[180:183], v[200:203], v[96:99]
	v_mfma_f32_16x16x32_bf16 v[84:87], v[172:175], v[208:211], v[84:87]
	v_mfma_f32_16x16x32_bf16 v[80:83], v[180:183], v[208:211], v[80:83]
	v_mfma_f32_16x16x32_bf16 v[68:71], v[172:175], v[216:219], v[68:71]
	v_mfma_f32_16x16x32_bf16 v[64:67], v[180:183], v[216:219], v[64:67]
	v_mfma_f32_16x16x32_bf16 v[116:119], v[176:179], v[196:199], v[116:119]
	v_mfma_f32_16x16x32_bf16 v[112:115], v[184:187], v[196:199], v[112:115]
	v_mfma_f32_16x16x32_bf16 v[100:103], v[176:179], v[204:207], v[100:103]
	v_mfma_f32_16x16x32_bf16 v[96:99], v[184:187], v[204:207], v[96:99]
	v_mfma_f32_16x16x32_bf16 v[84:87], v[176:179], v[212:215], v[84:87]
	v_mfma_f32_16x16x32_bf16 v[80:83], v[184:187], v[212:215], v[80:83]
	v_mfma_f32_16x16x32_bf16 v[68:71], v[176:179], v[220:223], v[68:71]
	v_mfma_f32_16x16x32_bf16 v[64:67], v[184:187], v[220:223], v[64:67]
	s_setprio 0
	s_barrier
	s_add_i32 s84, s78, s60
	v_lshl_add_u64 v[150:151], s[40:41], 0, v[132:133]
	s_mov_b32 m0, s84
	ds_read_b128 v[188:191], v157 offset:16384
	ds_read_b128 v[196:199], v157 offset:17408
	ds_read_b128 v[200:203], v157 offset:18432
	ds_read_b128 v[204:207], v157 offset:19456
	ds_read_b128 v[208:211], v157 offset:20480
	ds_read_b128 v[212:215], v157 offset:21504
	ds_read_b128 v[216:219], v157 offset:22528
	ds_read_b128 v[220:223], v157 offset:23552
	global_load_lds_dwordx4 v[150:151], off
	s_add_i32 m0, s84, 0x2000
	s_add_u32 s84, s40, 0x40000
	v_lshl_add_u64 v[192:193], s[40:41], 0, v[136:137]
	s_addc_u32 s85, s41, 0
	s_add_i32 s86, s79, s60
	global_load_lds_dwordx4 v[192:193], off
	v_lshl_add_u64 v[224:225], s[84:85], 0, v[132:133]
	s_mov_b32 m0, s86
	v_lshl_add_u64 v[226:227], s[42:43], 0, v[134:135]
	global_load_lds_dwordx4 v[224:225], off
	v_lshl_add_u64 v[224:225], s[84:85], 0, v[136:137]
	s_add_i32 m0, s86, 0x2000
	s_nop 0
	global_load_lds_dwordx4 v[224:225], off
	v_lshl_add_u64 v[224:225], s[42:43], 0, v[130:131]
	s_waitcnt vmcnt(6)
	s_waitcnt lgkmcnt(0)
	s_barrier
	s_setprio 1
	s_waitcnt lgkmcnt(0)
	v_mfma_f32_16x16x32_bf16 v[60:63], v[146:149], v[188:191], v[60:63]
	v_mfma_f32_16x16x32_bf16 v[56:59], v[164:167], v[188:191], v[56:59]
	v_mfma_f32_16x16x32_bf16 v[44:47], v[146:149], v[200:203], v[44:47]
	v_mfma_f32_16x16x32_bf16 v[40:43], v[164:167], v[200:203], v[40:43]
	v_mfma_f32_16x16x32_bf16 v[28:31], v[146:149], v[208:211], v[28:31]
	v_mfma_f32_16x16x32_bf16 v[24:27], v[164:167], v[208:211], v[24:27]
	v_mfma_f32_16x16x32_bf16 v[12:15], v[146:149], v[216:219], v[12:15]
	v_mfma_f32_16x16x32_bf16 v[8:11], v[164:167], v[216:219], v[8:11]
	v_mfma_f32_16x16x32_bf16 v[60:63], v[160:163], v[196:199], v[60:63]
	v_mfma_f32_16x16x32_bf16 v[56:59], v[168:171], v[196:199], v[56:59]
	v_mfma_f32_16x16x32_bf16 v[44:47], v[160:163], v[204:207], v[44:47]
	v_mfma_f32_16x16x32_bf16 v[40:43], v[168:171], v[204:207], v[40:43]
	v_mfma_f32_16x16x32_bf16 v[28:31], v[160:163], v[212:215], v[28:31]
	v_mfma_f32_16x16x32_bf16 v[24:27], v[168:171], v[212:215], v[24:27]
	v_mfma_f32_16x16x32_bf16 v[12:15], v[160:163], v[220:223], v[12:15]
	v_mfma_f32_16x16x32_bf16 v[8:11], v[168:171], v[220:223], v[8:11]
	s_setprio 0
	s_setprio 1
	v_mfma_f32_16x16x32_bf16 v[52:55], v[172:175], v[188:191], v[52:55]
	v_mfma_f32_16x16x32_bf16 v[48:51], v[180:183], v[188:191], v[48:51]
	v_mfma_f32_16x16x32_bf16 v[36:39], v[172:175], v[200:203], v[36:39]
	v_mfma_f32_16x16x32_bf16 v[32:35], v[180:183], v[200:203], v[32:35]
	v_mfma_f32_16x16x32_bf16 v[20:23], v[172:175], v[208:211], v[20:23]
	v_mfma_f32_16x16x32_bf16 v[16:19], v[180:183], v[208:211], v[16:19]
	v_mfma_f32_16x16x32_bf16 v[4:7], v[172:175], v[216:219], v[4:7]
	v_mfma_f32_16x16x32_bf16 v[0:3], v[180:183], v[216:219], v[0:3]
	v_mfma_f32_16x16x32_bf16 v[52:55], v[176:179], v[196:199], v[52:55]
	v_mfma_f32_16x16x32_bf16 v[48:51], v[184:187], v[196:199], v[48:51]
	v_mfma_f32_16x16x32_bf16 v[36:39], v[176:179], v[204:207], v[36:39]
	v_mfma_f32_16x16x32_bf16 v[32:35], v[184:187], v[204:207], v[32:35]
	v_mfma_f32_16x16x32_bf16 v[20:23], v[176:179], v[212:215], v[20:23]
	v_mfma_f32_16x16x32_bf16 v[16:19], v[184:187], v[212:215], v[16:19]
	v_mfma_f32_16x16x32_bf16 v[4:7], v[176:179], v[220:223], v[4:7]
	v_mfma_f32_16x16x32_bf16 v[0:3], v[184:187], v[220:223], v[0:3]
	s_setprio 0
	s_barrier
	s_add_i32 s84, 0, 0x18000
	v_add_u32_e32 v159, s84, v153
	s_add_i32 s85, 0, 0x1c000
	ds_read_b128 v[146:149], v159
	ds_read_b128 v[160:163], v159 offset:1024
	ds_read_b128 v[164:167], v159 offset:2048
	ds_read_b128 v[168:171], v159 offset:3072
	v_add_u32_e32 v159, s85, v153
	ds_read_b128 v[172:175], v159
	ds_read_b128 v[176:179], v159 offset:1024
	ds_read_b128 v[180:183], v159 offset:2048
	ds_read_b128 v[184:187], v159 offset:3072
	s_add_u32 s42, s42, 0x40000
	s_addc_u32 s43, s43, 0
	v_lshl_add_u64 v[228:229], s[42:43], 0, v[130:131]
	ds_read_b128 v[188:191], v157 offset:32768
	ds_read_b128 v[196:199], v157 offset:33792
	ds_read_b128 v[200:203], v157 offset:34816
	ds_read_b128 v[204:207], v157 offset:35840
	ds_read_b128 v[208:211], v157 offset:36864
	ds_read_b128 v[212:215], v157 offset:37888
	ds_read_b128 v[216:219], v157 offset:38912
	ds_read_b128 v[220:223], v157 offset:39936
	s_mov_b32 m0, s39
	s_nop 0
	global_load_lds_dwordx4 v[224:225], off
	s_mov_b32 m0, s61
	s_nop 0
	global_load_lds_dwordx4 v[226:227], off
	s_mov_b32 m0, s62
	s_nop 0
	global_load_lds_dwordx4 v[228:229], off
	v_lshl_add_u64 v[228:229], s[42:43], 0, v[134:135]
	s_mov_b32 m0, s63
	s_nop 0
	global_load_lds_dwordx4 v[228:229], off
	s_waitcnt vmcnt(8)
	s_waitcnt lgkmcnt(0)
	s_barrier
	s_setprio 1
	s_waitcnt lgkmcnt(0)
	v_mfma_f32_16x16x32_bf16 v[124:127], v[146:149], v[188:191], v[124:127]
	v_mfma_f32_16x16x32_bf16 v[120:123], v[164:167], v[188:191], v[120:123]
	v_mfma_f32_16x16x32_bf16 v[108:111], v[146:149], v[200:203], v[108:111]
	v_mfma_f32_16x16x32_bf16 v[104:107], v[164:167], v[200:203], v[104:107]
	v_mfma_f32_16x16x32_bf16 v[92:95], v[146:149], v[208:211], v[92:95]
	v_mfma_f32_16x16x32_bf16 v[88:91], v[164:167], v[208:211], v[88:91]
	v_mfma_f32_16x16x32_bf16 v[76:79], v[146:149], v[216:219], v[76:79]
	v_mfma_f32_16x16x32_bf16 v[72:75], v[164:167], v[216:219], v[72:75]
	v_mfma_f32_16x16x32_bf16 v[124:127], v[160:163], v[196:199], v[124:127]
	v_mfma_f32_16x16x32_bf16 v[120:123], v[168:171], v[196:199], v[120:123]
	v_mfma_f32_16x16x32_bf16 v[108:111], v[160:163], v[204:207], v[108:111]
	v_mfma_f32_16x16x32_bf16 v[104:107], v[168:171], v[204:207], v[104:107]
	v_mfma_f32_16x16x32_bf16 v[92:95], v[160:163], v[212:215], v[92:95]
	v_mfma_f32_16x16x32_bf16 v[88:91], v[168:171], v[212:215], v[88:91]
	v_mfma_f32_16x16x32_bf16 v[76:79], v[160:163], v[220:223], v[76:79]
	v_mfma_f32_16x16x32_bf16 v[72:75], v[168:171], v[220:223], v[72:75]
	s_setprio 0
	s_setprio 1
	v_mfma_f32_16x16x32_bf16 v[116:119], v[172:175], v[188:191], v[116:119]
	v_mfma_f32_16x16x32_bf16 v[112:115], v[180:183], v[188:191], v[112:115]
	v_mfma_f32_16x16x32_bf16 v[100:103], v[172:175], v[200:203], v[100:103]
	v_mfma_f32_16x16x32_bf16 v[96:99], v[180:183], v[200:203], v[96:99]
	v_mfma_f32_16x16x32_bf16 v[84:87], v[172:175], v[208:211], v[84:87]
	v_mfma_f32_16x16x32_bf16 v[80:83], v[180:183], v[208:211], v[80:83]
	v_mfma_f32_16x16x32_bf16 v[68:71], v[172:175], v[216:219], v[68:71]
	v_mfma_f32_16x16x32_bf16 v[64:67], v[180:183], v[216:219], v[64:67]
	v_mfma_f32_16x16x32_bf16 v[116:119], v[176:179], v[196:199], v[116:119]
	v_mfma_f32_16x16x32_bf16 v[112:115], v[184:187], v[196:199], v[112:115]
	v_mfma_f32_16x16x32_bf16 v[100:103], v[176:179], v[204:207], v[100:103]
	v_mfma_f32_16x16x32_bf16 v[96:99], v[184:187], v[204:207], v[96:99]
	v_mfma_f32_16x16x32_bf16 v[84:87], v[176:179], v[212:215], v[84:87]
	v_mfma_f32_16x16x32_bf16 v[80:83], v[184:187], v[212:215], v[80:83]
	v_mfma_f32_16x16x32_bf16 v[68:71], v[176:179], v[220:223], v[68:71]
	v_mfma_f32_16x16x32_bf16 v[64:67], v[184:187], v[220:223], v[64:67]
	s_setprio 0
	s_barrier
	s_add_i32 s42, s84, s60
	v_lshl_add_u64 v[150:151], v[150:151], 0, s[20:21]
	s_mov_b32 m0, s42
	ds_read_b128 v[188:191], v157 offset:49152
	ds_read_b128 v[196:199], v157 offset:50176
	ds_read_b128 v[200:203], v157 offset:51200
	ds_read_b128 v[204:207], v157 offset:52224
	ds_read_b128 v[208:211], v157 offset:53248
	ds_read_b128 v[212:215], v157 offset:54272
	ds_read_b128 v[216:219], v157 offset:55296
	ds_read_b128 v[220:223], v157 offset:56320
	global_load_lds_dwordx4 v[150:151], off
	s_add_i32 m0, s42, 0x2000
	s_add_u32 s40, s40, 0x40080
	v_lshl_add_u64 v[150:151], v[192:193], 0, s[20:21]
	s_addc_u32 s41, s41, 0
	s_add_i32 s42, s85, s60
	global_load_lds_dwordx4 v[150:151], off
	v_lshl_add_u64 v[150:151], s[40:41], 0, v[132:133]
	s_mov_b32 m0, s42
	s_nop 0
	global_load_lds_dwordx4 v[150:151], off
	v_lshl_add_u64 v[150:151], s[40:41], 0, v[136:137]
	s_add_i32 m0, s42, 0x2000
	s_nop 0
	global_load_lds_dwordx4 v[150:151], off
	s_waitcnt vmcnt(6)
	s_waitcnt lgkmcnt(0)
	s_barrier
	s_setprio 1
	s_waitcnt lgkmcnt(0)
	v_mfma_f32_16x16x32_bf16 v[60:63], v[146:149], v[188:191], v[60:63]
	v_mfma_f32_16x16x32_bf16 v[56:59], v[164:167], v[188:191], v[56:59]
	v_mfma_f32_16x16x32_bf16 v[44:47], v[146:149], v[200:203], v[44:47]
	v_mfma_f32_16x16x32_bf16 v[40:43], v[164:167], v[200:203], v[40:43]
	v_mfma_f32_16x16x32_bf16 v[28:31], v[146:149], v[208:211], v[28:31]
	v_mfma_f32_16x16x32_bf16 v[24:27], v[164:167], v[208:211], v[24:27]
	v_mfma_f32_16x16x32_bf16 v[12:15], v[146:149], v[216:219], v[12:15]
	v_mfma_f32_16x16x32_bf16 v[8:11], v[164:167], v[216:219], v[8:11]
	v_mfma_f32_16x16x32_bf16 v[60:63], v[160:163], v[196:199], v[60:63]
	v_mfma_f32_16x16x32_bf16 v[56:59], v[168:171], v[196:199], v[56:59]
	v_mfma_f32_16x16x32_bf16 v[44:47], v[160:163], v[204:207], v[44:47]
	v_mfma_f32_16x16x32_bf16 v[40:43], v[168:171], v[204:207], v[40:43]
	v_mfma_f32_16x16x32_bf16 v[28:31], v[160:163], v[212:215], v[28:31]
	v_mfma_f32_16x16x32_bf16 v[24:27], v[168:171], v[212:215], v[24:27]
	v_mfma_f32_16x16x32_bf16 v[12:15], v[160:163], v[220:223], v[12:15]
	v_mfma_f32_16x16x32_bf16 v[8:11], v[168:171], v[220:223], v[8:11]
	s_setprio 0
	s_setprio 1
	v_mfma_f32_16x16x32_bf16 v[52:55], v[172:175], v[188:191], v[52:55]
	v_mfma_f32_16x16x32_bf16 v[48:51], v[180:183], v[188:191], v[48:51]
	v_mfma_f32_16x16x32_bf16 v[36:39], v[172:175], v[200:203], v[36:39]
	v_mfma_f32_16x16x32_bf16 v[32:35], v[180:183], v[200:203], v[32:35]
	v_mfma_f32_16x16x32_bf16 v[20:23], v[172:175], v[208:211], v[20:23]
	v_mfma_f32_16x16x32_bf16 v[16:19], v[180:183], v[208:211], v[16:19]
	v_mfma_f32_16x16x32_bf16 v[4:7], v[172:175], v[216:219], v[4:7]
	v_mfma_f32_16x16x32_bf16 v[0:3], v[180:183], v[216:219], v[0:3]
	v_mfma_f32_16x16x32_bf16 v[52:55], v[176:179], v[196:199], v[52:55]
	v_mfma_f32_16x16x32_bf16 v[48:51], v[184:187], v[196:199], v[48:51]
	v_mfma_f32_16x16x32_bf16 v[36:39], v[176:179], v[204:207], v[36:39]
	v_mfma_f32_16x16x32_bf16 v[32:35], v[184:187], v[204:207], v[32:35]
	v_mfma_f32_16x16x32_bf16 v[20:23], v[176:179], v[212:215], v[20:23]
	v_mfma_f32_16x16x32_bf16 v[16:19], v[184:187], v[212:215], v[16:19]
	v_mfma_f32_16x16x32_bf16 v[4:7], v[176:179], v[220:223], v[4:7]
	v_mfma_f32_16x16x32_bf16 v[0:3], v[184:187], v[220:223], v[0:3]
	s_setprio 0
	s_barrier
	v_lshl_add_u64 v[224:225], v[224:225], 0, s[20:21]
	s_mov_b32 m0, s70
	s_nop 0
	global_load_lds_dwordx4 v[224:225], off
	v_lshl_add_u64 v[226:227], v[226:227], 0, s[20:21]
	s_mov_b32 m0, s71
	s_nop 0
	global_load_lds_dwordx4 v[226:227], off
	s_add_i32 s83, s83, 2
	s_add_u32 s0, s0, 0x100
	s_addc_u32 s1, s1, 0
	s_add_u32 s29, s29, 0x100
	s_addc_u32 s82, s82, 0
	s_cmp_gt_u32 s83, 13
	s_cbranch_scc0 .LBB0_1421
	s_and_b64 vcc, exec, s[22:23]
	s_cbranch_vccz .LBB0_1424
	s_barrier

.LBB0_1451:
	ds_read_b128 v[144:147], v159
	ds_read_b128 v[148:151], v159 offset:1024
	ds_read_b128 v[152:155], v159 offset:2048
	ds_read_b128 v[162:165], v159 offset:3072
	ds_read_b128 v[166:169], v160
	ds_read_b128 v[170:173], v160 offset:1024
	ds_read_b128 v[174:177], v160 offset:2048
	ds_read_b128 v[178:181], v160 offset:3072
	s_add_u32 s41, s58, 0xfffe0080
	s_addc_u32 s43, s59, -1
	s_cmp_eq_u32 s39, 4
	s_cselect_b32 s71, s1, s43
	s_cselect_b32 s70, s0, s41
	s_cselect_b32 s63, s45, s17
	s_cselect_b32 s62, s44, s15
	v_lshl_add_u64 v[216:217], s[58:59], 0, v[136:137]
	s_add_i32 m0, s83, 0xc000
	ds_read_b128 v[182:185], v161
	ds_read_b128 v[186:189], v161 offset:1024
	ds_read_b128 v[190:193], v161 offset:2048
	ds_read_b128 v[196:199], v161 offset:3072
	ds_read_b128 v[200:203], v161 offset:4096
	ds_read_b128 v[204:207], v161 offset:5120
	ds_read_b128 v[208:211], v161 offset:6144
	ds_read_b128 v[212:215], v161 offset:7168
	global_load_lds_dwordx4 v[216:217], off
	v_lshl_add_u64 v[216:217], s[58:59], 0, v[138:139]
	s_add_i32 m0, s83, 0xe000
	s_nop 0
	global_load_lds_dwordx4 v[216:217], off
	s_waitcnt vmcnt(8)
	s_waitcnt lgkmcnt(0)
	s_barrier
	s_setprio 1
	s_waitcnt lgkmcnt(0)
	v_mfma_f32_16x16x32_bf16 v[124:127], v[144:147], v[182:185], v[124:127]
	v_mfma_f32_16x16x32_bf16 v[120:123], v[152:155], v[182:185], v[120:123]
	v_mfma_f32_16x16x32_bf16 v[108:111], v[144:147], v[190:193], v[108:111]
	v_mfma_f32_16x16x32_bf16 v[104:107], v[152:155], v[190:193], v[104:107]
	v_mfma_f32_16x16x32_bf16 v[92:95], v[144:147], v[200:203], v[92:95]
	v_mfma_f32_16x16x32_bf16 v[88:91], v[152:155], v[200:203], v[88:91]
	v_mfma_f32_16x16x32_bf16 v[76:79], v[144:147], v[208:211], v[76:79]
	v_mfma_f32_16x16x32_bf16 v[72:75], v[152:155], v[208:211], v[72:75]
	v_mfma_f32_16x16x32_bf16 v[124:127], v[148:151], v[186:189], v[124:127]
	v_mfma_f32_16x16x32_bf16 v[120:123], v[162:165], v[186:189], v[120:123]
	v_mfma_f32_16x16x32_bf16 v[108:111], v[148:151], v[196:199], v[108:111]
	v_mfma_f32_16x16x32_bf16 v[104:107], v[162:165], v[196:199], v[104:107]
	v_mfma_f32_16x16x32_bf16 v[92:95], v[148:151], v[204:207], v[92:95]
	v_mfma_f32_16x16x32_bf16 v[88:91], v[162:165], v[204:207], v[88:91]
	v_mfma_f32_16x16x32_bf16 v[76:79], v[148:151], v[212:215], v[76:79]
	v_mfma_f32_16x16x32_bf16 v[72:75], v[162:165], v[212:215], v[72:75]
	s_setprio 0
	s_setprio 1
	v_mfma_f32_16x16x32_bf16 v[116:119], v[166:169], v[182:185], v[116:119]
	v_mfma_f32_16x16x32_bf16 v[112:115], v[174:177], v[182:185], v[112:115]
	v_mfma_f32_16x16x32_bf16 v[100:103], v[166:169], v[190:193], v[100:103]
	v_mfma_f32_16x16x32_bf16 v[96:99], v[174:177], v[190:193], v[96:99]
	v_mfma_f32_16x16x32_bf16 v[84:87], v[166:169], v[200:203], v[84:87]
	v_mfma_f32_16x16x32_bf16 v[80:83], v[174:177], v[200:203], v[80:83]
	v_mfma_f32_16x16x32_bf16 v[68:71], v[166:169], v[208:211], v[68:71]
	v_mfma_f32_16x16x32_bf16 v[64:67], v[174:177], v[208:211], v[64:67]
	v_mfma_f32_16x16x32_bf16 v[116:119], v[170:173], v[186:189], v[116:119]
	v_mfma_f32_16x16x32_bf16 v[112:115], v[178:181], v[186:189], v[112:115]
	v_mfma_f32_16x16x32_bf16 v[100:103], v[170:173], v[196:199], v[100:103]
	v_mfma_f32_16x16x32_bf16 v[96:99], v[178:181], v[196:199], v[96:99]
	v_mfma_f32_16x16x32_bf16 v[84:87], v[170:173], v[204:207], v[84:87]
	v_mfma_f32_16x16x32_bf16 v[80:83], v[178:181], v[204:207], v[80:83]
	v_mfma_f32_16x16x32_bf16 v[68:71], v[170:173], v[212:215], v[68:71]
	v_mfma_f32_16x16x32_bf16 v[64:67], v[178:181], v[212:215], v[64:67]
	s_setprio 0
	s_barrier
	s_add_i32 s41, s90, s80
	v_lshl_add_u64 v[216:217], s[62:63], 0, v[130:131]
	s_mov_b32 m0, s41
	ds_read_b128 v[182:185], v161 offset:16384
	ds_read_b128 v[186:189], v161 offset:17408
	ds_read_b128 v[190:193], v161 offset:18432
	ds_read_b128 v[196:199], v161 offset:19456
	ds_read_b128 v[200:203], v161 offset:20480
	ds_read_b128 v[204:207], v161 offset:21504
	ds_read_b128 v[208:211], v161 offset:22528
	ds_read_b128 v[212:215], v161 offset:23552
	global_load_lds_dwordx4 v[216:217], off
	s_add_i32 m0, s41, 0x2000
	s_add_u32 s94, s62, 0x20000
	v_lshl_add_u64 v[218:219], s[62:63], 0, v[134:135]
	s_addc_u32 s95, s63, 0
	s_add_i32 s41, s91, s80
	global_load_lds_dwordx4 v[218:219], off
	v_lshl_add_u64 v[220:221], s[94:95], 0, v[130:131]
	s_mov_b32 m0, s41
	v_lshl_add_u64 v[222:223], s[70:71], 0, v[132:133]
	global_load_lds_dwordx4 v[220:221], off
	v_lshl_add_u64 v[220:221], s[94:95], 0, v[134:135]
	s_add_i32 m0, s41, 0x2000
	s_nop 0
	global_load_lds_dwordx4 v[220:221], off
	v_lshl_add_u64 v[220:221], s[70:71], 0, v[128:129]
	s_waitcnt vmcnt(6)
	s_waitcnt lgkmcnt(0)
	s_barrier
	s_setprio 1
	s_waitcnt lgkmcnt(0)
	v_mfma_f32_16x16x32_bf16 v[60:63], v[144:147], v[182:185], v[60:63]
	v_mfma_f32_16x16x32_bf16 v[56:59], v[152:155], v[182:185], v[56:59]
	v_mfma_f32_16x16x32_bf16 v[44:47], v[144:147], v[190:193], v[44:47]
	v_mfma_f32_16x16x32_bf16 v[40:43], v[152:155], v[190:193], v[40:43]
	v_mfma_f32_16x16x32_bf16 v[28:31], v[144:147], v[200:203], v[28:31]
	v_mfma_f32_16x16x32_bf16 v[24:27], v[152:155], v[200:203], v[24:27]
	v_mfma_f32_16x16x32_bf16 v[12:15], v[144:147], v[208:211], v[12:15]
	v_mfma_f32_16x16x32_bf16 v[8:11], v[152:155], v[208:211], v[8:11]
	v_mfma_f32_16x16x32_bf16 v[60:63], v[148:151], v[186:189], v[60:63]
	v_mfma_f32_16x16x32_bf16 v[56:59], v[162:165], v[186:189], v[56:59]
	v_mfma_f32_16x16x32_bf16 v[44:47], v[148:151], v[196:199], v[44:47]
	v_mfma_f32_16x16x32_bf16 v[40:43], v[162:165], v[196:199], v[40:43]
	v_mfma_f32_16x16x32_bf16 v[28:31], v[148:151], v[204:207], v[28:31]
	v_mfma_f32_16x16x32_bf16 v[24:27], v[162:165], v[204:207], v[24:27]
	v_mfma_f32_16x16x32_bf16 v[12:15], v[148:151], v[212:215], v[12:15]
	v_mfma_f32_16x16x32_bf16 v[8:11], v[162:165], v[212:215], v[8:11]
	s_setprio 0
	s_setprio 1
	v_mfma_f32_16x16x32_bf16 v[52:55], v[166:169], v[182:185], v[52:55]
	v_mfma_f32_16x16x32_bf16 v[48:51], v[174:177], v[182:185], v[48:51]
	v_mfma_f32_16x16x32_bf16 v[36:39], v[166:169], v[190:193], v[36:39]
	v_mfma_f32_16x16x32_bf16 v[32:35], v[174:177], v[190:193], v[32:35]
	v_mfma_f32_16x16x32_bf16 v[20:23], v[166:169], v[200:203], v[20:23]
	v_mfma_f32_16x16x32_bf16 v[16:19], v[174:177], v[200:203], v[16:19]
	v_mfma_f32_16x16x32_bf16 v[4:7], v[166:169], v[208:211], v[4:7]
	v_mfma_f32_16x16x32_bf16 v[0:3], v[174:177], v[208:211], v[0:3]
	v_mfma_f32_16x16x32_bf16 v[52:55], v[170:173], v[186:189], v[52:55]
	v_mfma_f32_16x16x32_bf16 v[48:51], v[178:181], v[186:189], v[48:51]
	v_mfma_f32_16x16x32_bf16 v[36:39], v[170:173], v[196:199], v[36:39]
	v_mfma_f32_16x16x32_bf16 v[32:35], v[178:181], v[196:199], v[32:35]
	v_mfma_f32_16x16x32_bf16 v[20:23], v[170:173], v[204:207], v[20:23]
	v_mfma_f32_16x16x32_bf16 v[16:19], v[178:181], v[204:207], v[16:19]
	v_mfma_f32_16x16x32_bf16 v[4:7], v[170:173], v[212:215], v[4:7]
	v_mfma_f32_16x16x32_bf16 v[0:3], v[178:181], v[212:215], v[0:3]
	s_setprio 0
	s_barrier
	s_add_i32 s41, 0, 0x18000
	s_add_i32 s43, 0, 0x1c000
	v_add_u32_e32 v162, s41, v157
	v_add_u32_e32 v178, s43, v157
	ds_read_b128 v[144:147], v162
	ds_read_b128 v[148:151], v162 offset:1024
	ds_read_b128 v[152:155], v162 offset:2048
	ds_read_b128 v[162:165], v162 offset:3072
	ds_read_b128 v[166:169], v178
	ds_read_b128 v[170:173], v178 offset:1024
	ds_read_b128 v[174:177], v178 offset:2048
	ds_read_b128 v[178:181], v178 offset:3072
	s_add_u32 s70, s70, 0x20000
	s_addc_u32 s71, s71, 0
	v_lshl_add_u64 v[224:225], s[70:71], 0, v[128:129]
	ds_read_b128 v[182:185], v161 offset:32768
	ds_read_b128 v[186:189], v161 offset:33792
	ds_read_b128 v[190:193], v161 offset:34816
	ds_read_b128 v[196:199], v161 offset:35840
	ds_read_b128 v[200:203], v161 offset:36864
	ds_read_b128 v[204:207], v161 offset:37888
	ds_read_b128 v[208:211], v161 offset:38912
	ds_read_b128 v[212:215], v161 offset:39936
	s_mov_b32 m0, s83
	s_nop 0
	global_load_lds_dwordx4 v[220:221], off
	s_mov_b32 m0, s84
	s_nop 0
	global_load_lds_dwordx4 v[222:223], off
	s_mov_b32 m0, s85
	s_nop 0
	global_load_lds_dwordx4 v[224:225], off
	v_lshl_add_u64 v[224:225], s[70:71], 0, v[132:133]
	s_mov_b32 m0, s86
	s_nop 0
	global_load_lds_dwordx4 v[224:225], off
	s_waitcnt vmcnt(8)
	s_waitcnt lgkmcnt(0)
	s_barrier
	s_setprio 1
	s_waitcnt lgkmcnt(0)
	v_mfma_f32_16x16x32_bf16 v[124:127], v[144:147], v[182:185], v[124:127]
	v_mfma_f32_16x16x32_bf16 v[120:123], v[152:155], v[182:185], v[120:123]
	v_mfma_f32_16x16x32_bf16 v[108:111], v[144:147], v[190:193], v[108:111]
	v_mfma_f32_16x16x32_bf16 v[104:107], v[152:155], v[190:193], v[104:107]
	v_mfma_f32_16x16x32_bf16 v[92:95], v[144:147], v[200:203], v[92:95]
	v_mfma_f32_16x16x32_bf16 v[88:91], v[152:155], v[200:203], v[88:91]
	v_mfma_f32_16x16x32_bf16 v[76:79], v[144:147], v[208:211], v[76:79]
	v_mfma_f32_16x16x32_bf16 v[72:75], v[152:155], v[208:211], v[72:75]
	v_mfma_f32_16x16x32_bf16 v[124:127], v[148:151], v[186:189], v[124:127]
	v_mfma_f32_16x16x32_bf16 v[120:123], v[162:165], v[186:189], v[120:123]
	v_mfma_f32_16x16x32_bf16 v[108:111], v[148:151], v[196:199], v[108:111]
	v_mfma_f32_16x16x32_bf16 v[104:107], v[162:165], v[196:199], v[104:107]
	v_mfma_f32_16x16x32_bf16 v[92:95], v[148:151], v[204:207], v[92:95]
	v_mfma_f32_16x16x32_bf16 v[88:91], v[162:165], v[204:207], v[88:91]
	v_mfma_f32_16x16x32_bf16 v[76:79], v[148:151], v[212:215], v[76:79]
	v_mfma_f32_16x16x32_bf16 v[72:75], v[162:165], v[212:215], v[72:75]
	s_setprio 0
	s_setprio 1
	v_mfma_f32_16x16x32_bf16 v[116:119], v[166:169], v[182:185], v[116:119]
	v_mfma_f32_16x16x32_bf16 v[112:115], v[174:177], v[182:185], v[112:115]
	v_mfma_f32_16x16x32_bf16 v[100:103], v[166:169], v[190:193], v[100:103]
	v_mfma_f32_16x16x32_bf16 v[96:99], v[174:177], v[190:193], v[96:99]
	v_mfma_f32_16x16x32_bf16 v[84:87], v[166:169], v[200:203], v[84:87]
	v_mfma_f32_16x16x32_bf16 v[80:83], v[174:177], v[200:203], v[80:83]
	v_mfma_f32_16x16x32_bf16 v[68:71], v[166:169], v[208:211], v[68:71]
	v_mfma_f32_16x16x32_bf16 v[64:67], v[174:177], v[208:211], v[64:67]
	v_mfma_f32_16x16x32_bf16 v[116:119], v[170:173], v[186:189], v[116:119]
	v_mfma_f32_16x16x32_bf16 v[112:115], v[178:181], v[186:189], v[112:115]
	v_mfma_f32_16x16x32_bf16 v[100:103], v[170:173], v[196:199], v[100:103]
	v_mfma_f32_16x16x32_bf16 v[96:99], v[178:181], v[196:199], v[96:99]
	v_mfma_f32_16x16x32_bf16 v[84:87], v[170:173], v[204:207], v[84:87]
	v_mfma_f32_16x16x32_bf16 v[80:83], v[178:181], v[204:207], v[80:83]
	v_mfma_f32_16x16x32_bf16 v[68:71], v[170:173], v[212:215], v[68:71]
	v_mfma_f32_16x16x32_bf16 v[64:67], v[178:181], v[212:215], v[64:67]
	s_setprio 0
	s_barrier
	s_add_i32 s41, s41, s80
	v_lshl_add_u64 v[216:217], v[216:217], 0, s[26:27]
	s_mov_b32 m0, s41
	ds_read_b128 v[182:185], v161 offset:49152
	ds_read_b128 v[186:189], v161 offset:50176
	ds_read_b128 v[190:193], v161 offset:51200
	ds_read_b128 v[196:199], v161 offset:52224
	ds_read_b128 v[200:203], v161 offset:53248
	ds_read_b128 v[204:207], v161 offset:54272
	ds_read_b128 v[208:211], v161 offset:55296
	ds_read_b128 v[212:215], v161 offset:56320
	global_load_lds_dwordx4 v[216:217], off
	s_add_i32 m0, s41, 0x2000
	s_add_u32 s62, s62, 0x20080
	v_lshl_add_u64 v[216:217], v[218:219], 0, s[26:27]
	s_addc_u32 s63, s63, 0
	s_add_i32 s41, s43, s80
	global_load_lds_dwordx4 v[216:217], off
	v_lshl_add_u64 v[216:217], s[62:63], 0, v[130:131]
	s_mov_b32 m0, s41
	s_nop 0
	global_load_lds_dwordx4 v[216:217], off
	v_lshl_add_u64 v[216:217], s[62:63], 0, v[134:135]
	s_add_i32 m0, s41, 0x2000
	s_nop 0
	global_load_lds_dwordx4 v[216:217], off
	s_waitcnt vmcnt(6)
	s_waitcnt lgkmcnt(0)
	s_barrier
	s_setprio 1
	s_waitcnt lgkmcnt(0)
	v_mfma_f32_16x16x32_bf16 v[60:63], v[144:147], v[182:185], v[60:63]
	v_mfma_f32_16x16x32_bf16 v[56:59], v[152:155], v[182:185], v[56:59]
	v_mfma_f32_16x16x32_bf16 v[44:47], v[144:147], v[190:193], v[44:47]
	v_mfma_f32_16x16x32_bf16 v[40:43], v[152:155], v[190:193], v[40:43]
	v_mfma_f32_16x16x32_bf16 v[28:31], v[144:147], v[200:203], v[28:31]
	v_mfma_f32_16x16x32_bf16 v[24:27], v[152:155], v[200:203], v[24:27]
	v_mfma_f32_16x16x32_bf16 v[12:15], v[144:147], v[208:211], v[12:15]
	v_mfma_f32_16x16x32_bf16 v[8:11], v[152:155], v[208:211], v[8:11]
	v_mfma_f32_16x16x32_bf16 v[60:63], v[148:151], v[186:189], v[60:63]
	v_mfma_f32_16x16x32_bf16 v[56:59], v[162:165], v[186:189], v[56:59]
	v_mfma_f32_16x16x32_bf16 v[44:47], v[148:151], v[196:199], v[44:47]
	v_mfma_f32_16x16x32_bf16 v[40:43], v[162:165], v[196:199], v[40:43]
	v_mfma_f32_16x16x32_bf16 v[28:31], v[148:151], v[204:207], v[28:31]
	v_mfma_f32_16x16x32_bf16 v[24:27], v[162:165], v[204:207], v[24:27]
	v_mfma_f32_16x16x32_bf16 v[12:15], v[148:151], v[212:215], v[12:15]
	v_mfma_f32_16x16x32_bf16 v[8:11], v[162:165], v[212:215], v[8:11]
	s_setprio 0
	s_setprio 1
	v_mfma_f32_16x16x32_bf16 v[52:55], v[166:169], v[182:185], v[52:55]
	v_mfma_f32_16x16x32_bf16 v[48:51], v[174:177], v[182:185], v[48:51]
	v_mfma_f32_16x16x32_bf16 v[36:39], v[166:169], v[190:193], v[36:39]
	v_mfma_f32_16x16x32_bf16 v[32:35], v[174:177], v[190:193], v[32:35]
	v_mfma_f32_16x16x32_bf16 v[20:23], v[166:169], v[200:203], v[20:23]
	v_mfma_f32_16x16x32_bf16 v[16:19], v[174:177], v[200:203], v[16:19]
	v_mfma_f32_16x16x32_bf16 v[4:7], v[166:169], v[208:211], v[4:7]
	v_mfma_f32_16x16x32_bf16 v[0:3], v[174:177], v[208:211], v[0:3]
	v_mfma_f32_16x16x32_bf16 v[52:55], v[170:173], v[186:189], v[52:55]
	v_mfma_f32_16x16x32_bf16 v[48:51], v[178:181], v[186:189], v[48:51]
	v_mfma_f32_16x16x32_bf16 v[36:39], v[170:173], v[196:199], v[36:39]
	v_mfma_f32_16x16x32_bf16 v[32:35], v[178:181], v[196:199], v[32:35]
	v_mfma_f32_16x16x32_bf16 v[20:23], v[170:173], v[204:207], v[20:23]
	v_mfma_f32_16x16x32_bf16 v[16:19], v[178:181], v[204:207], v[16:19]
	v_mfma_f32_16x16x32_bf16 v[4:7], v[170:173], v[212:215], v[4:7]
	v_mfma_f32_16x16x32_bf16 v[0:3], v[178:181], v[212:215], v[0:3]
	s_setprio 0
	s_barrier
	v_lshl_add_u64 v[220:221], v[220:221], 0, s[26:27]
	s_mov_b32 m0, s87
	s_nop 0
	global_load_lds_dwordx4 v[220:221], off
	v_lshl_add_u64 v[222:223], v[222:223], 0, s[26:27]
	s_mov_b32 m0, s88
	s_nop 0
	global_load_lds_dwordx4 v[222:223], off
	s_add_i32 s39, s39, 2
	s_add_u32 s58, s58, 0x100
	s_addc_u32 s59, s59, 0
	s_add_u32 s15, s15, 0x100
	s_addc_u32 s17, s17, 0
	s_cmp_gt_u32 s39, 5
	s_cbranch_scc0 .LBB0_1451
	s_and_b64 vcc, exec, s[28:29]
	s_cbranch_vccz .LBB0_1454
	s_barrier

.LBB0_1625:
	ds_read_b128 v[144:147], v151
	ds_read_b128 v[156:159], v151 offset:1024
	ds_read_b128 v[160:163], v151 offset:2048
	ds_read_b128 v[164:167], v151 offset:3072
	ds_read_b128 v[168:171], v152
	ds_read_b128 v[172:175], v152 offset:1024
	ds_read_b128 v[176:179], v152 offset:2048
	ds_read_b128 v[180:183], v152 offset:3072
	s_add_u32 s42, s40, 0xfffc0080
	s_addc_u32 s43, s41, -1
	s_cmp_eq_u32 s87, 12
	s_cselect_b32 s45, s31, s43
	s_cselect_b32 s44, s39, s42
	s_cselect_b32 s43, s29, s86
	s_cselect_b32 s42, s84, s85
	v_lshl_add_u64 v[192:193], s[40:41], 0, v[136:137]
	s_add_i32 m0, s63, 0xc000
	ds_read_b128 v[184:187], v153
	ds_read_b128 v[188:191], v153 offset:1024
	ds_read_b128 v[196:199], v153 offset:2048
	ds_read_b128 v[200:203], v153 offset:3072
	ds_read_b128 v[204:207], v153 offset:4096
	ds_read_b128 v[208:211], v153 offset:5120
	ds_read_b128 v[212:215], v153 offset:6144
	ds_read_b128 v[216:219], v153 offset:7168
	global_load_lds_dwordx4 v[192:193], off
	v_lshl_add_u64 v[192:193], s[40:41], 0, v[138:139]
	s_add_i32 m0, s63, 0xe000
	s_nop 0
	global_load_lds_dwordx4 v[192:193], off
	s_waitcnt vmcnt(8)
	s_waitcnt lgkmcnt(0)
	s_barrier
	s_setprio 1
	s_waitcnt lgkmcnt(0)
	v_mfma_f32_16x16x32_bf16 v[124:127], v[144:147], v[184:187], v[124:127]
	v_mfma_f32_16x16x32_bf16 v[120:123], v[160:163], v[184:187], v[120:123]
	v_mfma_f32_16x16x32_bf16 v[108:111], v[144:147], v[196:199], v[108:111]
	v_mfma_f32_16x16x32_bf16 v[104:107], v[160:163], v[196:199], v[104:107]
	v_mfma_f32_16x16x32_bf16 v[92:95], v[144:147], v[204:207], v[92:95]
	v_mfma_f32_16x16x32_bf16 v[88:91], v[160:163], v[204:207], v[88:91]
	v_mfma_f32_16x16x32_bf16 v[76:79], v[144:147], v[212:215], v[76:79]
	v_mfma_f32_16x16x32_bf16 v[72:75], v[160:163], v[212:215], v[72:75]
	v_mfma_f32_16x16x32_bf16 v[124:127], v[156:159], v[188:191], v[124:127]
	v_mfma_f32_16x16x32_bf16 v[120:123], v[164:167], v[188:191], v[120:123]
	v_mfma_f32_16x16x32_bf16 v[108:111], v[156:159], v[200:203], v[108:111]
	v_mfma_f32_16x16x32_bf16 v[104:107], v[164:167], v[200:203], v[104:107]
	v_mfma_f32_16x16x32_bf16 v[92:95], v[156:159], v[208:211], v[92:95]
	v_mfma_f32_16x16x32_bf16 v[88:91], v[164:167], v[208:211], v[88:91]
	v_mfma_f32_16x16x32_bf16 v[76:79], v[156:159], v[216:219], v[76:79]
	v_mfma_f32_16x16x32_bf16 v[72:75], v[164:167], v[216:219], v[72:75]
	s_setprio 0
	s_setprio 1
	v_mfma_f32_16x16x32_bf16 v[116:119], v[168:171], v[184:187], v[116:119]
	v_mfma_f32_16x16x32_bf16 v[112:115], v[176:179], v[184:187], v[112:115]
	v_mfma_f32_16x16x32_bf16 v[100:103], v[168:171], v[196:199], v[100:103]
	v_mfma_f32_16x16x32_bf16 v[96:99], v[176:179], v[196:199], v[96:99]
	v_mfma_f32_16x16x32_bf16 v[84:87], v[168:171], v[204:207], v[84:87]
	v_mfma_f32_16x16x32_bf16 v[80:83], v[176:179], v[204:207], v[80:83]
	v_mfma_f32_16x16x32_bf16 v[68:71], v[168:171], v[212:215], v[68:71]
	v_mfma_f32_16x16x32_bf16 v[64:67], v[176:179], v[212:215], v[64:67]
	v_mfma_f32_16x16x32_bf16 v[116:119], v[172:175], v[188:191], v[116:119]
	v_mfma_f32_16x16x32_bf16 v[112:115], v[180:183], v[188:191], v[112:115]
	v_mfma_f32_16x16x32_bf16 v[100:103], v[172:175], v[200:203], v[100:103]
	v_mfma_f32_16x16x32_bf16 v[96:99], v[180:183], v[200:203], v[96:99]
	v_mfma_f32_16x16x32_bf16 v[84:87], v[172:175], v[208:211], v[84:87]
	v_mfma_f32_16x16x32_bf16 v[80:83], v[180:183], v[208:211], v[80:83]
	v_mfma_f32_16x16x32_bf16 v[68:71], v[172:175], v[216:219], v[68:71]
	v_mfma_f32_16x16x32_bf16 v[64:67], v[180:183], v[216:219], v[64:67]
	s_setprio 0
	s_barrier
	s_add_i32 s88, s81, s62
	v_lshl_add_u64 v[192:193], s[42:43], 0, v[130:131]
	s_mov_b32 m0, s88
	ds_read_b128 v[184:187], v153 offset:16384
	ds_read_b128 v[188:191], v153 offset:17408
	ds_read_b128 v[196:199], v153 offset:18432
	ds_read_b128 v[200:203], v153 offset:19456
	ds_read_b128 v[204:207], v153 offset:20480
	ds_read_b128 v[208:211], v153 offset:21504
	ds_read_b128 v[212:215], v153 offset:22528
	ds_read_b128 v[216:219], v153 offset:23552
	global_load_lds_dwordx4 v[192:193], off
	s_add_i32 m0, s88, 0x2000
	s_add_u32 s88, s42, 0x40000
	v_lshl_add_u64 v[220:221], s[42:43], 0, v[134:135]
	s_addc_u32 s89, s43, 0
	s_add_i32 s90, s82, s62
	global_load_lds_dwordx4 v[220:221], off
	v_lshl_add_u64 v[222:223], s[88:89], 0, v[130:131]
	s_mov_b32 m0, s90
	v_lshl_add_u64 v[224:225], s[44:45], 0, v[132:133]
	global_load_lds_dwordx4 v[222:223], off
	v_lshl_add_u64 v[222:223], s[88:89], 0, v[134:135]
	s_add_i32 m0, s90, 0x2000
	s_nop 0
	global_load_lds_dwordx4 v[222:223], off
	v_lshl_add_u64 v[222:223], s[44:45], 0, v[128:129]
	s_waitcnt vmcnt(6)
	s_waitcnt lgkmcnt(0)
	s_barrier
	s_setprio 1
	s_waitcnt lgkmcnt(0)
	v_mfma_f32_16x16x32_bf16 v[60:63], v[144:147], v[184:187], v[60:63]
	v_mfma_f32_16x16x32_bf16 v[56:59], v[160:163], v[184:187], v[56:59]
	v_mfma_f32_16x16x32_bf16 v[44:47], v[144:147], v[196:199], v[44:47]
	v_mfma_f32_16x16x32_bf16 v[40:43], v[160:163], v[196:199], v[40:43]
	v_mfma_f32_16x16x32_bf16 v[28:31], v[144:147], v[204:207], v[28:31]
	v_mfma_f32_16x16x32_bf16 v[24:27], v[160:163], v[204:207], v[24:27]
	v_mfma_f32_16x16x32_bf16 v[12:15], v[144:147], v[212:215], v[12:15]
	v_mfma_f32_16x16x32_bf16 v[8:11], v[160:163], v[212:215], v[8:11]
	v_mfma_f32_16x16x32_bf16 v[60:63], v[156:159], v[188:191], v[60:63]
	v_mfma_f32_16x16x32_bf16 v[56:59], v[164:167], v[188:191], v[56:59]
	v_mfma_f32_16x16x32_bf16 v[44:47], v[156:159], v[200:203], v[44:47]
	v_mfma_f32_16x16x32_bf16 v[40:43], v[164:167], v[200:203], v[40:43]
	v_mfma_f32_16x16x32_bf16 v[28:31], v[156:159], v[208:211], v[28:31]
	v_mfma_f32_16x16x32_bf16 v[24:27], v[164:167], v[208:211], v[24:27]
	v_mfma_f32_16x16x32_bf16 v[12:15], v[156:159], v[216:219], v[12:15]
	v_mfma_f32_16x16x32_bf16 v[8:11], v[164:167], v[216:219], v[8:11]
	s_setprio 0
	s_setprio 1
	v_mfma_f32_16x16x32_bf16 v[52:55], v[168:171], v[184:187], v[52:55]
	v_mfma_f32_16x16x32_bf16 v[48:51], v[176:179], v[184:187], v[48:51]
	v_mfma_f32_16x16x32_bf16 v[36:39], v[168:171], v[196:199], v[36:39]
	v_mfma_f32_16x16x32_bf16 v[32:35], v[176:179], v[196:199], v[32:35]
	v_mfma_f32_16x16x32_bf16 v[20:23], v[168:171], v[204:207], v[20:23]
	v_mfma_f32_16x16x32_bf16 v[16:19], v[176:179], v[204:207], v[16:19]
	v_mfma_f32_16x16x32_bf16 v[4:7], v[168:171], v[212:215], v[4:7]
	v_mfma_f32_16x16x32_bf16 v[0:3], v[176:179], v[212:215], v[0:3]
	v_mfma_f32_16x16x32_bf16 v[52:55], v[172:175], v[188:191], v[52:55]
	v_mfma_f32_16x16x32_bf16 v[48:51], v[180:183], v[188:191], v[48:51]
	v_mfma_f32_16x16x32_bf16 v[36:39], v[172:175], v[200:203], v[36:39]
	v_mfma_f32_16x16x32_bf16 v[32:35], v[180:183], v[200:203], v[32:35]
	v_mfma_f32_16x16x32_bf16 v[20:23], v[172:175], v[208:211], v[20:23]
	v_mfma_f32_16x16x32_bf16 v[16:19], v[180:183], v[208:211], v[16:19]
	v_mfma_f32_16x16x32_bf16 v[4:7], v[172:175], v[216:219], v[4:7]
	v_mfma_f32_16x16x32_bf16 v[0:3], v[180:183], v[216:219], v[0:3]
	s_setprio 0
	s_barrier
	s_add_i32 s88, 0, 0x18000
	v_add_u32_e32 v155, s88, v149
	s_add_i32 s89, 0, 0x1c000
	ds_read_b128 v[144:147], v155
	ds_read_b128 v[156:159], v155 offset:1024
	ds_read_b128 v[160:163], v155 offset:2048
	ds_read_b128 v[164:167], v155 offset:3072
	v_add_u32_e32 v155, s89, v149
	ds_read_b128 v[168:171], v155
	ds_read_b128 v[172:175], v155 offset:1024
	ds_read_b128 v[176:179], v155 offset:2048
	ds_read_b128 v[180:183], v155 offset:3072
	s_add_u32 s44, s44, 0x40000
	s_addc_u32 s45, s45, 0
	v_lshl_add_u64 v[226:227], s[44:45], 0, v[128:129]
	ds_read_b128 v[184:187], v153 offset:32768
	ds_read_b128 v[188:191], v153 offset:33792
	ds_read_b128 v[196:199], v153 offset:34816
	ds_read_b128 v[200:203], v153 offset:35840
	ds_read_b128 v[204:207], v153 offset:36864
	ds_read_b128 v[208:211], v153 offset:37888
	ds_read_b128 v[212:215], v153 offset:38912
	ds_read_b128 v[216:219], v153 offset:39936
	s_mov_b32 m0, s63
	s_nop 0
	global_load_lds_dwordx4 v[222:223], off
	s_mov_b32 m0, s70
	s_nop 0
	global_load_lds_dwordx4 v[224:225], off
	s_mov_b32 m0, s71
	s_nop 0
	global_load_lds_dwordx4 v[226:227], off
	v_lshl_add_u64 v[226:227], s[44:45], 0, v[132:133]
	s_mov_b32 m0, s72
	s_nop 0
	global_load_lds_dwordx4 v[226:227], off
	s_waitcnt vmcnt(8)
	s_waitcnt lgkmcnt(0)
	s_barrier
	s_setprio 1
	s_waitcnt lgkmcnt(0)
	v_mfma_f32_16x16x32_bf16 v[124:127], v[144:147], v[184:187], v[124:127]
	v_mfma_f32_16x16x32_bf16 v[120:123], v[160:163], v[184:187], v[120:123]
	v_mfma_f32_16x16x32_bf16 v[108:111], v[144:147], v[196:199], v[108:111]
	v_mfma_f32_16x16x32_bf16 v[104:107], v[160:163], v[196:199], v[104:107]
	v_mfma_f32_16x16x32_bf16 v[92:95], v[144:147], v[204:207], v[92:95]
	v_mfma_f32_16x16x32_bf16 v[88:91], v[160:163], v[204:207], v[88:91]
	v_mfma_f32_16x16x32_bf16 v[76:79], v[144:147], v[212:215], v[76:79]
	v_mfma_f32_16x16x32_bf16 v[72:75], v[160:163], v[212:215], v[72:75]
	v_mfma_f32_16x16x32_bf16 v[124:127], v[156:159], v[188:191], v[124:127]
	v_mfma_f32_16x16x32_bf16 v[120:123], v[164:167], v[188:191], v[120:123]
	v_mfma_f32_16x16x32_bf16 v[108:111], v[156:159], v[200:203], v[108:111]
	v_mfma_f32_16x16x32_bf16 v[104:107], v[164:167], v[200:203], v[104:107]
	v_mfma_f32_16x16x32_bf16 v[92:95], v[156:159], v[208:211], v[92:95]
	v_mfma_f32_16x16x32_bf16 v[88:91], v[164:167], v[208:211], v[88:91]
	v_mfma_f32_16x16x32_bf16 v[76:79], v[156:159], v[216:219], v[76:79]
	v_mfma_f32_16x16x32_bf16 v[72:75], v[164:167], v[216:219], v[72:75]
	s_setprio 0
	s_setprio 1
	v_mfma_f32_16x16x32_bf16 v[116:119], v[168:171], v[184:187], v[116:119]
	v_mfma_f32_16x16x32_bf16 v[112:115], v[176:179], v[184:187], v[112:115]
	v_mfma_f32_16x16x32_bf16 v[100:103], v[168:171], v[196:199], v[100:103]
	v_mfma_f32_16x16x32_bf16 v[96:99], v[176:179], v[196:199], v[96:99]
	v_mfma_f32_16x16x32_bf16 v[84:87], v[168:171], v[204:207], v[84:87]
	v_mfma_f32_16x16x32_bf16 v[80:83], v[176:179], v[204:207], v[80:83]
	v_mfma_f32_16x16x32_bf16 v[68:71], v[168:171], v[212:215], v[68:71]
	v_mfma_f32_16x16x32_bf16 v[64:67], v[176:179], v[212:215], v[64:67]
	v_mfma_f32_16x16x32_bf16 v[116:119], v[172:175], v[188:191], v[116:119]
	v_mfma_f32_16x16x32_bf16 v[112:115], v[180:183], v[188:191], v[112:115]
	v_mfma_f32_16x16x32_bf16 v[100:103], v[172:175], v[200:203], v[100:103]
	v_mfma_f32_16x16x32_bf16 v[96:99], v[180:183], v[200:203], v[96:99]
	v_mfma_f32_16x16x32_bf16 v[84:87], v[172:175], v[208:211], v[84:87]
	v_mfma_f32_16x16x32_bf16 v[80:83], v[180:183], v[208:211], v[80:83]
	v_mfma_f32_16x16x32_bf16 v[68:71], v[172:175], v[216:219], v[68:71]
	v_mfma_f32_16x16x32_bf16 v[64:67], v[180:183], v[216:219], v[64:67]
	s_setprio 0
	s_barrier
	s_add_i32 s44, s88, s62
	v_lshl_add_u64 v[192:193], v[192:193], 0, s[24:25]
	s_mov_b32 m0, s44
	ds_read_b128 v[184:187], v153 offset:49152
	ds_read_b128 v[188:191], v153 offset:50176
	ds_read_b128 v[196:199], v153 offset:51200
	ds_read_b128 v[200:203], v153 offset:52224
	ds_read_b128 v[204:207], v153 offset:53248
	ds_read_b128 v[208:211], v153 offset:54272
	ds_read_b128 v[212:215], v153 offset:55296
	ds_read_b128 v[216:219], v153 offset:56320
	global_load_lds_dwordx4 v[192:193], off
	s_add_i32 m0, s44, 0x2000
	s_add_u32 s42, s42, 0x40080
	v_lshl_add_u64 v[192:193], v[220:221], 0, s[24:25]
	s_addc_u32 s43, s43, 0
	s_add_i32 s44, s89, s62
	global_load_lds_dwordx4 v[192:193], off
	v_lshl_add_u64 v[192:193], s[42:43], 0, v[130:131]
	s_mov_b32 m0, s44
	s_nop 0
	global_load_lds_dwordx4 v[192:193], off
	v_lshl_add_u64 v[192:193], s[42:43], 0, v[134:135]
	s_add_i32 m0, s44, 0x2000
	s_nop 0
	global_load_lds_dwordx4 v[192:193], off
	s_waitcnt vmcnt(6)
	s_waitcnt lgkmcnt(0)
	s_barrier
	s_setprio 1
	s_waitcnt lgkmcnt(0)
	v_mfma_f32_16x16x32_bf16 v[60:63], v[144:147], v[184:187], v[60:63]
	v_mfma_f32_16x16x32_bf16 v[56:59], v[160:163], v[184:187], v[56:59]
	v_mfma_f32_16x16x32_bf16 v[44:47], v[144:147], v[196:199], v[44:47]
	v_mfma_f32_16x16x32_bf16 v[40:43], v[160:163], v[196:199], v[40:43]
	v_mfma_f32_16x16x32_bf16 v[28:31], v[144:147], v[204:207], v[28:31]
	v_mfma_f32_16x16x32_bf16 v[24:27], v[160:163], v[204:207], v[24:27]
	v_mfma_f32_16x16x32_bf16 v[12:15], v[144:147], v[212:215], v[12:15]
	v_mfma_f32_16x16x32_bf16 v[8:11], v[160:163], v[212:215], v[8:11]
	v_mfma_f32_16x16x32_bf16 v[60:63], v[156:159], v[188:191], v[60:63]
	v_mfma_f32_16x16x32_bf16 v[56:59], v[164:167], v[188:191], v[56:59]
	v_mfma_f32_16x16x32_bf16 v[44:47], v[156:159], v[200:203], v[44:47]
	v_mfma_f32_16x16x32_bf16 v[40:43], v[164:167], v[200:203], v[40:43]
	v_mfma_f32_16x16x32_bf16 v[28:31], v[156:159], v[208:211], v[28:31]
	v_mfma_f32_16x16x32_bf16 v[24:27], v[164:167], v[208:211], v[24:27]
	v_mfma_f32_16x16x32_bf16 v[12:15], v[156:159], v[216:219], v[12:15]
	v_mfma_f32_16x16x32_bf16 v[8:11], v[164:167], v[216:219], v[8:11]
	s_setprio 0
	s_setprio 1
	v_mfma_f32_16x16x32_bf16 v[52:55], v[168:171], v[184:187], v[52:55]
	v_mfma_f32_16x16x32_bf16 v[48:51], v[176:179], v[184:187], v[48:51]
	v_mfma_f32_16x16x32_bf16 v[36:39], v[168:171], v[196:199], v[36:39]
	v_mfma_f32_16x16x32_bf16 v[32:35], v[176:179], v[196:199], v[32:35]
	v_mfma_f32_16x16x32_bf16 v[20:23], v[168:171], v[204:207], v[20:23]
	v_mfma_f32_16x16x32_bf16 v[16:19], v[176:179], v[204:207], v[16:19]
	v_mfma_f32_16x16x32_bf16 v[4:7], v[168:171], v[212:215], v[4:7]
	v_mfma_f32_16x16x32_bf16 v[0:3], v[176:179], v[212:215], v[0:3]
	v_mfma_f32_16x16x32_bf16 v[52:55], v[172:175], v[188:191], v[52:55]
	v_mfma_f32_16x16x32_bf16 v[48:51], v[180:183], v[188:191], v[48:51]
	v_mfma_f32_16x16x32_bf16 v[36:39], v[172:175], v[200:203], v[36:39]
	v_mfma_f32_16x16x32_bf16 v[32:35], v[180:183], v[200:203], v[32:35]
	v_mfma_f32_16x16x32_bf16 v[20:23], v[172:175], v[208:211], v[20:23]
	v_mfma_f32_16x16x32_bf16 v[16:19], v[180:183], v[208:211], v[16:19]
	v_mfma_f32_16x16x32_bf16 v[4:7], v[172:175], v[216:219], v[4:7]
	v_mfma_f32_16x16x32_bf16 v[0:3], v[180:183], v[216:219], v[0:3]
	s_setprio 0
	s_barrier
	v_lshl_add_u64 v[222:223], v[222:223], 0, s[24:25]
	s_mov_b32 m0, s78
	s_nop 0
	global_load_lds_dwordx4 v[222:223], off
	v_lshl_add_u64 v[224:225], v[224:225], 0, s[24:25]
	s_mov_b32 m0, s79
	s_nop 0
	global_load_lds_dwordx4 v[224:225], off
	s_add_i32 s87, s87, 2
	s_add_u32 s40, s40, 0x100
	s_addc_u32 s41, s41, 0
	s_add_u32 s85, s85, 0x100
	s_addc_u32 s86, s86, 0
	s_cmp_gt_u32 s87, 13
	s_cbranch_scc0 .LBB0_1625
	s_and_b64 vcc, exec, s[26:27]
	s_cbranch_vccz .LBB0_1628
	s_barrier

.LBB0_1709:
	ds_read_b128 v[154:157], v149
	ds_read_b128 v[158:161], v149 offset:1024
	ds_read_b128 v[162:165], v149 offset:2048
	ds_read_b128 v[166:169], v149 offset:3072
	ds_read_b128 v[170:173], v150
	ds_read_b128 v[174:177], v150 offset:1024
	ds_read_b128 v[178:181], v150 offset:2048
	ds_read_b128 v[182:185], v150 offset:3072
	s_add_u32 s38, s36, 0xfffc0080
	s_addc_u32 s39, s37, -1
	s_cmp_eq_u32 s84, 12
	s_cselect_b32 s41, s27, s39
	s_cselect_b32 s40, s80, s38
	s_cselect_b32 s39, s25, s83
	s_cselect_b32 s38, s81, s82
	v_lshl_add_u64 v[144:145], s[36:37], 0, v[136:137]
	s_add_i32 m0, s35, 0xc000
	ds_read_b128 v[186:189], v151
	ds_read_b128 v[190:193], v151 offset:1024
	ds_read_b128 v[196:199], v151 offset:2048
	ds_read_b128 v[200:203], v151 offset:3072
	ds_read_b128 v[204:207], v151 offset:4096
	ds_read_b128 v[208:211], v151 offset:5120
	ds_read_b128 v[212:215], v151 offset:6144
	ds_read_b128 v[216:219], v151 offset:7168
	global_load_lds_dwordx4 v[144:145], off
	v_lshl_add_u64 v[144:145], s[36:37], 0, v[138:139]
	s_add_i32 m0, s35, 0xe000
	s_nop 0
	global_load_lds_dwordx4 v[144:145], off
	s_waitcnt vmcnt(8)
	s_waitcnt lgkmcnt(0)
	s_barrier
	s_setprio 1
	s_waitcnt lgkmcnt(0)
	v_mfma_f32_16x16x32_bf16 v[116:119], v[154:157], v[186:189], v[116:119]
	v_mfma_f32_16x16x32_bf16 v[112:115], v[162:165], v[186:189], v[112:115]
	v_mfma_f32_16x16x32_bf16 v[100:103], v[154:157], v[196:199], v[100:103]
	v_mfma_f32_16x16x32_bf16 v[96:99], v[162:165], v[196:199], v[96:99]
	v_mfma_f32_16x16x32_bf16 v[84:87], v[154:157], v[204:207], v[84:87]
	v_mfma_f32_16x16x32_bf16 v[80:83], v[162:165], v[204:207], v[80:83]
	v_mfma_f32_16x16x32_bf16 v[68:71], v[154:157], v[212:215], v[68:71]
	v_mfma_f32_16x16x32_bf16 v[64:67], v[162:165], v[212:215], v[64:67]
	v_mfma_f32_16x16x32_bf16 v[116:119], v[158:161], v[190:193], v[116:119]
	v_mfma_f32_16x16x32_bf16 v[112:115], v[166:169], v[190:193], v[112:115]
	v_mfma_f32_16x16x32_bf16 v[100:103], v[158:161], v[200:203], v[100:103]
	v_mfma_f32_16x16x32_bf16 v[96:99], v[166:169], v[200:203], v[96:99]
	v_mfma_f32_16x16x32_bf16 v[84:87], v[158:161], v[208:211], v[84:87]
	v_mfma_f32_16x16x32_bf16 v[80:83], v[166:169], v[208:211], v[80:83]
	v_mfma_f32_16x16x32_bf16 v[68:71], v[158:161], v[216:219], v[68:71]
	v_mfma_f32_16x16x32_bf16 v[64:67], v[166:169], v[216:219], v[64:67]
	s_setprio 0
	s_setprio 1
	v_mfma_f32_16x16x32_bf16 v[124:127], v[170:173], v[186:189], v[124:127]
	v_mfma_f32_16x16x32_bf16 v[120:123], v[178:181], v[186:189], v[120:123]
	v_mfma_f32_16x16x32_bf16 v[108:111], v[170:173], v[196:199], v[108:111]
	v_mfma_f32_16x16x32_bf16 v[104:107], v[178:181], v[196:199], v[104:107]
	v_mfma_f32_16x16x32_bf16 v[92:95], v[170:173], v[204:207], v[92:95]
	v_mfma_f32_16x16x32_bf16 v[88:91], v[178:181], v[204:207], v[88:91]
	v_mfma_f32_16x16x32_bf16 v[76:79], v[170:173], v[212:215], v[76:79]
	v_mfma_f32_16x16x32_bf16 v[72:75], v[178:181], v[212:215], v[72:75]
	v_mfma_f32_16x16x32_bf16 v[124:127], v[174:177], v[190:193], v[124:127]
	v_mfma_f32_16x16x32_bf16 v[120:123], v[182:185], v[190:193], v[120:123]
	v_mfma_f32_16x16x32_bf16 v[108:111], v[174:177], v[200:203], v[108:111]
	v_mfma_f32_16x16x32_bf16 v[104:107], v[182:185], v[200:203], v[104:107]
	v_mfma_f32_16x16x32_bf16 v[92:95], v[174:177], v[208:211], v[92:95]
	v_mfma_f32_16x16x32_bf16 v[88:91], v[182:185], v[208:211], v[88:91]
	v_mfma_f32_16x16x32_bf16 v[76:79], v[174:177], v[216:219], v[76:79]
	v_mfma_f32_16x16x32_bf16 v[72:75], v[182:185], v[216:219], v[72:75]
	s_setprio 0
	s_barrier
	s_add_i32 s85, s71, s56
	v_lshl_add_u64 v[144:145], s[38:39], 0, v[132:133]
	s_mov_b32 m0, s85
	ds_read_b128 v[186:189], v151 offset:16384
	ds_read_b128 v[190:193], v151 offset:17408
	ds_read_b128 v[196:199], v151 offset:18432
	ds_read_b128 v[200:203], v151 offset:19456
	ds_read_b128 v[204:207], v151 offset:20480
	ds_read_b128 v[208:211], v151 offset:21504
	ds_read_b128 v[212:215], v151 offset:22528
	ds_read_b128 v[216:219], v151 offset:23552
	global_load_lds_dwordx4 v[144:145], off
	s_add_i32 m0, s85, 0x2000
	s_add_u32 s86, s38, 0x40000
	v_lshl_add_u64 v[220:221], s[38:39], 0, v[128:129]
	s_addc_u32 s87, s39, 0
	s_add_i32 s85, s72, s56
	global_load_lds_dwordx4 v[220:221], off
	v_lshl_add_u64 v[222:223], s[86:87], 0, v[132:133]
	s_mov_b32 m0, s85
	v_lshl_add_u64 v[224:225], s[40:41], 0, v[130:131]
	global_load_lds_dwordx4 v[222:223], off
	v_lshl_add_u64 v[222:223], s[86:87], 0, v[128:129]
	s_add_i32 m0, s85, 0x2000
	s_nop 0
	global_load_lds_dwordx4 v[222:223], off
	v_lshl_add_u64 v[222:223], s[40:41], 0, v[134:135]
	s_waitcnt vmcnt(6)
	s_waitcnt lgkmcnt(0)
	s_barrier
	s_setprio 1
	s_waitcnt lgkmcnt(0)
	v_mfma_f32_16x16x32_bf16 v[52:55], v[154:157], v[186:189], v[52:55]
	v_mfma_f32_16x16x32_bf16 v[48:51], v[162:165], v[186:189], v[48:51]
	v_mfma_f32_16x16x32_bf16 v[36:39], v[154:157], v[196:199], v[36:39]
	v_mfma_f32_16x16x32_bf16 v[32:35], v[162:165], v[196:199], v[32:35]
	v_mfma_f32_16x16x32_bf16 v[20:23], v[154:157], v[204:207], v[20:23]
	v_mfma_f32_16x16x32_bf16 v[16:19], v[162:165], v[204:207], v[16:19]
	v_mfma_f32_16x16x32_bf16 v[4:7], v[154:157], v[212:215], v[4:7]
	v_mfma_f32_16x16x32_bf16 v[0:3], v[162:165], v[212:215], v[0:3]
	v_mfma_f32_16x16x32_bf16 v[52:55], v[158:161], v[190:193], v[52:55]
	v_mfma_f32_16x16x32_bf16 v[48:51], v[166:169], v[190:193], v[48:51]
	v_mfma_f32_16x16x32_bf16 v[36:39], v[158:161], v[200:203], v[36:39]
	v_mfma_f32_16x16x32_bf16 v[32:35], v[166:169], v[200:203], v[32:35]
	v_mfma_f32_16x16x32_bf16 v[20:23], v[158:161], v[208:211], v[20:23]
	v_mfma_f32_16x16x32_bf16 v[16:19], v[166:169], v[208:211], v[16:19]
	v_mfma_f32_16x16x32_bf16 v[4:7], v[158:161], v[216:219], v[4:7]
	v_mfma_f32_16x16x32_bf16 v[0:3], v[166:169], v[216:219], v[0:3]
	s_setprio 0
	s_setprio 1
	v_mfma_f32_16x16x32_bf16 v[60:63], v[170:173], v[186:189], v[60:63]
	v_mfma_f32_16x16x32_bf16 v[56:59], v[178:181], v[186:189], v[56:59]
	v_mfma_f32_16x16x32_bf16 v[44:47], v[170:173], v[196:199], v[44:47]
	v_mfma_f32_16x16x32_bf16 v[40:43], v[178:181], v[196:199], v[40:43]
	v_mfma_f32_16x16x32_bf16 v[28:31], v[170:173], v[204:207], v[28:31]
	v_mfma_f32_16x16x32_bf16 v[24:27], v[178:181], v[204:207], v[24:27]
	v_mfma_f32_16x16x32_bf16 v[12:15], v[170:173], v[212:215], v[12:15]
	v_mfma_f32_16x16x32_bf16 v[8:11], v[178:181], v[212:215], v[8:11]
	v_mfma_f32_16x16x32_bf16 v[60:63], v[174:177], v[190:193], v[60:63]
	v_mfma_f32_16x16x32_bf16 v[56:59], v[182:185], v[190:193], v[56:59]
	v_mfma_f32_16x16x32_bf16 v[44:47], v[174:177], v[200:203], v[44:47]
	v_mfma_f32_16x16x32_bf16 v[40:43], v[182:185], v[200:203], v[40:43]
	v_mfma_f32_16x16x32_bf16 v[28:31], v[174:177], v[208:211], v[28:31]
	v_mfma_f32_16x16x32_bf16 v[24:27], v[182:185], v[208:211], v[24:27]
	v_mfma_f32_16x16x32_bf16 v[12:15], v[174:177], v[216:219], v[12:15]
	v_mfma_f32_16x16x32_bf16 v[8:11], v[182:185], v[216:219], v[8:11]
	s_setprio 0
	s_barrier
	s_add_i32 s85, 0, 0x18000
	v_add_u32_e32 v153, s85, v147
	s_add_i32 s86, 0, 0x1c000
	ds_read_b128 v[154:157], v153
	ds_read_b128 v[158:161], v153 offset:1024
	ds_read_b128 v[162:165], v153 offset:2048
	ds_read_b128 v[166:169], v153 offset:3072
	v_add_u32_e32 v153, s86, v147
	ds_read_b128 v[170:173], v153
	ds_read_b128 v[174:177], v153 offset:1024
	ds_read_b128 v[178:181], v153 offset:2048
	ds_read_b128 v[182:185], v153 offset:3072
	s_add_u32 s40, s40, 0x40000
	s_addc_u32 s41, s41, 0
	v_lshl_add_u64 v[226:227], s[40:41], 0, v[134:135]
	ds_read_b128 v[186:189], v151 offset:32768
	ds_read_b128 v[190:193], v151 offset:33792
	ds_read_b128 v[196:199], v151 offset:34816
	ds_read_b128 v[200:203], v151 offset:35840
	ds_read_b128 v[204:207], v151 offset:36864
	ds_read_b128 v[208:211], v151 offset:37888
	ds_read_b128 v[212:215], v151 offset:38912
	ds_read_b128 v[216:219], v151 offset:39936
	s_mov_b32 m0, s35
	s_nop 0
	global_load_lds_dwordx4 v[222:223], off
	s_mov_b32 m0, s58
	s_nop 0
	global_load_lds_dwordx4 v[224:225], off
	s_mov_b32 m0, s59
	s_nop 0
	global_load_lds_dwordx4 v[226:227], off
	v_lshl_add_u64 v[226:227], s[40:41], 0, v[130:131]
	s_mov_b32 m0, s60
	s_nop 0
	global_load_lds_dwordx4 v[226:227], off
	s_waitcnt vmcnt(8)
	s_waitcnt lgkmcnt(0)
	s_barrier
	s_setprio 1
	s_waitcnt lgkmcnt(0)
	v_mfma_f32_16x16x32_bf16 v[116:119], v[154:157], v[186:189], v[116:119]
	v_mfma_f32_16x16x32_bf16 v[112:115], v[162:165], v[186:189], v[112:115]
	v_mfma_f32_16x16x32_bf16 v[100:103], v[154:157], v[196:199], v[100:103]
	v_mfma_f32_16x16x32_bf16 v[96:99], v[162:165], v[196:199], v[96:99]
	v_mfma_f32_16x16x32_bf16 v[84:87], v[154:157], v[204:207], v[84:87]
	v_mfma_f32_16x16x32_bf16 v[80:83], v[162:165], v[204:207], v[80:83]
	v_mfma_f32_16x16x32_bf16 v[68:71], v[154:157], v[212:215], v[68:71]
	v_mfma_f32_16x16x32_bf16 v[64:67], v[162:165], v[212:215], v[64:67]
	v_mfma_f32_16x16x32_bf16 v[116:119], v[158:161], v[190:193], v[116:119]
	v_mfma_f32_16x16x32_bf16 v[112:115], v[166:169], v[190:193], v[112:115]
	v_mfma_f32_16x16x32_bf16 v[100:103], v[158:161], v[200:203], v[100:103]
	v_mfma_f32_16x16x32_bf16 v[96:99], v[166:169], v[200:203], v[96:99]
	v_mfma_f32_16x16x32_bf16 v[84:87], v[158:161], v[208:211], v[84:87]
	v_mfma_f32_16x16x32_bf16 v[80:83], v[166:169], v[208:211], v[80:83]
	v_mfma_f32_16x16x32_bf16 v[68:71], v[158:161], v[216:219], v[68:71]
	v_mfma_f32_16x16x32_bf16 v[64:67], v[166:169], v[216:219], v[64:67]
	s_setprio 0
	s_setprio 1
	v_mfma_f32_16x16x32_bf16 v[124:127], v[170:173], v[186:189], v[124:127]
	v_mfma_f32_16x16x32_bf16 v[120:123], v[178:181], v[186:189], v[120:123]
	v_mfma_f32_16x16x32_bf16 v[108:111], v[170:173], v[196:199], v[108:111]
	v_mfma_f32_16x16x32_bf16 v[104:107], v[178:181], v[196:199], v[104:107]
	v_mfma_f32_16x16x32_bf16 v[92:95], v[170:173], v[204:207], v[92:95]
	v_mfma_f32_16x16x32_bf16 v[88:91], v[178:181], v[204:207], v[88:91]
	v_mfma_f32_16x16x32_bf16 v[76:79], v[170:173], v[212:215], v[76:79]
	v_mfma_f32_16x16x32_bf16 v[72:75], v[178:181], v[212:215], v[72:75]
	v_mfma_f32_16x16x32_bf16 v[124:127], v[174:177], v[190:193], v[124:127]
	v_mfma_f32_16x16x32_bf16 v[120:123], v[182:185], v[190:193], v[120:123]
	v_mfma_f32_16x16x32_bf16 v[108:111], v[174:177], v[200:203], v[108:111]
	v_mfma_f32_16x16x32_bf16 v[104:107], v[182:185], v[200:203], v[104:107]
	v_mfma_f32_16x16x32_bf16 v[92:95], v[174:177], v[208:211], v[92:95]
	v_mfma_f32_16x16x32_bf16 v[88:91], v[182:185], v[208:211], v[88:91]
	v_mfma_f32_16x16x32_bf16 v[76:79], v[174:177], v[216:219], v[76:79]
	v_mfma_f32_16x16x32_bf16 v[72:75], v[182:185], v[216:219], v[72:75]
	s_setprio 0
	s_barrier
	s_add_i32 s40, s85, s56
	v_lshl_add_u64 v[144:145], v[144:145], 0, s[20:21]
	s_mov_b32 m0, s40
	ds_read_b128 v[186:189], v151 offset:49152
	ds_read_b128 v[190:193], v151 offset:50176
	ds_read_b128 v[196:199], v151 offset:51200
	ds_read_b128 v[200:203], v151 offset:52224
	ds_read_b128 v[204:207], v151 offset:53248
	ds_read_b128 v[208:211], v151 offset:54272
	ds_read_b128 v[212:215], v151 offset:55296
	ds_read_b128 v[216:219], v151 offset:56320
	global_load_lds_dwordx4 v[144:145], off
	s_add_i32 m0, s40, 0x2000
	s_add_u32 s38, s38, 0x40080
	v_lshl_add_u64 v[144:145], v[220:221], 0, s[20:21]
	s_addc_u32 s39, s39, 0
	s_add_i32 s40, s86, s56
	global_load_lds_dwordx4 v[144:145], off
	v_lshl_add_u64 v[144:145], s[38:39], 0, v[132:133]
	s_mov_b32 m0, s40
	s_nop 0
	global_load_lds_dwordx4 v[144:145], off
	v_lshl_add_u64 v[144:145], s[38:39], 0, v[128:129]
	s_add_i32 m0, s40, 0x2000
	s_nop 0
	global_load_lds_dwordx4 v[144:145], off
	s_waitcnt vmcnt(6)
	s_waitcnt lgkmcnt(0)
	s_barrier
	s_setprio 1
	s_waitcnt lgkmcnt(0)
	v_mfma_f32_16x16x32_bf16 v[52:55], v[154:157], v[186:189], v[52:55]
	v_mfma_f32_16x16x32_bf16 v[48:51], v[162:165], v[186:189], v[48:51]
	v_mfma_f32_16x16x32_bf16 v[36:39], v[154:157], v[196:199], v[36:39]
	v_mfma_f32_16x16x32_bf16 v[32:35], v[162:165], v[196:199], v[32:35]
	v_mfma_f32_16x16x32_bf16 v[20:23], v[154:157], v[204:207], v[20:23]
	v_mfma_f32_16x16x32_bf16 v[16:19], v[162:165], v[204:207], v[16:19]
	v_mfma_f32_16x16x32_bf16 v[4:7], v[154:157], v[212:215], v[4:7]
	v_mfma_f32_16x16x32_bf16 v[0:3], v[162:165], v[212:215], v[0:3]
	v_mfma_f32_16x16x32_bf16 v[52:55], v[158:161], v[190:193], v[52:55]
	v_mfma_f32_16x16x32_bf16 v[48:51], v[166:169], v[190:193], v[48:51]
	v_mfma_f32_16x16x32_bf16 v[36:39], v[158:161], v[200:203], v[36:39]
	v_mfma_f32_16x16x32_bf16 v[32:35], v[166:169], v[200:203], v[32:35]
	v_mfma_f32_16x16x32_bf16 v[20:23], v[158:161], v[208:211], v[20:23]
	v_mfma_f32_16x16x32_bf16 v[16:19], v[166:169], v[208:211], v[16:19]
	v_mfma_f32_16x16x32_bf16 v[4:7], v[158:161], v[216:219], v[4:7]
	v_mfma_f32_16x16x32_bf16 v[0:3], v[166:169], v[216:219], v[0:3]
	s_setprio 0
	s_setprio 1
	v_mfma_f32_16x16x32_bf16 v[60:63], v[170:173], v[186:189], v[60:63]
	v_mfma_f32_16x16x32_bf16 v[56:59], v[178:181], v[186:189], v[56:59]
	v_mfma_f32_16x16x32_bf16 v[44:47], v[170:173], v[196:199], v[44:47]
	v_mfma_f32_16x16x32_bf16 v[40:43], v[178:181], v[196:199], v[40:43]
	v_mfma_f32_16x16x32_bf16 v[28:31], v[170:173], v[204:207], v[28:31]
	v_mfma_f32_16x16x32_bf16 v[24:27], v[178:181], v[204:207], v[24:27]
	v_mfma_f32_16x16x32_bf16 v[12:15], v[170:173], v[212:215], v[12:15]
	v_mfma_f32_16x16x32_bf16 v[8:11], v[178:181], v[212:215], v[8:11]
	v_mfma_f32_16x16x32_bf16 v[60:63], v[174:177], v[190:193], v[60:63]
	v_mfma_f32_16x16x32_bf16 v[56:59], v[182:185], v[190:193], v[56:59]
	v_mfma_f32_16x16x32_bf16 v[44:47], v[174:177], v[200:203], v[44:47]
	v_mfma_f32_16x16x32_bf16 v[40:43], v[182:185], v[200:203], v[40:43]
	v_mfma_f32_16x16x32_bf16 v[28:31], v[174:177], v[208:211], v[28:31]
	v_mfma_f32_16x16x32_bf16 v[24:27], v[182:185], v[208:211], v[24:27]
	v_mfma_f32_16x16x32_bf16 v[12:15], v[174:177], v[216:219], v[12:15]
	v_mfma_f32_16x16x32_bf16 v[8:11], v[182:185], v[216:219], v[8:11]
	s_setprio 0
	s_barrier
	v_lshl_add_u64 v[222:223], v[222:223], 0, s[20:21]
	s_mov_b32 m0, s62
	s_nop 0
	global_load_lds_dwordx4 v[222:223], off
	v_lshl_add_u64 v[224:225], v[224:225], 0, s[20:21]
	s_mov_b32 m0, s63
	s_nop 0
	global_load_lds_dwordx4 v[224:225], off
	s_add_i32 s84, s84, 2
	s_add_u32 s36, s36, 0x100
	s_addc_u32 s37, s37, 0
	s_add_u32 s82, s82, 0x100
	s_addc_u32 s83, s83, 0
	s_cmp_gt_u32 s84, 13
	s_cbranch_scc0 .LBB0_1709
	s_and_b64 vcc, exec, s[22:23]
	s_cbranch_vccz .LBB0_1712
	s_barrier

.LBB0_1791:
	ds_read_b128 v[144:147], v151
	ds_read_b128 v[156:159], v151 offset:1024
	ds_read_b128 v[160:163], v151 offset:2048
	ds_read_b128 v[164:167], v151 offset:3072
	ds_read_b128 v[168:171], v152
	ds_read_b128 v[172:175], v152 offset:1024
	ds_read_b128 v[176:179], v152 offset:2048
	ds_read_b128 v[180:183], v152 offset:3072
	s_add_u32 s38, s36, 0x100
	s_addc_u32 s39, s37, 0
	s_cmp_eq_u32 s85, 40
	s_cselect_b32 s43, s1, s39
	s_cselect_b32 s42, s0, s38
	s_cselect_b32 s41, s35, s84
	s_cselect_b32 s40, s34, s83
	v_lshl_add_u64 v[192:193], s[36:37], 0, v[136:137]
	s_add_i32 m0, s59, 0xc000
	ds_read_b128 v[184:187], v153
	ds_read_b128 v[188:191], v153 offset:1024
	ds_read_b128 v[196:199], v153 offset:2048
	ds_read_b128 v[200:203], v153 offset:3072
	ds_read_b128 v[204:207], v153 offset:4096
	ds_read_b128 v[208:211], v153 offset:5120
	ds_read_b128 v[212:215], v153 offset:6144
	ds_read_b128 v[216:219], v153 offset:7168
	global_load_lds_dwordx4 v[192:193], off
	v_lshl_add_u64 v[192:193], s[36:37], 0, v[138:139]
	s_add_i32 m0, s59, 0xe000
	s_nop 0
	global_load_lds_dwordx4 v[192:193], off
	s_waitcnt vmcnt(8)
	s_waitcnt lgkmcnt(0)
	s_barrier
	s_setprio 1
	s_waitcnt lgkmcnt(0)
	v_mfma_f32_16x16x32_bf16 v[124:127], v[144:147], v[184:187], v[124:127]
	v_mfma_f32_16x16x32_bf16 v[120:123], v[160:163], v[184:187], v[120:123]
	v_mfma_f32_16x16x32_bf16 v[108:111], v[144:147], v[196:199], v[108:111]
	v_mfma_f32_16x16x32_bf16 v[104:107], v[160:163], v[196:199], v[104:107]
	v_mfma_f32_16x16x32_bf16 v[92:95], v[144:147], v[204:207], v[92:95]
	v_mfma_f32_16x16x32_bf16 v[88:91], v[160:163], v[204:207], v[88:91]
	v_mfma_f32_16x16x32_bf16 v[76:79], v[144:147], v[212:215], v[76:79]
	v_mfma_f32_16x16x32_bf16 v[72:75], v[160:163], v[212:215], v[72:75]
	v_mfma_f32_16x16x32_bf16 v[124:127], v[156:159], v[188:191], v[124:127]
	v_mfma_f32_16x16x32_bf16 v[120:123], v[164:167], v[188:191], v[120:123]
	v_mfma_f32_16x16x32_bf16 v[108:111], v[156:159], v[200:203], v[108:111]
	v_mfma_f32_16x16x32_bf16 v[104:107], v[164:167], v[200:203], v[104:107]
	v_mfma_f32_16x16x32_bf16 v[92:95], v[156:159], v[208:211], v[92:95]
	v_mfma_f32_16x16x32_bf16 v[88:91], v[164:167], v[208:211], v[88:91]
	v_mfma_f32_16x16x32_bf16 v[76:79], v[156:159], v[216:219], v[76:79]
	v_mfma_f32_16x16x32_bf16 v[72:75], v[164:167], v[216:219], v[72:75]
	s_setprio 0
	s_setprio 1
	v_mfma_f32_16x16x32_bf16 v[116:119], v[168:171], v[184:187], v[116:119]
	v_mfma_f32_16x16x32_bf16 v[112:115], v[176:179], v[184:187], v[112:115]
	v_mfma_f32_16x16x32_bf16 v[100:103], v[168:171], v[196:199], v[100:103]
	v_mfma_f32_16x16x32_bf16 v[96:99], v[176:179], v[196:199], v[96:99]
	v_mfma_f32_16x16x32_bf16 v[84:87], v[168:171], v[204:207], v[84:87]
	v_mfma_f32_16x16x32_bf16 v[80:83], v[176:179], v[204:207], v[80:83]
	v_mfma_f32_16x16x32_bf16 v[68:71], v[168:171], v[212:215], v[68:71]
	v_mfma_f32_16x16x32_bf16 v[64:67], v[176:179], v[212:215], v[64:67]
	v_mfma_f32_16x16x32_bf16 v[116:119], v[172:175], v[188:191], v[116:119]
	v_mfma_f32_16x16x32_bf16 v[112:115], v[180:183], v[188:191], v[112:115]
	v_mfma_f32_16x16x32_bf16 v[100:103], v[172:175], v[200:203], v[100:103]
	v_mfma_f32_16x16x32_bf16 v[96:99], v[180:183], v[200:203], v[96:99]
	v_mfma_f32_16x16x32_bf16 v[84:87], v[172:175], v[208:211], v[84:87]
	v_mfma_f32_16x16x32_bf16 v[80:83], v[180:183], v[208:211], v[80:83]
	v_mfma_f32_16x16x32_bf16 v[68:71], v[172:175], v[216:219], v[68:71]
	v_mfma_f32_16x16x32_bf16 v[64:67], v[180:183], v[216:219], v[64:67]
	s_setprio 0
	s_barrier
	s_add_i32 s36, s73, s58
	v_lshl_add_u64 v[192:193], s[40:41], 0, v[130:131]
	s_mov_b32 m0, s36
	ds_read_b128 v[184:187], v153 offset:16384
	ds_read_b128 v[188:191], v153 offset:17408
	ds_read_b128 v[196:199], v153 offset:18432
	ds_read_b128 v[200:203], v153 offset:19456
	ds_read_b128 v[204:207], v153 offset:20480
	ds_read_b128 v[208:211], v153 offset:21504
	ds_read_b128 v[212:215], v153 offset:22528
	ds_read_b128 v[216:219], v153 offset:23552
	global_load_lds_dwordx4 v[192:193], off
	s_add_i32 m0, s36, 0x2000
	s_add_u32 s36, s40, 0xb0000
	v_lshl_add_u64 v[220:221], s[40:41], 0, v[134:135]
	s_addc_u32 s37, s41, 0
	s_add_i32 s86, s78, s58
	global_load_lds_dwordx4 v[220:221], off
	v_lshl_add_u64 v[222:223], s[36:37], 0, v[130:131]
	s_mov_b32 m0, s86
	v_lshl_add_u64 v[224:225], s[42:43], 0, v[132:133]
	global_load_lds_dwordx4 v[222:223], off
	v_lshl_add_u64 v[222:223], s[36:37], 0, v[134:135]
	s_add_i32 m0, s86, 0x2000
	s_nop 0
	global_load_lds_dwordx4 v[222:223], off
	v_lshl_add_u64 v[222:223], s[42:43], 0, v[128:129]
	s_waitcnt vmcnt(6)
	s_waitcnt lgkmcnt(0)
	s_barrier
	s_setprio 1
	s_waitcnt lgkmcnt(0)
	v_mfma_f32_16x16x32_bf16 v[60:63], v[144:147], v[184:187], v[60:63]
	v_mfma_f32_16x16x32_bf16 v[56:59], v[160:163], v[184:187], v[56:59]
	v_mfma_f32_16x16x32_bf16 v[44:47], v[144:147], v[196:199], v[44:47]
	v_mfma_f32_16x16x32_bf16 v[40:43], v[160:163], v[196:199], v[40:43]
	v_mfma_f32_16x16x32_bf16 v[28:31], v[144:147], v[204:207], v[28:31]
	v_mfma_f32_16x16x32_bf16 v[24:27], v[160:163], v[204:207], v[24:27]
	v_mfma_f32_16x16x32_bf16 v[12:15], v[144:147], v[212:215], v[12:15]
	v_mfma_f32_16x16x32_bf16 v[8:11], v[160:163], v[212:215], v[8:11]
	v_mfma_f32_16x16x32_bf16 v[60:63], v[156:159], v[188:191], v[60:63]
	v_mfma_f32_16x16x32_bf16 v[56:59], v[164:167], v[188:191], v[56:59]
	v_mfma_f32_16x16x32_bf16 v[44:47], v[156:159], v[200:203], v[44:47]
	v_mfma_f32_16x16x32_bf16 v[40:43], v[164:167], v[200:203], v[40:43]
	v_mfma_f32_16x16x32_bf16 v[28:31], v[156:159], v[208:211], v[28:31]
	v_mfma_f32_16x16x32_bf16 v[24:27], v[164:167], v[208:211], v[24:27]
	v_mfma_f32_16x16x32_bf16 v[12:15], v[156:159], v[216:219], v[12:15]
	v_mfma_f32_16x16x32_bf16 v[8:11], v[164:167], v[216:219], v[8:11]
	s_setprio 0
	s_setprio 1
	v_mfma_f32_16x16x32_bf16 v[52:55], v[168:171], v[184:187], v[52:55]
	v_mfma_f32_16x16x32_bf16 v[48:51], v[176:179], v[184:187], v[48:51]
	v_mfma_f32_16x16x32_bf16 v[36:39], v[168:171], v[196:199], v[36:39]
	v_mfma_f32_16x16x32_bf16 v[32:35], v[176:179], v[196:199], v[32:35]
	v_mfma_f32_16x16x32_bf16 v[20:23], v[168:171], v[204:207], v[20:23]
	v_mfma_f32_16x16x32_bf16 v[16:19], v[176:179], v[204:207], v[16:19]
	v_mfma_f32_16x16x32_bf16 v[4:7], v[168:171], v[212:215], v[4:7]
	v_mfma_f32_16x16x32_bf16 v[0:3], v[176:179], v[212:215], v[0:3]
	v_mfma_f32_16x16x32_bf16 v[52:55], v[172:175], v[188:191], v[52:55]
	v_mfma_f32_16x16x32_bf16 v[48:51], v[180:183], v[188:191], v[48:51]
	v_mfma_f32_16x16x32_bf16 v[36:39], v[172:175], v[200:203], v[36:39]
	v_mfma_f32_16x16x32_bf16 v[32:35], v[180:183], v[200:203], v[32:35]
	v_mfma_f32_16x16x32_bf16 v[20:23], v[172:175], v[208:211], v[20:23]
	v_mfma_f32_16x16x32_bf16 v[16:19], v[180:183], v[208:211], v[16:19]
	v_mfma_f32_16x16x32_bf16 v[4:7], v[172:175], v[216:219], v[4:7]
	v_mfma_f32_16x16x32_bf16 v[0:3], v[180:183], v[216:219], v[0:3]
	s_setprio 0
	s_barrier
	s_add_i32 s86, 0, 0x18000
	v_add_u32_e32 v155, s86, v149
	s_add_i32 s87, 0, 0x1c000
	ds_read_b128 v[144:147], v155
	ds_read_b128 v[156:159], v155 offset:1024
	ds_read_b128 v[160:163], v155 offset:2048
	ds_read_b128 v[164:167], v155 offset:3072
	v_add_u32_e32 v155, s87, v149
	ds_read_b128 v[168:171], v155
	ds_read_b128 v[172:175], v155 offset:1024
	ds_read_b128 v[176:179], v155 offset:2048
	ds_read_b128 v[180:183], v155 offset:3072
	s_add_u32 s36, s42, 0xb0000
	s_addc_u32 s37, s43, 0
	v_lshl_add_u64 v[226:227], s[36:37], 0, v[128:129]
	ds_read_b128 v[184:187], v153 offset:32768
	ds_read_b128 v[188:191], v153 offset:33792
	ds_read_b128 v[196:199], v153 offset:34816
	ds_read_b128 v[200:203], v153 offset:35840
	ds_read_b128 v[204:207], v153 offset:36864
	ds_read_b128 v[208:211], v153 offset:37888
	ds_read_b128 v[212:215], v153 offset:38912
	ds_read_b128 v[216:219], v153 offset:39936
	s_mov_b32 m0, s59
	s_nop 0
	global_load_lds_dwordx4 v[222:223], off
	s_mov_b32 m0, s60
	s_nop 0
	global_load_lds_dwordx4 v[224:225], off
	s_mov_b32 m0, s61
	s_nop 0
	global_load_lds_dwordx4 v[226:227], off
	v_lshl_add_u64 v[226:227], s[36:37], 0, v[132:133]
	s_mov_b32 m0, s62
	s_nop 0
	global_load_lds_dwordx4 v[226:227], off
	s_waitcnt vmcnt(8)
	s_waitcnt lgkmcnt(0)
	s_barrier
	s_setprio 1
	s_waitcnt lgkmcnt(0)
	v_mfma_f32_16x16x32_bf16 v[124:127], v[144:147], v[184:187], v[124:127]
	v_mfma_f32_16x16x32_bf16 v[120:123], v[160:163], v[184:187], v[120:123]
	v_mfma_f32_16x16x32_bf16 v[108:111], v[144:147], v[196:199], v[108:111]
	v_mfma_f32_16x16x32_bf16 v[104:107], v[160:163], v[196:199], v[104:107]
	v_mfma_f32_16x16x32_bf16 v[92:95], v[144:147], v[204:207], v[92:95]
	v_mfma_f32_16x16x32_bf16 v[88:91], v[160:163], v[204:207], v[88:91]
	v_mfma_f32_16x16x32_bf16 v[76:79], v[144:147], v[212:215], v[76:79]
	v_mfma_f32_16x16x32_bf16 v[72:75], v[160:163], v[212:215], v[72:75]
	v_mfma_f32_16x16x32_bf16 v[124:127], v[156:159], v[188:191], v[124:127]
	v_mfma_f32_16x16x32_bf16 v[120:123], v[164:167], v[188:191], v[120:123]
	v_mfma_f32_16x16x32_bf16 v[108:111], v[156:159], v[200:203], v[108:111]
	v_mfma_f32_16x16x32_bf16 v[104:107], v[164:167], v[200:203], v[104:107]
	v_mfma_f32_16x16x32_bf16 v[92:95], v[156:159], v[208:211], v[92:95]
	v_mfma_f32_16x16x32_bf16 v[88:91], v[164:167], v[208:211], v[88:91]
	v_mfma_f32_16x16x32_bf16 v[76:79], v[156:159], v[216:219], v[76:79]
	v_mfma_f32_16x16x32_bf16 v[72:75], v[164:167], v[216:219], v[72:75]
	s_setprio 0
	s_setprio 1
	v_mfma_f32_16x16x32_bf16 v[116:119], v[168:171], v[184:187], v[116:119]
	v_mfma_f32_16x16x32_bf16 v[112:115], v[176:179], v[184:187], v[112:115]
	v_mfma_f32_16x16x32_bf16 v[100:103], v[168:171], v[196:199], v[100:103]
	v_mfma_f32_16x16x32_bf16 v[96:99], v[176:179], v[196:199], v[96:99]
	v_mfma_f32_16x16x32_bf16 v[84:87], v[168:171], v[204:207], v[84:87]
	v_mfma_f32_16x16x32_bf16 v[80:83], v[176:179], v[204:207], v[80:83]
	v_mfma_f32_16x16x32_bf16 v[68:71], v[168:171], v[212:215], v[68:71]
	v_mfma_f32_16x16x32_bf16 v[64:67], v[176:179], v[212:215], v[64:67]
	v_mfma_f32_16x16x32_bf16 v[116:119], v[172:175], v[188:191], v[116:119]
	v_mfma_f32_16x16x32_bf16 v[112:115], v[180:183], v[188:191], v[112:115]
	v_mfma_f32_16x16x32_bf16 v[100:103], v[172:175], v[200:203], v[100:103]
	v_mfma_f32_16x16x32_bf16 v[96:99], v[180:183], v[200:203], v[96:99]
	v_mfma_f32_16x16x32_bf16 v[84:87], v[172:175], v[208:211], v[84:87]
	v_mfma_f32_16x16x32_bf16 v[80:83], v[180:183], v[208:211], v[80:83]
	v_mfma_f32_16x16x32_bf16 v[68:71], v[172:175], v[216:219], v[68:71]
	v_mfma_f32_16x16x32_bf16 v[64:67], v[180:183], v[216:219], v[64:67]
	s_setprio 0
	s_barrier
	s_add_i32 s36, s86, s58
	v_lshl_add_u64 v[192:193], v[192:193], 0, s[28:29]
	s_mov_b32 m0, s36
	ds_read_b128 v[184:187], v153 offset:49152
	ds_read_b128 v[188:191], v153 offset:50176
	ds_read_b128 v[196:199], v153 offset:51200
	ds_read_b128 v[200:203], v153 offset:52224
	ds_read_b128 v[204:207], v153 offset:53248
	ds_read_b128 v[208:211], v153 offset:54272
	ds_read_b128 v[212:215], v153 offset:55296
	ds_read_b128 v[216:219], v153 offset:56320
	global_load_lds_dwordx4 v[192:193], off
	s_add_i32 m0, s36, 0x2000
	s_add_u32 s36, s40, 0xb0080
	v_lshl_add_u64 v[192:193], v[220:221], 0, s[28:29]
	s_addc_u32 s37, s41, 0
	s_add_i32 s40, s87, s58
	global_load_lds_dwordx4 v[192:193], off
	v_lshl_add_u64 v[192:193], s[36:37], 0, v[130:131]
	s_mov_b32 m0, s40
	s_nop 0
	global_load_lds_dwordx4 v[192:193], off
	v_lshl_add_u64 v[192:193], s[36:37], 0, v[134:135]
	s_add_i32 m0, s40, 0x2000
	s_nop 0
	global_load_lds_dwordx4 v[192:193], off
	s_waitcnt vmcnt(6)
	s_waitcnt lgkmcnt(0)
	s_barrier
	s_setprio 1
	s_waitcnt lgkmcnt(0)
	v_mfma_f32_16x16x32_bf16 v[60:63], v[144:147], v[184:187], v[60:63]
	v_mfma_f32_16x16x32_bf16 v[56:59], v[160:163], v[184:187], v[56:59]
	v_mfma_f32_16x16x32_bf16 v[44:47], v[144:147], v[196:199], v[44:47]
	v_mfma_f32_16x16x32_bf16 v[40:43], v[160:163], v[196:199], v[40:43]
	v_mfma_f32_16x16x32_bf16 v[28:31], v[144:147], v[204:207], v[28:31]
	v_mfma_f32_16x16x32_bf16 v[24:27], v[160:163], v[204:207], v[24:27]
	v_mfma_f32_16x16x32_bf16 v[12:15], v[144:147], v[212:215], v[12:15]
	v_mfma_f32_16x16x32_bf16 v[8:11], v[160:163], v[212:215], v[8:11]
	v_mfma_f32_16x16x32_bf16 v[60:63], v[156:159], v[188:191], v[60:63]
	v_mfma_f32_16x16x32_bf16 v[56:59], v[164:167], v[188:191], v[56:59]
	v_mfma_f32_16x16x32_bf16 v[44:47], v[156:159], v[200:203], v[44:47]
	v_mfma_f32_16x16x32_bf16 v[40:43], v[164:167], v[200:203], v[40:43]
	v_mfma_f32_16x16x32_bf16 v[28:31], v[156:159], v[208:211], v[28:31]
	v_mfma_f32_16x16x32_bf16 v[24:27], v[164:167], v[208:211], v[24:27]
	v_mfma_f32_16x16x32_bf16 v[12:15], v[156:159], v[216:219], v[12:15]
	v_mfma_f32_16x16x32_bf16 v[8:11], v[164:167], v[216:219], v[8:11]
	s_setprio 0
	s_setprio 1
	v_mfma_f32_16x16x32_bf16 v[52:55], v[168:171], v[184:187], v[52:55]
	v_mfma_f32_16x16x32_bf16 v[48:51], v[176:179], v[184:187], v[48:51]
	v_mfma_f32_16x16x32_bf16 v[36:39], v[168:171], v[196:199], v[36:39]
	v_mfma_f32_16x16x32_bf16 v[32:35], v[176:179], v[196:199], v[32:35]
	v_mfma_f32_16x16x32_bf16 v[20:23], v[168:171], v[204:207], v[20:23]
	v_mfma_f32_16x16x32_bf16 v[16:19], v[176:179], v[204:207], v[16:19]
	v_mfma_f32_16x16x32_bf16 v[4:7], v[168:171], v[212:215], v[4:7]
	v_mfma_f32_16x16x32_bf16 v[0:3], v[176:179], v[212:215], v[0:3]
	v_mfma_f32_16x16x32_bf16 v[52:55], v[172:175], v[188:191], v[52:55]
	v_mfma_f32_16x16x32_bf16 v[48:51], v[180:183], v[188:191], v[48:51]
	v_mfma_f32_16x16x32_bf16 v[36:39], v[172:175], v[200:203], v[36:39]
	v_mfma_f32_16x16x32_bf16 v[32:35], v[180:183], v[200:203], v[32:35]
	v_mfma_f32_16x16x32_bf16 v[20:23], v[172:175], v[208:211], v[20:23]
	v_mfma_f32_16x16x32_bf16 v[16:19], v[180:183], v[208:211], v[16:19]
	v_mfma_f32_16x16x32_bf16 v[4:7], v[172:175], v[216:219], v[4:7]
	v_mfma_f32_16x16x32_bf16 v[0:3], v[180:183], v[216:219], v[0:3]
	s_setprio 0
	s_barrier
	v_lshl_add_u64 v[222:223], v[222:223], 0, s[28:29]
	s_mov_b32 m0, s70
	s_nop 0
	global_load_lds_dwordx4 v[222:223], off
	v_lshl_add_u64 v[224:225], v[224:225], 0, s[28:29]
	s_mov_b32 m0, s71
	s_nop 0
	global_load_lds_dwordx4 v[224:225], off
	s_add_i32 s85, s85, 2
	s_add_u32 s83, s83, 0x100
	s_addc_u32 s84, s84, 0
	s_cmp_gt_u32 s85, 41
	s_mov_b64 s[36:37], s[38:39]
	s_cbranch_scc0 .LBB0_1791
	s_and_b64 vcc, exec, s[30:31]
	s_cbranch_vccz .LBB0_1794
	s_barrier

.LBB0_2142:
	ds_read_b128 v[144:147], v151
	ds_read_b128 v[156:159], v151 offset:1024
	ds_read_b128 v[160:163], v151 offset:2048
	ds_read_b128 v[164:167], v151 offset:3072
	ds_read_b128 v[168:171], v152
	ds_read_b128 v[172:175], v152 offset:1024
	ds_read_b128 v[176:179], v152 offset:2048
	ds_read_b128 v[180:183], v152 offset:3072
	s_add_u32 s38, s36, 0x100
	s_addc_u32 s39, s37, 0
	s_cmp_eq_u32 s83, 40
	s_cselect_b32 s43, s1, s39
	s_cselect_b32 s42, s0, s38
	s_cselect_b32 s41, s35, s82
	s_cselect_b32 s40, s34, s81
	v_lshl_add_u64 v[192:193], s[36:37], 0, v[136:137]
	s_add_i32 m0, s57, 0xc000
	ds_read_b128 v[184:187], v153
	ds_read_b128 v[188:191], v153 offset:1024
	ds_read_b128 v[196:199], v153 offset:2048
	ds_read_b128 v[200:203], v153 offset:3072
	ds_read_b128 v[204:207], v153 offset:4096
	ds_read_b128 v[208:211], v153 offset:5120
	ds_read_b128 v[212:215], v153 offset:6144
	ds_read_b128 v[216:219], v153 offset:7168
	global_load_lds_dwordx4 v[192:193], off
	v_lshl_add_u64 v[192:193], s[36:37], 0, v[138:139]
	s_add_i32 m0, s57, 0xe000
	s_nop 0
	global_load_lds_dwordx4 v[192:193], off
	s_waitcnt vmcnt(8)
	s_waitcnt lgkmcnt(0)
	s_barrier
	s_setprio 1
	s_waitcnt lgkmcnt(0)
	v_mfma_f32_16x16x32_bf16 v[124:127], v[144:147], v[184:187], v[124:127]
	v_mfma_f32_16x16x32_bf16 v[120:123], v[160:163], v[184:187], v[120:123]
	v_mfma_f32_16x16x32_bf16 v[108:111], v[144:147], v[196:199], v[108:111]
	v_mfma_f32_16x16x32_bf16 v[104:107], v[160:163], v[196:199], v[104:107]
	v_mfma_f32_16x16x32_bf16 v[92:95], v[144:147], v[204:207], v[92:95]
	v_mfma_f32_16x16x32_bf16 v[88:91], v[160:163], v[204:207], v[88:91]
	v_mfma_f32_16x16x32_bf16 v[76:79], v[144:147], v[212:215], v[76:79]
	v_mfma_f32_16x16x32_bf16 v[72:75], v[160:163], v[212:215], v[72:75]
	v_mfma_f32_16x16x32_bf16 v[124:127], v[156:159], v[188:191], v[124:127]
	v_mfma_f32_16x16x32_bf16 v[120:123], v[164:167], v[188:191], v[120:123]
	v_mfma_f32_16x16x32_bf16 v[108:111], v[156:159], v[200:203], v[108:111]
	v_mfma_f32_16x16x32_bf16 v[104:107], v[164:167], v[200:203], v[104:107]
	v_mfma_f32_16x16x32_bf16 v[92:95], v[156:159], v[208:211], v[92:95]
	v_mfma_f32_16x16x32_bf16 v[88:91], v[164:167], v[208:211], v[88:91]
	v_mfma_f32_16x16x32_bf16 v[76:79], v[156:159], v[216:219], v[76:79]
	v_mfma_f32_16x16x32_bf16 v[72:75], v[164:167], v[216:219], v[72:75]
	s_setprio 0
	s_setprio 1
	v_mfma_f32_16x16x32_bf16 v[116:119], v[168:171], v[184:187], v[116:119]
	v_mfma_f32_16x16x32_bf16 v[112:115], v[176:179], v[184:187], v[112:115]
	v_mfma_f32_16x16x32_bf16 v[100:103], v[168:171], v[196:199], v[100:103]
	v_mfma_f32_16x16x32_bf16 v[96:99], v[176:179], v[196:199], v[96:99]
	v_mfma_f32_16x16x32_bf16 v[84:87], v[168:171], v[204:207], v[84:87]
	v_mfma_f32_16x16x32_bf16 v[80:83], v[176:179], v[204:207], v[80:83]
	v_mfma_f32_16x16x32_bf16 v[68:71], v[168:171], v[212:215], v[68:71]
	v_mfma_f32_16x16x32_bf16 v[64:67], v[176:179], v[212:215], v[64:67]
	v_mfma_f32_16x16x32_bf16 v[116:119], v[172:175], v[188:191], v[116:119]
	v_mfma_f32_16x16x32_bf16 v[112:115], v[180:183], v[188:191], v[112:115]
	v_mfma_f32_16x16x32_bf16 v[100:103], v[172:175], v[200:203], v[100:103]
	v_mfma_f32_16x16x32_bf16 v[96:99], v[180:183], v[200:203], v[96:99]
	v_mfma_f32_16x16x32_bf16 v[84:87], v[172:175], v[208:211], v[84:87]
	v_mfma_f32_16x16x32_bf16 v[80:83], v[180:183], v[208:211], v[80:83]
	v_mfma_f32_16x16x32_bf16 v[68:71], v[172:175], v[216:219], v[68:71]
	v_mfma_f32_16x16x32_bf16 v[64:67], v[180:183], v[216:219], v[64:67]
	s_setprio 0
	s_barrier
	s_add_i32 s36, s71, s56
	v_lshl_add_u64 v[192:193], s[40:41], 0, v[130:131]
	s_mov_b32 m0, s36
	ds_read_b128 v[184:187], v153 offset:16384
	ds_read_b128 v[188:191], v153 offset:17408
	ds_read_b128 v[196:199], v153 offset:18432
	ds_read_b128 v[200:203], v153 offset:19456
	ds_read_b128 v[204:207], v153 offset:20480
	ds_read_b128 v[208:211], v153 offset:21504
	ds_read_b128 v[212:215], v153 offset:22528
	ds_read_b128 v[216:219], v153 offset:23552
	global_load_lds_dwordx4 v[192:193], off
	s_add_i32 m0, s36, 0x2000
	s_add_u32 s36, s40, 0xb0000
	v_lshl_add_u64 v[220:221], s[40:41], 0, v[134:135]
	s_addc_u32 s37, s41, 0
	s_add_i32 s84, s72, s56
	global_load_lds_dwordx4 v[220:221], off
	v_lshl_add_u64 v[222:223], s[36:37], 0, v[130:131]
	s_mov_b32 m0, s84
	v_lshl_add_u64 v[224:225], s[42:43], 0, v[132:133]
	global_load_lds_dwordx4 v[222:223], off
	v_lshl_add_u64 v[222:223], s[36:37], 0, v[134:135]
	s_add_i32 m0, s84, 0x2000
	s_nop 0
	global_load_lds_dwordx4 v[222:223], off
	v_lshl_add_u64 v[222:223], s[42:43], 0, v[128:129]
	s_waitcnt vmcnt(6)
	s_waitcnt lgkmcnt(0)
	s_barrier
	s_setprio 1
	s_waitcnt lgkmcnt(0)
	v_mfma_f32_16x16x32_bf16 v[60:63], v[144:147], v[184:187], v[60:63]
	v_mfma_f32_16x16x32_bf16 v[56:59], v[160:163], v[184:187], v[56:59]
	v_mfma_f32_16x16x32_bf16 v[44:47], v[144:147], v[196:199], v[44:47]
	v_mfma_f32_16x16x32_bf16 v[40:43], v[160:163], v[196:199], v[40:43]
	v_mfma_f32_16x16x32_bf16 v[28:31], v[144:147], v[204:207], v[28:31]
	v_mfma_f32_16x16x32_bf16 v[24:27], v[160:163], v[204:207], v[24:27]
	v_mfma_f32_16x16x32_bf16 v[12:15], v[144:147], v[212:215], v[12:15]
	v_mfma_f32_16x16x32_bf16 v[8:11], v[160:163], v[212:215], v[8:11]
	v_mfma_f32_16x16x32_bf16 v[60:63], v[156:159], v[188:191], v[60:63]
	v_mfma_f32_16x16x32_bf16 v[56:59], v[164:167], v[188:191], v[56:59]
	v_mfma_f32_16x16x32_bf16 v[44:47], v[156:159], v[200:203], v[44:47]
	v_mfma_f32_16x16x32_bf16 v[40:43], v[164:167], v[200:203], v[40:43]
	v_mfma_f32_16x16x32_bf16 v[28:31], v[156:159], v[208:211], v[28:31]
	v_mfma_f32_16x16x32_bf16 v[24:27], v[164:167], v[208:211], v[24:27]
	v_mfma_f32_16x16x32_bf16 v[12:15], v[156:159], v[216:219], v[12:15]
	v_mfma_f32_16x16x32_bf16 v[8:11], v[164:167], v[216:219], v[8:11]
	s_setprio 0
	s_setprio 1
	v_mfma_f32_16x16x32_bf16 v[52:55], v[168:171], v[184:187], v[52:55]
	v_mfma_f32_16x16x32_bf16 v[48:51], v[176:179], v[184:187], v[48:51]
	v_mfma_f32_16x16x32_bf16 v[36:39], v[168:171], v[196:199], v[36:39]
	v_mfma_f32_16x16x32_bf16 v[32:35], v[176:179], v[196:199], v[32:35]
	v_mfma_f32_16x16x32_bf16 v[20:23], v[168:171], v[204:207], v[20:23]
	v_mfma_f32_16x16x32_bf16 v[16:19], v[176:179], v[204:207], v[16:19]
	v_mfma_f32_16x16x32_bf16 v[4:7], v[168:171], v[212:215], v[4:7]
	v_mfma_f32_16x16x32_bf16 v[0:3], v[176:179], v[212:215], v[0:3]
	v_mfma_f32_16x16x32_bf16 v[52:55], v[172:175], v[188:191], v[52:55]
	v_mfma_f32_16x16x32_bf16 v[48:51], v[180:183], v[188:191], v[48:51]
	v_mfma_f32_16x16x32_bf16 v[36:39], v[172:175], v[200:203], v[36:39]
	v_mfma_f32_16x16x32_bf16 v[32:35], v[180:183], v[200:203], v[32:35]
	v_mfma_f32_16x16x32_bf16 v[20:23], v[172:175], v[208:211], v[20:23]
	v_mfma_f32_16x16x32_bf16 v[16:19], v[180:183], v[208:211], v[16:19]
	v_mfma_f32_16x16x32_bf16 v[4:7], v[172:175], v[216:219], v[4:7]
	v_mfma_f32_16x16x32_bf16 v[0:3], v[180:183], v[216:219], v[0:3]
	s_setprio 0
	s_barrier
	s_add_i32 s84, 0, 0x18000
	v_add_u32_e32 v155, s84, v149
	s_add_i32 s85, 0, 0x1c000
	ds_read_b128 v[144:147], v155
	ds_read_b128 v[156:159], v155 offset:1024
	ds_read_b128 v[160:163], v155 offset:2048
	ds_read_b128 v[164:167], v155 offset:3072
	v_add_u32_e32 v155, s85, v149
	ds_read_b128 v[168:171], v155
	ds_read_b128 v[172:175], v155 offset:1024
	ds_read_b128 v[176:179], v155 offset:2048
	ds_read_b128 v[180:183], v155 offset:3072
	s_add_u32 s36, s42, 0xb0000
	s_addc_u32 s37, s43, 0
	v_lshl_add_u64 v[226:227], s[36:37], 0, v[128:129]
	ds_read_b128 v[184:187], v153 offset:32768
	ds_read_b128 v[188:191], v153 offset:33792
	ds_read_b128 v[196:199], v153 offset:34816
	ds_read_b128 v[200:203], v153 offset:35840
	ds_read_b128 v[204:207], v153 offset:36864
	ds_read_b128 v[208:211], v153 offset:37888
	ds_read_b128 v[212:215], v153 offset:38912
	ds_read_b128 v[216:219], v153 offset:39936
	s_mov_b32 m0, s57
	s_nop 0
	global_load_lds_dwordx4 v[222:223], off
	s_mov_b32 m0, s58
	s_nop 0
	global_load_lds_dwordx4 v[224:225], off
	s_mov_b32 m0, s59
	s_nop 0
	global_load_lds_dwordx4 v[226:227], off
	v_lshl_add_u64 v[226:227], s[36:37], 0, v[132:133]
	s_mov_b32 m0, s60
	s_nop 0
	global_load_lds_dwordx4 v[226:227], off
	s_waitcnt vmcnt(8)
	s_waitcnt lgkmcnt(0)
	s_barrier
	s_setprio 1
	s_waitcnt lgkmcnt(0)
	v_mfma_f32_16x16x32_bf16 v[124:127], v[144:147], v[184:187], v[124:127]
	v_mfma_f32_16x16x32_bf16 v[120:123], v[160:163], v[184:187], v[120:123]
	v_mfma_f32_16x16x32_bf16 v[108:111], v[144:147], v[196:199], v[108:111]
	v_mfma_f32_16x16x32_bf16 v[104:107], v[160:163], v[196:199], v[104:107]
	v_mfma_f32_16x16x32_bf16 v[92:95], v[144:147], v[204:207], v[92:95]
	v_mfma_f32_16x16x32_bf16 v[88:91], v[160:163], v[204:207], v[88:91]
	v_mfma_f32_16x16x32_bf16 v[76:79], v[144:147], v[212:215], v[76:79]
	v_mfma_f32_16x16x32_bf16 v[72:75], v[160:163], v[212:215], v[72:75]
	v_mfma_f32_16x16x32_bf16 v[124:127], v[156:159], v[188:191], v[124:127]
	v_mfma_f32_16x16x32_bf16 v[120:123], v[164:167], v[188:191], v[120:123]
	v_mfma_f32_16x16x32_bf16 v[108:111], v[156:159], v[200:203], v[108:111]
	v_mfma_f32_16x16x32_bf16 v[104:107], v[164:167], v[200:203], v[104:107]
	v_mfma_f32_16x16x32_bf16 v[92:95], v[156:159], v[208:211], v[92:95]
	v_mfma_f32_16x16x32_bf16 v[88:91], v[164:167], v[208:211], v[88:91]
	v_mfma_f32_16x16x32_bf16 v[76:79], v[156:159], v[216:219], v[76:79]
	v_mfma_f32_16x16x32_bf16 v[72:75], v[164:167], v[216:219], v[72:75]
	s_setprio 0
	s_setprio 1
	v_mfma_f32_16x16x32_bf16 v[116:119], v[168:171], v[184:187], v[116:119]
	v_mfma_f32_16x16x32_bf16 v[112:115], v[176:179], v[184:187], v[112:115]
	v_mfma_f32_16x16x32_bf16 v[100:103], v[168:171], v[196:199], v[100:103]
	v_mfma_f32_16x16x32_bf16 v[96:99], v[176:179], v[196:199], v[96:99]
	v_mfma_f32_16x16x32_bf16 v[84:87], v[168:171], v[204:207], v[84:87]
	v_mfma_f32_16x16x32_bf16 v[80:83], v[176:179], v[204:207], v[80:83]
	v_mfma_f32_16x16x32_bf16 v[68:71], v[168:171], v[212:215], v[68:71]
	v_mfma_f32_16x16x32_bf16 v[64:67], v[176:179], v[212:215], v[64:67]
	v_mfma_f32_16x16x32_bf16 v[116:119], v[172:175], v[188:191], v[116:119]
	v_mfma_f32_16x16x32_bf16 v[112:115], v[180:183], v[188:191], v[112:115]
	v_mfma_f32_16x16x32_bf16 v[100:103], v[172:175], v[200:203], v[100:103]
	v_mfma_f32_16x16x32_bf16 v[96:99], v[180:183], v[200:203], v[96:99]
	v_mfma_f32_16x16x32_bf16 v[84:87], v[172:175], v[208:211], v[84:87]
	v_mfma_f32_16x16x32_bf16 v[80:83], v[180:183], v[208:211], v[80:83]
	v_mfma_f32_16x16x32_bf16 v[68:71], v[172:175], v[216:219], v[68:71]
	v_mfma_f32_16x16x32_bf16 v[64:67], v[180:183], v[216:219], v[64:67]
	s_setprio 0
	s_barrier
	s_add_i32 s36, s84, s56
	v_lshl_add_u64 v[192:193], v[192:193], 0, s[28:29]
	s_mov_b32 m0, s36
	ds_read_b128 v[184:187], v153 offset:49152
	ds_read_b128 v[188:191], v153 offset:50176
	ds_read_b128 v[196:199], v153 offset:51200
	ds_read_b128 v[200:203], v153 offset:52224
	ds_read_b128 v[204:207], v153 offset:53248
	ds_read_b128 v[208:211], v153 offset:54272
	ds_read_b128 v[212:215], v153 offset:55296
	ds_read_b128 v[216:219], v153 offset:56320
	global_load_lds_dwordx4 v[192:193], off
	s_add_i32 m0, s36, 0x2000
	s_add_u32 s36, s40, 0xb0080
	v_lshl_add_u64 v[192:193], v[220:221], 0, s[28:29]
	s_addc_u32 s37, s41, 0
	s_add_i32 s40, s85, s56
	global_load_lds_dwordx4 v[192:193], off
	v_lshl_add_u64 v[192:193], s[36:37], 0, v[130:131]
	s_mov_b32 m0, s40
	s_nop 0
	global_load_lds_dwordx4 v[192:193], off
	v_lshl_add_u64 v[192:193], s[36:37], 0, v[134:135]
	s_add_i32 m0, s40, 0x2000
	s_nop 0
	global_load_lds_dwordx4 v[192:193], off
	s_waitcnt vmcnt(6)
	s_waitcnt lgkmcnt(0)
	s_barrier
	s_setprio 1
	s_waitcnt lgkmcnt(0)
	v_mfma_f32_16x16x32_bf16 v[60:63], v[144:147], v[184:187], v[60:63]
	v_mfma_f32_16x16x32_bf16 v[56:59], v[160:163], v[184:187], v[56:59]
	v_mfma_f32_16x16x32_bf16 v[44:47], v[144:147], v[196:199], v[44:47]
	v_mfma_f32_16x16x32_bf16 v[40:43], v[160:163], v[196:199], v[40:43]
	v_mfma_f32_16x16x32_bf16 v[28:31], v[144:147], v[204:207], v[28:31]
	v_mfma_f32_16x16x32_bf16 v[24:27], v[160:163], v[204:207], v[24:27]
	v_mfma_f32_16x16x32_bf16 v[12:15], v[144:147], v[212:215], v[12:15]
	v_mfma_f32_16x16x32_bf16 v[8:11], v[160:163], v[212:215], v[8:11]
	v_mfma_f32_16x16x32_bf16 v[60:63], v[156:159], v[188:191], v[60:63]
	v_mfma_f32_16x16x32_bf16 v[56:59], v[164:167], v[188:191], v[56:59]
	v_mfma_f32_16x16x32_bf16 v[44:47], v[156:159], v[200:203], v[44:47]
	v_mfma_f32_16x16x32_bf16 v[40:43], v[164:167], v[200:203], v[40:43]
	v_mfma_f32_16x16x32_bf16 v[28:31], v[156:159], v[208:211], v[28:31]
	v_mfma_f32_16x16x32_bf16 v[24:27], v[164:167], v[208:211], v[24:27]
	v_mfma_f32_16x16x32_bf16 v[12:15], v[156:159], v[216:219], v[12:15]
	v_mfma_f32_16x16x32_bf16 v[8:11], v[164:167], v[216:219], v[8:11]
	s_setprio 0
	s_setprio 1
	v_mfma_f32_16x16x32_bf16 v[52:55], v[168:171], v[184:187], v[52:55]
	v_mfma_f32_16x16x32_bf16 v[48:51], v[176:179], v[184:187], v[48:51]
	v_mfma_f32_16x16x32_bf16 v[36:39], v[168:171], v[196:199], v[36:39]
	v_mfma_f32_16x16x32_bf16 v[32:35], v[176:179], v[196:199], v[32:35]
	v_mfma_f32_16x16x32_bf16 v[20:23], v[168:171], v[204:207], v[20:23]
	v_mfma_f32_16x16x32_bf16 v[16:19], v[176:179], v[204:207], v[16:19]
	v_mfma_f32_16x16x32_bf16 v[4:7], v[168:171], v[212:215], v[4:7]
	v_mfma_f32_16x16x32_bf16 v[0:3], v[176:179], v[212:215], v[0:3]
	v_mfma_f32_16x16x32_bf16 v[52:55], v[172:175], v[188:191], v[52:55]
	v_mfma_f32_16x16x32_bf16 v[48:51], v[180:183], v[188:191], v[48:51]
	v_mfma_f32_16x16x32_bf16 v[36:39], v[172:175], v[200:203], v[36:39]
	v_mfma_f32_16x16x32_bf16 v[32:35], v[180:183], v[200:203], v[32:35]
	v_mfma_f32_16x16x32_bf16 v[20:23], v[172:175], v[208:211], v[20:23]
	v_mfma_f32_16x16x32_bf16 v[16:19], v[180:183], v[208:211], v[16:19]
	v_mfma_f32_16x16x32_bf16 v[4:7], v[172:175], v[216:219], v[4:7]
	v_mfma_f32_16x16x32_bf16 v[0:3], v[180:183], v[216:219], v[0:3]
	s_setprio 0
	s_barrier
	v_lshl_add_u64 v[222:223], v[222:223], 0, s[28:29]
	s_mov_b32 m0, s62
	s_nop 0
	global_load_lds_dwordx4 v[222:223], off
	v_lshl_add_u64 v[224:225], v[224:225], 0, s[28:29]
	s_mov_b32 m0, s63
	s_nop 0
	global_load_lds_dwordx4 v[224:225], off
	s_add_i32 s83, s83, 2
	s_add_u32 s81, s81, 0x100
	s_addc_u32 s82, s82, 0
	s_cmp_gt_u32 s83, 41
	s_mov_b64 s[36:37], s[38:39]
	s_cbranch_scc0 .LBB0_2142
	s_and_b64 vcc, exec, s[30:31]
	s_cbranch_vccz .LBB0_2145
	s_barrier

.LBB0_2236:
	ds_read_b128 v[152:155], v157
	ds_read_b128 v[162:165], v157 offset:1024
	ds_read_b128 v[166:169], v157 offset:2048
	ds_read_b128 v[170:173], v157 offset:3072
	ds_read_b128 v[174:177], v158
	ds_read_b128 v[178:181], v158 offset:1024
	ds_read_b128 v[182:185], v158 offset:2048
	ds_read_b128 v[186:189], v158 offset:3072
	s_add_u32 s42, s40, 0xfffc0080
	s_addc_u32 s43, s41, -1
	s_cmp_eq_u32 s88, 12
	s_cselect_b32 s45, s1, s43
	s_cselect_b32 s44, s15, s42
	s_cselect_b32 s43, s16, s87
	s_cselect_b32 s42, s31, s35
	v_lshl_add_u64 v[224:225], s[40:41], 0, v[144:145]
	s_add_i32 m0, s59, 0xc000
	ds_read_b128 v[190:193], v159
	ds_read_b128 v[196:199], v159 offset:1024
	ds_read_b128 v[200:203], v159 offset:2048
	ds_read_b128 v[204:207], v159 offset:3072
	ds_read_b128 v[208:211], v159 offset:4096
	ds_read_b128 v[212:215], v159 offset:5120
	ds_read_b128 v[216:219], v159 offset:6144
	ds_read_b128 v[220:223], v159 offset:7168
	global_load_lds_dwordx4 v[224:225], off
	v_lshl_add_u64 v[224:225], s[40:41], 0, v[146:147]
	s_add_i32 m0, s59, 0xe000
	s_nop 0
	global_load_lds_dwordx4 v[224:225], off
	s_waitcnt vmcnt(8)
	s_waitcnt lgkmcnt(0)
	s_barrier
	s_setprio 1
	s_waitcnt lgkmcnt(0)
	v_mfma_f32_16x16x32_bf16 v[124:127], v[152:155], v[190:193], v[124:127]
	v_mfma_f32_16x16x32_bf16 v[120:123], v[166:169], v[190:193], v[120:123]
	v_mfma_f32_16x16x32_bf16 v[108:111], v[152:155], v[200:203], v[108:111]
	v_mfma_f32_16x16x32_bf16 v[104:107], v[166:169], v[200:203], v[104:107]
	v_mfma_f32_16x16x32_bf16 v[92:95], v[152:155], v[208:211], v[92:95]
	v_mfma_f32_16x16x32_bf16 v[88:91], v[166:169], v[208:211], v[88:91]
	v_mfma_f32_16x16x32_bf16 v[76:79], v[152:155], v[216:219], v[76:79]
	v_mfma_f32_16x16x32_bf16 v[72:75], v[166:169], v[216:219], v[72:75]
	v_mfma_f32_16x16x32_bf16 v[124:127], v[162:165], v[196:199], v[124:127]
	v_mfma_f32_16x16x32_bf16 v[120:123], v[170:173], v[196:199], v[120:123]
	v_mfma_f32_16x16x32_bf16 v[108:111], v[162:165], v[204:207], v[108:111]
	v_mfma_f32_16x16x32_bf16 v[104:107], v[170:173], v[204:207], v[104:107]
	v_mfma_f32_16x16x32_bf16 v[92:95], v[162:165], v[212:215], v[92:95]
	v_mfma_f32_16x16x32_bf16 v[88:91], v[170:173], v[212:215], v[88:91]
	v_mfma_f32_16x16x32_bf16 v[76:79], v[162:165], v[220:223], v[76:79]
	v_mfma_f32_16x16x32_bf16 v[72:75], v[170:173], v[220:223], v[72:75]
	s_setprio 0
	s_setprio 1
	v_mfma_f32_16x16x32_bf16 v[116:119], v[174:177], v[190:193], v[116:119]
	v_mfma_f32_16x16x32_bf16 v[112:115], v[182:185], v[190:193], v[112:115]
	v_mfma_f32_16x16x32_bf16 v[100:103], v[174:177], v[200:203], v[100:103]
	v_mfma_f32_16x16x32_bf16 v[96:99], v[182:185], v[200:203], v[96:99]
	v_mfma_f32_16x16x32_bf16 v[84:87], v[174:177], v[208:211], v[84:87]
	v_mfma_f32_16x16x32_bf16 v[80:83], v[182:185], v[208:211], v[80:83]
	v_mfma_f32_16x16x32_bf16 v[68:71], v[174:177], v[216:219], v[68:71]
	v_mfma_f32_16x16x32_bf16 v[64:67], v[182:185], v[216:219], v[64:67]
	v_mfma_f32_16x16x32_bf16 v[116:119], v[178:181], v[196:199], v[116:119]
	v_mfma_f32_16x16x32_bf16 v[112:115], v[186:189], v[196:199], v[112:115]
	v_mfma_f32_16x16x32_bf16 v[100:103], v[178:181], v[204:207], v[100:103]
	v_mfma_f32_16x16x32_bf16 v[96:99], v[186:189], v[204:207], v[96:99]
	v_mfma_f32_16x16x32_bf16 v[84:87], v[178:181], v[212:215], v[84:87]
	v_mfma_f32_16x16x32_bf16 v[80:83], v[186:189], v[212:215], v[80:83]
	v_mfma_f32_16x16x32_bf16 v[68:71], v[178:181], v[220:223], v[68:71]
	v_mfma_f32_16x16x32_bf16 v[64:67], v[186:189], v[220:223], v[64:67]
	s_setprio 0
	s_barrier
	s_add_i32 s89, s78, s58
	v_lshl_add_u64 v[224:225], s[42:43], 0, v[130:131]
	s_mov_b32 m0, s89
	ds_read_b128 v[190:193], v159 offset:16384
	ds_read_b128 v[196:199], v159 offset:17408
	ds_read_b128 v[200:203], v159 offset:18432
	ds_read_b128 v[204:207], v159 offset:19456
	ds_read_b128 v[208:211], v159 offset:20480
	ds_read_b128 v[212:215], v159 offset:21504
	ds_read_b128 v[216:219], v159 offset:22528
	ds_read_b128 v[220:223], v159 offset:23552
	global_load_lds_dwordx4 v[224:225], off
	s_add_i32 m0, s89, 0x2000
	s_add_u32 s90, s42, 0x40000
	v_lshl_add_u64 v[226:227], s[42:43], 0, v[134:135]
	s_addc_u32 s91, s43, 0
	s_add_i32 s89, s79, s58
	global_load_lds_dwordx4 v[226:227], off
	v_lshl_add_u64 v[228:229], s[90:91], 0, v[130:131]
	s_mov_b32 m0, s89
	v_lshl_add_u64 v[230:231], s[44:45], 0, v[132:133]
	global_load_lds_dwordx4 v[228:229], off
	v_lshl_add_u64 v[228:229], s[90:91], 0, v[134:135]
	s_add_i32 m0, s89, 0x2000
	s_nop 0
	global_load_lds_dwordx4 v[228:229], off
	v_lshl_add_u64 v[228:229], s[44:45], 0, v[128:129]
	s_waitcnt vmcnt(6)
	s_waitcnt lgkmcnt(0)
	s_barrier
	s_setprio 1
	s_waitcnt lgkmcnt(0)
	v_mfma_f32_16x16x32_bf16 v[60:63], v[152:155], v[190:193], v[60:63]
	v_mfma_f32_16x16x32_bf16 v[56:59], v[166:169], v[190:193], v[56:59]
	v_mfma_f32_16x16x32_bf16 v[44:47], v[152:155], v[200:203], v[44:47]
	v_mfma_f32_16x16x32_bf16 v[40:43], v[166:169], v[200:203], v[40:43]
	v_mfma_f32_16x16x32_bf16 v[28:31], v[152:155], v[208:211], v[28:31]
	v_mfma_f32_16x16x32_bf16 v[24:27], v[166:169], v[208:211], v[24:27]
	v_mfma_f32_16x16x32_bf16 v[12:15], v[152:155], v[216:219], v[12:15]
	v_mfma_f32_16x16x32_bf16 v[8:11], v[166:169], v[216:219], v[8:11]
	v_mfma_f32_16x16x32_bf16 v[60:63], v[162:165], v[196:199], v[60:63]
	v_mfma_f32_16x16x32_bf16 v[56:59], v[170:173], v[196:199], v[56:59]
	v_mfma_f32_16x16x32_bf16 v[44:47], v[162:165], v[204:207], v[44:47]
	v_mfma_f32_16x16x32_bf16 v[40:43], v[170:173], v[204:207], v[40:43]
	v_mfma_f32_16x16x32_bf16 v[28:31], v[162:165], v[212:215], v[28:31]
	v_mfma_f32_16x16x32_bf16 v[24:27], v[170:173], v[212:215], v[24:27]
	v_mfma_f32_16x16x32_bf16 v[12:15], v[162:165], v[220:223], v[12:15]
	v_mfma_f32_16x16x32_bf16 v[8:11], v[170:173], v[220:223], v[8:11]
	s_setprio 0
	s_setprio 1
	v_mfma_f32_16x16x32_bf16 v[52:55], v[174:177], v[190:193], v[52:55]
	v_mfma_f32_16x16x32_bf16 v[48:51], v[182:185], v[190:193], v[48:51]
	v_mfma_f32_16x16x32_bf16 v[36:39], v[174:177], v[200:203], v[36:39]
	v_mfma_f32_16x16x32_bf16 v[32:35], v[182:185], v[200:203], v[32:35]
	v_mfma_f32_16x16x32_bf16 v[20:23], v[174:177], v[208:211], v[20:23]
	v_mfma_f32_16x16x32_bf16 v[16:19], v[182:185], v[208:211], v[16:19]
	v_mfma_f32_16x16x32_bf16 v[4:7], v[174:177], v[216:219], v[4:7]
	v_mfma_f32_16x16x32_bf16 v[0:3], v[182:185], v[216:219], v[0:3]
	v_mfma_f32_16x16x32_bf16 v[52:55], v[178:181], v[196:199], v[52:55]
	v_mfma_f32_16x16x32_bf16 v[48:51], v[186:189], v[196:199], v[48:51]
	v_mfma_f32_16x16x32_bf16 v[36:39], v[178:181], v[204:207], v[36:39]
	v_mfma_f32_16x16x32_bf16 v[32:35], v[186:189], v[204:207], v[32:35]
	v_mfma_f32_16x16x32_bf16 v[20:23], v[178:181], v[212:215], v[20:23]
	v_mfma_f32_16x16x32_bf16 v[16:19], v[186:189], v[212:215], v[16:19]
	v_mfma_f32_16x16x32_bf16 v[4:7], v[178:181], v[220:223], v[4:7]
	v_mfma_f32_16x16x32_bf16 v[0:3], v[186:189], v[220:223], v[0:3]
	s_setprio 0
	s_barrier
	s_add_i32 s89, 0, 0x18000
	v_add_u32_e32 v136, s89, v141
	s_add_i32 s90, 0, 0x1c000
	ds_read_b128 v[152:155], v136
	ds_read_b128 v[162:165], v136 offset:1024
	ds_read_b128 v[166:169], v136 offset:2048
	ds_read_b128 v[170:173], v136 offset:3072
	v_add_u32_e32 v136, s90, v141
	ds_read_b128 v[174:177], v136
	ds_read_b128 v[178:181], v136 offset:1024
	ds_read_b128 v[182:185], v136 offset:2048
	ds_read_b128 v[186:189], v136 offset:3072
	s_add_u32 s44, s44, 0x40000
	s_addc_u32 s45, s45, 0
	v_lshl_add_u64 v[232:233], s[44:45], 0, v[128:129]
	ds_read_b128 v[190:193], v159 offset:32768
	ds_read_b128 v[196:199], v159 offset:33792
	ds_read_b128 v[200:203], v159 offset:34816
	ds_read_b128 v[204:207], v159 offset:35840
	ds_read_b128 v[208:211], v159 offset:36864
	ds_read_b128 v[212:215], v159 offset:37888
	ds_read_b128 v[216:219], v159 offset:38912
	ds_read_b128 v[220:223], v159 offset:39936
	s_mov_b32 m0, s59
	s_nop 0
	global_load_lds_dwordx4 v[228:229], off
	s_mov_b32 m0, s60
	s_nop 0
	global_load_lds_dwordx4 v[230:231], off
	s_mov_b32 m0, s61
	s_nop 0
	global_load_lds_dwordx4 v[232:233], off
	v_lshl_add_u64 v[232:233], s[44:45], 0, v[132:133]
	s_mov_b32 m0, s62
	s_nop 0
	global_load_lds_dwordx4 v[232:233], off
	s_waitcnt vmcnt(8)
	s_waitcnt lgkmcnt(0)
	s_barrier
	s_setprio 1
	s_waitcnt lgkmcnt(0)
	v_mfma_f32_16x16x32_bf16 v[124:127], v[152:155], v[190:193], v[124:127]
	v_mfma_f32_16x16x32_bf16 v[120:123], v[166:169], v[190:193], v[120:123]
	v_mfma_f32_16x16x32_bf16 v[108:111], v[152:155], v[200:203], v[108:111]
	v_mfma_f32_16x16x32_bf16 v[104:107], v[166:169], v[200:203], v[104:107]
	v_mfma_f32_16x16x32_bf16 v[92:95], v[152:155], v[208:211], v[92:95]
	v_mfma_f32_16x16x32_bf16 v[88:91], v[166:169], v[208:211], v[88:91]
	v_mfma_f32_16x16x32_bf16 v[76:79], v[152:155], v[216:219], v[76:79]
	v_mfma_f32_16x16x32_bf16 v[72:75], v[166:169], v[216:219], v[72:75]
	v_mfma_f32_16x16x32_bf16 v[124:127], v[162:165], v[196:199], v[124:127]
	v_mfma_f32_16x16x32_bf16 v[120:123], v[170:173], v[196:199], v[120:123]
	v_mfma_f32_16x16x32_bf16 v[108:111], v[162:165], v[204:207], v[108:111]
	v_mfma_f32_16x16x32_bf16 v[104:107], v[170:173], v[204:207], v[104:107]
	v_mfma_f32_16x16x32_bf16 v[92:95], v[162:165], v[212:215], v[92:95]
	v_mfma_f32_16x16x32_bf16 v[88:91], v[170:173], v[212:215], v[88:91]
	v_mfma_f32_16x16x32_bf16 v[76:79], v[162:165], v[220:223], v[76:79]
	v_mfma_f32_16x16x32_bf16 v[72:75], v[170:173], v[220:223], v[72:75]
	s_setprio 0
	s_setprio 1
	v_mfma_f32_16x16x32_bf16 v[116:119], v[174:177], v[190:193], v[116:119]
	v_mfma_f32_16x16x32_bf16 v[112:115], v[182:185], v[190:193], v[112:115]
	v_mfma_f32_16x16x32_bf16 v[100:103], v[174:177], v[200:203], v[100:103]
	v_mfma_f32_16x16x32_bf16 v[96:99], v[182:185], v[200:203], v[96:99]
	v_mfma_f32_16x16x32_bf16 v[84:87], v[174:177], v[208:211], v[84:87]
	v_mfma_f32_16x16x32_bf16 v[80:83], v[182:185], v[208:211], v[80:83]
	v_mfma_f32_16x16x32_bf16 v[68:71], v[174:177], v[216:219], v[68:71]
	v_mfma_f32_16x16x32_bf16 v[64:67], v[182:185], v[216:219], v[64:67]
	v_mfma_f32_16x16x32_bf16 v[116:119], v[178:181], v[196:199], v[116:119]
	v_mfma_f32_16x16x32_bf16 v[112:115], v[186:189], v[196:199], v[112:115]
	v_mfma_f32_16x16x32_bf16 v[100:103], v[178:181], v[204:207], v[100:103]
	v_mfma_f32_16x16x32_bf16 v[96:99], v[186:189], v[204:207], v[96:99]
	v_mfma_f32_16x16x32_bf16 v[84:87], v[178:181], v[212:215], v[84:87]
	v_mfma_f32_16x16x32_bf16 v[80:83], v[186:189], v[212:215], v[80:83]
	v_mfma_f32_16x16x32_bf16 v[68:71], v[178:181], v[220:223], v[68:71]
	v_mfma_f32_16x16x32_bf16 v[64:67], v[186:189], v[220:223], v[64:67]
	s_setprio 0
	s_barrier
	s_add_i32 s44, s89, s58
	v_lshl_add_u64 v[224:225], v[224:225], 0, s[26:27]
	s_mov_b32 m0, s44
	ds_read_b128 v[190:193], v159 offset:49152
	ds_read_b128 v[196:199], v159 offset:50176
	ds_read_b128 v[200:203], v159 offset:51200
	ds_read_b128 v[204:207], v159 offset:52224
	ds_read_b128 v[208:211], v159 offset:53248
	ds_read_b128 v[212:215], v159 offset:54272
	ds_read_b128 v[216:219], v159 offset:55296
	ds_read_b128 v[220:223], v159 offset:56320
	global_load_lds_dwordx4 v[224:225], off
	s_add_i32 m0, s44, 0x2000
	s_add_u32 s42, s42, 0x40080
	v_lshl_add_u64 v[224:225], v[226:227], 0, s[26:27]
	s_addc_u32 s43, s43, 0
	s_add_i32 s44, s90, s58
	global_load_lds_dwordx4 v[224:225], off
	v_lshl_add_u64 v[224:225], s[42:43], 0, v[130:131]
	s_mov_b32 m0, s44
	s_nop 0
	global_load_lds_dwordx4 v[224:225], off
	v_lshl_add_u64 v[224:225], s[42:43], 0, v[134:135]
	s_add_i32 m0, s44, 0x2000
	s_nop 0
	global_load_lds_dwordx4 v[224:225], off
	s_waitcnt vmcnt(6)
	s_waitcnt lgkmcnt(0)
	s_barrier
	s_setprio 1
	s_waitcnt lgkmcnt(0)
	v_mfma_f32_16x16x32_bf16 v[60:63], v[152:155], v[190:193], v[60:63]
	v_mfma_f32_16x16x32_bf16 v[56:59], v[166:169], v[190:193], v[56:59]
	v_mfma_f32_16x16x32_bf16 v[44:47], v[152:155], v[200:203], v[44:47]
	v_mfma_f32_16x16x32_bf16 v[40:43], v[166:169], v[200:203], v[40:43]
	v_mfma_f32_16x16x32_bf16 v[28:31], v[152:155], v[208:211], v[28:31]
	v_mfma_f32_16x16x32_bf16 v[24:27], v[166:169], v[208:211], v[24:27]
	v_mfma_f32_16x16x32_bf16 v[12:15], v[152:155], v[216:219], v[12:15]
	v_mfma_f32_16x16x32_bf16 v[8:11], v[166:169], v[216:219], v[8:11]
	v_mfma_f32_16x16x32_bf16 v[60:63], v[162:165], v[196:199], v[60:63]
	v_mfma_f32_16x16x32_bf16 v[56:59], v[170:173], v[196:199], v[56:59]
	v_mfma_f32_16x16x32_bf16 v[44:47], v[162:165], v[204:207], v[44:47]
	v_mfma_f32_16x16x32_bf16 v[40:43], v[170:173], v[204:207], v[40:43]
	v_mfma_f32_16x16x32_bf16 v[28:31], v[162:165], v[212:215], v[28:31]
	v_mfma_f32_16x16x32_bf16 v[24:27], v[170:173], v[212:215], v[24:27]
	v_mfma_f32_16x16x32_bf16 v[12:15], v[162:165], v[220:223], v[12:15]
	v_mfma_f32_16x16x32_bf16 v[8:11], v[170:173], v[220:223], v[8:11]
	s_setprio 0
	s_setprio 1
	v_mfma_f32_16x16x32_bf16 v[52:55], v[174:177], v[190:193], v[52:55]
	v_mfma_f32_16x16x32_bf16 v[48:51], v[182:185], v[190:193], v[48:51]
	v_mfma_f32_16x16x32_bf16 v[36:39], v[174:177], v[200:203], v[36:39]
	v_mfma_f32_16x16x32_bf16 v[32:35], v[182:185], v[200:203], v[32:35]
	v_mfma_f32_16x16x32_bf16 v[20:23], v[174:177], v[208:211], v[20:23]
	v_mfma_f32_16x16x32_bf16 v[16:19], v[182:185], v[208:211], v[16:19]
	v_mfma_f32_16x16x32_bf16 v[4:7], v[174:177], v[216:219], v[4:7]
	v_mfma_f32_16x16x32_bf16 v[0:3], v[182:185], v[216:219], v[0:3]
	v_mfma_f32_16x16x32_bf16 v[52:55], v[178:181], v[196:199], v[52:55]
	v_mfma_f32_16x16x32_bf16 v[48:51], v[186:189], v[196:199], v[48:51]
	v_mfma_f32_16x16x32_bf16 v[36:39], v[178:181], v[204:207], v[36:39]
	v_mfma_f32_16x16x32_bf16 v[32:35], v[186:189], v[204:207], v[32:35]
	v_mfma_f32_16x16x32_bf16 v[20:23], v[178:181], v[212:215], v[20:23]
	v_mfma_f32_16x16x32_bf16 v[16:19], v[186:189], v[212:215], v[16:19]
	v_mfma_f32_16x16x32_bf16 v[4:7], v[178:181], v[220:223], v[4:7]
	v_mfma_f32_16x16x32_bf16 v[0:3], v[186:189], v[220:223], v[0:3]
	s_setprio 0
	s_barrier
	v_lshl_add_u64 v[228:229], v[228:229], 0, s[26:27]
	s_mov_b32 m0, s71
	s_nop 0
	global_load_lds_dwordx4 v[228:229], off
	v_lshl_add_u64 v[230:231], v[230:231], 0, s[26:27]
	s_mov_b32 m0, s72
	s_nop 0
	global_load_lds_dwordx4 v[230:231], off
	s_add_i32 s88, s88, 2
	s_add_u32 s40, s40, 0x100
	s_addc_u32 s41, s41, 0
	s_add_u32 s35, s35, 0x100
	s_addc_u32 s87, s87, 0
	s_cmp_gt_u32 s88, 13
	s_cbranch_scc0 .LBB0_2236
	s_and_b64 vcc, exec, s[28:29]
	s_cbranch_vccz .LBB0_2239
	s_barrier

.LBB0_2370:
	ds_read_b128 v[148:151], v144
	ds_read_b128 v[152:155], v144 offset:1024
	ds_read_b128 v[156:159], v144 offset:2048
	ds_read_b128 v[160:163], v144 offset:3072
	ds_read_b128 v[164:167], v145
	ds_read_b128 v[168:171], v145 offset:1024
	ds_read_b128 v[172:175], v145 offset:2048
	ds_read_b128 v[176:179], v145 offset:3072
	s_add_u32 s38, s36, 0x100
	s_addc_u32 s39, s37, 0
	s_cmp_eq_u32 s81, 4
	s_cselect_b32 s43, s31, s39
	s_cselect_b32 s42, s30, s38
	s_cselect_b32 s41, s35, s27
	s_cselect_b32 s40, s34, s17
	v_lshl_add_u64 v[192:193], s[36:37], 0, v[138:139]
	s_add_i32 m0, s55, 0xc000
	ds_read_b128 v[180:183], v146
	ds_read_b128 v[184:187], v146 offset:1024
	ds_read_b128 v[188:191], v146 offset:2048
	ds_read_b128 v[196:199], v146 offset:3072
	ds_read_b128 v[200:203], v146 offset:4096
	ds_read_b128 v[204:207], v146 offset:5120
	ds_read_b128 v[208:211], v146 offset:6144
	ds_read_b128 v[212:215], v146 offset:7168
	global_load_lds_dwordx4 v[192:193], off
	v_lshl_add_u64 v[192:193], s[36:37], 0, v[140:141]
	s_add_i32 m0, s55, 0xe000
	s_nop 0
	global_load_lds_dwordx4 v[192:193], off
	s_waitcnt vmcnt(8)
	s_waitcnt lgkmcnt(0)
	s_barrier
	s_setprio 1
	s_waitcnt lgkmcnt(0)
	v_mfma_f32_16x16x32_bf16 v[124:127], v[148:151], v[180:183], v[124:127]
	v_mfma_f32_16x16x32_bf16 v[120:123], v[156:159], v[180:183], v[120:123]
	v_mfma_f32_16x16x32_bf16 v[116:119], v[148:151], v[188:191], v[116:119]
	v_mfma_f32_16x16x32_bf16 v[112:115], v[156:159], v[188:191], v[112:115]
	v_mfma_f32_16x16x32_bf16 v[104:107], v[148:151], v[200:203], v[104:107]
	v_mfma_f32_16x16x32_bf16 v[96:99], v[156:159], v[200:203], v[96:99]
	v_mfma_f32_16x16x32_bf16 v[88:91], v[148:151], v[208:211], v[88:91]
	v_mfma_f32_16x16x32_bf16 v[80:83], v[156:159], v[208:211], v[80:83]
	v_mfma_f32_16x16x32_bf16 v[124:127], v[152:155], v[184:187], v[124:127]
	v_mfma_f32_16x16x32_bf16 v[120:123], v[160:163], v[184:187], v[120:123]
	v_mfma_f32_16x16x32_bf16 v[116:119], v[152:155], v[196:199], v[116:119]
	v_mfma_f32_16x16x32_bf16 v[112:115], v[160:163], v[196:199], v[112:115]
	v_mfma_f32_16x16x32_bf16 v[104:107], v[152:155], v[204:207], v[104:107]
	v_mfma_f32_16x16x32_bf16 v[96:99], v[160:163], v[204:207], v[96:99]
	v_mfma_f32_16x16x32_bf16 v[88:91], v[152:155], v[212:215], v[88:91]
	v_mfma_f32_16x16x32_bf16 v[80:83], v[160:163], v[212:215], v[80:83]
	s_setprio 0
	s_setprio 1
	v_mfma_f32_16x16x32_bf16 v[108:111], v[164:167], v[180:183], v[108:111]
	v_mfma_f32_16x16x32_bf16 v[100:103], v[172:175], v[180:183], v[100:103]
	v_mfma_f32_16x16x32_bf16 v[92:95], v[164:167], v[188:191], v[92:95]
	v_mfma_f32_16x16x32_bf16 v[84:87], v[172:175], v[188:191], v[84:87]
	v_mfma_f32_16x16x32_bf16 v[76:79], v[164:167], v[200:203], v[76:79]
	v_mfma_f32_16x16x32_bf16 v[72:75], v[172:175], v[200:203], v[72:75]
	v_mfma_f32_16x16x32_bf16 v[68:71], v[164:167], v[208:211], v[68:71]
	v_mfma_f32_16x16x32_bf16 v[64:67], v[172:175], v[208:211], v[64:67]
	v_mfma_f32_16x16x32_bf16 v[108:111], v[168:171], v[184:187], v[108:111]
	v_mfma_f32_16x16x32_bf16 v[100:103], v[176:179], v[184:187], v[100:103]
	v_mfma_f32_16x16x32_bf16 v[92:95], v[168:171], v[196:199], v[92:95]
	v_mfma_f32_16x16x32_bf16 v[84:87], v[176:179], v[196:199], v[84:87]
	v_mfma_f32_16x16x32_bf16 v[76:79], v[168:171], v[204:207], v[76:79]
	v_mfma_f32_16x16x32_bf16 v[72:75], v[176:179], v[204:207], v[72:75]
	v_mfma_f32_16x16x32_bf16 v[68:71], v[168:171], v[212:215], v[68:71]
	v_mfma_f32_16x16x32_bf16 v[64:67], v[176:179], v[212:215], v[64:67]
	s_setprio 0
	s_barrier
	s_add_i32 s36, s71, s54
	v_lshl_add_u64 v[192:193], s[40:41], 0, v[132:133]
	s_mov_b32 m0, s36
	ds_read_b128 v[180:183], v146 offset:16384
	ds_read_b128 v[184:187], v146 offset:17408
	ds_read_b128 v[188:191], v146 offset:18432
	ds_read_b128 v[196:199], v146 offset:19456
	ds_read_b128 v[200:203], v146 offset:20480
	ds_read_b128 v[204:207], v146 offset:21504
	ds_read_b128 v[208:211], v146 offset:22528
	ds_read_b128 v[212:215], v146 offset:23552
	global_load_lds_dwordx4 v[192:193], off
	s_add_i32 m0, s36, 0x2000
	s_add_u32 s36, s40, 0x20000
	v_lshl_add_u64 v[216:217], s[40:41], 0, v[128:129]
	s_addc_u32 s37, s41, 0
	s_add_i32 s82, s72, s54
	global_load_lds_dwordx4 v[216:217], off
	v_lshl_add_u64 v[218:219], s[36:37], 0, v[132:133]
	s_mov_b32 m0, s82
	v_lshl_add_u64 v[220:221], s[42:43], 0, v[130:131]
	global_load_lds_dwordx4 v[218:219], off
	v_lshl_add_u64 v[218:219], s[36:37], 0, v[128:129]
	s_add_i32 m0, s82, 0x2000
	s_nop 0
	global_load_lds_dwordx4 v[218:219], off
	v_lshl_add_u64 v[218:219], s[42:43], 0, v[134:135]
	s_waitcnt vmcnt(6)
	s_waitcnt lgkmcnt(0)
	s_barrier
	s_setprio 1
	s_waitcnt lgkmcnt(0)
	v_mfma_f32_16x16x32_bf16 v[60:63], v[148:151], v[180:183], v[60:63]
	v_mfma_f32_16x16x32_bf16 v[56:59], v[156:159], v[180:183], v[56:59]
	v_mfma_f32_16x16x32_bf16 v[52:55], v[148:151], v[188:191], v[52:55]
	v_mfma_f32_16x16x32_bf16 v[48:51], v[156:159], v[188:191], v[48:51]
	v_mfma_f32_16x16x32_bf16 v[40:43], v[148:151], v[200:203], v[40:43]
	v_mfma_f32_16x16x32_bf16 v[32:35], v[156:159], v[200:203], v[32:35]
	v_mfma_f32_16x16x32_bf16 v[24:27], v[148:151], v[208:211], v[24:27]
	v_mfma_f32_16x16x32_bf16 v[16:19], v[156:159], v[208:211], v[16:19]
	v_mfma_f32_16x16x32_bf16 v[60:63], v[152:155], v[184:187], v[60:63]
	v_mfma_f32_16x16x32_bf16 v[56:59], v[160:163], v[184:187], v[56:59]
	v_mfma_f32_16x16x32_bf16 v[52:55], v[152:155], v[196:199], v[52:55]
	v_mfma_f32_16x16x32_bf16 v[48:51], v[160:163], v[196:199], v[48:51]
	v_mfma_f32_16x16x32_bf16 v[40:43], v[152:155], v[204:207], v[40:43]
	v_mfma_f32_16x16x32_bf16 v[32:35], v[160:163], v[204:207], v[32:35]
	v_mfma_f32_16x16x32_bf16 v[24:27], v[152:155], v[212:215], v[24:27]
	v_mfma_f32_16x16x32_bf16 v[16:19], v[160:163], v[212:215], v[16:19]
	s_setprio 0
	s_setprio 1
	v_mfma_f32_16x16x32_bf16 v[44:47], v[164:167], v[180:183], v[44:47]
	v_mfma_f32_16x16x32_bf16 v[36:39], v[172:175], v[180:183], v[36:39]
	v_mfma_f32_16x16x32_bf16 v[28:31], v[164:167], v[188:191], v[28:31]
	v_mfma_f32_16x16x32_bf16 v[20:23], v[172:175], v[188:191], v[20:23]
	v_mfma_f32_16x16x32_bf16 v[12:15], v[164:167], v[200:203], v[12:15]
	v_mfma_f32_16x16x32_bf16 v[8:11], v[172:175], v[200:203], v[8:11]
	v_mfma_f32_16x16x32_bf16 v[4:7], v[164:167], v[208:211], v[4:7]
	v_mfma_f32_16x16x32_bf16 v[0:3], v[172:175], v[208:211], v[0:3]
	v_mfma_f32_16x16x32_bf16 v[44:47], v[168:171], v[184:187], v[44:47]
	v_mfma_f32_16x16x32_bf16 v[36:39], v[176:179], v[184:187], v[36:39]
	v_mfma_f32_16x16x32_bf16 v[28:31], v[168:171], v[196:199], v[28:31]
	v_mfma_f32_16x16x32_bf16 v[20:23], v[176:179], v[196:199], v[20:23]
	v_mfma_f32_16x16x32_bf16 v[12:15], v[168:171], v[204:207], v[12:15]
	v_mfma_f32_16x16x32_bf16 v[8:11], v[176:179], v[204:207], v[8:11]
	v_mfma_f32_16x16x32_bf16 v[4:7], v[168:171], v[212:215], v[4:7]
	v_mfma_f32_16x16x32_bf16 v[0:3], v[176:179], v[212:215], v[0:3]
	s_setprio 0
	s_barrier
	s_add_i32 s82, 0, 0x18000
	v_add_u32_e32 v147, s82, v143
	s_add_i32 s83, 0, 0x1c000
	ds_read_b128 v[148:151], v147
	ds_read_b128 v[152:155], v147 offset:1024
	ds_read_b128 v[156:159], v147 offset:2048
	ds_read_b128 v[160:163], v147 offset:3072
	v_add_u32_e32 v147, s83, v143
	ds_read_b128 v[164:167], v147
	ds_read_b128 v[168:171], v147 offset:1024
	ds_read_b128 v[172:175], v147 offset:2048
	ds_read_b128 v[176:179], v147 offset:3072
	s_add_u32 s36, s42, 0x30000
	s_addc_u32 s37, s43, 0
	v_lshl_add_u64 v[222:223], s[36:37], 0, v[134:135]
	ds_read_b128 v[180:183], v146 offset:32768
	ds_read_b128 v[184:187], v146 offset:33792
	ds_read_b128 v[188:191], v146 offset:34816
	ds_read_b128 v[196:199], v146 offset:35840
	ds_read_b128 v[200:203], v146 offset:36864
	ds_read_b128 v[204:207], v146 offset:37888
	ds_read_b128 v[208:211], v146 offset:38912
	ds_read_b128 v[212:215], v146 offset:39936
	s_mov_b32 m0, s55
	s_nop 0
	global_load_lds_dwordx4 v[218:219], off
	s_mov_b32 m0, s56
	s_nop 0
	global_load_lds_dwordx4 v[220:221], off
	s_mov_b32 m0, s57
	s_nop 0
	global_load_lds_dwordx4 v[222:223], off
	v_lshl_add_u64 v[222:223], s[36:37], 0, v[130:131]
	s_mov_b32 m0, s58
	s_nop 0
	global_load_lds_dwordx4 v[222:223], off
	s_waitcnt vmcnt(8)
	s_waitcnt lgkmcnt(0)
	s_barrier
	s_setprio 1
	s_waitcnt lgkmcnt(0)
	v_mfma_f32_16x16x32_bf16 v[124:127], v[148:151], v[180:183], v[124:127]
	v_mfma_f32_16x16x32_bf16 v[120:123], v[156:159], v[180:183], v[120:123]
	v_mfma_f32_16x16x32_bf16 v[116:119], v[148:151], v[188:191], v[116:119]
	v_mfma_f32_16x16x32_bf16 v[112:115], v[156:159], v[188:191], v[112:115]
	v_mfma_f32_16x16x32_bf16 v[104:107], v[148:151], v[200:203], v[104:107]
	v_mfma_f32_16x16x32_bf16 v[96:99], v[156:159], v[200:203], v[96:99]
	v_mfma_f32_16x16x32_bf16 v[88:91], v[148:151], v[208:211], v[88:91]
	v_mfma_f32_16x16x32_bf16 v[80:83], v[156:159], v[208:211], v[80:83]
	v_mfma_f32_16x16x32_bf16 v[124:127], v[152:155], v[184:187], v[124:127]
	v_mfma_f32_16x16x32_bf16 v[120:123], v[160:163], v[184:187], v[120:123]
	v_mfma_f32_16x16x32_bf16 v[116:119], v[152:155], v[196:199], v[116:119]
	v_mfma_f32_16x16x32_bf16 v[112:115], v[160:163], v[196:199], v[112:115]
	v_mfma_f32_16x16x32_bf16 v[104:107], v[152:155], v[204:207], v[104:107]
	v_mfma_f32_16x16x32_bf16 v[96:99], v[160:163], v[204:207], v[96:99]
	v_mfma_f32_16x16x32_bf16 v[88:91], v[152:155], v[212:215], v[88:91]
	v_mfma_f32_16x16x32_bf16 v[80:83], v[160:163], v[212:215], v[80:83]
	s_setprio 0
	s_setprio 1
	v_mfma_f32_16x16x32_bf16 v[108:111], v[164:167], v[180:183], v[108:111]
	v_mfma_f32_16x16x32_bf16 v[100:103], v[172:175], v[180:183], v[100:103]
	v_mfma_f32_16x16x32_bf16 v[92:95], v[164:167], v[188:191], v[92:95]
	v_mfma_f32_16x16x32_bf16 v[84:87], v[172:175], v[188:191], v[84:87]
	v_mfma_f32_16x16x32_bf16 v[76:79], v[164:167], v[200:203], v[76:79]
	v_mfma_f32_16x16x32_bf16 v[72:75], v[172:175], v[200:203], v[72:75]
	v_mfma_f32_16x16x32_bf16 v[68:71], v[164:167], v[208:211], v[68:71]
	v_mfma_f32_16x16x32_bf16 v[64:67], v[172:175], v[208:211], v[64:67]
	v_mfma_f32_16x16x32_bf16 v[108:111], v[168:171], v[184:187], v[108:111]
	v_mfma_f32_16x16x32_bf16 v[100:103], v[176:179], v[184:187], v[100:103]
	v_mfma_f32_16x16x32_bf16 v[92:95], v[168:171], v[196:199], v[92:95]
	v_mfma_f32_16x16x32_bf16 v[84:87], v[176:179], v[196:199], v[84:87]
	v_mfma_f32_16x16x32_bf16 v[76:79], v[168:171], v[204:207], v[76:79]
	v_mfma_f32_16x16x32_bf16 v[72:75], v[176:179], v[204:207], v[72:75]
	v_mfma_f32_16x16x32_bf16 v[68:71], v[168:171], v[212:215], v[68:71]
	v_mfma_f32_16x16x32_bf16 v[64:67], v[176:179], v[212:215], v[64:67]
	s_setprio 0
	s_barrier
	s_add_i32 s36, s82, s54
	v_lshl_add_u64 v[192:193], v[192:193], 0, s[14:15]
	s_mov_b32 m0, s36
	ds_read_b128 v[180:183], v146 offset:49152
	ds_read_b128 v[184:187], v146 offset:50176
	ds_read_b128 v[188:191], v146 offset:51200
	ds_read_b128 v[196:199], v146 offset:52224
	ds_read_b128 v[200:203], v146 offset:53248
	ds_read_b128 v[204:207], v146 offset:54272
	ds_read_b128 v[208:211], v146 offset:55296
	ds_read_b128 v[212:215], v146 offset:56320
	global_load_lds_dwordx4 v[192:193], off
	s_add_i32 m0, s36, 0x2000
	s_add_u32 s36, s40, 0x20080
	v_lshl_add_u64 v[192:193], v[216:217], 0, s[14:15]
	s_addc_u32 s37, s41, 0
	s_add_i32 s40, s83, s54
	global_load_lds_dwordx4 v[192:193], off
	v_lshl_add_u64 v[192:193], s[36:37], 0, v[132:133]
	s_mov_b32 m0, s40
	s_nop 0
	global_load_lds_dwordx4 v[192:193], off
	v_lshl_add_u64 v[192:193], s[36:37], 0, v[128:129]
	s_add_i32 m0, s40, 0x2000
	s_nop 0
	global_load_lds_dwordx4 v[192:193], off
	s_waitcnt vmcnt(6)
	s_waitcnt lgkmcnt(0)
	s_barrier
	s_setprio 1
	s_waitcnt lgkmcnt(0)
	v_mfma_f32_16x16x32_bf16 v[60:63], v[148:151], v[180:183], v[60:63]
	v_mfma_f32_16x16x32_bf16 v[56:59], v[156:159], v[180:183], v[56:59]
	v_mfma_f32_16x16x32_bf16 v[52:55], v[148:151], v[188:191], v[52:55]
	v_mfma_f32_16x16x32_bf16 v[48:51], v[156:159], v[188:191], v[48:51]
	v_mfma_f32_16x16x32_bf16 v[40:43], v[148:151], v[200:203], v[40:43]
	v_mfma_f32_16x16x32_bf16 v[32:35], v[156:159], v[200:203], v[32:35]
	v_mfma_f32_16x16x32_bf16 v[24:27], v[148:151], v[208:211], v[24:27]
	v_mfma_f32_16x16x32_bf16 v[16:19], v[156:159], v[208:211], v[16:19]
	v_mfma_f32_16x16x32_bf16 v[60:63], v[152:155], v[184:187], v[60:63]
	v_mfma_f32_16x16x32_bf16 v[56:59], v[160:163], v[184:187], v[56:59]
	v_mfma_f32_16x16x32_bf16 v[52:55], v[152:155], v[196:199], v[52:55]
	v_mfma_f32_16x16x32_bf16 v[48:51], v[160:163], v[196:199], v[48:51]
	v_mfma_f32_16x16x32_bf16 v[40:43], v[152:155], v[204:207], v[40:43]
	v_mfma_f32_16x16x32_bf16 v[32:35], v[160:163], v[204:207], v[32:35]
	v_mfma_f32_16x16x32_bf16 v[24:27], v[152:155], v[212:215], v[24:27]
	v_mfma_f32_16x16x32_bf16 v[16:19], v[160:163], v[212:215], v[16:19]
	s_setprio 0
	s_setprio 1
	v_mfma_f32_16x16x32_bf16 v[44:47], v[164:167], v[180:183], v[44:47]
	v_mfma_f32_16x16x32_bf16 v[36:39], v[172:175], v[180:183], v[36:39]
	v_mfma_f32_16x16x32_bf16 v[28:31], v[164:167], v[188:191], v[28:31]
	v_mfma_f32_16x16x32_bf16 v[20:23], v[172:175], v[188:191], v[20:23]
	v_mfma_f32_16x16x32_bf16 v[12:15], v[164:167], v[200:203], v[12:15]
	v_mfma_f32_16x16x32_bf16 v[8:11], v[172:175], v[200:203], v[8:11]
	v_mfma_f32_16x16x32_bf16 v[4:7], v[164:167], v[208:211], v[4:7]
	v_mfma_f32_16x16x32_bf16 v[0:3], v[172:175], v[208:211], v[0:3]
	v_mfma_f32_16x16x32_bf16 v[44:47], v[168:171], v[184:187], v[44:47]
	v_mfma_f32_16x16x32_bf16 v[36:39], v[176:179], v[184:187], v[36:39]
	v_mfma_f32_16x16x32_bf16 v[28:31], v[168:171], v[196:199], v[28:31]
	v_mfma_f32_16x16x32_bf16 v[20:23], v[176:179], v[196:199], v[20:23]
	v_mfma_f32_16x16x32_bf16 v[12:15], v[168:171], v[204:207], v[12:15]
	v_mfma_f32_16x16x32_bf16 v[8:11], v[176:179], v[204:207], v[8:11]
	v_mfma_f32_16x16x32_bf16 v[4:7], v[168:171], v[212:215], v[4:7]
	v_mfma_f32_16x16x32_bf16 v[0:3], v[176:179], v[212:215], v[0:3]
	s_setprio 0
	s_barrier
	v_lshl_add_u64 v[218:219], v[218:219], 0, s[14:15]
	s_mov_b32 m0, s62
	s_nop 0
	global_load_lds_dwordx4 v[218:219], off
	v_lshl_add_u64 v[220:221], v[220:221], 0, s[14:15]
	s_mov_b32 m0, s63
	s_nop 0
	global_load_lds_dwordx4 v[220:221], off
	s_add_i32 s81, s81, 2
	s_add_u32 s17, s17, 0x100
	s_addc_u32 s27, s27, 0
	s_cmp_gt_u32 s81, 5
	s_mov_b64 s[36:37], s[38:39]
	s_cbranch_scc0 .LBB0_2370
	s_and_b64 vcc, exec, s[18:19]
	s_cbranch_vccz .LBB0_2373
	s_barrier

.LBB0_2396:
	ds_read_b128 v[144:147], v153
	ds_read_b128 v[158:161], v153 offset:1024
	ds_read_b128 v[162:165], v153 offset:2048
	ds_read_b128 v[166:169], v153 offset:3072
	ds_read_b128 v[170:173], v154
	ds_read_b128 v[174:177], v154 offset:1024
	ds_read_b128 v[178:181], v154 offset:2048
	ds_read_b128 v[182:185], v154 offset:3072
	s_add_u32 s36, s34, 0xfffc0080
	s_addc_u32 s37, s35, -1
	s_cmp_eq_u32 s78, 12
	s_cselect_b32 s39, s27, s37
	s_cselect_b32 s38, s71, s36
	s_cselect_b32 s37, s25, s77
	s_cselect_b32 s36, s72, s73
	v_lshl_add_u64 v[148:149], s[34:35], 0, v[136:137]
	s_add_i32 m0, s53, 0xc000
	ds_read_b128 v[186:189], v155
	ds_read_b128 v[190:193], v155 offset:1024
	ds_read_b128 v[196:199], v155 offset:2048
	ds_read_b128 v[200:203], v155 offset:3072
	ds_read_b128 v[204:207], v155 offset:4096
	ds_read_b128 v[208:211], v155 offset:5120
	ds_read_b128 v[212:215], v155 offset:6144
	ds_read_b128 v[216:219], v155 offset:7168
	global_load_lds_dwordx4 v[148:149], off
	v_lshl_add_u64 v[148:149], s[34:35], 0, v[138:139]
	s_add_i32 m0, s53, 0xe000
	s_nop 0
	global_load_lds_dwordx4 v[148:149], off
	s_waitcnt vmcnt(8)
	s_waitcnt lgkmcnt(0)
	s_barrier
	s_setprio 1
	s_waitcnt lgkmcnt(0)
	v_mfma_f32_16x16x32_bf16 v[124:127], v[144:147], v[186:189], v[124:127]
	v_mfma_f32_16x16x32_bf16 v[120:123], v[162:165], v[186:189], v[120:123]
	v_mfma_f32_16x16x32_bf16 v[108:111], v[144:147], v[196:199], v[108:111]
	v_mfma_f32_16x16x32_bf16 v[104:107], v[162:165], v[196:199], v[104:107]
	v_mfma_f32_16x16x32_bf16 v[92:95], v[144:147], v[204:207], v[92:95]
	v_mfma_f32_16x16x32_bf16 v[88:91], v[162:165], v[204:207], v[88:91]
	v_mfma_f32_16x16x32_bf16 v[76:79], v[144:147], v[212:215], v[76:79]
	v_mfma_f32_16x16x32_bf16 v[72:75], v[162:165], v[212:215], v[72:75]
	v_mfma_f32_16x16x32_bf16 v[124:127], v[158:161], v[190:193], v[124:127]
	v_mfma_f32_16x16x32_bf16 v[120:123], v[166:169], v[190:193], v[120:123]
	v_mfma_f32_16x16x32_bf16 v[108:111], v[158:161], v[200:203], v[108:111]
	v_mfma_f32_16x16x32_bf16 v[104:107], v[166:169], v[200:203], v[104:107]
	v_mfma_f32_16x16x32_bf16 v[92:95], v[158:161], v[208:211], v[92:95]
	v_mfma_f32_16x16x32_bf16 v[88:91], v[166:169], v[208:211], v[88:91]
	v_mfma_f32_16x16x32_bf16 v[76:79], v[158:161], v[216:219], v[76:79]
	v_mfma_f32_16x16x32_bf16 v[72:75], v[166:169], v[216:219], v[72:75]
	s_setprio 0
	s_setprio 1
	v_mfma_f32_16x16x32_bf16 v[116:119], v[170:173], v[186:189], v[116:119]
	v_mfma_f32_16x16x32_bf16 v[112:115], v[178:181], v[186:189], v[112:115]
	v_mfma_f32_16x16x32_bf16 v[100:103], v[170:173], v[196:199], v[100:103]
	v_mfma_f32_16x16x32_bf16 v[96:99], v[178:181], v[196:199], v[96:99]
	v_mfma_f32_16x16x32_bf16 v[84:87], v[170:173], v[204:207], v[84:87]
	v_mfma_f32_16x16x32_bf16 v[80:83], v[178:181], v[204:207], v[80:83]
	v_mfma_f32_16x16x32_bf16 v[68:71], v[170:173], v[212:215], v[68:71]
	v_mfma_f32_16x16x32_bf16 v[64:67], v[178:181], v[212:215], v[64:67]
	v_mfma_f32_16x16x32_bf16 v[116:119], v[174:177], v[190:193], v[116:119]
	v_mfma_f32_16x16x32_bf16 v[112:115], v[182:185], v[190:193], v[112:115]
	v_mfma_f32_16x16x32_bf16 v[100:103], v[174:177], v[200:203], v[100:103]
	v_mfma_f32_16x16x32_bf16 v[96:99], v[182:185], v[200:203], v[96:99]
	v_mfma_f32_16x16x32_bf16 v[84:87], v[174:177], v[208:211], v[84:87]
	v_mfma_f32_16x16x32_bf16 v[80:83], v[182:185], v[208:211], v[80:83]
	v_mfma_f32_16x16x32_bf16 v[68:71], v[174:177], v[216:219], v[68:71]
	v_mfma_f32_16x16x32_bf16 v[64:67], v[182:185], v[216:219], v[64:67]
	s_setprio 0
	s_barrier
	s_add_i32 s79, s61, s52
	v_lshl_add_u64 v[148:149], s[36:37], 0, v[130:131]
	s_mov_b32 m0, s79
	ds_read_b128 v[186:189], v155 offset:16384
	ds_read_b128 v[190:193], v155 offset:17408
	ds_read_b128 v[196:199], v155 offset:18432
	ds_read_b128 v[200:203], v155 offset:19456
	ds_read_b128 v[204:207], v155 offset:20480
	ds_read_b128 v[208:211], v155 offset:21504
	ds_read_b128 v[212:215], v155 offset:22528
	ds_read_b128 v[216:219], v155 offset:23552
	global_load_lds_dwordx4 v[148:149], off
	s_add_i32 m0, s79, 0x2000
	s_add_u32 s80, s36, 0x40000
	v_lshl_add_u64 v[220:221], s[36:37], 0, v[134:135]
	s_addc_u32 s81, s37, 0
	s_add_i32 s79, s62, s52
	global_load_lds_dwordx4 v[220:221], off
	v_lshl_add_u64 v[222:223], s[80:81], 0, v[130:131]
	s_mov_b32 m0, s79
	v_lshl_add_u64 v[224:225], s[38:39], 0, v[132:133]
	global_load_lds_dwordx4 v[222:223], off
	v_lshl_add_u64 v[222:223], s[80:81], 0, v[134:135]
	s_add_i32 m0, s79, 0x2000
	s_nop 0
	global_load_lds_dwordx4 v[222:223], off
	v_lshl_add_u64 v[222:223], s[38:39], 0, v[128:129]
	s_waitcnt vmcnt(6)
	s_waitcnt lgkmcnt(0)
	s_barrier
	s_setprio 1
	s_waitcnt lgkmcnt(0)
	v_mfma_f32_16x16x32_bf16 v[60:63], v[144:147], v[186:189], v[60:63]
	v_mfma_f32_16x16x32_bf16 v[56:59], v[162:165], v[186:189], v[56:59]
	v_mfma_f32_16x16x32_bf16 v[44:47], v[144:147], v[196:199], v[44:47]
	v_mfma_f32_16x16x32_bf16 v[40:43], v[162:165], v[196:199], v[40:43]
	v_mfma_f32_16x16x32_bf16 v[28:31], v[144:147], v[204:207], v[28:31]
	v_mfma_f32_16x16x32_bf16 v[24:27], v[162:165], v[204:207], v[24:27]
	v_mfma_f32_16x16x32_bf16 v[12:15], v[144:147], v[212:215], v[12:15]
	v_mfma_f32_16x16x32_bf16 v[8:11], v[162:165], v[212:215], v[8:11]
	v_mfma_f32_16x16x32_bf16 v[60:63], v[158:161], v[190:193], v[60:63]
	v_mfma_f32_16x16x32_bf16 v[56:59], v[166:169], v[190:193], v[56:59]
	v_mfma_f32_16x16x32_bf16 v[44:47], v[158:161], v[200:203], v[44:47]
	v_mfma_f32_16x16x32_bf16 v[40:43], v[166:169], v[200:203], v[40:43]
	v_mfma_f32_16x16x32_bf16 v[28:31], v[158:161], v[208:211], v[28:31]
	v_mfma_f32_16x16x32_bf16 v[24:27], v[166:169], v[208:211], v[24:27]
	v_mfma_f32_16x16x32_bf16 v[12:15], v[158:161], v[216:219], v[12:15]
	v_mfma_f32_16x16x32_bf16 v[8:11], v[166:169], v[216:219], v[8:11]
	s_setprio 0
	s_setprio 1
	v_mfma_f32_16x16x32_bf16 v[52:55], v[170:173], v[186:189], v[52:55]
	v_mfma_f32_16x16x32_bf16 v[48:51], v[178:181], v[186:189], v[48:51]
	v_mfma_f32_16x16x32_bf16 v[36:39], v[170:173], v[196:199], v[36:39]
	v_mfma_f32_16x16x32_bf16 v[32:35], v[178:181], v[196:199], v[32:35]
	v_mfma_f32_16x16x32_bf16 v[20:23], v[170:173], v[204:207], v[20:23]
	v_mfma_f32_16x16x32_bf16 v[16:19], v[178:181], v[204:207], v[16:19]
	v_mfma_f32_16x16x32_bf16 v[4:7], v[170:173], v[212:215], v[4:7]
	v_mfma_f32_16x16x32_bf16 v[0:3], v[178:181], v[212:215], v[0:3]
	v_mfma_f32_16x16x32_bf16 v[52:55], v[174:177], v[190:193], v[52:55]
	v_mfma_f32_16x16x32_bf16 v[48:51], v[182:185], v[190:193], v[48:51]
	v_mfma_f32_16x16x32_bf16 v[36:39], v[174:177], v[200:203], v[36:39]
	v_mfma_f32_16x16x32_bf16 v[32:35], v[182:185], v[200:203], v[32:35]
	v_mfma_f32_16x16x32_bf16 v[20:23], v[174:177], v[208:211], v[20:23]
	v_mfma_f32_16x16x32_bf16 v[16:19], v[182:185], v[208:211], v[16:19]
	v_mfma_f32_16x16x32_bf16 v[4:7], v[174:177], v[216:219], v[4:7]
	v_mfma_f32_16x16x32_bf16 v[0:3], v[182:185], v[216:219], v[0:3]
	s_setprio 0
	s_barrier
	s_add_i32 s79, 0, 0x18000
	v_add_u32_e32 v157, s79, v151
	s_add_i32 s80, 0, 0x1c000
	ds_read_b128 v[144:147], v157
	ds_read_b128 v[158:161], v157 offset:1024
	ds_read_b128 v[162:165], v157 offset:2048
	ds_read_b128 v[166:169], v157 offset:3072
	v_add_u32_e32 v157, s80, v151
	ds_read_b128 v[170:173], v157
	ds_read_b128 v[174:177], v157 offset:1024
	ds_read_b128 v[178:181], v157 offset:2048
	ds_read_b128 v[182:185], v157 offset:3072
	s_add_u32 s38, s38, 0x40000
	s_addc_u32 s39, s39, 0
	v_lshl_add_u64 v[226:227], s[38:39], 0, v[128:129]
	ds_read_b128 v[186:189], v155 offset:32768
	ds_read_b128 v[190:193], v155 offset:33792
	ds_read_b128 v[196:199], v155 offset:34816
	ds_read_b128 v[200:203], v155 offset:35840
	ds_read_b128 v[204:207], v155 offset:36864
	ds_read_b128 v[208:211], v155 offset:37888
	ds_read_b128 v[212:215], v155 offset:38912
	ds_read_b128 v[216:219], v155 offset:39936
	s_mov_b32 m0, s53
	s_nop 0
	global_load_lds_dwordx4 v[222:223], off
	s_mov_b32 m0, s54
	s_nop 0
	global_load_lds_dwordx4 v[224:225], off
	s_mov_b32 m0, s55
	s_nop 0
	global_load_lds_dwordx4 v[226:227], off
	v_lshl_add_u64 v[226:227], s[38:39], 0, v[132:133]
	s_mov_b32 m0, s56
	s_nop 0
	global_load_lds_dwordx4 v[226:227], off
	s_waitcnt vmcnt(8)
	s_waitcnt lgkmcnt(0)
	s_barrier
	s_setprio 1
	s_waitcnt lgkmcnt(0)
	v_mfma_f32_16x16x32_bf16 v[124:127], v[144:147], v[186:189], v[124:127]
	v_mfma_f32_16x16x32_bf16 v[120:123], v[162:165], v[186:189], v[120:123]
	v_mfma_f32_16x16x32_bf16 v[108:111], v[144:147], v[196:199], v[108:111]
	v_mfma_f32_16x16x32_bf16 v[104:107], v[162:165], v[196:199], v[104:107]
	v_mfma_f32_16x16x32_bf16 v[92:95], v[144:147], v[204:207], v[92:95]
	v_mfma_f32_16x16x32_bf16 v[88:91], v[162:165], v[204:207], v[88:91]
	v_mfma_f32_16x16x32_bf16 v[76:79], v[144:147], v[212:215], v[76:79]
	v_mfma_f32_16x16x32_bf16 v[72:75], v[162:165], v[212:215], v[72:75]
	v_mfma_f32_16x16x32_bf16 v[124:127], v[158:161], v[190:193], v[124:127]
	v_mfma_f32_16x16x32_bf16 v[120:123], v[166:169], v[190:193], v[120:123]
	v_mfma_f32_16x16x32_bf16 v[108:111], v[158:161], v[200:203], v[108:111]
	v_mfma_f32_16x16x32_bf16 v[104:107], v[166:169], v[200:203], v[104:107]
	v_mfma_f32_16x16x32_bf16 v[92:95], v[158:161], v[208:211], v[92:95]
	v_mfma_f32_16x16x32_bf16 v[88:91], v[166:169], v[208:211], v[88:91]
	v_mfma_f32_16x16x32_bf16 v[76:79], v[158:161], v[216:219], v[76:79]
	v_mfma_f32_16x16x32_bf16 v[72:75], v[166:169], v[216:219], v[72:75]
	s_setprio 0
	s_setprio 1
	v_mfma_f32_16x16x32_bf16 v[116:119], v[170:173], v[186:189], v[116:119]
	v_mfma_f32_16x16x32_bf16 v[112:115], v[178:181], v[186:189], v[112:115]
	v_mfma_f32_16x16x32_bf16 v[100:103], v[170:173], v[196:199], v[100:103]
	v_mfma_f32_16x16x32_bf16 v[96:99], v[178:181], v[196:199], v[96:99]
	v_mfma_f32_16x16x32_bf16 v[84:87], v[170:173], v[204:207], v[84:87]
	v_mfma_f32_16x16x32_bf16 v[80:83], v[178:181], v[204:207], v[80:83]
	v_mfma_f32_16x16x32_bf16 v[68:71], v[170:173], v[212:215], v[68:71]
	v_mfma_f32_16x16x32_bf16 v[64:67], v[178:181], v[212:215], v[64:67]
	v_mfma_f32_16x16x32_bf16 v[116:119], v[174:177], v[190:193], v[116:119]
	v_mfma_f32_16x16x32_bf16 v[112:115], v[182:185], v[190:193], v[112:115]
	v_mfma_f32_16x16x32_bf16 v[100:103], v[174:177], v[200:203], v[100:103]
	v_mfma_f32_16x16x32_bf16 v[96:99], v[182:185], v[200:203], v[96:99]
	v_mfma_f32_16x16x32_bf16 v[84:87], v[174:177], v[208:211], v[84:87]
	v_mfma_f32_16x16x32_bf16 v[80:83], v[182:185], v[208:211], v[80:83]
	v_mfma_f32_16x16x32_bf16 v[68:71], v[174:177], v[216:219], v[68:71]
	v_mfma_f32_16x16x32_bf16 v[64:67], v[182:185], v[216:219], v[64:67]
	s_setprio 0
	s_barrier
	s_add_i32 s38, s79, s52
	v_lshl_add_u64 v[148:149], v[148:149], 0, s[20:21]
	s_mov_b32 m0, s38
	ds_read_b128 v[186:189], v155 offset:49152
	ds_read_b128 v[190:193], v155 offset:50176
	ds_read_b128 v[196:199], v155 offset:51200
	ds_read_b128 v[200:203], v155 offset:52224
	ds_read_b128 v[204:207], v155 offset:53248
	ds_read_b128 v[208:211], v155 offset:54272
	ds_read_b128 v[212:215], v155 offset:55296
	ds_read_b128 v[216:219], v155 offset:56320
	global_load_lds_dwordx4 v[148:149], off
	s_add_i32 m0, s38, 0x2000
	s_add_u32 s36, s36, 0x40080
	v_lshl_add_u64 v[148:149], v[220:221], 0, s[20:21]
	s_addc_u32 s37, s37, 0
	s_add_i32 s38, s80, s52
	global_load_lds_dwordx4 v[148:149], off
	v_lshl_add_u64 v[148:149], s[36:37], 0, v[130:131]
	s_mov_b32 m0, s38
	s_nop 0
	global_load_lds_dwordx4 v[148:149], off
	v_lshl_add_u64 v[148:149], s[36:37], 0, v[134:135]
	s_add_i32 m0, s38, 0x2000
	s_nop 0
	global_load_lds_dwordx4 v[148:149], off
	s_waitcnt vmcnt(6)
	s_waitcnt lgkmcnt(0)
	s_barrier
	s_setprio 1
	s_waitcnt lgkmcnt(0)
	v_mfma_f32_16x16x32_bf16 v[60:63], v[144:147], v[186:189], v[60:63]
	v_mfma_f32_16x16x32_bf16 v[56:59], v[162:165], v[186:189], v[56:59]
	v_mfma_f32_16x16x32_bf16 v[44:47], v[144:147], v[196:199], v[44:47]
	v_mfma_f32_16x16x32_bf16 v[40:43], v[162:165], v[196:199], v[40:43]
	v_mfma_f32_16x16x32_bf16 v[28:31], v[144:147], v[204:207], v[28:31]
	v_mfma_f32_16x16x32_bf16 v[24:27], v[162:165], v[204:207], v[24:27]
	v_mfma_f32_16x16x32_bf16 v[12:15], v[144:147], v[212:215], v[12:15]
	v_mfma_f32_16x16x32_bf16 v[8:11], v[162:165], v[212:215], v[8:11]
	v_mfma_f32_16x16x32_bf16 v[60:63], v[158:161], v[190:193], v[60:63]
	v_mfma_f32_16x16x32_bf16 v[56:59], v[166:169], v[190:193], v[56:59]
	v_mfma_f32_16x16x32_bf16 v[44:47], v[158:161], v[200:203], v[44:47]
	v_mfma_f32_16x16x32_bf16 v[40:43], v[166:169], v[200:203], v[40:43]
	v_mfma_f32_16x16x32_bf16 v[28:31], v[158:161], v[208:211], v[28:31]
	v_mfma_f32_16x16x32_bf16 v[24:27], v[166:169], v[208:211], v[24:27]
	v_mfma_f32_16x16x32_bf16 v[12:15], v[158:161], v[216:219], v[12:15]
	v_mfma_f32_16x16x32_bf16 v[8:11], v[166:169], v[216:219], v[8:11]
	s_setprio 0
	s_setprio 1
	v_mfma_f32_16x16x32_bf16 v[52:55], v[170:173], v[186:189], v[52:55]
	v_mfma_f32_16x16x32_bf16 v[48:51], v[178:181], v[186:189], v[48:51]
	v_mfma_f32_16x16x32_bf16 v[36:39], v[170:173], v[196:199], v[36:39]
	v_mfma_f32_16x16x32_bf16 v[32:35], v[178:181], v[196:199], v[32:35]
	v_mfma_f32_16x16x32_bf16 v[20:23], v[170:173], v[204:207], v[20:23]
	v_mfma_f32_16x16x32_bf16 v[16:19], v[178:181], v[204:207], v[16:19]
	v_mfma_f32_16x16x32_bf16 v[4:7], v[170:173], v[212:215], v[4:7]
	v_mfma_f32_16x16x32_bf16 v[0:3], v[178:181], v[212:215], v[0:3]
	v_mfma_f32_16x16x32_bf16 v[52:55], v[174:177], v[190:193], v[52:55]
	v_mfma_f32_16x16x32_bf16 v[48:51], v[182:185], v[190:193], v[48:51]
	v_mfma_f32_16x16x32_bf16 v[36:39], v[174:177], v[200:203], v[36:39]
	v_mfma_f32_16x16x32_bf16 v[32:35], v[182:185], v[200:203], v[32:35]
	v_mfma_f32_16x16x32_bf16 v[20:23], v[174:177], v[208:211], v[20:23]
	v_mfma_f32_16x16x32_bf16 v[16:19], v[182:185], v[208:211], v[16:19]
	v_mfma_f32_16x16x32_bf16 v[4:7], v[174:177], v[216:219], v[4:7]
	v_mfma_f32_16x16x32_bf16 v[0:3], v[182:185], v[216:219], v[0:3]
	s_setprio 0
	s_barrier
	v_lshl_add_u64 v[222:223], v[222:223], 0, s[20:21]
	s_mov_b32 m0, s58
	s_nop 0
	global_load_lds_dwordx4 v[222:223], off
	v_lshl_add_u64 v[224:225], v[224:225], 0, s[20:21]
	s_mov_b32 m0, s59
	s_nop 0
	global_load_lds_dwordx4 v[224:225], off
	s_add_i32 s78, s78, 2
	s_add_u32 s34, s34, 0x100
	s_addc_u32 s35, s35, 0
	s_add_u32 s73, s73, 0x100
	s_addc_u32 s77, s77, 0
	s_cmp_gt_u32 s78, 13
	s_cbranch_scc0 .LBB0_2396
	s_and_b64 vcc, exec, s[22:23]
	s_cbranch_vccz .LBB0_2399
	s_barrier

.LBB0_2533:
	ds_read_b128 v[152:155], v148
	ds_read_b128 v[156:159], v148 offset:1024
	ds_read_b128 v[160:163], v148 offset:2048
	ds_read_b128 v[164:167], v148 offset:3072
	ds_read_b128 v[168:171], v149
	ds_read_b128 v[172:175], v149 offset:1024
	ds_read_b128 v[176:179], v149 offset:2048
	ds_read_b128 v[180:183], v149 offset:3072
	s_add_u32 s26, s24, 0x100
	s_addc_u32 s27, s25, 0
	s_cmp_eq_u32 s62, 8
	s_cselect_b32 s31, s21, s27
	s_cselect_b32 s30, s20, s26
	s_cselect_b32 s29, s23, s61
	s_cselect_b32 s28, s22, s60
	s_mov_b32 m0, s53
	v_lshl_add_u64 v[192:193], s[24:25], 0, v[138:139]
	ds_read_b128 v[184:187], v150
	ds_read_b128 v[188:191], v150 offset:1024
	ds_read_b128 v[196:199], v150 offset:2048
	ds_read_b128 v[200:203], v150 offset:3072
	ds_read_b128 v[204:207], v150 offset:4096
	ds_read_b128 v[208:211], v150 offset:5120
	ds_read_b128 v[212:215], v150 offset:6144
	ds_read_b128 v[216:219], v150 offset:7168
	global_load_lds_dwordx4 v[192:193], off
	v_lshl_add_u64 v[192:193], s[24:25], 0, v[140:141]
	s_add_i32 m0, s40, 0xe000
	s_nop 0
	global_load_lds_dwordx4 v[192:193], off
	s_waitcnt vmcnt(8)
	s_waitcnt lgkmcnt(0)
	s_barrier
	s_setprio 1
	s_waitcnt lgkmcnt(0)
	v_mfma_f32_16x16x32_bf16 v[124:127], v[152:155], v[184:187], v[124:127]
	v_mfma_f32_16x16x32_bf16 v[120:123], v[160:163], v[184:187], v[120:123]
	v_mfma_f32_16x16x32_bf16 v[108:111], v[152:155], v[196:199], v[108:111]
	v_mfma_f32_16x16x32_bf16 v[104:107], v[160:163], v[196:199], v[104:107]
	v_mfma_f32_16x16x32_bf16 v[92:95], v[152:155], v[204:207], v[92:95]
	v_mfma_f32_16x16x32_bf16 v[88:91], v[160:163], v[204:207], v[88:91]
	v_mfma_f32_16x16x32_bf16 v[76:79], v[152:155], v[212:215], v[76:79]
	v_mfma_f32_16x16x32_bf16 v[72:75], v[160:163], v[212:215], v[72:75]
	v_mfma_f32_16x16x32_bf16 v[124:127], v[156:159], v[188:191], v[124:127]
	v_mfma_f32_16x16x32_bf16 v[120:123], v[164:167], v[188:191], v[120:123]
	v_mfma_f32_16x16x32_bf16 v[108:111], v[156:159], v[200:203], v[108:111]
	v_mfma_f32_16x16x32_bf16 v[104:107], v[164:167], v[200:203], v[104:107]
	v_mfma_f32_16x16x32_bf16 v[92:95], v[156:159], v[208:211], v[92:95]
	v_mfma_f32_16x16x32_bf16 v[88:91], v[164:167], v[208:211], v[88:91]
	v_mfma_f32_16x16x32_bf16 v[76:79], v[156:159], v[216:219], v[76:79]
	v_mfma_f32_16x16x32_bf16 v[72:75], v[164:167], v[216:219], v[72:75]
	s_setprio 0
	s_setprio 1
	v_mfma_f32_16x16x32_bf16 v[116:119], v[168:171], v[184:187], v[116:119]
	v_mfma_f32_16x16x32_bf16 v[112:115], v[176:179], v[184:187], v[112:115]
	v_mfma_f32_16x16x32_bf16 v[100:103], v[168:171], v[196:199], v[100:103]
	v_mfma_f32_16x16x32_bf16 v[96:99], v[176:179], v[196:199], v[96:99]
	v_mfma_f32_16x16x32_bf16 v[84:87], v[168:171], v[204:207], v[84:87]
	v_mfma_f32_16x16x32_bf16 v[80:83], v[176:179], v[204:207], v[80:83]
	v_mfma_f32_16x16x32_bf16 v[68:71], v[168:171], v[212:215], v[68:71]
	v_mfma_f32_16x16x32_bf16 v[64:67], v[176:179], v[212:215], v[64:67]
	v_mfma_f32_16x16x32_bf16 v[116:119], v[172:175], v[188:191], v[116:119]
	v_mfma_f32_16x16x32_bf16 v[112:115], v[180:183], v[188:191], v[112:115]
	v_mfma_f32_16x16x32_bf16 v[100:103], v[172:175], v[200:203], v[100:103]
	v_mfma_f32_16x16x32_bf16 v[96:99], v[180:183], v[200:203], v[96:99]
	v_mfma_f32_16x16x32_bf16 v[84:87], v[172:175], v[208:211], v[84:87]
	v_mfma_f32_16x16x32_bf16 v[80:83], v[180:183], v[208:211], v[80:83]
	v_mfma_f32_16x16x32_bf16 v[68:71], v[172:175], v[216:219], v[68:71]
	v_mfma_f32_16x16x32_bf16 v[64:67], v[180:183], v[216:219], v[64:67]
	s_setprio 0
	s_barrier
	s_add_i32 s24, s51, s39
	v_lshl_add_u64 v[192:193], s[28:29], 0, v[132:133]
	s_mov_b32 m0, s24
	ds_read_b128 v[184:187], v150 offset:16384
	ds_read_b128 v[188:191], v150 offset:17408
	ds_read_b128 v[196:199], v150 offset:18432
	ds_read_b128 v[200:203], v150 offset:19456
	ds_read_b128 v[204:207], v150 offset:20480
	ds_read_b128 v[208:211], v150 offset:21504
	ds_read_b128 v[212:215], v150 offset:22528
	ds_read_b128 v[216:219], v150 offset:23552
	global_load_lds_dwordx4 v[192:193], off
	s_add_i32 m0, s24, 0x2000
	s_add_u32 s24, s28, 0x30000
	v_lshl_add_u64 v[220:221], s[28:29], 0, v[128:129]
	s_addc_u32 s25, s29, 0
	s_add_i32 s63, s52, s39
	global_load_lds_dwordx4 v[220:221], off
	v_lshl_add_u64 v[222:223], s[24:25], 0, v[132:133]
	s_mov_b32 m0, s63
	v_lshl_add_u64 v[224:225], s[30:31], 0, v[130:131]
	global_load_lds_dwordx4 v[222:223], off
	v_lshl_add_u64 v[222:223], s[24:25], 0, v[128:129]
	s_add_i32 m0, s63, 0x2000
	s_nop 0
	global_load_lds_dwordx4 v[222:223], off
	v_lshl_add_u64 v[222:223], s[30:31], 0, v[134:135]
	s_waitcnt vmcnt(6)
	s_waitcnt lgkmcnt(0)
	s_barrier
	s_setprio 1
	s_waitcnt lgkmcnt(0)
	v_mfma_f32_16x16x32_bf16 v[60:63], v[152:155], v[184:187], v[60:63]
	v_mfma_f32_16x16x32_bf16 v[56:59], v[160:163], v[184:187], v[56:59]
	v_mfma_f32_16x16x32_bf16 v[44:47], v[152:155], v[196:199], v[44:47]
	v_mfma_f32_16x16x32_bf16 v[40:43], v[160:163], v[196:199], v[40:43]
	v_mfma_f32_16x16x32_bf16 v[28:31], v[152:155], v[204:207], v[28:31]
	v_mfma_f32_16x16x32_bf16 v[24:27], v[160:163], v[204:207], v[24:27]
	v_mfma_f32_16x16x32_bf16 v[12:15], v[152:155], v[212:215], v[12:15]
	v_mfma_f32_16x16x32_bf16 v[8:11], v[160:163], v[212:215], v[8:11]
	v_mfma_f32_16x16x32_bf16 v[60:63], v[156:159], v[188:191], v[60:63]
	v_mfma_f32_16x16x32_bf16 v[56:59], v[164:167], v[188:191], v[56:59]
	v_mfma_f32_16x16x32_bf16 v[44:47], v[156:159], v[200:203], v[44:47]
	v_mfma_f32_16x16x32_bf16 v[40:43], v[164:167], v[200:203], v[40:43]
	v_mfma_f32_16x16x32_bf16 v[28:31], v[156:159], v[208:211], v[28:31]
	v_mfma_f32_16x16x32_bf16 v[24:27], v[164:167], v[208:211], v[24:27]
	v_mfma_f32_16x16x32_bf16 v[12:15], v[156:159], v[216:219], v[12:15]
	v_mfma_f32_16x16x32_bf16 v[8:11], v[164:167], v[216:219], v[8:11]
	s_setprio 0
	s_setprio 1
	v_mfma_f32_16x16x32_bf16 v[52:55], v[168:171], v[184:187], v[52:55]
	v_mfma_f32_16x16x32_bf16 v[48:51], v[176:179], v[184:187], v[48:51]
	v_mfma_f32_16x16x32_bf16 v[36:39], v[168:171], v[196:199], v[36:39]
	v_mfma_f32_16x16x32_bf16 v[32:35], v[176:179], v[196:199], v[32:35]
	v_mfma_f32_16x16x32_bf16 v[20:23], v[168:171], v[204:207], v[20:23]
	v_mfma_f32_16x16x32_bf16 v[16:19], v[176:179], v[204:207], v[16:19]
	v_mfma_f32_16x16x32_bf16 v[4:7], v[168:171], v[212:215], v[4:7]
	v_mfma_f32_16x16x32_bf16 v[0:3], v[176:179], v[212:215], v[0:3]
	v_mfma_f32_16x16x32_bf16 v[52:55], v[172:175], v[188:191], v[52:55]
	v_mfma_f32_16x16x32_bf16 v[48:51], v[180:183], v[188:191], v[48:51]
	v_mfma_f32_16x16x32_bf16 v[36:39], v[172:175], v[200:203], v[36:39]
	v_mfma_f32_16x16x32_bf16 v[32:35], v[180:183], v[200:203], v[32:35]
	v_mfma_f32_16x16x32_bf16 v[20:23], v[172:175], v[208:211], v[20:23]
	v_mfma_f32_16x16x32_bf16 v[16:19], v[180:183], v[208:211], v[16:19]
	v_mfma_f32_16x16x32_bf16 v[4:7], v[172:175], v[216:219], v[4:7]
	v_mfma_f32_16x16x32_bf16 v[0:3], v[180:183], v[216:219], v[0:3]
	s_setprio 0
	s_barrier
	s_add_i32 s63, 0, 0x18000
	v_add_u32_e32 v151, s63, v142
	s_add_i32 s70, 0, 0x1c000
	ds_read_b128 v[152:155], v151
	ds_read_b128 v[156:159], v151 offset:1024
	ds_read_b128 v[160:163], v151 offset:2048
	ds_read_b128 v[164:167], v151 offset:3072
	v_add_u32_e32 v151, s70, v142
	ds_read_b128 v[168:171], v151
	ds_read_b128 v[172:175], v151 offset:1024
	ds_read_b128 v[176:179], v151 offset:2048
	ds_read_b128 v[180:183], v151 offset:3072
	s_add_u32 s24, s30, 0x30000
	s_addc_u32 s25, s31, 0
	v_lshl_add_u64 v[226:227], s[24:25], 0, v[134:135]
	ds_read_b128 v[184:187], v150 offset:32768
	ds_read_b128 v[188:191], v150 offset:33792
	ds_read_b128 v[196:199], v150 offset:34816
	ds_read_b128 v[200:203], v150 offset:35840
	ds_read_b128 v[204:207], v150 offset:36864
	ds_read_b128 v[208:211], v150 offset:37888
	ds_read_b128 v[212:215], v150 offset:38912
	ds_read_b128 v[216:219], v150 offset:39936
	s_mov_b32 m0, s40
	s_nop 0
	global_load_lds_dwordx4 v[222:223], off
	s_mov_b32 m0, s41
	s_nop 0
	global_load_lds_dwordx4 v[224:225], off
	s_mov_b32 m0, s42
	s_nop 0
	global_load_lds_dwordx4 v[226:227], off
	v_lshl_add_u64 v[226:227], s[24:25], 0, v[130:131]
	s_mov_b32 m0, s43
	s_nop 0
	global_load_lds_dwordx4 v[226:227], off
	s_waitcnt vmcnt(8)
	s_waitcnt lgkmcnt(0)
	s_barrier
	s_setprio 1
	s_waitcnt lgkmcnt(0)
	v_mfma_f32_16x16x32_bf16 v[124:127], v[152:155], v[184:187], v[124:127]
	v_mfma_f32_16x16x32_bf16 v[120:123], v[160:163], v[184:187], v[120:123]
	v_mfma_f32_16x16x32_bf16 v[108:111], v[152:155], v[196:199], v[108:111]
	v_mfma_f32_16x16x32_bf16 v[104:107], v[160:163], v[196:199], v[104:107]
	v_mfma_f32_16x16x32_bf16 v[92:95], v[152:155], v[204:207], v[92:95]
	v_mfma_f32_16x16x32_bf16 v[88:91], v[160:163], v[204:207], v[88:91]
	v_mfma_f32_16x16x32_bf16 v[76:79], v[152:155], v[212:215], v[76:79]
	v_mfma_f32_16x16x32_bf16 v[72:75], v[160:163], v[212:215], v[72:75]
	v_mfma_f32_16x16x32_bf16 v[124:127], v[156:159], v[188:191], v[124:127]
	v_mfma_f32_16x16x32_bf16 v[120:123], v[164:167], v[188:191], v[120:123]
	v_mfma_f32_16x16x32_bf16 v[108:111], v[156:159], v[200:203], v[108:111]
	v_mfma_f32_16x16x32_bf16 v[104:107], v[164:167], v[200:203], v[104:107]
	v_mfma_f32_16x16x32_bf16 v[92:95], v[156:159], v[208:211], v[92:95]
	v_mfma_f32_16x16x32_bf16 v[88:91], v[164:167], v[208:211], v[88:91]
	v_mfma_f32_16x16x32_bf16 v[76:79], v[156:159], v[216:219], v[76:79]
	v_mfma_f32_16x16x32_bf16 v[72:75], v[164:167], v[216:219], v[72:75]
	s_setprio 0
	s_setprio 1
	v_mfma_f32_16x16x32_bf16 v[116:119], v[168:171], v[184:187], v[116:119]
	v_mfma_f32_16x16x32_bf16 v[112:115], v[176:179], v[184:187], v[112:115]
	v_mfma_f32_16x16x32_bf16 v[100:103], v[168:171], v[196:199], v[100:103]
	v_mfma_f32_16x16x32_bf16 v[96:99], v[176:179], v[196:199], v[96:99]
	v_mfma_f32_16x16x32_bf16 v[84:87], v[168:171], v[204:207], v[84:87]
	v_mfma_f32_16x16x32_bf16 v[80:83], v[176:179], v[204:207], v[80:83]
	v_mfma_f32_16x16x32_bf16 v[68:71], v[168:171], v[212:215], v[68:71]
	v_mfma_f32_16x16x32_bf16 v[64:67], v[176:179], v[212:215], v[64:67]
	v_mfma_f32_16x16x32_bf16 v[116:119], v[172:175], v[188:191], v[116:119]
	v_mfma_f32_16x16x32_bf16 v[112:115], v[180:183], v[188:191], v[112:115]
	v_mfma_f32_16x16x32_bf16 v[100:103], v[172:175], v[200:203], v[100:103]
	v_mfma_f32_16x16x32_bf16 v[96:99], v[180:183], v[200:203], v[96:99]
	v_mfma_f32_16x16x32_bf16 v[84:87], v[172:175], v[208:211], v[84:87]
	v_mfma_f32_16x16x32_bf16 v[80:83], v[180:183], v[208:211], v[80:83]
	v_mfma_f32_16x16x32_bf16 v[68:71], v[172:175], v[216:219], v[68:71]
	v_mfma_f32_16x16x32_bf16 v[64:67], v[180:183], v[216:219], v[64:67]
	s_setprio 0
	s_barrier
	s_add_i32 s24, s63, s39
	v_lshl_add_u64 v[192:193], v[192:193], 0, s[16:17]
	s_mov_b32 m0, s24
	ds_read_b128 v[184:187], v150 offset:49152
	ds_read_b128 v[188:191], v150 offset:50176
	ds_read_b128 v[196:199], v150 offset:51200
	ds_read_b128 v[200:203], v150 offset:52224
	ds_read_b128 v[204:207], v150 offset:53248
	ds_read_b128 v[208:211], v150 offset:54272
	ds_read_b128 v[212:215], v150 offset:55296
	ds_read_b128 v[216:219], v150 offset:56320
	global_load_lds_dwordx4 v[192:193], off
	s_add_i32 m0, s24, 0x2000
	s_add_u32 s24, s28, 0x30080
	v_lshl_add_u64 v[192:193], v[220:221], 0, s[16:17]
	s_addc_u32 s25, s29, 0
	s_add_i32 s28, s70, s39
	global_load_lds_dwordx4 v[192:193], off
	v_lshl_add_u64 v[192:193], s[24:25], 0, v[132:133]
	s_mov_b32 m0, s28
	s_nop 0
	global_load_lds_dwordx4 v[192:193], off
	v_lshl_add_u64 v[192:193], s[24:25], 0, v[128:129]
	s_add_i32 m0, s28, 0x2000
	s_nop 0
	global_load_lds_dwordx4 v[192:193], off
	s_waitcnt vmcnt(6)
	s_waitcnt lgkmcnt(0)
	s_barrier
	s_setprio 1
	s_waitcnt lgkmcnt(0)
	v_mfma_f32_16x16x32_bf16 v[60:63], v[152:155], v[184:187], v[60:63]
	v_mfma_f32_16x16x32_bf16 v[56:59], v[160:163], v[184:187], v[56:59]
	v_mfma_f32_16x16x32_bf16 v[44:47], v[152:155], v[196:199], v[44:47]
	v_mfma_f32_16x16x32_bf16 v[40:43], v[160:163], v[196:199], v[40:43]
	v_mfma_f32_16x16x32_bf16 v[28:31], v[152:155], v[204:207], v[28:31]
	v_mfma_f32_16x16x32_bf16 v[24:27], v[160:163], v[204:207], v[24:27]
	v_mfma_f32_16x16x32_bf16 v[12:15], v[152:155], v[212:215], v[12:15]
	v_mfma_f32_16x16x32_bf16 v[8:11], v[160:163], v[212:215], v[8:11]
	v_mfma_f32_16x16x32_bf16 v[60:63], v[156:159], v[188:191], v[60:63]
	v_mfma_f32_16x16x32_bf16 v[56:59], v[164:167], v[188:191], v[56:59]
	v_mfma_f32_16x16x32_bf16 v[44:47], v[156:159], v[200:203], v[44:47]
	v_mfma_f32_16x16x32_bf16 v[40:43], v[164:167], v[200:203], v[40:43]
	v_mfma_f32_16x16x32_bf16 v[28:31], v[156:159], v[208:211], v[28:31]
	v_mfma_f32_16x16x32_bf16 v[24:27], v[164:167], v[208:211], v[24:27]
	v_mfma_f32_16x16x32_bf16 v[12:15], v[156:159], v[216:219], v[12:15]
	v_mfma_f32_16x16x32_bf16 v[8:11], v[164:167], v[216:219], v[8:11]
	s_setprio 0
	s_setprio 1
	v_mfma_f32_16x16x32_bf16 v[52:55], v[168:171], v[184:187], v[52:55]
	v_mfma_f32_16x16x32_bf16 v[48:51], v[176:179], v[184:187], v[48:51]
	v_mfma_f32_16x16x32_bf16 v[36:39], v[168:171], v[196:199], v[36:39]
	v_mfma_f32_16x16x32_bf16 v[32:35], v[176:179], v[196:199], v[32:35]
	v_mfma_f32_16x16x32_bf16 v[20:23], v[168:171], v[204:207], v[20:23]
	v_mfma_f32_16x16x32_bf16 v[16:19], v[176:179], v[204:207], v[16:19]
	v_mfma_f32_16x16x32_bf16 v[4:7], v[168:171], v[212:215], v[4:7]
	v_mfma_f32_16x16x32_bf16 v[0:3], v[176:179], v[212:215], v[0:3]
	v_mfma_f32_16x16x32_bf16 v[52:55], v[172:175], v[188:191], v[52:55]
	v_mfma_f32_16x16x32_bf16 v[48:51], v[180:183], v[188:191], v[48:51]
	v_mfma_f32_16x16x32_bf16 v[36:39], v[172:175], v[200:203], v[36:39]
	v_mfma_f32_16x16x32_bf16 v[32:35], v[180:183], v[200:203], v[32:35]
	v_mfma_f32_16x16x32_bf16 v[20:23], v[172:175], v[208:211], v[20:23]
	v_mfma_f32_16x16x32_bf16 v[16:19], v[180:183], v[208:211], v[16:19]
	v_mfma_f32_16x16x32_bf16 v[4:7], v[172:175], v[216:219], v[4:7]
	v_mfma_f32_16x16x32_bf16 v[0:3], v[180:183], v[216:219], v[0:3]
	s_setprio 0
	s_barrier
	v_lshl_add_u64 v[222:223], v[222:223], 0, s[16:17]
	s_mov_b32 m0, s45
	s_nop 0
	global_load_lds_dwordx4 v[222:223], off
	v_lshl_add_u64 v[224:225], v[224:225], 0, s[16:17]
	s_mov_b32 m0, s48
	s_nop 0
	global_load_lds_dwordx4 v[224:225], off
	s_add_i32 s62, s62, 2
	s_add_u32 s60, s60, 0x100
	s_addc_u32 s61, s61, 0
	s_cmp_gt_u32 s62, 9
	s_mov_b64 s[24:25], s[26:27]
	s_cbranch_scc0 .LBB0_2533
	s_and_b64 vcc, exec, s[18:19]
	s_cbranch_vccz .LBB0_2536
	s_barrier

.LBB0_2557:
	ds_read_b128 v[144:147], v153
	ds_read_b128 v[158:161], v153 offset:1024
	ds_read_b128 v[162:165], v153 offset:2048
	ds_read_b128 v[166:169], v153 offset:3072
	ds_read_b128 v[170:173], v154
	ds_read_b128 v[174:177], v154 offset:1024
	ds_read_b128 v[178:181], v154 offset:2048
	ds_read_b128 v[182:185], v154 offset:3072
	s_add_u32 s36, s34, 0xfffc0080
	s_addc_u32 s37, s35, -1
	s_cmp_eq_u32 s73, 12
	s_cselect_b32 s39, s27, s37
	s_cselect_b32 s38, s63, s36
	s_cselect_b32 s37, s25, s72
	s_cselect_b32 s36, s70, s71
	v_lshl_add_u64 v[148:149], s[34:35], 0, v[136:137]
	s_add_i32 m0, s51, 0xc000
	ds_read_b128 v[186:189], v155
	ds_read_b128 v[190:193], v155 offset:1024
	ds_read_b128 v[196:199], v155 offset:2048
	ds_read_b128 v[200:203], v155 offset:3072
	ds_read_b128 v[204:207], v155 offset:4096
	ds_read_b128 v[208:211], v155 offset:5120
	ds_read_b128 v[212:215], v155 offset:6144
	ds_read_b128 v[216:219], v155 offset:7168
	global_load_lds_dwordx4 v[148:149], off
	v_lshl_add_u64 v[148:149], s[34:35], 0, v[138:139]
	s_add_i32 m0, s51, 0xe000
	s_nop 0
	global_load_lds_dwordx4 v[148:149], off
	s_waitcnt vmcnt(8)
	s_waitcnt lgkmcnt(0)
	s_barrier
	s_setprio 1
	s_waitcnt lgkmcnt(0)
	v_mfma_f32_16x16x32_bf16 v[124:127], v[144:147], v[186:189], v[124:127]
	v_mfma_f32_16x16x32_bf16 v[120:123], v[162:165], v[186:189], v[120:123]
	v_mfma_f32_16x16x32_bf16 v[108:111], v[144:147], v[196:199], v[108:111]
	v_mfma_f32_16x16x32_bf16 v[104:107], v[162:165], v[196:199], v[104:107]
	v_mfma_f32_16x16x32_bf16 v[92:95], v[144:147], v[204:207], v[92:95]
	v_mfma_f32_16x16x32_bf16 v[88:91], v[162:165], v[204:207], v[88:91]
	v_mfma_f32_16x16x32_bf16 v[76:79], v[144:147], v[212:215], v[76:79]
	v_mfma_f32_16x16x32_bf16 v[72:75], v[162:165], v[212:215], v[72:75]
	v_mfma_f32_16x16x32_bf16 v[124:127], v[158:161], v[190:193], v[124:127]
	v_mfma_f32_16x16x32_bf16 v[120:123], v[166:169], v[190:193], v[120:123]
	v_mfma_f32_16x16x32_bf16 v[108:111], v[158:161], v[200:203], v[108:111]
	v_mfma_f32_16x16x32_bf16 v[104:107], v[166:169], v[200:203], v[104:107]
	v_mfma_f32_16x16x32_bf16 v[92:95], v[158:161], v[208:211], v[92:95]
	v_mfma_f32_16x16x32_bf16 v[88:91], v[166:169], v[208:211], v[88:91]
	v_mfma_f32_16x16x32_bf16 v[76:79], v[158:161], v[216:219], v[76:79]
	v_mfma_f32_16x16x32_bf16 v[72:75], v[166:169], v[216:219], v[72:75]
	s_setprio 0
	s_setprio 1
	v_mfma_f32_16x16x32_bf16 v[116:119], v[170:173], v[186:189], v[116:119]
	v_mfma_f32_16x16x32_bf16 v[112:115], v[178:181], v[186:189], v[112:115]
	v_mfma_f32_16x16x32_bf16 v[100:103], v[170:173], v[196:199], v[100:103]
	v_mfma_f32_16x16x32_bf16 v[96:99], v[178:181], v[196:199], v[96:99]
	v_mfma_f32_16x16x32_bf16 v[84:87], v[170:173], v[204:207], v[84:87]
	v_mfma_f32_16x16x32_bf16 v[80:83], v[178:181], v[204:207], v[80:83]
	v_mfma_f32_16x16x32_bf16 v[68:71], v[170:173], v[212:215], v[68:71]
	v_mfma_f32_16x16x32_bf16 v[64:67], v[178:181], v[212:215], v[64:67]
	v_mfma_f32_16x16x32_bf16 v[116:119], v[174:177], v[190:193], v[116:119]
	v_mfma_f32_16x16x32_bf16 v[112:115], v[182:185], v[190:193], v[112:115]
	v_mfma_f32_16x16x32_bf16 v[100:103], v[174:177], v[200:203], v[100:103]
	v_mfma_f32_16x16x32_bf16 v[96:99], v[182:185], v[200:203], v[96:99]
	v_mfma_f32_16x16x32_bf16 v[84:87], v[174:177], v[208:211], v[84:87]
	v_mfma_f32_16x16x32_bf16 v[80:83], v[182:185], v[208:211], v[80:83]
	v_mfma_f32_16x16x32_bf16 v[68:71], v[174:177], v[216:219], v[68:71]
	v_mfma_f32_16x16x32_bf16 v[64:67], v[182:185], v[216:219], v[64:67]
	s_setprio 0
	s_barrier
	s_add_i32 s77, s59, s49
	v_lshl_add_u64 v[148:149], s[36:37], 0, v[130:131]
	s_mov_b32 m0, s77
	ds_read_b128 v[186:189], v155 offset:16384
	ds_read_b128 v[190:193], v155 offset:17408
	ds_read_b128 v[196:199], v155 offset:18432
	ds_read_b128 v[200:203], v155 offset:19456
	ds_read_b128 v[204:207], v155 offset:20480
	ds_read_b128 v[208:211], v155 offset:21504
	ds_read_b128 v[212:215], v155 offset:22528
	ds_read_b128 v[216:219], v155 offset:23552
	global_load_lds_dwordx4 v[148:149], off
	s_add_i32 m0, s77, 0x2000
	s_add_u32 s78, s36, 0x40000
	v_lshl_add_u64 v[220:221], s[36:37], 0, v[134:135]
	s_addc_u32 s79, s37, 0
	s_add_i32 s77, s60, s49
	global_load_lds_dwordx4 v[220:221], off
	v_lshl_add_u64 v[222:223], s[78:79], 0, v[130:131]
	s_mov_b32 m0, s77
	v_lshl_add_u64 v[224:225], s[38:39], 0, v[132:133]
	global_load_lds_dwordx4 v[222:223], off
	v_lshl_add_u64 v[222:223], s[78:79], 0, v[134:135]
	s_add_i32 m0, s77, 0x2000
	s_nop 0
	global_load_lds_dwordx4 v[222:223], off
	v_lshl_add_u64 v[222:223], s[38:39], 0, v[128:129]
	s_waitcnt vmcnt(6)
	s_waitcnt lgkmcnt(0)
	s_barrier
	s_setprio 1
	s_waitcnt lgkmcnt(0)
	v_mfma_f32_16x16x32_bf16 v[60:63], v[144:147], v[186:189], v[60:63]
	v_mfma_f32_16x16x32_bf16 v[56:59], v[162:165], v[186:189], v[56:59]
	v_mfma_f32_16x16x32_bf16 v[44:47], v[144:147], v[196:199], v[44:47]
	v_mfma_f32_16x16x32_bf16 v[40:43], v[162:165], v[196:199], v[40:43]
	v_mfma_f32_16x16x32_bf16 v[28:31], v[144:147], v[204:207], v[28:31]
	v_mfma_f32_16x16x32_bf16 v[24:27], v[162:165], v[204:207], v[24:27]
	v_mfma_f32_16x16x32_bf16 v[12:15], v[144:147], v[212:215], v[12:15]
	v_mfma_f32_16x16x32_bf16 v[8:11], v[162:165], v[212:215], v[8:11]
	v_mfma_f32_16x16x32_bf16 v[60:63], v[158:161], v[190:193], v[60:63]
	v_mfma_f32_16x16x32_bf16 v[56:59], v[166:169], v[190:193], v[56:59]
	v_mfma_f32_16x16x32_bf16 v[44:47], v[158:161], v[200:203], v[44:47]
	v_mfma_f32_16x16x32_bf16 v[40:43], v[166:169], v[200:203], v[40:43]
	v_mfma_f32_16x16x32_bf16 v[28:31], v[158:161], v[208:211], v[28:31]
	v_mfma_f32_16x16x32_bf16 v[24:27], v[166:169], v[208:211], v[24:27]
	v_mfma_f32_16x16x32_bf16 v[12:15], v[158:161], v[216:219], v[12:15]
	v_mfma_f32_16x16x32_bf16 v[8:11], v[166:169], v[216:219], v[8:11]
	s_setprio 0
	s_setprio 1
	v_mfma_f32_16x16x32_bf16 v[52:55], v[170:173], v[186:189], v[52:55]
	v_mfma_f32_16x16x32_bf16 v[48:51], v[178:181], v[186:189], v[48:51]
	v_mfma_f32_16x16x32_bf16 v[36:39], v[170:173], v[196:199], v[36:39]
	v_mfma_f32_16x16x32_bf16 v[32:35], v[178:181], v[196:199], v[32:35]
	v_mfma_f32_16x16x32_bf16 v[20:23], v[170:173], v[204:207], v[20:23]
	v_mfma_f32_16x16x32_bf16 v[16:19], v[178:181], v[204:207], v[16:19]
	v_mfma_f32_16x16x32_bf16 v[4:7], v[170:173], v[212:215], v[4:7]
	v_mfma_f32_16x16x32_bf16 v[0:3], v[178:181], v[212:215], v[0:3]
	v_mfma_f32_16x16x32_bf16 v[52:55], v[174:177], v[190:193], v[52:55]
	v_mfma_f32_16x16x32_bf16 v[48:51], v[182:185], v[190:193], v[48:51]
	v_mfma_f32_16x16x32_bf16 v[36:39], v[174:177], v[200:203], v[36:39]
	v_mfma_f32_16x16x32_bf16 v[32:35], v[182:185], v[200:203], v[32:35]
	v_mfma_f32_16x16x32_bf16 v[20:23], v[174:177], v[208:211], v[20:23]
	v_mfma_f32_16x16x32_bf16 v[16:19], v[182:185], v[208:211], v[16:19]
	v_mfma_f32_16x16x32_bf16 v[4:7], v[174:177], v[216:219], v[4:7]
	v_mfma_f32_16x16x32_bf16 v[0:3], v[182:185], v[216:219], v[0:3]
	s_setprio 0
	s_barrier
	s_add_i32 s77, 0, 0x18000
	v_add_u32_e32 v157, s77, v151
	s_add_i32 s78, 0, 0x1c000
	ds_read_b128 v[144:147], v157
	ds_read_b128 v[158:161], v157 offset:1024
	ds_read_b128 v[162:165], v157 offset:2048
	ds_read_b128 v[166:169], v157 offset:3072
	v_add_u32_e32 v157, s78, v151
	ds_read_b128 v[170:173], v157
	ds_read_b128 v[174:177], v157 offset:1024
	ds_read_b128 v[178:181], v157 offset:2048
	ds_read_b128 v[182:185], v157 offset:3072
	s_add_u32 s38, s38, 0x40000
	s_addc_u32 s39, s39, 0
	v_lshl_add_u64 v[226:227], s[38:39], 0, v[128:129]
	ds_read_b128 v[186:189], v155 offset:32768
	ds_read_b128 v[190:193], v155 offset:33792
	ds_read_b128 v[196:199], v155 offset:34816
	ds_read_b128 v[200:203], v155 offset:35840
	ds_read_b128 v[204:207], v155 offset:36864
	ds_read_b128 v[208:211], v155 offset:37888
	ds_read_b128 v[212:215], v155 offset:38912
	ds_read_b128 v[216:219], v155 offset:39936
	s_mov_b32 m0, s51
	s_nop 0
	global_load_lds_dwordx4 v[222:223], off
	s_mov_b32 m0, s52
	s_nop 0
	global_load_lds_dwordx4 v[224:225], off
	s_mov_b32 m0, s53
	s_nop 0
	global_load_lds_dwordx4 v[226:227], off
	v_lshl_add_u64 v[226:227], s[38:39], 0, v[132:133]
	s_mov_b32 m0, s54
	s_nop 0
	global_load_lds_dwordx4 v[226:227], off
	s_waitcnt vmcnt(8)
	s_waitcnt lgkmcnt(0)
	s_barrier
	s_setprio 1
	s_waitcnt lgkmcnt(0)
	v_mfma_f32_16x16x32_bf16 v[124:127], v[144:147], v[186:189], v[124:127]
	v_mfma_f32_16x16x32_bf16 v[120:123], v[162:165], v[186:189], v[120:123]
	v_mfma_f32_16x16x32_bf16 v[108:111], v[144:147], v[196:199], v[108:111]
	v_mfma_f32_16x16x32_bf16 v[104:107], v[162:165], v[196:199], v[104:107]
	v_mfma_f32_16x16x32_bf16 v[92:95], v[144:147], v[204:207], v[92:95]
	v_mfma_f32_16x16x32_bf16 v[88:91], v[162:165], v[204:207], v[88:91]
	v_mfma_f32_16x16x32_bf16 v[76:79], v[144:147], v[212:215], v[76:79]
	v_mfma_f32_16x16x32_bf16 v[72:75], v[162:165], v[212:215], v[72:75]
	v_mfma_f32_16x16x32_bf16 v[124:127], v[158:161], v[190:193], v[124:127]
	v_mfma_f32_16x16x32_bf16 v[120:123], v[166:169], v[190:193], v[120:123]
	v_mfma_f32_16x16x32_bf16 v[108:111], v[158:161], v[200:203], v[108:111]
	v_mfma_f32_16x16x32_bf16 v[104:107], v[166:169], v[200:203], v[104:107]
	v_mfma_f32_16x16x32_bf16 v[92:95], v[158:161], v[208:211], v[92:95]
	v_mfma_f32_16x16x32_bf16 v[88:91], v[166:169], v[208:211], v[88:91]
	v_mfma_f32_16x16x32_bf16 v[76:79], v[158:161], v[216:219], v[76:79]
	v_mfma_f32_16x16x32_bf16 v[72:75], v[166:169], v[216:219], v[72:75]
	s_setprio 0
	s_setprio 1
	v_mfma_f32_16x16x32_bf16 v[116:119], v[170:173], v[186:189], v[116:119]
	v_mfma_f32_16x16x32_bf16 v[112:115], v[178:181], v[186:189], v[112:115]
	v_mfma_f32_16x16x32_bf16 v[100:103], v[170:173], v[196:199], v[100:103]
	v_mfma_f32_16x16x32_bf16 v[96:99], v[178:181], v[196:199], v[96:99]
	v_mfma_f32_16x16x32_bf16 v[84:87], v[170:173], v[204:207], v[84:87]
	v_mfma_f32_16x16x32_bf16 v[80:83], v[178:181], v[204:207], v[80:83]
	v_mfma_f32_16x16x32_bf16 v[68:71], v[170:173], v[212:215], v[68:71]
	v_mfma_f32_16x16x32_bf16 v[64:67], v[178:181], v[212:215], v[64:67]
	v_mfma_f32_16x16x32_bf16 v[116:119], v[174:177], v[190:193], v[116:119]
	v_mfma_f32_16x16x32_bf16 v[112:115], v[182:185], v[190:193], v[112:115]
	v_mfma_f32_16x16x32_bf16 v[100:103], v[174:177], v[200:203], v[100:103]
	v_mfma_f32_16x16x32_bf16 v[96:99], v[182:185], v[200:203], v[96:99]
	v_mfma_f32_16x16x32_bf16 v[84:87], v[174:177], v[208:211], v[84:87]
	v_mfma_f32_16x16x32_bf16 v[80:83], v[182:185], v[208:211], v[80:83]
	v_mfma_f32_16x16x32_bf16 v[68:71], v[174:177], v[216:219], v[68:71]
	v_mfma_f32_16x16x32_bf16 v[64:67], v[182:185], v[216:219], v[64:67]
	s_setprio 0
	s_barrier
	s_add_i32 s38, s77, s49
	v_lshl_add_u64 v[148:149], v[148:149], 0, s[20:21]
	s_mov_b32 m0, s38
	ds_read_b128 v[186:189], v155 offset:49152
	ds_read_b128 v[190:193], v155 offset:50176
	ds_read_b128 v[196:199], v155 offset:51200
	ds_read_b128 v[200:203], v155 offset:52224
	ds_read_b128 v[204:207], v155 offset:53248
	ds_read_b128 v[208:211], v155 offset:54272
	ds_read_b128 v[212:215], v155 offset:55296
	ds_read_b128 v[216:219], v155 offset:56320
	global_load_lds_dwordx4 v[148:149], off
	s_add_i32 m0, s38, 0x2000
	s_add_u32 s36, s36, 0x40080
	v_lshl_add_u64 v[148:149], v[220:221], 0, s[20:21]
	s_addc_u32 s37, s37, 0
	s_add_i32 s38, s78, s49
	global_load_lds_dwordx4 v[148:149], off
	v_lshl_add_u64 v[148:149], s[36:37], 0, v[130:131]
	s_mov_b32 m0, s38
	s_nop 0
	global_load_lds_dwordx4 v[148:149], off
	v_lshl_add_u64 v[148:149], s[36:37], 0, v[134:135]
	s_add_i32 m0, s38, 0x2000
	s_nop 0
	global_load_lds_dwordx4 v[148:149], off
	s_waitcnt vmcnt(6)
	s_waitcnt lgkmcnt(0)
	s_barrier
	s_setprio 1
	s_waitcnt lgkmcnt(0)
	v_mfma_f32_16x16x32_bf16 v[60:63], v[144:147], v[186:189], v[60:63]
	v_mfma_f32_16x16x32_bf16 v[56:59], v[162:165], v[186:189], v[56:59]
	v_mfma_f32_16x16x32_bf16 v[44:47], v[144:147], v[196:199], v[44:47]
	v_mfma_f32_16x16x32_bf16 v[40:43], v[162:165], v[196:199], v[40:43]
	v_mfma_f32_16x16x32_bf16 v[28:31], v[144:147], v[204:207], v[28:31]
	v_mfma_f32_16x16x32_bf16 v[24:27], v[162:165], v[204:207], v[24:27]
	v_mfma_f32_16x16x32_bf16 v[12:15], v[144:147], v[212:215], v[12:15]
	v_mfma_f32_16x16x32_bf16 v[8:11], v[162:165], v[212:215], v[8:11]
	v_mfma_f32_16x16x32_bf16 v[60:63], v[158:161], v[190:193], v[60:63]
	v_mfma_f32_16x16x32_bf16 v[56:59], v[166:169], v[190:193], v[56:59]
	v_mfma_f32_16x16x32_bf16 v[44:47], v[158:161], v[200:203], v[44:47]
	v_mfma_f32_16x16x32_bf16 v[40:43], v[166:169], v[200:203], v[40:43]
	v_mfma_f32_16x16x32_bf16 v[28:31], v[158:161], v[208:211], v[28:31]
	v_mfma_f32_16x16x32_bf16 v[24:27], v[166:169], v[208:211], v[24:27]
	v_mfma_f32_16x16x32_bf16 v[12:15], v[158:161], v[216:219], v[12:15]
	v_mfma_f32_16x16x32_bf16 v[8:11], v[166:169], v[216:219], v[8:11]
	s_setprio 0
	s_setprio 1
	v_mfma_f32_16x16x32_bf16 v[52:55], v[170:173], v[186:189], v[52:55]
	v_mfma_f32_16x16x32_bf16 v[48:51], v[178:181], v[186:189], v[48:51]
	v_mfma_f32_16x16x32_bf16 v[36:39], v[170:173], v[196:199], v[36:39]
	v_mfma_f32_16x16x32_bf16 v[32:35], v[178:181], v[196:199], v[32:35]
	v_mfma_f32_16x16x32_bf16 v[20:23], v[170:173], v[204:207], v[20:23]
	v_mfma_f32_16x16x32_bf16 v[16:19], v[178:181], v[204:207], v[16:19]
	v_mfma_f32_16x16x32_bf16 v[4:7], v[170:173], v[212:215], v[4:7]
	v_mfma_f32_16x16x32_bf16 v[0:3], v[178:181], v[212:215], v[0:3]
	v_mfma_f32_16x16x32_bf16 v[52:55], v[174:177], v[190:193], v[52:55]
	v_mfma_f32_16x16x32_bf16 v[48:51], v[182:185], v[190:193], v[48:51]
	v_mfma_f32_16x16x32_bf16 v[36:39], v[174:177], v[200:203], v[36:39]
	v_mfma_f32_16x16x32_bf16 v[32:35], v[182:185], v[200:203], v[32:35]
	v_mfma_f32_16x16x32_bf16 v[20:23], v[174:177], v[208:211], v[20:23]
	v_mfma_f32_16x16x32_bf16 v[16:19], v[182:185], v[208:211], v[16:19]
	v_mfma_f32_16x16x32_bf16 v[4:7], v[174:177], v[216:219], v[4:7]
	v_mfma_f32_16x16x32_bf16 v[0:3], v[182:185], v[216:219], v[0:3]
	s_setprio 0
	s_barrier
	v_lshl_add_u64 v[222:223], v[222:223], 0, s[20:21]
	s_mov_b32 m0, s56
	s_nop 0
	global_load_lds_dwordx4 v[222:223], off
	v_lshl_add_u64 v[224:225], v[224:225], 0, s[20:21]
	s_mov_b32 m0, s57
	s_nop 0
	global_load_lds_dwordx4 v[224:225], off
	s_add_i32 s73, s73, 2
	s_add_u32 s34, s34, 0x100
	s_addc_u32 s35, s35, 0
	s_add_u32 s71, s71, 0x100
	s_addc_u32 s72, s72, 0
	s_cmp_gt_u32 s73, 13
	s_cbranch_scc0 .LBB0_2557
	s_and_b64 vcc, exec, s[22:23]
	s_cbranch_vccz .LBB0_2560
	s_barrier

.LBB0_2633:
	ds_read_b128 v[144:147], v153
	ds_read_b128 v[156:159], v153 offset:1024
	ds_read_b128 v[160:163], v153 offset:2048
	ds_read_b128 v[164:167], v153 offset:3072
	ds_read_b128 v[168:171], v154
	ds_read_b128 v[172:175], v154 offset:1024
	ds_read_b128 v[176:179], v154 offset:2048
	ds_read_b128 v[180:183], v154 offset:3072
	s_add_u32 s42, s40, 0xfffe0080
	s_addc_u32 s43, s41, -1
	s_cmp_eq_u32 s73, 4
	s_cselect_b32 s45, s31, s43
	s_cselect_b32 s44, s63, s42
	s_cselect_b32 s43, s29, s72
	s_cselect_b32 s42, s70, s71
	v_lshl_add_u64 v[148:149], s[40:41], 0, v[136:137]
	s_add_i32 m0, s39, 0xc000
	ds_read_b128 v[184:187], v155
	ds_read_b128 v[188:191], v155 offset:1024
	ds_read_b128 v[196:199], v155 offset:2048
	ds_read_b128 v[200:203], v155 offset:3072
	ds_read_b128 v[204:207], v155 offset:4096
	ds_read_b128 v[208:211], v155 offset:5120
	ds_read_b128 v[212:215], v155 offset:6144
	ds_read_b128 v[216:219], v155 offset:7168
	global_load_lds_dwordx4 v[148:149], off
	v_lshl_add_u64 v[148:149], s[40:41], 0, v[138:139]
	s_add_i32 m0, s39, 0xe000
	s_nop 0
	global_load_lds_dwordx4 v[148:149], off
	s_waitcnt vmcnt(8)
	s_waitcnt lgkmcnt(0)
	s_barrier
	s_setprio 1
	s_waitcnt lgkmcnt(0)
	v_mfma_f32_16x16x32_bf16 v[124:127], v[144:147], v[184:187], v[124:127]
	v_mfma_f32_16x16x32_bf16 v[120:123], v[160:163], v[184:187], v[120:123]
	v_mfma_f32_16x16x32_bf16 v[108:111], v[144:147], v[196:199], v[108:111]
	v_mfma_f32_16x16x32_bf16 v[104:107], v[160:163], v[196:199], v[104:107]
	v_mfma_f32_16x16x32_bf16 v[92:95], v[144:147], v[204:207], v[92:95]
	v_mfma_f32_16x16x32_bf16 v[88:91], v[160:163], v[204:207], v[88:91]
	v_mfma_f32_16x16x32_bf16 v[76:79], v[144:147], v[212:215], v[76:79]
	v_mfma_f32_16x16x32_bf16 v[72:75], v[160:163], v[212:215], v[72:75]
	v_mfma_f32_16x16x32_bf16 v[124:127], v[156:159], v[188:191], v[124:127]
	v_mfma_f32_16x16x32_bf16 v[120:123], v[164:167], v[188:191], v[120:123]
	v_mfma_f32_16x16x32_bf16 v[108:111], v[156:159], v[200:203], v[108:111]
	v_mfma_f32_16x16x32_bf16 v[104:107], v[164:167], v[200:203], v[104:107]
	v_mfma_f32_16x16x32_bf16 v[92:95], v[156:159], v[208:211], v[92:95]
	v_mfma_f32_16x16x32_bf16 v[88:91], v[164:167], v[208:211], v[88:91]
	v_mfma_f32_16x16x32_bf16 v[76:79], v[156:159], v[216:219], v[76:79]
	v_mfma_f32_16x16x32_bf16 v[72:75], v[164:167], v[216:219], v[72:75]
	s_setprio 0
	s_setprio 1
	v_mfma_f32_16x16x32_bf16 v[116:119], v[168:171], v[184:187], v[116:119]
	v_mfma_f32_16x16x32_bf16 v[112:115], v[176:179], v[184:187], v[112:115]
	v_mfma_f32_16x16x32_bf16 v[100:103], v[168:171], v[196:199], v[100:103]
	v_mfma_f32_16x16x32_bf16 v[96:99], v[176:179], v[196:199], v[96:99]
	v_mfma_f32_16x16x32_bf16 v[84:87], v[168:171], v[204:207], v[84:87]
	v_mfma_f32_16x16x32_bf16 v[80:83], v[176:179], v[204:207], v[80:83]
	v_mfma_f32_16x16x32_bf16 v[68:71], v[168:171], v[212:215], v[68:71]
	v_mfma_f32_16x16x32_bf16 v[64:67], v[176:179], v[212:215], v[64:67]
	v_mfma_f32_16x16x32_bf16 v[116:119], v[172:175], v[188:191], v[116:119]
	v_mfma_f32_16x16x32_bf16 v[112:115], v[180:183], v[188:191], v[112:115]
	v_mfma_f32_16x16x32_bf16 v[100:103], v[172:175], v[200:203], v[100:103]
	v_mfma_f32_16x16x32_bf16 v[96:99], v[180:183], v[200:203], v[96:99]
	v_mfma_f32_16x16x32_bf16 v[84:87], v[172:175], v[208:211], v[84:87]
	v_mfma_f32_16x16x32_bf16 v[80:83], v[180:183], v[208:211], v[80:83]
	v_mfma_f32_16x16x32_bf16 v[68:71], v[172:175], v[216:219], v[68:71]
	v_mfma_f32_16x16x32_bf16 v[64:67], v[180:183], v[216:219], v[64:67]
	s_setprio 0
	s_barrier
	s_add_i32 s77, s60, s52
	v_lshl_add_u64 v[148:149], s[42:43], 0, v[130:131]
	s_mov_b32 m0, s77
	ds_read_b128 v[184:187], v155 offset:16384
	ds_read_b128 v[188:191], v155 offset:17408
	ds_read_b128 v[196:199], v155 offset:18432
	ds_read_b128 v[200:203], v155 offset:19456
	ds_read_b128 v[204:207], v155 offset:20480
	ds_read_b128 v[208:211], v155 offset:21504
	ds_read_b128 v[212:215], v155 offset:22528
	ds_read_b128 v[216:219], v155 offset:23552
	global_load_lds_dwordx4 v[148:149], off
	s_add_i32 m0, s77, 0x2000
	s_add_u32 s78, s42, 0x20000
	v_lshl_add_u64 v[192:193], s[42:43], 0, v[134:135]
	s_addc_u32 s79, s43, 0
	s_add_i32 s77, s61, s52
	global_load_lds_dwordx4 v[192:193], off
	v_lshl_add_u64 v[220:221], s[78:79], 0, v[130:131]
	s_mov_b32 m0, s77
	v_lshl_add_u64 v[222:223], s[44:45], 0, v[132:133]
	global_load_lds_dwordx4 v[220:221], off
	v_lshl_add_u64 v[220:221], s[78:79], 0, v[134:135]
	s_add_i32 m0, s77, 0x2000
	s_nop 0
	global_load_lds_dwordx4 v[220:221], off
	v_lshl_add_u64 v[220:221], s[44:45], 0, v[128:129]
	s_waitcnt vmcnt(6)
	s_waitcnt lgkmcnt(0)
	s_barrier
	s_setprio 1
	s_waitcnt lgkmcnt(0)
	v_mfma_f32_16x16x32_bf16 v[60:63], v[144:147], v[184:187], v[60:63]
	v_mfma_f32_16x16x32_bf16 v[56:59], v[160:163], v[184:187], v[56:59]
	v_mfma_f32_16x16x32_bf16 v[44:47], v[144:147], v[196:199], v[44:47]
	v_mfma_f32_16x16x32_bf16 v[40:43], v[160:163], v[196:199], v[40:43]
	v_mfma_f32_16x16x32_bf16 v[28:31], v[144:147], v[204:207], v[28:31]
	v_mfma_f32_16x16x32_bf16 v[24:27], v[160:163], v[204:207], v[24:27]
	v_mfma_f32_16x16x32_bf16 v[12:15], v[144:147], v[212:215], v[12:15]
	v_mfma_f32_16x16x32_bf16 v[8:11], v[160:163], v[212:215], v[8:11]
	v_mfma_f32_16x16x32_bf16 v[60:63], v[156:159], v[188:191], v[60:63]
	v_mfma_f32_16x16x32_bf16 v[56:59], v[164:167], v[188:191], v[56:59]
	v_mfma_f32_16x16x32_bf16 v[44:47], v[156:159], v[200:203], v[44:47]
	v_mfma_f32_16x16x32_bf16 v[40:43], v[164:167], v[200:203], v[40:43]
	v_mfma_f32_16x16x32_bf16 v[28:31], v[156:159], v[208:211], v[28:31]
	v_mfma_f32_16x16x32_bf16 v[24:27], v[164:167], v[208:211], v[24:27]
	v_mfma_f32_16x16x32_bf16 v[12:15], v[156:159], v[216:219], v[12:15]
	v_mfma_f32_16x16x32_bf16 v[8:11], v[164:167], v[216:219], v[8:11]
	s_setprio 0
	s_setprio 1
	v_mfma_f32_16x16x32_bf16 v[52:55], v[168:171], v[184:187], v[52:55]
	v_mfma_f32_16x16x32_bf16 v[48:51], v[176:179], v[184:187], v[48:51]
	v_mfma_f32_16x16x32_bf16 v[36:39], v[168:171], v[196:199], v[36:39]
	v_mfma_f32_16x16x32_bf16 v[32:35], v[176:179], v[196:199], v[32:35]
	v_mfma_f32_16x16x32_bf16 v[20:23], v[168:171], v[204:207], v[20:23]
	v_mfma_f32_16x16x32_bf16 v[16:19], v[176:179], v[204:207], v[16:19]
	v_mfma_f32_16x16x32_bf16 v[4:7], v[168:171], v[212:215], v[4:7]
	v_mfma_f32_16x16x32_bf16 v[0:3], v[176:179], v[212:215], v[0:3]
	v_mfma_f32_16x16x32_bf16 v[52:55], v[172:175], v[188:191], v[52:55]
	v_mfma_f32_16x16x32_bf16 v[48:51], v[180:183], v[188:191], v[48:51]
	v_mfma_f32_16x16x32_bf16 v[36:39], v[172:175], v[200:203], v[36:39]
	v_mfma_f32_16x16x32_bf16 v[32:35], v[180:183], v[200:203], v[32:35]
	v_mfma_f32_16x16x32_bf16 v[20:23], v[172:175], v[208:211], v[20:23]
	v_mfma_f32_16x16x32_bf16 v[16:19], v[180:183], v[208:211], v[16:19]
	v_mfma_f32_16x16x32_bf16 v[4:7], v[172:175], v[216:219], v[4:7]
	v_mfma_f32_16x16x32_bf16 v[0:3], v[180:183], v[216:219], v[0:3]
	s_setprio 0
	s_barrier
	s_add_i32 s77, 0, 0x18000
	s_add_i32 s78, 0, 0x1c000
	v_add_u32_e32 v164, s77, v151
	v_add_u32_e32 v180, s78, v151
	ds_read_b128 v[144:147], v164
	ds_read_b128 v[156:159], v164 offset:1024
	ds_read_b128 v[160:163], v164 offset:2048
	ds_read_b128 v[164:167], v164 offset:3072
	ds_read_b128 v[168:171], v180
	ds_read_b128 v[172:175], v180 offset:1024
	ds_read_b128 v[176:179], v180 offset:2048
	ds_read_b128 v[180:183], v180 offset:3072
	s_add_u32 s44, s44, 0x20000
	s_addc_u32 s45, s45, 0
	v_lshl_add_u64 v[224:225], s[44:45], 0, v[128:129]
	ds_read_b128 v[184:187], v155 offset:32768
	ds_read_b128 v[188:191], v155 offset:33792
	ds_read_b128 v[196:199], v155 offset:34816
	ds_read_b128 v[200:203], v155 offset:35840
	ds_read_b128 v[204:207], v155 offset:36864
	ds_read_b128 v[208:211], v155 offset:37888
	ds_read_b128 v[212:215], v155 offset:38912
	ds_read_b128 v[216:219], v155 offset:39936
	s_mov_b32 m0, s39
	s_nop 0
	global_load_lds_dwordx4 v[220:221], off
	s_mov_b32 m0, s53
	s_nop 0
	global_load_lds_dwordx4 v[222:223], off
	s_mov_b32 m0, s54
	s_nop 0
	global_load_lds_dwordx4 v[224:225], off
	v_lshl_add_u64 v[224:225], s[44:45], 0, v[132:133]
	s_mov_b32 m0, s55
	s_nop 0
	global_load_lds_dwordx4 v[224:225], off
	s_waitcnt vmcnt(8)
	s_waitcnt lgkmcnt(0)
	s_barrier
	s_setprio 1
	s_waitcnt lgkmcnt(0)
	v_mfma_f32_16x16x32_bf16 v[124:127], v[144:147], v[184:187], v[124:127]
	v_mfma_f32_16x16x32_bf16 v[120:123], v[160:163], v[184:187], v[120:123]
	v_mfma_f32_16x16x32_bf16 v[108:111], v[144:147], v[196:199], v[108:111]
	v_mfma_f32_16x16x32_bf16 v[104:107], v[160:163], v[196:199], v[104:107]
	v_mfma_f32_16x16x32_bf16 v[92:95], v[144:147], v[204:207], v[92:95]
	v_mfma_f32_16x16x32_bf16 v[88:91], v[160:163], v[204:207], v[88:91]
	v_mfma_f32_16x16x32_bf16 v[76:79], v[144:147], v[212:215], v[76:79]
	v_mfma_f32_16x16x32_bf16 v[72:75], v[160:163], v[212:215], v[72:75]
	v_mfma_f32_16x16x32_bf16 v[124:127], v[156:159], v[188:191], v[124:127]
	v_mfma_f32_16x16x32_bf16 v[120:123], v[164:167], v[188:191], v[120:123]
	v_mfma_f32_16x16x32_bf16 v[108:111], v[156:159], v[200:203], v[108:111]
	v_mfma_f32_16x16x32_bf16 v[104:107], v[164:167], v[200:203], v[104:107]
	v_mfma_f32_16x16x32_bf16 v[92:95], v[156:159], v[208:211], v[92:95]
	v_mfma_f32_16x16x32_bf16 v[88:91], v[164:167], v[208:211], v[88:91]
	v_mfma_f32_16x16x32_bf16 v[76:79], v[156:159], v[216:219], v[76:79]
	v_mfma_f32_16x16x32_bf16 v[72:75], v[164:167], v[216:219], v[72:75]
	s_setprio 0
	s_setprio 1
	v_mfma_f32_16x16x32_bf16 v[116:119], v[168:171], v[184:187], v[116:119]
	v_mfma_f32_16x16x32_bf16 v[112:115], v[176:179], v[184:187], v[112:115]
	v_mfma_f32_16x16x32_bf16 v[100:103], v[168:171], v[196:199], v[100:103]
	v_mfma_f32_16x16x32_bf16 v[96:99], v[176:179], v[196:199], v[96:99]
	v_mfma_f32_16x16x32_bf16 v[84:87], v[168:171], v[204:207], v[84:87]
	v_mfma_f32_16x16x32_bf16 v[80:83], v[176:179], v[204:207], v[80:83]
	v_mfma_f32_16x16x32_bf16 v[68:71], v[168:171], v[212:215], v[68:71]
	v_mfma_f32_16x16x32_bf16 v[64:67], v[176:179], v[212:215], v[64:67]
	v_mfma_f32_16x16x32_bf16 v[116:119], v[172:175], v[188:191], v[116:119]
	v_mfma_f32_16x16x32_bf16 v[112:115], v[180:183], v[188:191], v[112:115]
	v_mfma_f32_16x16x32_bf16 v[100:103], v[172:175], v[200:203], v[100:103]
	v_mfma_f32_16x16x32_bf16 v[96:99], v[180:183], v[200:203], v[96:99]
	v_mfma_f32_16x16x32_bf16 v[84:87], v[172:175], v[208:211], v[84:87]
	v_mfma_f32_16x16x32_bf16 v[80:83], v[180:183], v[208:211], v[80:83]
	v_mfma_f32_16x16x32_bf16 v[68:71], v[172:175], v[216:219], v[68:71]
	v_mfma_f32_16x16x32_bf16 v[64:67], v[180:183], v[216:219], v[64:67]
	s_setprio 0
	s_barrier
	s_add_i32 s44, s77, s52
	v_lshl_add_u64 v[148:149], v[148:149], 0, s[18:19]
	s_mov_b32 m0, s44
	ds_read_b128 v[184:187], v155 offset:49152
	ds_read_b128 v[188:191], v155 offset:50176
	ds_read_b128 v[196:199], v155 offset:51200
	ds_read_b128 v[200:203], v155 offset:52224
	ds_read_b128 v[204:207], v155 offset:53248
	ds_read_b128 v[208:211], v155 offset:54272
	ds_read_b128 v[212:215], v155 offset:55296
	ds_read_b128 v[216:219], v155 offset:56320
	global_load_lds_dwordx4 v[148:149], off
	s_add_i32 m0, s44, 0x2000
	s_add_u32 s42, s42, 0x20080
	v_lshl_add_u64 v[148:149], v[192:193], 0, s[18:19]
	s_addc_u32 s43, s43, 0
	s_add_i32 s44, s78, s52
	global_load_lds_dwordx4 v[148:149], off
	v_lshl_add_u64 v[148:149], s[42:43], 0, v[130:131]
	s_mov_b32 m0, s44
	s_nop 0
	global_load_lds_dwordx4 v[148:149], off
	v_lshl_add_u64 v[148:149], s[42:43], 0, v[134:135]
	s_add_i32 m0, s44, 0x2000
	s_nop 0
	global_load_lds_dwordx4 v[148:149], off
	s_waitcnt vmcnt(6)
	s_waitcnt lgkmcnt(0)
	s_barrier
	s_setprio 1
	s_waitcnt lgkmcnt(0)
	v_mfma_f32_16x16x32_bf16 v[60:63], v[144:147], v[184:187], v[60:63]
	v_mfma_f32_16x16x32_bf16 v[56:59], v[160:163], v[184:187], v[56:59]
	v_mfma_f32_16x16x32_bf16 v[44:47], v[144:147], v[196:199], v[44:47]
	v_mfma_f32_16x16x32_bf16 v[40:43], v[160:163], v[196:199], v[40:43]
	v_mfma_f32_16x16x32_bf16 v[28:31], v[144:147], v[204:207], v[28:31]
	v_mfma_f32_16x16x32_bf16 v[24:27], v[160:163], v[204:207], v[24:27]
	v_mfma_f32_16x16x32_bf16 v[12:15], v[144:147], v[212:215], v[12:15]
	v_mfma_f32_16x16x32_bf16 v[8:11], v[160:163], v[212:215], v[8:11]
	v_mfma_f32_16x16x32_bf16 v[60:63], v[156:159], v[188:191], v[60:63]
	v_mfma_f32_16x16x32_bf16 v[56:59], v[164:167], v[188:191], v[56:59]
	v_mfma_f32_16x16x32_bf16 v[44:47], v[156:159], v[200:203], v[44:47]
	v_mfma_f32_16x16x32_bf16 v[40:43], v[164:167], v[200:203], v[40:43]
	v_mfma_f32_16x16x32_bf16 v[28:31], v[156:159], v[208:211], v[28:31]
	v_mfma_f32_16x16x32_bf16 v[24:27], v[164:167], v[208:211], v[24:27]
	v_mfma_f32_16x16x32_bf16 v[12:15], v[156:159], v[216:219], v[12:15]
	v_mfma_f32_16x16x32_bf16 v[8:11], v[164:167], v[216:219], v[8:11]
	s_setprio 0
	s_setprio 1
	v_mfma_f32_16x16x32_bf16 v[52:55], v[168:171], v[184:187], v[52:55]
	v_mfma_f32_16x16x32_bf16 v[48:51], v[176:179], v[184:187], v[48:51]
	v_mfma_f32_16x16x32_bf16 v[36:39], v[168:171], v[196:199], v[36:39]
	v_mfma_f32_16x16x32_bf16 v[32:35], v[176:179], v[196:199], v[32:35]
	v_mfma_f32_16x16x32_bf16 v[20:23], v[168:171], v[204:207], v[20:23]
	v_mfma_f32_16x16x32_bf16 v[16:19], v[176:179], v[204:207], v[16:19]
	v_mfma_f32_16x16x32_bf16 v[4:7], v[168:171], v[212:215], v[4:7]
	v_mfma_f32_16x16x32_bf16 v[0:3], v[176:179], v[212:215], v[0:3]
	v_mfma_f32_16x16x32_bf16 v[52:55], v[172:175], v[188:191], v[52:55]
	v_mfma_f32_16x16x32_bf16 v[48:51], v[180:183], v[188:191], v[48:51]
	v_mfma_f32_16x16x32_bf16 v[36:39], v[172:175], v[200:203], v[36:39]
	v_mfma_f32_16x16x32_bf16 v[32:35], v[180:183], v[200:203], v[32:35]
	v_mfma_f32_16x16x32_bf16 v[20:23], v[172:175], v[208:211], v[20:23]
	v_mfma_f32_16x16x32_bf16 v[16:19], v[180:183], v[208:211], v[16:19]
	v_mfma_f32_16x16x32_bf16 v[4:7], v[172:175], v[216:219], v[4:7]
	v_mfma_f32_16x16x32_bf16 v[0:3], v[180:183], v[216:219], v[0:3]
	s_setprio 0
	s_barrier
	v_lshl_add_u64 v[220:221], v[220:221], 0, s[18:19]
	s_mov_b32 m0, s57
	s_nop 0
	global_load_lds_dwordx4 v[220:221], off
	v_lshl_add_u64 v[222:223], v[222:223], 0, s[18:19]
	s_mov_b32 m0, s58
	s_nop 0
	global_load_lds_dwordx4 v[222:223], off
	s_add_i32 s73, s73, 2
	s_add_u32 s40, s40, 0x100
	s_addc_u32 s41, s41, 0
	s_add_u32 s71, s71, 0x100
	s_addc_u32 s72, s72, 0
	s_cmp_gt_u32 s73, 5
	s_cbranch_scc0 .LBB0_2633
	s_and_b64 vcc, exec, s[20:21]
	s_cbranch_vccz .LBB0_2636
	s_barrier

.LBB0_2657:
	ds_read_b128 v[144:147], v153
	ds_read_b128 v[158:161], v153 offset:1024
	ds_read_b128 v[162:165], v153 offset:2048
	ds_read_b128 v[166:169], v153 offset:3072
	ds_read_b128 v[170:173], v154
	ds_read_b128 v[174:177], v154 offset:1024
	ds_read_b128 v[178:181], v154 offset:2048
	ds_read_b128 v[182:185], v154 offset:3072
	s_add_u32 s34, s30, 0xfffc0080
	s_addc_u32 s35, s31, -1
	s_cmp_eq_u32 s70, 12
	s_cselect_b32 s37, s25, s35
	s_cselect_b32 s36, s60, s34
	s_cselect_b32 s35, s23, s63
	s_cselect_b32 s34, s61, s62
	v_lshl_add_u64 v[148:149], s[30:31], 0, v[136:137]
	s_add_i32 m0, s48, 0xc000
	ds_read_b128 v[186:189], v155
	ds_read_b128 v[190:193], v155 offset:1024
	ds_read_b128 v[196:199], v155 offset:2048
	ds_read_b128 v[200:203], v155 offset:3072
	ds_read_b128 v[204:207], v155 offset:4096
	ds_read_b128 v[208:211], v155 offset:5120
	ds_read_b128 v[212:215], v155 offset:6144
	ds_read_b128 v[216:219], v155 offset:7168
	global_load_lds_dwordx4 v[148:149], off
	v_lshl_add_u64 v[148:149], s[30:31], 0, v[138:139]
	s_add_i32 m0, s48, 0xe000
	s_nop 0
	global_load_lds_dwordx4 v[148:149], off
	s_waitcnt vmcnt(8)
	s_waitcnt lgkmcnt(0)
	s_barrier
	s_setprio 1
	s_waitcnt lgkmcnt(0)
	v_mfma_f32_16x16x32_bf16 v[124:127], v[144:147], v[186:189], v[124:127]
	v_mfma_f32_16x16x32_bf16 v[120:123], v[162:165], v[186:189], v[120:123]
	v_mfma_f32_16x16x32_bf16 v[108:111], v[144:147], v[196:199], v[108:111]
	v_mfma_f32_16x16x32_bf16 v[104:107], v[162:165], v[196:199], v[104:107]
	v_mfma_f32_16x16x32_bf16 v[92:95], v[144:147], v[204:207], v[92:95]
	v_mfma_f32_16x16x32_bf16 v[88:91], v[162:165], v[204:207], v[88:91]
	v_mfma_f32_16x16x32_bf16 v[76:79], v[144:147], v[212:215], v[76:79]
	v_mfma_f32_16x16x32_bf16 v[72:75], v[162:165], v[212:215], v[72:75]
	v_mfma_f32_16x16x32_bf16 v[124:127], v[158:161], v[190:193], v[124:127]
	v_mfma_f32_16x16x32_bf16 v[120:123], v[166:169], v[190:193], v[120:123]
	v_mfma_f32_16x16x32_bf16 v[108:111], v[158:161], v[200:203], v[108:111]
	v_mfma_f32_16x16x32_bf16 v[104:107], v[166:169], v[200:203], v[104:107]
	v_mfma_f32_16x16x32_bf16 v[92:95], v[158:161], v[208:211], v[92:95]
	v_mfma_f32_16x16x32_bf16 v[88:91], v[166:169], v[208:211], v[88:91]
	v_mfma_f32_16x16x32_bf16 v[76:79], v[158:161], v[216:219], v[76:79]
	v_mfma_f32_16x16x32_bf16 v[72:75], v[166:169], v[216:219], v[72:75]
	s_setprio 0
	s_setprio 1
	v_mfma_f32_16x16x32_bf16 v[116:119], v[170:173], v[186:189], v[116:119]
	v_mfma_f32_16x16x32_bf16 v[112:115], v[178:181], v[186:189], v[112:115]
	v_mfma_f32_16x16x32_bf16 v[100:103], v[170:173], v[196:199], v[100:103]
	v_mfma_f32_16x16x32_bf16 v[96:99], v[178:181], v[196:199], v[96:99]
	v_mfma_f32_16x16x32_bf16 v[84:87], v[170:173], v[204:207], v[84:87]
	v_mfma_f32_16x16x32_bf16 v[80:83], v[178:181], v[204:207], v[80:83]
	v_mfma_f32_16x16x32_bf16 v[68:71], v[170:173], v[212:215], v[68:71]
	v_mfma_f32_16x16x32_bf16 v[64:67], v[178:181], v[212:215], v[64:67]
	v_mfma_f32_16x16x32_bf16 v[116:119], v[174:177], v[190:193], v[116:119]
	v_mfma_f32_16x16x32_bf16 v[112:115], v[182:185], v[190:193], v[112:115]
	v_mfma_f32_16x16x32_bf16 v[100:103], v[174:177], v[200:203], v[100:103]
	v_mfma_f32_16x16x32_bf16 v[96:99], v[182:185], v[200:203], v[96:99]
	v_mfma_f32_16x16x32_bf16 v[84:87], v[174:177], v[208:211], v[84:87]
	v_mfma_f32_16x16x32_bf16 v[80:83], v[182:185], v[208:211], v[80:83]
	v_mfma_f32_16x16x32_bf16 v[68:71], v[174:177], v[216:219], v[68:71]
	v_mfma_f32_16x16x32_bf16 v[64:67], v[182:185], v[216:219], v[64:67]
	s_setprio 0
	s_barrier
	s_add_i32 s71, s56, s45
	v_lshl_add_u64 v[148:149], s[34:35], 0, v[130:131]
	s_mov_b32 m0, s71
	ds_read_b128 v[186:189], v155 offset:16384
	ds_read_b128 v[190:193], v155 offset:17408
	ds_read_b128 v[196:199], v155 offset:18432
	ds_read_b128 v[200:203], v155 offset:19456
	ds_read_b128 v[204:207], v155 offset:20480
	ds_read_b128 v[208:211], v155 offset:21504
	ds_read_b128 v[212:215], v155 offset:22528
	ds_read_b128 v[216:219], v155 offset:23552
	global_load_lds_dwordx4 v[148:149], off
	s_add_i32 m0, s71, 0x2000
	s_add_u32 s72, s34, 0x40000
	v_lshl_add_u64 v[220:221], s[34:35], 0, v[134:135]
	s_addc_u32 s73, s35, 0
	s_add_i32 s71, s57, s45
	global_load_lds_dwordx4 v[220:221], off
	v_lshl_add_u64 v[222:223], s[72:73], 0, v[130:131]
	s_mov_b32 m0, s71
	v_lshl_add_u64 v[224:225], s[36:37], 0, v[132:133]
	global_load_lds_dwordx4 v[222:223], off
	v_lshl_add_u64 v[222:223], s[72:73], 0, v[134:135]
	s_add_i32 m0, s71, 0x2000
	s_nop 0
	global_load_lds_dwordx4 v[222:223], off
	v_lshl_add_u64 v[222:223], s[36:37], 0, v[128:129]
	s_waitcnt vmcnt(6)
	s_waitcnt lgkmcnt(0)
	s_barrier
	s_setprio 1
	s_waitcnt lgkmcnt(0)
	v_mfma_f32_16x16x32_bf16 v[60:63], v[144:147], v[186:189], v[60:63]
	v_mfma_f32_16x16x32_bf16 v[56:59], v[162:165], v[186:189], v[56:59]
	v_mfma_f32_16x16x32_bf16 v[44:47], v[144:147], v[196:199], v[44:47]
	v_mfma_f32_16x16x32_bf16 v[40:43], v[162:165], v[196:199], v[40:43]
	v_mfma_f32_16x16x32_bf16 v[28:31], v[144:147], v[204:207], v[28:31]
	v_mfma_f32_16x16x32_bf16 v[24:27], v[162:165], v[204:207], v[24:27]
	v_mfma_f32_16x16x32_bf16 v[12:15], v[144:147], v[212:215], v[12:15]
	v_mfma_f32_16x16x32_bf16 v[8:11], v[162:165], v[212:215], v[8:11]
	v_mfma_f32_16x16x32_bf16 v[60:63], v[158:161], v[190:193], v[60:63]
	v_mfma_f32_16x16x32_bf16 v[56:59], v[166:169], v[190:193], v[56:59]
	v_mfma_f32_16x16x32_bf16 v[44:47], v[158:161], v[200:203], v[44:47]
	v_mfma_f32_16x16x32_bf16 v[40:43], v[166:169], v[200:203], v[40:43]
	v_mfma_f32_16x16x32_bf16 v[28:31], v[158:161], v[208:211], v[28:31]
	v_mfma_f32_16x16x32_bf16 v[24:27], v[166:169], v[208:211], v[24:27]
	v_mfma_f32_16x16x32_bf16 v[12:15], v[158:161], v[216:219], v[12:15]
	v_mfma_f32_16x16x32_bf16 v[8:11], v[166:169], v[216:219], v[8:11]
	s_setprio 0
	s_setprio 1
	v_mfma_f32_16x16x32_bf16 v[52:55], v[170:173], v[186:189], v[52:55]
	v_mfma_f32_16x16x32_bf16 v[48:51], v[178:181], v[186:189], v[48:51]
	v_mfma_f32_16x16x32_bf16 v[36:39], v[170:173], v[196:199], v[36:39]
	v_mfma_f32_16x16x32_bf16 v[32:35], v[178:181], v[196:199], v[32:35]
	v_mfma_f32_16x16x32_bf16 v[20:23], v[170:173], v[204:207], v[20:23]
	v_mfma_f32_16x16x32_bf16 v[16:19], v[178:181], v[204:207], v[16:19]
	v_mfma_f32_16x16x32_bf16 v[4:7], v[170:173], v[212:215], v[4:7]
	v_mfma_f32_16x16x32_bf16 v[0:3], v[178:181], v[212:215], v[0:3]
	v_mfma_f32_16x16x32_bf16 v[52:55], v[174:177], v[190:193], v[52:55]
	v_mfma_f32_16x16x32_bf16 v[48:51], v[182:185], v[190:193], v[48:51]
	v_mfma_f32_16x16x32_bf16 v[36:39], v[174:177], v[200:203], v[36:39]
	v_mfma_f32_16x16x32_bf16 v[32:35], v[182:185], v[200:203], v[32:35]
	v_mfma_f32_16x16x32_bf16 v[20:23], v[174:177], v[208:211], v[20:23]
	v_mfma_f32_16x16x32_bf16 v[16:19], v[182:185], v[208:211], v[16:19]
	v_mfma_f32_16x16x32_bf16 v[4:7], v[174:177], v[216:219], v[4:7]
	v_mfma_f32_16x16x32_bf16 v[0:3], v[182:185], v[216:219], v[0:3]
	s_setprio 0
	s_barrier
	s_add_i32 s71, 0, 0x18000
	v_add_u32_e32 v157, s71, v151
	s_add_i32 s72, 0, 0x1c000
	ds_read_b128 v[144:147], v157
	ds_read_b128 v[158:161], v157 offset:1024
	ds_read_b128 v[162:165], v157 offset:2048
	ds_read_b128 v[166:169], v157 offset:3072
	v_add_u32_e32 v157, s72, v151
	ds_read_b128 v[170:173], v157
	ds_read_b128 v[174:177], v157 offset:1024
	ds_read_b128 v[178:181], v157 offset:2048
	ds_read_b128 v[182:185], v157 offset:3072
	s_add_u32 s36, s36, 0x40000
	s_addc_u32 s37, s37, 0
	v_lshl_add_u64 v[226:227], s[36:37], 0, v[128:129]
	ds_read_b128 v[186:189], v155 offset:32768
	ds_read_b128 v[190:193], v155 offset:33792
	ds_read_b128 v[196:199], v155 offset:34816
	ds_read_b128 v[200:203], v155 offset:35840
	ds_read_b128 v[204:207], v155 offset:36864
	ds_read_b128 v[208:211], v155 offset:37888
	ds_read_b128 v[212:215], v155 offset:38912
	ds_read_b128 v[216:219], v155 offset:39936
	s_mov_b32 m0, s48
	s_nop 0
	global_load_lds_dwordx4 v[222:223], off
	s_mov_b32 m0, s49
	s_nop 0
	global_load_lds_dwordx4 v[224:225], off
	s_mov_b32 m0, s50
	s_nop 0
	global_load_lds_dwordx4 v[226:227], off
	v_lshl_add_u64 v[226:227], s[36:37], 0, v[132:133]
	s_mov_b32 m0, s51
	s_nop 0
	global_load_lds_dwordx4 v[226:227], off
	s_waitcnt vmcnt(8)
	s_waitcnt lgkmcnt(0)
	s_barrier
	s_setprio 1
	s_waitcnt lgkmcnt(0)
	v_mfma_f32_16x16x32_bf16 v[124:127], v[144:147], v[186:189], v[124:127]
	v_mfma_f32_16x16x32_bf16 v[120:123], v[162:165], v[186:189], v[120:123]
	v_mfma_f32_16x16x32_bf16 v[108:111], v[144:147], v[196:199], v[108:111]
	v_mfma_f32_16x16x32_bf16 v[104:107], v[162:165], v[196:199], v[104:107]
	v_mfma_f32_16x16x32_bf16 v[92:95], v[144:147], v[204:207], v[92:95]
	v_mfma_f32_16x16x32_bf16 v[88:91], v[162:165], v[204:207], v[88:91]
	v_mfma_f32_16x16x32_bf16 v[76:79], v[144:147], v[212:215], v[76:79]
	v_mfma_f32_16x16x32_bf16 v[72:75], v[162:165], v[212:215], v[72:75]
	v_mfma_f32_16x16x32_bf16 v[124:127], v[158:161], v[190:193], v[124:127]
	v_mfma_f32_16x16x32_bf16 v[120:123], v[166:169], v[190:193], v[120:123]
	v_mfma_f32_16x16x32_bf16 v[108:111], v[158:161], v[200:203], v[108:111]
	v_mfma_f32_16x16x32_bf16 v[104:107], v[166:169], v[200:203], v[104:107]
	v_mfma_f32_16x16x32_bf16 v[92:95], v[158:161], v[208:211], v[92:95]
	v_mfma_f32_16x16x32_bf16 v[88:91], v[166:169], v[208:211], v[88:91]
	v_mfma_f32_16x16x32_bf16 v[76:79], v[158:161], v[216:219], v[76:79]
	v_mfma_f32_16x16x32_bf16 v[72:75], v[166:169], v[216:219], v[72:75]
	s_setprio 0
	s_setprio 1
	v_mfma_f32_16x16x32_bf16 v[116:119], v[170:173], v[186:189], v[116:119]
	v_mfma_f32_16x16x32_bf16 v[112:115], v[178:181], v[186:189], v[112:115]
	v_mfma_f32_16x16x32_bf16 v[100:103], v[170:173], v[196:199], v[100:103]
	v_mfma_f32_16x16x32_bf16 v[96:99], v[178:181], v[196:199], v[96:99]
	v_mfma_f32_16x16x32_bf16 v[84:87], v[170:173], v[204:207], v[84:87]
	v_mfma_f32_16x16x32_bf16 v[80:83], v[178:181], v[204:207], v[80:83]
	v_mfma_f32_16x16x32_bf16 v[68:71], v[170:173], v[212:215], v[68:71]
	v_mfma_f32_16x16x32_bf16 v[64:67], v[178:181], v[212:215], v[64:67]
	v_mfma_f32_16x16x32_bf16 v[116:119], v[174:177], v[190:193], v[116:119]
	v_mfma_f32_16x16x32_bf16 v[112:115], v[182:185], v[190:193], v[112:115]
	v_mfma_f32_16x16x32_bf16 v[100:103], v[174:177], v[200:203], v[100:103]
	v_mfma_f32_16x16x32_bf16 v[96:99], v[182:185], v[200:203], v[96:99]
	v_mfma_f32_16x16x32_bf16 v[84:87], v[174:177], v[208:211], v[84:87]
	v_mfma_f32_16x16x32_bf16 v[80:83], v[182:185], v[208:211], v[80:83]
	v_mfma_f32_16x16x32_bf16 v[68:71], v[174:177], v[216:219], v[68:71]
	v_mfma_f32_16x16x32_bf16 v[64:67], v[182:185], v[216:219], v[64:67]
	s_setprio 0
	s_barrier
	s_add_i32 s36, s71, s45
	v_lshl_add_u64 v[148:149], v[148:149], 0, s[18:19]
	s_mov_b32 m0, s36
	ds_read_b128 v[186:189], v155 offset:49152
	ds_read_b128 v[190:193], v155 offset:50176
	ds_read_b128 v[196:199], v155 offset:51200
	ds_read_b128 v[200:203], v155 offset:52224
	ds_read_b128 v[204:207], v155 offset:53248
	ds_read_b128 v[208:211], v155 offset:54272
	ds_read_b128 v[212:215], v155 offset:55296
	ds_read_b128 v[216:219], v155 offset:56320
	global_load_lds_dwordx4 v[148:149], off
	s_add_i32 m0, s36, 0x2000
	s_add_u32 s34, s34, 0x40080
	v_lshl_add_u64 v[148:149], v[220:221], 0, s[18:19]
	s_addc_u32 s35, s35, 0
	s_add_i32 s36, s72, s45
	global_load_lds_dwordx4 v[148:149], off
	v_lshl_add_u64 v[148:149], s[34:35], 0, v[130:131]
	s_mov_b32 m0, s36
	s_nop 0
	global_load_lds_dwordx4 v[148:149], off
	v_lshl_add_u64 v[148:149], s[34:35], 0, v[134:135]
	s_add_i32 m0, s36, 0x2000
	s_nop 0
	global_load_lds_dwordx4 v[148:149], off
	s_waitcnt vmcnt(6)
	s_waitcnt lgkmcnt(0)
	s_barrier
	s_setprio 1
	s_waitcnt lgkmcnt(0)
	v_mfma_f32_16x16x32_bf16 v[60:63], v[144:147], v[186:189], v[60:63]
	v_mfma_f32_16x16x32_bf16 v[56:59], v[162:165], v[186:189], v[56:59]
	v_mfma_f32_16x16x32_bf16 v[44:47], v[144:147], v[196:199], v[44:47]
	v_mfma_f32_16x16x32_bf16 v[40:43], v[162:165], v[196:199], v[40:43]
	v_mfma_f32_16x16x32_bf16 v[28:31], v[144:147], v[204:207], v[28:31]
	v_mfma_f32_16x16x32_bf16 v[24:27], v[162:165], v[204:207], v[24:27]
	v_mfma_f32_16x16x32_bf16 v[12:15], v[144:147], v[212:215], v[12:15]
	v_mfma_f32_16x16x32_bf16 v[8:11], v[162:165], v[212:215], v[8:11]
	v_mfma_f32_16x16x32_bf16 v[60:63], v[158:161], v[190:193], v[60:63]
	v_mfma_f32_16x16x32_bf16 v[56:59], v[166:169], v[190:193], v[56:59]
	v_mfma_f32_16x16x32_bf16 v[44:47], v[158:161], v[200:203], v[44:47]
	v_mfma_f32_16x16x32_bf16 v[40:43], v[166:169], v[200:203], v[40:43]
	v_mfma_f32_16x16x32_bf16 v[28:31], v[158:161], v[208:211], v[28:31]
	v_mfma_f32_16x16x32_bf16 v[24:27], v[166:169], v[208:211], v[24:27]
	v_mfma_f32_16x16x32_bf16 v[12:15], v[158:161], v[216:219], v[12:15]
	v_mfma_f32_16x16x32_bf16 v[8:11], v[166:169], v[216:219], v[8:11]
	s_setprio 0
	s_setprio 1
	v_mfma_f32_16x16x32_bf16 v[52:55], v[170:173], v[186:189], v[52:55]
	v_mfma_f32_16x16x32_bf16 v[48:51], v[178:181], v[186:189], v[48:51]
	v_mfma_f32_16x16x32_bf16 v[36:39], v[170:173], v[196:199], v[36:39]
	v_mfma_f32_16x16x32_bf16 v[32:35], v[178:181], v[196:199], v[32:35]
	v_mfma_f32_16x16x32_bf16 v[20:23], v[170:173], v[204:207], v[20:23]
	v_mfma_f32_16x16x32_bf16 v[16:19], v[178:181], v[204:207], v[16:19]
	v_mfma_f32_16x16x32_bf16 v[4:7], v[170:173], v[212:215], v[4:7]
	v_mfma_f32_16x16x32_bf16 v[0:3], v[178:181], v[212:215], v[0:3]
	v_mfma_f32_16x16x32_bf16 v[52:55], v[174:177], v[190:193], v[52:55]
	v_mfma_f32_16x16x32_bf16 v[48:51], v[182:185], v[190:193], v[48:51]
	v_mfma_f32_16x16x32_bf16 v[36:39], v[174:177], v[200:203], v[36:39]
	v_mfma_f32_16x16x32_bf16 v[32:35], v[182:185], v[200:203], v[32:35]
	v_mfma_f32_16x16x32_bf16 v[20:23], v[174:177], v[208:211], v[20:23]
	v_mfma_f32_16x16x32_bf16 v[16:19], v[182:185], v[208:211], v[16:19]
	v_mfma_f32_16x16x32_bf16 v[4:7], v[174:177], v[216:219], v[4:7]
	v_mfma_f32_16x16x32_bf16 v[0:3], v[182:185], v[216:219], v[0:3]
	s_setprio 0
	s_barrier
	v_lshl_add_u64 v[222:223], v[222:223], 0, s[18:19]
	s_mov_b32 m0, s53
	s_nop 0
	global_load_lds_dwordx4 v[222:223], off
	v_lshl_add_u64 v[224:225], v[224:225], 0, s[18:19]
	s_mov_b32 m0, s54
	s_nop 0
	global_load_lds_dwordx4 v[224:225], off
	s_add_i32 s70, s70, 2
	s_add_u32 s30, s30, 0x100
	s_addc_u32 s31, s31, 0
	s_add_u32 s62, s62, 0x100
	s_addc_u32 s63, s63, 0
	s_cmp_gt_u32 s70, 13
	s_cbranch_scc0 .LBB0_2657
	s_and_b64 vcc, exec, s[20:21]
	s_cbranch_vccz .LBB0_2660
	s_barrier

.LBB0_3031:
	ds_read_b128 v[146:149], v155
	ds_read_b128 v[160:163], v155 offset:1024
	ds_read_b128 v[164:167], v155 offset:2048
	ds_read_b128 v[168:171], v155 offset:3072
	ds_read_b128 v[172:175], v156
	ds_read_b128 v[176:179], v156 offset:1024
	ds_read_b128 v[180:183], v156 offset:2048
	ds_read_b128 v[184:187], v156 offset:3072
	s_add_u32 s36, s0, 0xfffc0080
	s_addc_u32 s37, s1, -1
	s_cmp_eq_u32 s60, 12
	s_cselect_b32 s39, s21, s37
	s_cselect_b32 s38, s23, s36
	s_cselect_b32 s37, s27, s59
	s_cselect_b32 s36, s26, s25
	v_lshl_add_u64 v[150:151], s[0:1], 0, v[138:139]
	s_add_i32 m0, s35, 0xc000
	ds_read_b128 v[188:191], v157
	ds_read_b128 v[196:199], v157 offset:1024
	ds_read_b128 v[200:203], v157 offset:2048
	ds_read_b128 v[204:207], v157 offset:3072
	ds_read_b128 v[208:211], v157 offset:4096
	ds_read_b128 v[212:215], v157 offset:5120
	ds_read_b128 v[216:219], v157 offset:6144
	ds_read_b128 v[220:223], v157 offset:7168
	global_load_lds_dwordx4 v[150:151], off
	v_lshl_add_u64 v[150:151], s[0:1], 0, v[140:141]
	s_add_i32 m0, s35, 0xe000
	s_nop 0
	global_load_lds_dwordx4 v[150:151], off
	s_waitcnt vmcnt(8)
	s_waitcnt lgkmcnt(0)
	s_barrier
	s_setprio 1
	s_waitcnt lgkmcnt(0)
	v_mfma_f32_16x16x32_bf16 v[124:127], v[146:149], v[188:191], v[124:127]
	v_mfma_f32_16x16x32_bf16 v[120:123], v[164:167], v[188:191], v[120:123]
	v_mfma_f32_16x16x32_bf16 v[108:111], v[146:149], v[200:203], v[108:111]
	v_mfma_f32_16x16x32_bf16 v[104:107], v[164:167], v[200:203], v[104:107]
	v_mfma_f32_16x16x32_bf16 v[92:95], v[146:149], v[208:211], v[92:95]
	v_mfma_f32_16x16x32_bf16 v[88:91], v[164:167], v[208:211], v[88:91]
	v_mfma_f32_16x16x32_bf16 v[76:79], v[146:149], v[216:219], v[76:79]
	v_mfma_f32_16x16x32_bf16 v[72:75], v[164:167], v[216:219], v[72:75]
	v_mfma_f32_16x16x32_bf16 v[124:127], v[160:163], v[196:199], v[124:127]
	v_mfma_f32_16x16x32_bf16 v[120:123], v[168:171], v[196:199], v[120:123]
	v_mfma_f32_16x16x32_bf16 v[108:111], v[160:163], v[204:207], v[108:111]
	v_mfma_f32_16x16x32_bf16 v[104:107], v[168:171], v[204:207], v[104:107]
	v_mfma_f32_16x16x32_bf16 v[92:95], v[160:163], v[212:215], v[92:95]
	v_mfma_f32_16x16x32_bf16 v[88:91], v[168:171], v[212:215], v[88:91]
	v_mfma_f32_16x16x32_bf16 v[76:79], v[160:163], v[220:223], v[76:79]
	v_mfma_f32_16x16x32_bf16 v[72:75], v[168:171], v[220:223], v[72:75]
	s_setprio 0
	s_setprio 1
	v_mfma_f32_16x16x32_bf16 v[116:119], v[172:175], v[188:191], v[116:119]
	v_mfma_f32_16x16x32_bf16 v[112:115], v[180:183], v[188:191], v[112:115]
	v_mfma_f32_16x16x32_bf16 v[100:103], v[172:175], v[200:203], v[100:103]
	v_mfma_f32_16x16x32_bf16 v[96:99], v[180:183], v[200:203], v[96:99]
	v_mfma_f32_16x16x32_bf16 v[84:87], v[172:175], v[208:211], v[84:87]
	v_mfma_f32_16x16x32_bf16 v[80:83], v[180:183], v[208:211], v[80:83]
	v_mfma_f32_16x16x32_bf16 v[68:71], v[172:175], v[216:219], v[68:71]
	v_mfma_f32_16x16x32_bf16 v[64:67], v[180:183], v[216:219], v[64:67]
	v_mfma_f32_16x16x32_bf16 v[116:119], v[176:179], v[196:199], v[116:119]
	v_mfma_f32_16x16x32_bf16 v[112:115], v[184:187], v[196:199], v[112:115]
	v_mfma_f32_16x16x32_bf16 v[100:103], v[176:179], v[204:207], v[100:103]
	v_mfma_f32_16x16x32_bf16 v[96:99], v[184:187], v[204:207], v[96:99]
	v_mfma_f32_16x16x32_bf16 v[84:87], v[176:179], v[212:215], v[84:87]
	v_mfma_f32_16x16x32_bf16 v[80:83], v[184:187], v[212:215], v[80:83]
	v_mfma_f32_16x16x32_bf16 v[68:71], v[176:179], v[220:223], v[68:71]
	v_mfma_f32_16x16x32_bf16 v[64:67], v[184:187], v[220:223], v[64:67]
	s_setprio 0
	s_barrier
	s_add_i32 s61, s55, s44
	v_lshl_add_u64 v[150:151], s[36:37], 0, v[130:131]
	s_mov_b32 m0, s61
	ds_read_b128 v[188:191], v157 offset:16384
	ds_read_b128 v[196:199], v157 offset:17408
	ds_read_b128 v[200:203], v157 offset:18432
	ds_read_b128 v[204:207], v157 offset:19456
	ds_read_b128 v[208:211], v157 offset:20480
	ds_read_b128 v[212:215], v157 offset:21504
	ds_read_b128 v[216:219], v157 offset:22528
	ds_read_b128 v[220:223], v157 offset:23552
	global_load_lds_dwordx4 v[150:151], off
	s_add_i32 m0, s61, 0x2000
	s_add_u32 s62, s36, 0x40000
	v_lshl_add_u64 v[192:193], s[36:37], 0, v[134:135]
	s_addc_u32 s63, s37, 0
	s_add_i32 s61, s56, s44
	global_load_lds_dwordx4 v[192:193], off
	v_lshl_add_u64 v[224:225], s[62:63], 0, v[130:131]
	s_mov_b32 m0, s61
	v_lshl_add_u64 v[226:227], s[38:39], 0, v[132:133]
	global_load_lds_dwordx4 v[224:225], off
	v_lshl_add_u64 v[224:225], s[62:63], 0, v[134:135]
	s_add_i32 m0, s61, 0x2000
	s_nop 0
	global_load_lds_dwordx4 v[224:225], off
	v_lshl_add_u64 v[224:225], s[38:39], 0, v[128:129]
	s_waitcnt vmcnt(6)
	s_waitcnt lgkmcnt(0)
	s_barrier
	s_setprio 1
	s_waitcnt lgkmcnt(0)
	v_mfma_f32_16x16x32_bf16 v[60:63], v[146:149], v[188:191], v[60:63]
	v_mfma_f32_16x16x32_bf16 v[56:59], v[164:167], v[188:191], v[56:59]
	v_mfma_f32_16x16x32_bf16 v[44:47], v[146:149], v[200:203], v[44:47]
	v_mfma_f32_16x16x32_bf16 v[40:43], v[164:167], v[200:203], v[40:43]
	v_mfma_f32_16x16x32_bf16 v[28:31], v[146:149], v[208:211], v[28:31]
	v_mfma_f32_16x16x32_bf16 v[24:27], v[164:167], v[208:211], v[24:27]
	v_mfma_f32_16x16x32_bf16 v[12:15], v[146:149], v[216:219], v[12:15]
	v_mfma_f32_16x16x32_bf16 v[8:11], v[164:167], v[216:219], v[8:11]
	v_mfma_f32_16x16x32_bf16 v[60:63], v[160:163], v[196:199], v[60:63]
	v_mfma_f32_16x16x32_bf16 v[56:59], v[168:171], v[196:199], v[56:59]
	v_mfma_f32_16x16x32_bf16 v[44:47], v[160:163], v[204:207], v[44:47]
	v_mfma_f32_16x16x32_bf16 v[40:43], v[168:171], v[204:207], v[40:43]
	v_mfma_f32_16x16x32_bf16 v[28:31], v[160:163], v[212:215], v[28:31]
	v_mfma_f32_16x16x32_bf16 v[24:27], v[168:171], v[212:215], v[24:27]
	v_mfma_f32_16x16x32_bf16 v[12:15], v[160:163], v[220:223], v[12:15]
	v_mfma_f32_16x16x32_bf16 v[8:11], v[168:171], v[220:223], v[8:11]
	s_setprio 0
	s_setprio 1
	v_mfma_f32_16x16x32_bf16 v[52:55], v[172:175], v[188:191], v[52:55]
	v_mfma_f32_16x16x32_bf16 v[48:51], v[180:183], v[188:191], v[48:51]
	v_mfma_f32_16x16x32_bf16 v[36:39], v[172:175], v[200:203], v[36:39]
	v_mfma_f32_16x16x32_bf16 v[32:35], v[180:183], v[200:203], v[32:35]
	v_mfma_f32_16x16x32_bf16 v[20:23], v[172:175], v[208:211], v[20:23]
	v_mfma_f32_16x16x32_bf16 v[16:19], v[180:183], v[208:211], v[16:19]
	v_mfma_f32_16x16x32_bf16 v[4:7], v[172:175], v[216:219], v[4:7]
	v_mfma_f32_16x16x32_bf16 v[0:3], v[180:183], v[216:219], v[0:3]
	v_mfma_f32_16x16x32_bf16 v[52:55], v[176:179], v[196:199], v[52:55]
	v_mfma_f32_16x16x32_bf16 v[48:51], v[184:187], v[196:199], v[48:51]
	v_mfma_f32_16x16x32_bf16 v[36:39], v[176:179], v[204:207], v[36:39]
	v_mfma_f32_16x16x32_bf16 v[32:35], v[184:187], v[204:207], v[32:35]
	v_mfma_f32_16x16x32_bf16 v[20:23], v[176:179], v[212:215], v[20:23]
	v_mfma_f32_16x16x32_bf16 v[16:19], v[184:187], v[212:215], v[16:19]
	v_mfma_f32_16x16x32_bf16 v[4:7], v[176:179], v[220:223], v[4:7]
	v_mfma_f32_16x16x32_bf16 v[0:3], v[184:187], v[220:223], v[0:3]
	s_setprio 0
	s_barrier
	s_add_i32 s61, 0, 0x18000
	v_add_u32_e32 v159, s61, v153
	s_add_i32 s62, 0, 0x1c000
	ds_read_b128 v[146:149], v159
	ds_read_b128 v[160:163], v159 offset:1024
	ds_read_b128 v[164:167], v159 offset:2048
	ds_read_b128 v[168:171], v159 offset:3072
	v_add_u32_e32 v159, s62, v153
	ds_read_b128 v[172:175], v159
	ds_read_b128 v[176:179], v159 offset:1024
	ds_read_b128 v[180:183], v159 offset:2048
	ds_read_b128 v[184:187], v159 offset:3072
	s_add_u32 s38, s38, 0x40000
	s_addc_u32 s39, s39, 0
	v_lshl_add_u64 v[228:229], s[38:39], 0, v[128:129]
	ds_read_b128 v[188:191], v157 offset:32768
	ds_read_b128 v[196:199], v157 offset:33792
	ds_read_b128 v[200:203], v157 offset:34816
	ds_read_b128 v[204:207], v157 offset:35840
	ds_read_b128 v[208:211], v157 offset:36864
	ds_read_b128 v[212:215], v157 offset:37888
	ds_read_b128 v[216:219], v157 offset:38912
	ds_read_b128 v[220:223], v157 offset:39936
	s_mov_b32 m0, s35
	s_nop 0
	global_load_lds_dwordx4 v[224:225], off
	s_mov_b32 m0, s45
	s_nop 0
	global_load_lds_dwordx4 v[226:227], off
	s_mov_b32 m0, s48
	s_nop 0
	global_load_lds_dwordx4 v[228:229], off
	v_lshl_add_u64 v[228:229], s[38:39], 0, v[132:133]
	s_mov_b32 m0, s49
	s_nop 0
	global_load_lds_dwordx4 v[228:229], off
	s_waitcnt vmcnt(8)
	s_waitcnt lgkmcnt(0)
	s_barrier
	s_setprio 1
	s_waitcnt lgkmcnt(0)
	v_mfma_f32_16x16x32_bf16 v[124:127], v[146:149], v[188:191], v[124:127]
	v_mfma_f32_16x16x32_bf16 v[120:123], v[164:167], v[188:191], v[120:123]
	v_mfma_f32_16x16x32_bf16 v[108:111], v[146:149], v[200:203], v[108:111]
	v_mfma_f32_16x16x32_bf16 v[104:107], v[164:167], v[200:203], v[104:107]
	v_mfma_f32_16x16x32_bf16 v[92:95], v[146:149], v[208:211], v[92:95]
	v_mfma_f32_16x16x32_bf16 v[88:91], v[164:167], v[208:211], v[88:91]
	v_mfma_f32_16x16x32_bf16 v[76:79], v[146:149], v[216:219], v[76:79]
	v_mfma_f32_16x16x32_bf16 v[72:75], v[164:167], v[216:219], v[72:75]
	v_mfma_f32_16x16x32_bf16 v[124:127], v[160:163], v[196:199], v[124:127]
	v_mfma_f32_16x16x32_bf16 v[120:123], v[168:171], v[196:199], v[120:123]
	v_mfma_f32_16x16x32_bf16 v[108:111], v[160:163], v[204:207], v[108:111]
	v_mfma_f32_16x16x32_bf16 v[104:107], v[168:171], v[204:207], v[104:107]
	v_mfma_f32_16x16x32_bf16 v[92:95], v[160:163], v[212:215], v[92:95]
	v_mfma_f32_16x16x32_bf16 v[88:91], v[168:171], v[212:215], v[88:91]
	v_mfma_f32_16x16x32_bf16 v[76:79], v[160:163], v[220:223], v[76:79]
	v_mfma_f32_16x16x32_bf16 v[72:75], v[168:171], v[220:223], v[72:75]
	s_setprio 0
	s_setprio 1
	v_mfma_f32_16x16x32_bf16 v[116:119], v[172:175], v[188:191], v[116:119]
	v_mfma_f32_16x16x32_bf16 v[112:115], v[180:183], v[188:191], v[112:115]
	v_mfma_f32_16x16x32_bf16 v[100:103], v[172:175], v[200:203], v[100:103]
	v_mfma_f32_16x16x32_bf16 v[96:99], v[180:183], v[200:203], v[96:99]
	v_mfma_f32_16x16x32_bf16 v[84:87], v[172:175], v[208:211], v[84:87]
	v_mfma_f32_16x16x32_bf16 v[80:83], v[180:183], v[208:211], v[80:83]
	v_mfma_f32_16x16x32_bf16 v[68:71], v[172:175], v[216:219], v[68:71]
	v_mfma_f32_16x16x32_bf16 v[64:67], v[180:183], v[216:219], v[64:67]
	v_mfma_f32_16x16x32_bf16 v[116:119], v[176:179], v[196:199], v[116:119]
	v_mfma_f32_16x16x32_bf16 v[112:115], v[184:187], v[196:199], v[112:115]
	v_mfma_f32_16x16x32_bf16 v[100:103], v[176:179], v[204:207], v[100:103]
	v_mfma_f32_16x16x32_bf16 v[96:99], v[184:187], v[204:207], v[96:99]
	v_mfma_f32_16x16x32_bf16 v[84:87], v[176:179], v[212:215], v[84:87]
	v_mfma_f32_16x16x32_bf16 v[80:83], v[184:187], v[212:215], v[80:83]
	v_mfma_f32_16x16x32_bf16 v[68:71], v[176:179], v[220:223], v[68:71]
	v_mfma_f32_16x16x32_bf16 v[64:67], v[184:187], v[220:223], v[64:67]
	s_setprio 0
	s_barrier
	s_add_i32 s38, s61, s44
	v_lshl_add_u64 v[150:151], v[150:151], 0, s[16:17]
	s_mov_b32 m0, s38
	ds_read_b128 v[188:191], v157 offset:49152
	ds_read_b128 v[196:199], v157 offset:50176
	ds_read_b128 v[200:203], v157 offset:51200
	ds_read_b128 v[204:207], v157 offset:52224
	ds_read_b128 v[208:211], v157 offset:53248
	ds_read_b128 v[212:215], v157 offset:54272
	ds_read_b128 v[216:219], v157 offset:55296
	ds_read_b128 v[220:223], v157 offset:56320
	global_load_lds_dwordx4 v[150:151], off
	s_add_i32 m0, s38, 0x2000
	s_add_u32 s36, s36, 0x40080
	v_lshl_add_u64 v[150:151], v[192:193], 0, s[16:17]
	s_addc_u32 s37, s37, 0
	s_add_i32 s38, s62, s44
	global_load_lds_dwordx4 v[150:151], off
	v_lshl_add_u64 v[150:151], s[36:37], 0, v[130:131]
	s_mov_b32 m0, s38
	s_nop 0
	global_load_lds_dwordx4 v[150:151], off
	v_lshl_add_u64 v[150:151], s[36:37], 0, v[134:135]
	s_add_i32 m0, s38, 0x2000
	s_nop 0
	global_load_lds_dwordx4 v[150:151], off
	s_waitcnt vmcnt(6)
	s_waitcnt lgkmcnt(0)
	s_barrier
	s_setprio 1
	s_waitcnt lgkmcnt(0)
	v_mfma_f32_16x16x32_bf16 v[60:63], v[146:149], v[188:191], v[60:63]
	v_mfma_f32_16x16x32_bf16 v[56:59], v[164:167], v[188:191], v[56:59]
	v_mfma_f32_16x16x32_bf16 v[44:47], v[146:149], v[200:203], v[44:47]
	v_mfma_f32_16x16x32_bf16 v[40:43], v[164:167], v[200:203], v[40:43]
	v_mfma_f32_16x16x32_bf16 v[28:31], v[146:149], v[208:211], v[28:31]
	v_mfma_f32_16x16x32_bf16 v[24:27], v[164:167], v[208:211], v[24:27]
	v_mfma_f32_16x16x32_bf16 v[12:15], v[146:149], v[216:219], v[12:15]
	v_mfma_f32_16x16x32_bf16 v[8:11], v[164:167], v[216:219], v[8:11]
	v_mfma_f32_16x16x32_bf16 v[60:63], v[160:163], v[196:199], v[60:63]
	v_mfma_f32_16x16x32_bf16 v[56:59], v[168:171], v[196:199], v[56:59]
	v_mfma_f32_16x16x32_bf16 v[44:47], v[160:163], v[204:207], v[44:47]
	v_mfma_f32_16x16x32_bf16 v[40:43], v[168:171], v[204:207], v[40:43]
	v_mfma_f32_16x16x32_bf16 v[28:31], v[160:163], v[212:215], v[28:31]
	v_mfma_f32_16x16x32_bf16 v[24:27], v[168:171], v[212:215], v[24:27]
	v_mfma_f32_16x16x32_bf16 v[12:15], v[160:163], v[220:223], v[12:15]
	v_mfma_f32_16x16x32_bf16 v[8:11], v[168:171], v[220:223], v[8:11]
	s_setprio 0
	s_setprio 1
	v_mfma_f32_16x16x32_bf16 v[52:55], v[172:175], v[188:191], v[52:55]
	v_mfma_f32_16x16x32_bf16 v[48:51], v[180:183], v[188:191], v[48:51]
	v_mfma_f32_16x16x32_bf16 v[36:39], v[172:175], v[200:203], v[36:39]
	v_mfma_f32_16x16x32_bf16 v[32:35], v[180:183], v[200:203], v[32:35]
	v_mfma_f32_16x16x32_bf16 v[20:23], v[172:175], v[208:211], v[20:23]
	v_mfma_f32_16x16x32_bf16 v[16:19], v[180:183], v[208:211], v[16:19]
	v_mfma_f32_16x16x32_bf16 v[4:7], v[172:175], v[216:219], v[4:7]
	v_mfma_f32_16x16x32_bf16 v[0:3], v[180:183], v[216:219], v[0:3]
	v_mfma_f32_16x16x32_bf16 v[52:55], v[176:179], v[196:199], v[52:55]
	v_mfma_f32_16x16x32_bf16 v[48:51], v[184:187], v[196:199], v[48:51]
	v_mfma_f32_16x16x32_bf16 v[36:39], v[176:179], v[204:207], v[36:39]
	v_mfma_f32_16x16x32_bf16 v[32:35], v[184:187], v[204:207], v[32:35]
	v_mfma_f32_16x16x32_bf16 v[20:23], v[176:179], v[212:215], v[20:23]
	v_mfma_f32_16x16x32_bf16 v[16:19], v[184:187], v[212:215], v[16:19]
	v_mfma_f32_16x16x32_bf16 v[4:7], v[176:179], v[220:223], v[4:7]
	v_mfma_f32_16x16x32_bf16 v[0:3], v[184:187], v[220:223], v[0:3]
	s_setprio 0
	s_barrier
	v_lshl_add_u64 v[224:225], v[224:225], 0, s[16:17]
	s_mov_b32 m0, s50
	s_nop 0
	global_load_lds_dwordx4 v[224:225], off
	v_lshl_add_u64 v[226:227], v[226:227], 0, s[16:17]
	s_mov_b32 m0, s51
	s_nop 0
	global_load_lds_dwordx4 v[226:227], off
	s_add_i32 s60, s60, 2
	s_add_u32 s0, s0, 0x100
	s_addc_u32 s1, s1, 0
	s_add_u32 s25, s25, 0x100
	s_addc_u32 s59, s59, 0
	s_cmp_gt_u32 s60, 13
	s_cbranch_scc0 .LBB0_3031
	s_and_b64 vcc, exec, s[18:19]
	s_cbranch_vccz .LBB0_3034
	s_barrier

.LBB0_3061:
	ds_read_b128 v[144:147], v159
	ds_read_b128 v[148:151], v159 offset:1024
	ds_read_b128 v[152:155], v159 offset:2048
	ds_read_b128 v[162:165], v159 offset:3072
	ds_read_b128 v[166:169], v160
	ds_read_b128 v[170:173], v160 offset:1024
	ds_read_b128 v[174:177], v160 offset:2048
	ds_read_b128 v[178:181], v160 offset:3072
	s_add_u32 s37, s42, 0xfffe0080
	s_addc_u32 s39, s43, -1
	s_cmp_eq_u32 s35, 4
	s_cselect_b32 s51, s1, s39
	s_cselect_b32 s50, s0, s37
	s_cselect_b32 s49, s41, s13
	s_cselect_b32 s48, s40, s11
	v_lshl_add_u64 v[216:217], s[42:43], 0, v[136:137]
	s_add_i32 m0, s60, 0xc000
	ds_read_b128 v[182:185], v161
	ds_read_b128 v[186:189], v161 offset:1024
	ds_read_b128 v[190:193], v161 offset:2048
	ds_read_b128 v[196:199], v161 offset:3072
	ds_read_b128 v[200:203], v161 offset:4096
	ds_read_b128 v[204:207], v161 offset:5120
	ds_read_b128 v[208:211], v161 offset:6144
	ds_read_b128 v[212:215], v161 offset:7168
	global_load_lds_dwordx4 v[216:217], off
	v_lshl_add_u64 v[216:217], s[42:43], 0, v[138:139]
	s_add_i32 m0, s60, 0xe000
	s_nop 0
	global_load_lds_dwordx4 v[216:217], off
	s_waitcnt vmcnt(8)
	s_waitcnt lgkmcnt(0)
	s_barrier
	s_setprio 1
	s_waitcnt lgkmcnt(0)
	v_mfma_f32_16x16x32_bf16 v[124:127], v[144:147], v[182:185], v[124:127]
	v_mfma_f32_16x16x32_bf16 v[120:123], v[152:155], v[182:185], v[120:123]
	v_mfma_f32_16x16x32_bf16 v[108:111], v[144:147], v[190:193], v[108:111]
	v_mfma_f32_16x16x32_bf16 v[104:107], v[152:155], v[190:193], v[104:107]
	v_mfma_f32_16x16x32_bf16 v[92:95], v[144:147], v[200:203], v[92:95]
	v_mfma_f32_16x16x32_bf16 v[88:91], v[152:155], v[200:203], v[88:91]
	v_mfma_f32_16x16x32_bf16 v[76:79], v[144:147], v[208:211], v[76:79]
	v_mfma_f32_16x16x32_bf16 v[72:75], v[152:155], v[208:211], v[72:75]
	v_mfma_f32_16x16x32_bf16 v[124:127], v[148:151], v[186:189], v[124:127]
	v_mfma_f32_16x16x32_bf16 v[120:123], v[162:165], v[186:189], v[120:123]
	v_mfma_f32_16x16x32_bf16 v[108:111], v[148:151], v[196:199], v[108:111]
	v_mfma_f32_16x16x32_bf16 v[104:107], v[162:165], v[196:199], v[104:107]
	v_mfma_f32_16x16x32_bf16 v[92:95], v[148:151], v[204:207], v[92:95]
	v_mfma_f32_16x16x32_bf16 v[88:91], v[162:165], v[204:207], v[88:91]
	v_mfma_f32_16x16x32_bf16 v[76:79], v[148:151], v[212:215], v[76:79]
	v_mfma_f32_16x16x32_bf16 v[72:75], v[162:165], v[212:215], v[72:75]
	s_setprio 0
	s_setprio 1
	v_mfma_f32_16x16x32_bf16 v[116:119], v[166:169], v[182:185], v[116:119]
	v_mfma_f32_16x16x32_bf16 v[112:115], v[174:177], v[182:185], v[112:115]
	v_mfma_f32_16x16x32_bf16 v[100:103], v[166:169], v[190:193], v[100:103]
	v_mfma_f32_16x16x32_bf16 v[96:99], v[174:177], v[190:193], v[96:99]
	v_mfma_f32_16x16x32_bf16 v[84:87], v[166:169], v[200:203], v[84:87]
	v_mfma_f32_16x16x32_bf16 v[80:83], v[174:177], v[200:203], v[80:83]
	v_mfma_f32_16x16x32_bf16 v[68:71], v[166:169], v[208:211], v[68:71]
	v_mfma_f32_16x16x32_bf16 v[64:67], v[174:177], v[208:211], v[64:67]
	v_mfma_f32_16x16x32_bf16 v[116:119], v[170:173], v[186:189], v[116:119]
	v_mfma_f32_16x16x32_bf16 v[112:115], v[178:181], v[186:189], v[112:115]
	v_mfma_f32_16x16x32_bf16 v[100:103], v[170:173], v[196:199], v[100:103]
	v_mfma_f32_16x16x32_bf16 v[96:99], v[178:181], v[196:199], v[96:99]
	v_mfma_f32_16x16x32_bf16 v[84:87], v[170:173], v[204:207], v[84:87]
	v_mfma_f32_16x16x32_bf16 v[80:83], v[178:181], v[204:207], v[80:83]
	v_mfma_f32_16x16x32_bf16 v[68:71], v[170:173], v[212:215], v[68:71]
	v_mfma_f32_16x16x32_bf16 v[64:67], v[178:181], v[212:215], v[64:67]
	s_setprio 0
	s_barrier
	s_add_i32 s37, s73, s57
	v_lshl_add_u64 v[216:217], s[48:49], 0, v[130:131]
	s_mov_b32 m0, s37
	ds_read_b128 v[182:185], v161 offset:16384
	ds_read_b128 v[186:189], v161 offset:17408
	ds_read_b128 v[190:193], v161 offset:18432
	ds_read_b128 v[196:199], v161 offset:19456
	ds_read_b128 v[200:203], v161 offset:20480
	ds_read_b128 v[204:207], v161 offset:21504
	ds_read_b128 v[208:211], v161 offset:22528
	ds_read_b128 v[212:215], v161 offset:23552
	global_load_lds_dwordx4 v[216:217], off
	s_add_i32 m0, s37, 0x2000
	s_add_u32 s80, s48, 0x20000
	v_lshl_add_u64 v[218:219], s[48:49], 0, v[134:135]
	s_addc_u32 s81, s49, 0
	s_add_i32 s37, s77, s57
	global_load_lds_dwordx4 v[218:219], off
	v_lshl_add_u64 v[220:221], s[80:81], 0, v[130:131]
	s_mov_b32 m0, s37
	v_lshl_add_u64 v[222:223], s[50:51], 0, v[132:133]
	global_load_lds_dwordx4 v[220:221], off
	v_lshl_add_u64 v[220:221], s[80:81], 0, v[134:135]
	s_add_i32 m0, s37, 0x2000
	s_nop 0
	global_load_lds_dwordx4 v[220:221], off
	v_lshl_add_u64 v[220:221], s[50:51], 0, v[128:129]
	s_waitcnt vmcnt(6)
	s_waitcnt lgkmcnt(0)
	s_barrier
	s_setprio 1
	s_waitcnt lgkmcnt(0)
	v_mfma_f32_16x16x32_bf16 v[60:63], v[144:147], v[182:185], v[60:63]
	v_mfma_f32_16x16x32_bf16 v[56:59], v[152:155], v[182:185], v[56:59]
	v_mfma_f32_16x16x32_bf16 v[44:47], v[144:147], v[190:193], v[44:47]
	v_mfma_f32_16x16x32_bf16 v[40:43], v[152:155], v[190:193], v[40:43]
	v_mfma_f32_16x16x32_bf16 v[28:31], v[144:147], v[200:203], v[28:31]
	v_mfma_f32_16x16x32_bf16 v[24:27], v[152:155], v[200:203], v[24:27]
	v_mfma_f32_16x16x32_bf16 v[12:15], v[144:147], v[208:211], v[12:15]
	v_mfma_f32_16x16x32_bf16 v[8:11], v[152:155], v[208:211], v[8:11]
	v_mfma_f32_16x16x32_bf16 v[60:63], v[148:151], v[186:189], v[60:63]
	v_mfma_f32_16x16x32_bf16 v[56:59], v[162:165], v[186:189], v[56:59]
	v_mfma_f32_16x16x32_bf16 v[44:47], v[148:151], v[196:199], v[44:47]
	v_mfma_f32_16x16x32_bf16 v[40:43], v[162:165], v[196:199], v[40:43]
	v_mfma_f32_16x16x32_bf16 v[28:31], v[148:151], v[204:207], v[28:31]
	v_mfma_f32_16x16x32_bf16 v[24:27], v[162:165], v[204:207], v[24:27]
	v_mfma_f32_16x16x32_bf16 v[12:15], v[148:151], v[212:215], v[12:15]
	v_mfma_f32_16x16x32_bf16 v[8:11], v[162:165], v[212:215], v[8:11]
	s_setprio 0
	s_setprio 1
	v_mfma_f32_16x16x32_bf16 v[52:55], v[166:169], v[182:185], v[52:55]
	v_mfma_f32_16x16x32_bf16 v[48:51], v[174:177], v[182:185], v[48:51]
	v_mfma_f32_16x16x32_bf16 v[36:39], v[166:169], v[190:193], v[36:39]
	v_mfma_f32_16x16x32_bf16 v[32:35], v[174:177], v[190:193], v[32:35]
	v_mfma_f32_16x16x32_bf16 v[20:23], v[166:169], v[200:203], v[20:23]
	v_mfma_f32_16x16x32_bf16 v[16:19], v[174:177], v[200:203], v[16:19]
	v_mfma_f32_16x16x32_bf16 v[4:7], v[166:169], v[208:211], v[4:7]
	v_mfma_f32_16x16x32_bf16 v[0:3], v[174:177], v[208:211], v[0:3]
	v_mfma_f32_16x16x32_bf16 v[52:55], v[170:173], v[186:189], v[52:55]
	v_mfma_f32_16x16x32_bf16 v[48:51], v[178:181], v[186:189], v[48:51]
	v_mfma_f32_16x16x32_bf16 v[36:39], v[170:173], v[196:199], v[36:39]
	v_mfma_f32_16x16x32_bf16 v[32:35], v[178:181], v[196:199], v[32:35]
	v_mfma_f32_16x16x32_bf16 v[20:23], v[170:173], v[204:207], v[20:23]
	v_mfma_f32_16x16x32_bf16 v[16:19], v[178:181], v[204:207], v[16:19]
	v_mfma_f32_16x16x32_bf16 v[4:7], v[170:173], v[212:215], v[4:7]
	v_mfma_f32_16x16x32_bf16 v[0:3], v[178:181], v[212:215], v[0:3]
	s_setprio 0
	s_barrier
	s_add_i32 s37, 0, 0x18000
	s_add_i32 s39, 0, 0x1c000
	v_add_u32_e32 v162, s37, v157
	v_add_u32_e32 v178, s39, v157
	ds_read_b128 v[144:147], v162
	ds_read_b128 v[148:151], v162 offset:1024
	ds_read_b128 v[152:155], v162 offset:2048
	ds_read_b128 v[162:165], v162 offset:3072
	ds_read_b128 v[166:169], v178
	ds_read_b128 v[170:173], v178 offset:1024
	ds_read_b128 v[174:177], v178 offset:2048
	ds_read_b128 v[178:181], v178 offset:3072
	s_add_u32 s50, s50, 0x20000
	s_addc_u32 s51, s51, 0
	v_lshl_add_u64 v[224:225], s[50:51], 0, v[128:129]
	ds_read_b128 v[182:185], v161 offset:32768
	ds_read_b128 v[186:189], v161 offset:33792
	ds_read_b128 v[190:193], v161 offset:34816
	ds_read_b128 v[196:199], v161 offset:35840
	ds_read_b128 v[200:203], v161 offset:36864
	ds_read_b128 v[204:207], v161 offset:37888
	ds_read_b128 v[208:211], v161 offset:38912
	ds_read_b128 v[212:215], v161 offset:39936
	s_mov_b32 m0, s60
	s_nop 0
	global_load_lds_dwordx4 v[220:221], off
	s_mov_b32 m0, s61
	s_nop 0
	global_load_lds_dwordx4 v[222:223], off
	s_mov_b32 m0, s62
	s_nop 0
	global_load_lds_dwordx4 v[224:225], off
	v_lshl_add_u64 v[224:225], s[50:51], 0, v[132:133]
	s_mov_b32 m0, s63
	s_nop 0
	global_load_lds_dwordx4 v[224:225], off
	s_waitcnt vmcnt(8)
	s_waitcnt lgkmcnt(0)
	s_barrier
	s_setprio 1
	s_waitcnt lgkmcnt(0)
	v_mfma_f32_16x16x32_bf16 v[124:127], v[144:147], v[182:185], v[124:127]
	v_mfma_f32_16x16x32_bf16 v[120:123], v[152:155], v[182:185], v[120:123]
	v_mfma_f32_16x16x32_bf16 v[108:111], v[144:147], v[190:193], v[108:111]
	v_mfma_f32_16x16x32_bf16 v[104:107], v[152:155], v[190:193], v[104:107]
	v_mfma_f32_16x16x32_bf16 v[92:95], v[144:147], v[200:203], v[92:95]
	v_mfma_f32_16x16x32_bf16 v[88:91], v[152:155], v[200:203], v[88:91]
	v_mfma_f32_16x16x32_bf16 v[76:79], v[144:147], v[208:211], v[76:79]
	v_mfma_f32_16x16x32_bf16 v[72:75], v[152:155], v[208:211], v[72:75]
	v_mfma_f32_16x16x32_bf16 v[124:127], v[148:151], v[186:189], v[124:127]
	v_mfma_f32_16x16x32_bf16 v[120:123], v[162:165], v[186:189], v[120:123]
	v_mfma_f32_16x16x32_bf16 v[108:111], v[148:151], v[196:199], v[108:111]
	v_mfma_f32_16x16x32_bf16 v[104:107], v[162:165], v[196:199], v[104:107]
	v_mfma_f32_16x16x32_bf16 v[92:95], v[148:151], v[204:207], v[92:95]
	v_mfma_f32_16x16x32_bf16 v[88:91], v[162:165], v[204:207], v[88:91]
	v_mfma_f32_16x16x32_bf16 v[76:79], v[148:151], v[212:215], v[76:79]
	v_mfma_f32_16x16x32_bf16 v[72:75], v[162:165], v[212:215], v[72:75]
	s_setprio 0
	s_setprio 1
	v_mfma_f32_16x16x32_bf16 v[116:119], v[166:169], v[182:185], v[116:119]
	v_mfma_f32_16x16x32_bf16 v[112:115], v[174:177], v[182:185], v[112:115]
	v_mfma_f32_16x16x32_bf16 v[100:103], v[166:169], v[190:193], v[100:103]
	v_mfma_f32_16x16x32_bf16 v[96:99], v[174:177], v[190:193], v[96:99]
	v_mfma_f32_16x16x32_bf16 v[84:87], v[166:169], v[200:203], v[84:87]
	v_mfma_f32_16x16x32_bf16 v[80:83], v[174:177], v[200:203], v[80:83]
	v_mfma_f32_16x16x32_bf16 v[68:71], v[166:169], v[208:211], v[68:71]
	v_mfma_f32_16x16x32_bf16 v[64:67], v[174:177], v[208:211], v[64:67]
	v_mfma_f32_16x16x32_bf16 v[116:119], v[170:173], v[186:189], v[116:119]
	v_mfma_f32_16x16x32_bf16 v[112:115], v[178:181], v[186:189], v[112:115]
	v_mfma_f32_16x16x32_bf16 v[100:103], v[170:173], v[196:199], v[100:103]
	v_mfma_f32_16x16x32_bf16 v[96:99], v[178:181], v[196:199], v[96:99]
	v_mfma_f32_16x16x32_bf16 v[84:87], v[170:173], v[204:207], v[84:87]
	v_mfma_f32_16x16x32_bf16 v[80:83], v[178:181], v[204:207], v[80:83]
	v_mfma_f32_16x16x32_bf16 v[68:71], v[170:173], v[212:215], v[68:71]
	v_mfma_f32_16x16x32_bf16 v[64:67], v[178:181], v[212:215], v[64:67]
	s_setprio 0
	s_barrier
	s_add_i32 s37, s37, s57
	v_lshl_add_u64 v[216:217], v[216:217], 0, s[22:23]
	s_mov_b32 m0, s37
	ds_read_b128 v[182:185], v161 offset:49152
	ds_read_b128 v[186:189], v161 offset:50176
	ds_read_b128 v[190:193], v161 offset:51200
	ds_read_b128 v[196:199], v161 offset:52224
	ds_read_b128 v[200:203], v161 offset:53248
	ds_read_b128 v[204:207], v161 offset:54272
	ds_read_b128 v[208:211], v161 offset:55296
	ds_read_b128 v[212:215], v161 offset:56320
	global_load_lds_dwordx4 v[216:217], off
	s_add_i32 m0, s37, 0x2000
	s_add_u32 s48, s48, 0x20080
	v_lshl_add_u64 v[216:217], v[218:219], 0, s[22:23]
	s_addc_u32 s49, s49, 0
	s_add_i32 s37, s39, s57
	global_load_lds_dwordx4 v[216:217], off
	v_lshl_add_u64 v[216:217], s[48:49], 0, v[130:131]
	s_mov_b32 m0, s37
	s_nop 0
	global_load_lds_dwordx4 v[216:217], off
	v_lshl_add_u64 v[216:217], s[48:49], 0, v[134:135]
	s_add_i32 m0, s37, 0x2000
	s_nop 0
	global_load_lds_dwordx4 v[216:217], off
	s_waitcnt vmcnt(6)
	s_waitcnt lgkmcnt(0)
	s_barrier
	s_setprio 1
	s_waitcnt lgkmcnt(0)
	v_mfma_f32_16x16x32_bf16 v[60:63], v[144:147], v[182:185], v[60:63]
	v_mfma_f32_16x16x32_bf16 v[56:59], v[152:155], v[182:185], v[56:59]
	v_mfma_f32_16x16x32_bf16 v[44:47], v[144:147], v[190:193], v[44:47]
	v_mfma_f32_16x16x32_bf16 v[40:43], v[152:155], v[190:193], v[40:43]
	v_mfma_f32_16x16x32_bf16 v[28:31], v[144:147], v[200:203], v[28:31]
	v_mfma_f32_16x16x32_bf16 v[24:27], v[152:155], v[200:203], v[24:27]
	v_mfma_f32_16x16x32_bf16 v[12:15], v[144:147], v[208:211], v[12:15]
	v_mfma_f32_16x16x32_bf16 v[8:11], v[152:155], v[208:211], v[8:11]
	v_mfma_f32_16x16x32_bf16 v[60:63], v[148:151], v[186:189], v[60:63]
	v_mfma_f32_16x16x32_bf16 v[56:59], v[162:165], v[186:189], v[56:59]
	v_mfma_f32_16x16x32_bf16 v[44:47], v[148:151], v[196:199], v[44:47]
	v_mfma_f32_16x16x32_bf16 v[40:43], v[162:165], v[196:199], v[40:43]
	v_mfma_f32_16x16x32_bf16 v[28:31], v[148:151], v[204:207], v[28:31]
	v_mfma_f32_16x16x32_bf16 v[24:27], v[162:165], v[204:207], v[24:27]
	v_mfma_f32_16x16x32_bf16 v[12:15], v[148:151], v[212:215], v[12:15]
	v_mfma_f32_16x16x32_bf16 v[8:11], v[162:165], v[212:215], v[8:11]
	s_setprio 0
	s_setprio 1
	v_mfma_f32_16x16x32_bf16 v[52:55], v[166:169], v[182:185], v[52:55]
	v_mfma_f32_16x16x32_bf16 v[48:51], v[174:177], v[182:185], v[48:51]
	v_mfma_f32_16x16x32_bf16 v[36:39], v[166:169], v[190:193], v[36:39]
	v_mfma_f32_16x16x32_bf16 v[32:35], v[174:177], v[190:193], v[32:35]
	v_mfma_f32_16x16x32_bf16 v[20:23], v[166:169], v[200:203], v[20:23]
	v_mfma_f32_16x16x32_bf16 v[16:19], v[174:177], v[200:203], v[16:19]
	v_mfma_f32_16x16x32_bf16 v[4:7], v[166:169], v[208:211], v[4:7]
	v_mfma_f32_16x16x32_bf16 v[0:3], v[174:177], v[208:211], v[0:3]
	v_mfma_f32_16x16x32_bf16 v[52:55], v[170:173], v[186:189], v[52:55]
	v_mfma_f32_16x16x32_bf16 v[48:51], v[178:181], v[186:189], v[48:51]
	v_mfma_f32_16x16x32_bf16 v[36:39], v[170:173], v[196:199], v[36:39]
	v_mfma_f32_16x16x32_bf16 v[32:35], v[178:181], v[196:199], v[32:35]
	v_mfma_f32_16x16x32_bf16 v[20:23], v[170:173], v[204:207], v[20:23]
	v_mfma_f32_16x16x32_bf16 v[16:19], v[178:181], v[204:207], v[16:19]
	v_mfma_f32_16x16x32_bf16 v[4:7], v[170:173], v[212:215], v[4:7]
	v_mfma_f32_16x16x32_bf16 v[0:3], v[178:181], v[212:215], v[0:3]
	s_setprio 0
	s_barrier
	v_lshl_add_u64 v[220:221], v[220:221], 0, s[22:23]
	s_mov_b32 m0, s70
	s_nop 0
	global_load_lds_dwordx4 v[220:221], off
	v_lshl_add_u64 v[222:223], v[222:223], 0, s[22:23]
	s_mov_b32 m0, s71
	s_nop 0
	global_load_lds_dwordx4 v[222:223], off
	s_add_i32 s35, s35, 2
	s_add_u32 s42, s42, 0x100
	s_addc_u32 s43, s43, 0
	s_add_u32 s11, s11, 0x100
	s_addc_u32 s13, s13, 0
	s_cmp_gt_u32 s35, 5
	s_cbranch_scc0 .LBB0_3061
	s_and_b64 vcc, exec, s[24:25]
	s_cbranch_vccz .LBB0_3064
	s_barrier

.LBB0_3235:
	ds_read_b128 v[144:147], v151
	ds_read_b128 v[156:159], v151 offset:1024
	ds_read_b128 v[160:163], v151 offset:2048
	ds_read_b128 v[164:167], v151 offset:3072
	ds_read_b128 v[168:171], v152
	ds_read_b128 v[172:175], v152 offset:1024
	ds_read_b128 v[176:179], v152 offset:2048
	ds_read_b128 v[180:183], v152 offset:3072
	s_add_u32 s38, s36, 0xfffc0080
	s_addc_u32 s39, s37, -1
	s_cmp_eq_u32 s70, 12
	s_cselect_b32 s41, s27, s39
	s_cselect_b32 s40, s35, s38
	s_cselect_b32 s39, s25, s63
	s_cselect_b32 s38, s61, s62
	v_lshl_add_u64 v[192:193], s[36:37], 0, v[136:137]
	s_add_i32 m0, s50, 0xc000
	ds_read_b128 v[184:187], v153
	ds_read_b128 v[188:191], v153 offset:1024
	ds_read_b128 v[196:199], v153 offset:2048
	ds_read_b128 v[200:203], v153 offset:3072
	ds_read_b128 v[204:207], v153 offset:4096
	ds_read_b128 v[208:211], v153 offset:5120
	ds_read_b128 v[212:215], v153 offset:6144
	ds_read_b128 v[216:219], v153 offset:7168
	global_load_lds_dwordx4 v[192:193], off
	v_lshl_add_u64 v[192:193], s[36:37], 0, v[138:139]
	s_add_i32 m0, s50, 0xe000
	s_nop 0
	global_load_lds_dwordx4 v[192:193], off
	s_waitcnt vmcnt(8)
	s_waitcnt lgkmcnt(0)
	s_barrier
	s_setprio 1
	s_waitcnt lgkmcnt(0)
	v_mfma_f32_16x16x32_bf16 v[124:127], v[144:147], v[184:187], v[124:127]
	v_mfma_f32_16x16x32_bf16 v[120:123], v[160:163], v[184:187], v[120:123]
	v_mfma_f32_16x16x32_bf16 v[108:111], v[144:147], v[196:199], v[108:111]
	v_mfma_f32_16x16x32_bf16 v[104:107], v[160:163], v[196:199], v[104:107]
	v_mfma_f32_16x16x32_bf16 v[92:95], v[144:147], v[204:207], v[92:95]
	v_mfma_f32_16x16x32_bf16 v[88:91], v[160:163], v[204:207], v[88:91]
	v_mfma_f32_16x16x32_bf16 v[76:79], v[144:147], v[212:215], v[76:79]
	v_mfma_f32_16x16x32_bf16 v[72:75], v[160:163], v[212:215], v[72:75]
	v_mfma_f32_16x16x32_bf16 v[124:127], v[156:159], v[188:191], v[124:127]
	v_mfma_f32_16x16x32_bf16 v[120:123], v[164:167], v[188:191], v[120:123]
	v_mfma_f32_16x16x32_bf16 v[108:111], v[156:159], v[200:203], v[108:111]
	v_mfma_f32_16x16x32_bf16 v[104:107], v[164:167], v[200:203], v[104:107]
	v_mfma_f32_16x16x32_bf16 v[92:95], v[156:159], v[208:211], v[92:95]
	v_mfma_f32_16x16x32_bf16 v[88:91], v[164:167], v[208:211], v[88:91]
	v_mfma_f32_16x16x32_bf16 v[76:79], v[156:159], v[216:219], v[76:79]
	v_mfma_f32_16x16x32_bf16 v[72:75], v[164:167], v[216:219], v[72:75]
	s_setprio 0
	s_setprio 1
	v_mfma_f32_16x16x32_bf16 v[116:119], v[168:171], v[184:187], v[116:119]
	v_mfma_f32_16x16x32_bf16 v[112:115], v[176:179], v[184:187], v[112:115]
	v_mfma_f32_16x16x32_bf16 v[100:103], v[168:171], v[196:199], v[100:103]
	v_mfma_f32_16x16x32_bf16 v[96:99], v[176:179], v[196:199], v[96:99]
	v_mfma_f32_16x16x32_bf16 v[84:87], v[168:171], v[204:207], v[84:87]
	v_mfma_f32_16x16x32_bf16 v[80:83], v[176:179], v[204:207], v[80:83]
	v_mfma_f32_16x16x32_bf16 v[68:71], v[168:171], v[212:215], v[68:71]
	v_mfma_f32_16x16x32_bf16 v[64:67], v[176:179], v[212:215], v[64:67]
	v_mfma_f32_16x16x32_bf16 v[116:119], v[172:175], v[188:191], v[116:119]
	v_mfma_f32_16x16x32_bf16 v[112:115], v[180:183], v[188:191], v[112:115]
	v_mfma_f32_16x16x32_bf16 v[100:103], v[172:175], v[200:203], v[100:103]
	v_mfma_f32_16x16x32_bf16 v[96:99], v[180:183], v[200:203], v[96:99]
	v_mfma_f32_16x16x32_bf16 v[84:87], v[172:175], v[208:211], v[84:87]
	v_mfma_f32_16x16x32_bf16 v[80:83], v[180:183], v[208:211], v[80:83]
	v_mfma_f32_16x16x32_bf16 v[68:71], v[172:175], v[216:219], v[68:71]
	v_mfma_f32_16x16x32_bf16 v[64:67], v[180:183], v[216:219], v[64:67]
	s_setprio 0
	s_barrier
	s_add_i32 s71, s58, s49
	v_lshl_add_u64 v[192:193], s[38:39], 0, v[130:131]
	s_mov_b32 m0, s71
	ds_read_b128 v[184:187], v153 offset:16384
	ds_read_b128 v[188:191], v153 offset:17408
	ds_read_b128 v[196:199], v153 offset:18432
	ds_read_b128 v[200:203], v153 offset:19456
	ds_read_b128 v[204:207], v153 offset:20480
	ds_read_b128 v[208:211], v153 offset:21504
	ds_read_b128 v[212:215], v153 offset:22528
	ds_read_b128 v[216:219], v153 offset:23552
	global_load_lds_dwordx4 v[192:193], off
	s_add_i32 m0, s71, 0x2000
	s_add_u32 s72, s38, 0x40000
	v_lshl_add_u64 v[220:221], s[38:39], 0, v[134:135]
	s_addc_u32 s73, s39, 0
	s_add_i32 s71, s59, s49
	global_load_lds_dwordx4 v[220:221], off
	v_lshl_add_u64 v[222:223], s[72:73], 0, v[130:131]
	s_mov_b32 m0, s71
	v_lshl_add_u64 v[224:225], s[40:41], 0, v[132:133]
	global_load_lds_dwordx4 v[222:223], off
	v_lshl_add_u64 v[222:223], s[72:73], 0, v[134:135]
	s_add_i32 m0, s71, 0x2000
	s_nop 0
	global_load_lds_dwordx4 v[222:223], off
	v_lshl_add_u64 v[222:223], s[40:41], 0, v[128:129]
	s_waitcnt vmcnt(6)
	s_waitcnt lgkmcnt(0)
	s_barrier
	s_setprio 1
	s_waitcnt lgkmcnt(0)
	v_mfma_f32_16x16x32_bf16 v[60:63], v[144:147], v[184:187], v[60:63]
	v_mfma_f32_16x16x32_bf16 v[56:59], v[160:163], v[184:187], v[56:59]
	v_mfma_f32_16x16x32_bf16 v[44:47], v[144:147], v[196:199], v[44:47]
	v_mfma_f32_16x16x32_bf16 v[40:43], v[160:163], v[196:199], v[40:43]
	v_mfma_f32_16x16x32_bf16 v[28:31], v[144:147], v[204:207], v[28:31]
	v_mfma_f32_16x16x32_bf16 v[24:27], v[160:163], v[204:207], v[24:27]
	v_mfma_f32_16x16x32_bf16 v[12:15], v[144:147], v[212:215], v[12:15]
	v_mfma_f32_16x16x32_bf16 v[8:11], v[160:163], v[212:215], v[8:11]
	v_mfma_f32_16x16x32_bf16 v[60:63], v[156:159], v[188:191], v[60:63]
	v_mfma_f32_16x16x32_bf16 v[56:59], v[164:167], v[188:191], v[56:59]
	v_mfma_f32_16x16x32_bf16 v[44:47], v[156:159], v[200:203], v[44:47]
	v_mfma_f32_16x16x32_bf16 v[40:43], v[164:167], v[200:203], v[40:43]
	v_mfma_f32_16x16x32_bf16 v[28:31], v[156:159], v[208:211], v[28:31]
	v_mfma_f32_16x16x32_bf16 v[24:27], v[164:167], v[208:211], v[24:27]
	v_mfma_f32_16x16x32_bf16 v[12:15], v[156:159], v[216:219], v[12:15]
	v_mfma_f32_16x16x32_bf16 v[8:11], v[164:167], v[216:219], v[8:11]
	s_setprio 0
	s_setprio 1
	v_mfma_f32_16x16x32_bf16 v[52:55], v[168:171], v[184:187], v[52:55]
	v_mfma_f32_16x16x32_bf16 v[48:51], v[176:179], v[184:187], v[48:51]
	v_mfma_f32_16x16x32_bf16 v[36:39], v[168:171], v[196:199], v[36:39]
	v_mfma_f32_16x16x32_bf16 v[32:35], v[176:179], v[196:199], v[32:35]
	v_mfma_f32_16x16x32_bf16 v[20:23], v[168:171], v[204:207], v[20:23]
	v_mfma_f32_16x16x32_bf16 v[16:19], v[176:179], v[204:207], v[16:19]
	v_mfma_f32_16x16x32_bf16 v[4:7], v[168:171], v[212:215], v[4:7]
	v_mfma_f32_16x16x32_bf16 v[0:3], v[176:179], v[212:215], v[0:3]
	v_mfma_f32_16x16x32_bf16 v[52:55], v[172:175], v[188:191], v[52:55]
	v_mfma_f32_16x16x32_bf16 v[48:51], v[180:183], v[188:191], v[48:51]
	v_mfma_f32_16x16x32_bf16 v[36:39], v[172:175], v[200:203], v[36:39]
	v_mfma_f32_16x16x32_bf16 v[32:35], v[180:183], v[200:203], v[32:35]
	v_mfma_f32_16x16x32_bf16 v[20:23], v[172:175], v[208:211], v[20:23]
	v_mfma_f32_16x16x32_bf16 v[16:19], v[180:183], v[208:211], v[16:19]
	v_mfma_f32_16x16x32_bf16 v[4:7], v[172:175], v[216:219], v[4:7]
	v_mfma_f32_16x16x32_bf16 v[0:3], v[180:183], v[216:219], v[0:3]
	s_setprio 0
	s_barrier
	s_add_i32 s71, 0, 0x18000
	v_add_u32_e32 v155, s71, v149
	s_add_i32 s72, 0, 0x1c000
	ds_read_b128 v[144:147], v155
	ds_read_b128 v[156:159], v155 offset:1024
	ds_read_b128 v[160:163], v155 offset:2048
	ds_read_b128 v[164:167], v155 offset:3072
	v_add_u32_e32 v155, s72, v149
	ds_read_b128 v[168:171], v155
	ds_read_b128 v[172:175], v155 offset:1024
	ds_read_b128 v[176:179], v155 offset:2048
	ds_read_b128 v[180:183], v155 offset:3072
	s_add_u32 s40, s40, 0x40000
	s_addc_u32 s41, s41, 0
	v_lshl_add_u64 v[226:227], s[40:41], 0, v[128:129]
	ds_read_b128 v[184:187], v153 offset:32768
	ds_read_b128 v[188:191], v153 offset:33792
	ds_read_b128 v[196:199], v153 offset:34816
	ds_read_b128 v[200:203], v153 offset:35840
	ds_read_b128 v[204:207], v153 offset:36864
	ds_read_b128 v[208:211], v153 offset:37888
	ds_read_b128 v[212:215], v153 offset:38912
	ds_read_b128 v[216:219], v153 offset:39936
	s_mov_b32 m0, s50
	s_nop 0
	global_load_lds_dwordx4 v[222:223], off
	s_mov_b32 m0, s51
	s_nop 0
	global_load_lds_dwordx4 v[224:225], off
	s_mov_b32 m0, s52
	s_nop 0
	global_load_lds_dwordx4 v[226:227], off
	v_lshl_add_u64 v[226:227], s[40:41], 0, v[132:133]
	s_mov_b32 m0, s53
	s_nop 0
	global_load_lds_dwordx4 v[226:227], off
	s_waitcnt vmcnt(8)
	s_waitcnt lgkmcnt(0)
	s_barrier
	s_setprio 1
	s_waitcnt lgkmcnt(0)
	v_mfma_f32_16x16x32_bf16 v[124:127], v[144:147], v[184:187], v[124:127]
	v_mfma_f32_16x16x32_bf16 v[120:123], v[160:163], v[184:187], v[120:123]
	v_mfma_f32_16x16x32_bf16 v[108:111], v[144:147], v[196:199], v[108:111]
	v_mfma_f32_16x16x32_bf16 v[104:107], v[160:163], v[196:199], v[104:107]
	v_mfma_f32_16x16x32_bf16 v[92:95], v[144:147], v[204:207], v[92:95]
	v_mfma_f32_16x16x32_bf16 v[88:91], v[160:163], v[204:207], v[88:91]
	v_mfma_f32_16x16x32_bf16 v[76:79], v[144:147], v[212:215], v[76:79]
	v_mfma_f32_16x16x32_bf16 v[72:75], v[160:163], v[212:215], v[72:75]
	v_mfma_f32_16x16x32_bf16 v[124:127], v[156:159], v[188:191], v[124:127]
	v_mfma_f32_16x16x32_bf16 v[120:123], v[164:167], v[188:191], v[120:123]
	v_mfma_f32_16x16x32_bf16 v[108:111], v[156:159], v[200:203], v[108:111]
	v_mfma_f32_16x16x32_bf16 v[104:107], v[164:167], v[200:203], v[104:107]
	v_mfma_f32_16x16x32_bf16 v[92:95], v[156:159], v[208:211], v[92:95]
	v_mfma_f32_16x16x32_bf16 v[88:91], v[164:167], v[208:211], v[88:91]
	v_mfma_f32_16x16x32_bf16 v[76:79], v[156:159], v[216:219], v[76:79]
	v_mfma_f32_16x16x32_bf16 v[72:75], v[164:167], v[216:219], v[72:75]
	s_setprio 0
	s_setprio 1
	v_mfma_f32_16x16x32_bf16 v[116:119], v[168:171], v[184:187], v[116:119]
	v_mfma_f32_16x16x32_bf16 v[112:115], v[176:179], v[184:187], v[112:115]
	v_mfma_f32_16x16x32_bf16 v[100:103], v[168:171], v[196:199], v[100:103]
	v_mfma_f32_16x16x32_bf16 v[96:99], v[176:179], v[196:199], v[96:99]
	v_mfma_f32_16x16x32_bf16 v[84:87], v[168:171], v[204:207], v[84:87]
	v_mfma_f32_16x16x32_bf16 v[80:83], v[176:179], v[204:207], v[80:83]
	v_mfma_f32_16x16x32_bf16 v[68:71], v[168:171], v[212:215], v[68:71]
	v_mfma_f32_16x16x32_bf16 v[64:67], v[176:179], v[212:215], v[64:67]
	v_mfma_f32_16x16x32_bf16 v[116:119], v[172:175], v[188:191], v[116:119]
	v_mfma_f32_16x16x32_bf16 v[112:115], v[180:183], v[188:191], v[112:115]
	v_mfma_f32_16x16x32_bf16 v[100:103], v[172:175], v[200:203], v[100:103]
	v_mfma_f32_16x16x32_bf16 v[96:99], v[180:183], v[200:203], v[96:99]
	v_mfma_f32_16x16x32_bf16 v[84:87], v[172:175], v[208:211], v[84:87]
	v_mfma_f32_16x16x32_bf16 v[80:83], v[180:183], v[208:211], v[80:83]
	v_mfma_f32_16x16x32_bf16 v[68:71], v[172:175], v[216:219], v[68:71]
	v_mfma_f32_16x16x32_bf16 v[64:67], v[180:183], v[216:219], v[64:67]
	s_setprio 0
	s_barrier
	s_add_i32 s40, s71, s49
	v_lshl_add_u64 v[192:193], v[192:193], 0, s[20:21]
	s_mov_b32 m0, s40
	ds_read_b128 v[184:187], v153 offset:49152
	ds_read_b128 v[188:191], v153 offset:50176
	ds_read_b128 v[196:199], v153 offset:51200
	ds_read_b128 v[200:203], v153 offset:52224
	ds_read_b128 v[204:207], v153 offset:53248
	ds_read_b128 v[208:211], v153 offset:54272
	ds_read_b128 v[212:215], v153 offset:55296
	ds_read_b128 v[216:219], v153 offset:56320
	global_load_lds_dwordx4 v[192:193], off
	s_add_i32 m0, s40, 0x2000
	s_add_u32 s38, s38, 0x40080
	v_lshl_add_u64 v[192:193], v[220:221], 0, s[20:21]
	s_addc_u32 s39, s39, 0
	s_add_i32 s40, s72, s49
	global_load_lds_dwordx4 v[192:193], off
	v_lshl_add_u64 v[192:193], s[38:39], 0, v[130:131]
	s_mov_b32 m0, s40
	s_nop 0
	global_load_lds_dwordx4 v[192:193], off
	v_lshl_add_u64 v[192:193], s[38:39], 0, v[134:135]
	s_add_i32 m0, s40, 0x2000
	s_nop 0
	global_load_lds_dwordx4 v[192:193], off
	s_waitcnt vmcnt(6)
	s_waitcnt lgkmcnt(0)
	s_barrier
	s_setprio 1
	s_waitcnt lgkmcnt(0)
	v_mfma_f32_16x16x32_bf16 v[60:63], v[144:147], v[184:187], v[60:63]
	v_mfma_f32_16x16x32_bf16 v[56:59], v[160:163], v[184:187], v[56:59]
	v_mfma_f32_16x16x32_bf16 v[44:47], v[144:147], v[196:199], v[44:47]
	v_mfma_f32_16x16x32_bf16 v[40:43], v[160:163], v[196:199], v[40:43]
	v_mfma_f32_16x16x32_bf16 v[28:31], v[144:147], v[204:207], v[28:31]
	v_mfma_f32_16x16x32_bf16 v[24:27], v[160:163], v[204:207], v[24:27]
	v_mfma_f32_16x16x32_bf16 v[12:15], v[144:147], v[212:215], v[12:15]
	v_mfma_f32_16x16x32_bf16 v[8:11], v[160:163], v[212:215], v[8:11]
	v_mfma_f32_16x16x32_bf16 v[60:63], v[156:159], v[188:191], v[60:63]
	v_mfma_f32_16x16x32_bf16 v[56:59], v[164:167], v[188:191], v[56:59]
	v_mfma_f32_16x16x32_bf16 v[44:47], v[156:159], v[200:203], v[44:47]
	v_mfma_f32_16x16x32_bf16 v[40:43], v[164:167], v[200:203], v[40:43]
	v_mfma_f32_16x16x32_bf16 v[28:31], v[156:159], v[208:211], v[28:31]
	v_mfma_f32_16x16x32_bf16 v[24:27], v[164:167], v[208:211], v[24:27]
	v_mfma_f32_16x16x32_bf16 v[12:15], v[156:159], v[216:219], v[12:15]
	v_mfma_f32_16x16x32_bf16 v[8:11], v[164:167], v[216:219], v[8:11]
	s_setprio 0
	s_setprio 1
	v_mfma_f32_16x16x32_bf16 v[52:55], v[168:171], v[184:187], v[52:55]
	v_mfma_f32_16x16x32_bf16 v[48:51], v[176:179], v[184:187], v[48:51]
	v_mfma_f32_16x16x32_bf16 v[36:39], v[168:171], v[196:199], v[36:39]
	v_mfma_f32_16x16x32_bf16 v[32:35], v[176:179], v[196:199], v[32:35]
	v_mfma_f32_16x16x32_bf16 v[20:23], v[168:171], v[204:207], v[20:23]
	v_mfma_f32_16x16x32_bf16 v[16:19], v[176:179], v[204:207], v[16:19]
	v_mfma_f32_16x16x32_bf16 v[4:7], v[168:171], v[212:215], v[4:7]
	v_mfma_f32_16x16x32_bf16 v[0:3], v[176:179], v[212:215], v[0:3]
	v_mfma_f32_16x16x32_bf16 v[52:55], v[172:175], v[188:191], v[52:55]
	v_mfma_f32_16x16x32_bf16 v[48:51], v[180:183], v[188:191], v[48:51]
	v_mfma_f32_16x16x32_bf16 v[36:39], v[172:175], v[200:203], v[36:39]
	v_mfma_f32_16x16x32_bf16 v[32:35], v[180:183], v[200:203], v[32:35]
	v_mfma_f32_16x16x32_bf16 v[20:23], v[172:175], v[208:211], v[20:23]
	v_mfma_f32_16x16x32_bf16 v[16:19], v[180:183], v[208:211], v[16:19]
	v_mfma_f32_16x16x32_bf16 v[4:7], v[172:175], v[216:219], v[4:7]
	v_mfma_f32_16x16x32_bf16 v[0:3], v[180:183], v[216:219], v[0:3]
	s_setprio 0
	s_barrier
	v_lshl_add_u64 v[222:223], v[222:223], 0, s[20:21]
	s_mov_b32 m0, s55
	s_nop 0
	global_load_lds_dwordx4 v[222:223], off
	v_lshl_add_u64 v[224:225], v[224:225], 0, s[20:21]
	s_mov_b32 m0, s56
	s_nop 0
	global_load_lds_dwordx4 v[224:225], off
	s_add_i32 s70, s70, 2
	s_add_u32 s36, s36, 0x100
	s_addc_u32 s37, s37, 0
	s_add_u32 s62, s62, 0x100
	s_addc_u32 s63, s63, 0
	s_cmp_gt_u32 s70, 13
	s_cbranch_scc0 .LBB0_3235
	s_and_b64 vcc, exec, s[22:23]
	s_cbranch_vccz .LBB0_3238
	s_barrier

.LBB0_3319:
	ds_read_b128 v[154:157], v149
	ds_read_b128 v[158:161], v149 offset:1024
	ds_read_b128 v[162:165], v149 offset:2048
	ds_read_b128 v[166:169], v149 offset:3072
	ds_read_b128 v[170:173], v150
	ds_read_b128 v[174:177], v150 offset:1024
	ds_read_b128 v[178:181], v150 offset:2048
	ds_read_b128 v[182:185], v150 offset:3072
	s_add_u32 s28, s26, 0xfffc0080
	s_addc_u32 s29, s27, -1
	s_cmp_eq_u32 s59, 12
	s_cselect_b32 s31, s19, s29
	s_cselect_b32 s30, s55, s28
	s_cselect_b32 s29, s17, s58
	s_cselect_b32 s28, s56, s57
	v_lshl_add_u64 v[144:145], s[26:27], 0, v[136:137]
	s_add_i32 m0, s25, 0xc000
	ds_read_b128 v[186:189], v151
	ds_read_b128 v[190:193], v151 offset:1024
	ds_read_b128 v[196:199], v151 offset:2048
	ds_read_b128 v[200:203], v151 offset:3072
	ds_read_b128 v[204:207], v151 offset:4096
	ds_read_b128 v[208:211], v151 offset:5120
	ds_read_b128 v[212:215], v151 offset:6144
	ds_read_b128 v[216:219], v151 offset:7168
	global_load_lds_dwordx4 v[144:145], off
	v_lshl_add_u64 v[144:145], s[26:27], 0, v[138:139]
	s_add_i32 m0, s25, 0xe000
	s_nop 0
	global_load_lds_dwordx4 v[144:145], off
	s_waitcnt vmcnt(8)
	s_waitcnt lgkmcnt(0)
	s_barrier
	s_setprio 1
	s_waitcnt lgkmcnt(0)
	v_mfma_f32_16x16x32_bf16 v[116:119], v[154:157], v[186:189], v[116:119]
	v_mfma_f32_16x16x32_bf16 v[112:115], v[162:165], v[186:189], v[112:115]
	v_mfma_f32_16x16x32_bf16 v[100:103], v[154:157], v[196:199], v[100:103]
	v_mfma_f32_16x16x32_bf16 v[96:99], v[162:165], v[196:199], v[96:99]
	v_mfma_f32_16x16x32_bf16 v[84:87], v[154:157], v[204:207], v[84:87]
	v_mfma_f32_16x16x32_bf16 v[80:83], v[162:165], v[204:207], v[80:83]
	v_mfma_f32_16x16x32_bf16 v[68:71], v[154:157], v[212:215], v[68:71]
	v_mfma_f32_16x16x32_bf16 v[64:67], v[162:165], v[212:215], v[64:67]
	v_mfma_f32_16x16x32_bf16 v[116:119], v[158:161], v[190:193], v[116:119]
	v_mfma_f32_16x16x32_bf16 v[112:115], v[166:169], v[190:193], v[112:115]
	v_mfma_f32_16x16x32_bf16 v[100:103], v[158:161], v[200:203], v[100:103]
	v_mfma_f32_16x16x32_bf16 v[96:99], v[166:169], v[200:203], v[96:99]
	v_mfma_f32_16x16x32_bf16 v[84:87], v[158:161], v[208:211], v[84:87]
	v_mfma_f32_16x16x32_bf16 v[80:83], v[166:169], v[208:211], v[80:83]
	v_mfma_f32_16x16x32_bf16 v[68:71], v[158:161], v[216:219], v[68:71]
	v_mfma_f32_16x16x32_bf16 v[64:67], v[166:169], v[216:219], v[64:67]
	s_setprio 0
	s_setprio 1
	v_mfma_f32_16x16x32_bf16 v[124:127], v[170:173], v[186:189], v[124:127]
	v_mfma_f32_16x16x32_bf16 v[120:123], v[178:181], v[186:189], v[120:123]
	v_mfma_f32_16x16x32_bf16 v[108:111], v[170:173], v[196:199], v[108:111]
	v_mfma_f32_16x16x32_bf16 v[104:107], v[178:181], v[196:199], v[104:107]
	v_mfma_f32_16x16x32_bf16 v[92:95], v[170:173], v[204:207], v[92:95]
	v_mfma_f32_16x16x32_bf16 v[88:91], v[178:181], v[204:207], v[88:91]
	v_mfma_f32_16x16x32_bf16 v[76:79], v[170:173], v[212:215], v[76:79]
	v_mfma_f32_16x16x32_bf16 v[72:75], v[178:181], v[212:215], v[72:75]
	v_mfma_f32_16x16x32_bf16 v[124:127], v[174:177], v[190:193], v[124:127]
	v_mfma_f32_16x16x32_bf16 v[120:123], v[182:185], v[190:193], v[120:123]
	v_mfma_f32_16x16x32_bf16 v[108:111], v[174:177], v[200:203], v[108:111]
	v_mfma_f32_16x16x32_bf16 v[104:107], v[182:185], v[200:203], v[104:107]
	v_mfma_f32_16x16x32_bf16 v[92:95], v[174:177], v[208:211], v[92:95]
	v_mfma_f32_16x16x32_bf16 v[88:91], v[182:185], v[208:211], v[88:91]
	v_mfma_f32_16x16x32_bf16 v[76:79], v[174:177], v[216:219], v[76:79]
	v_mfma_f32_16x16x32_bf16 v[72:75], v[182:185], v[216:219], v[72:75]
	s_setprio 0
	s_barrier
	s_add_i32 s60, s50, s39
	v_lshl_add_u64 v[144:145], s[28:29], 0, v[132:133]
	s_mov_b32 m0, s60
	ds_read_b128 v[186:189], v151 offset:16384
	ds_read_b128 v[190:193], v151 offset:17408
	ds_read_b128 v[196:199], v151 offset:18432
	ds_read_b128 v[200:203], v151 offset:19456
	ds_read_b128 v[204:207], v151 offset:20480
	ds_read_b128 v[208:211], v151 offset:21504
	ds_read_b128 v[212:215], v151 offset:22528
	ds_read_b128 v[216:219], v151 offset:23552
	global_load_lds_dwordx4 v[144:145], off
	s_add_i32 m0, s60, 0x2000
	s_add_u32 s60, s28, 0x40000
	v_lshl_add_u64 v[220:221], s[28:29], 0, v[128:129]
	s_addc_u32 s61, s29, 0
	s_add_i32 s62, s51, s39
	global_load_lds_dwordx4 v[220:221], off
	v_lshl_add_u64 v[222:223], s[60:61], 0, v[132:133]
	s_mov_b32 m0, s62
	v_lshl_add_u64 v[224:225], s[30:31], 0, v[130:131]
	global_load_lds_dwordx4 v[222:223], off
	v_lshl_add_u64 v[222:223], s[60:61], 0, v[128:129]
	s_add_i32 m0, s62, 0x2000
	s_nop 0
	global_load_lds_dwordx4 v[222:223], off
	v_lshl_add_u64 v[222:223], s[30:31], 0, v[134:135]
	s_waitcnt vmcnt(6)
	s_waitcnt lgkmcnt(0)
	s_barrier
	s_setprio 1
	s_waitcnt lgkmcnt(0)
	v_mfma_f32_16x16x32_bf16 v[52:55], v[154:157], v[186:189], v[52:55]
	v_mfma_f32_16x16x32_bf16 v[48:51], v[162:165], v[186:189], v[48:51]
	v_mfma_f32_16x16x32_bf16 v[36:39], v[154:157], v[196:199], v[36:39]
	v_mfma_f32_16x16x32_bf16 v[32:35], v[162:165], v[196:199], v[32:35]
	v_mfma_f32_16x16x32_bf16 v[20:23], v[154:157], v[204:207], v[20:23]
	v_mfma_f32_16x16x32_bf16 v[16:19], v[162:165], v[204:207], v[16:19]
	v_mfma_f32_16x16x32_bf16 v[4:7], v[154:157], v[212:215], v[4:7]
	v_mfma_f32_16x16x32_bf16 v[0:3], v[162:165], v[212:215], v[0:3]
	v_mfma_f32_16x16x32_bf16 v[52:55], v[158:161], v[190:193], v[52:55]
	v_mfma_f32_16x16x32_bf16 v[48:51], v[166:169], v[190:193], v[48:51]
	v_mfma_f32_16x16x32_bf16 v[36:39], v[158:161], v[200:203], v[36:39]
	v_mfma_f32_16x16x32_bf16 v[32:35], v[166:169], v[200:203], v[32:35]
	v_mfma_f32_16x16x32_bf16 v[20:23], v[158:161], v[208:211], v[20:23]
	v_mfma_f32_16x16x32_bf16 v[16:19], v[166:169], v[208:211], v[16:19]
	v_mfma_f32_16x16x32_bf16 v[4:7], v[158:161], v[216:219], v[4:7]
	v_mfma_f32_16x16x32_bf16 v[0:3], v[166:169], v[216:219], v[0:3]
	s_setprio 0
	s_setprio 1
	v_mfma_f32_16x16x32_bf16 v[60:63], v[170:173], v[186:189], v[60:63]
	v_mfma_f32_16x16x32_bf16 v[56:59], v[178:181], v[186:189], v[56:59]
	v_mfma_f32_16x16x32_bf16 v[44:47], v[170:173], v[196:199], v[44:47]
	v_mfma_f32_16x16x32_bf16 v[40:43], v[178:181], v[196:199], v[40:43]
	v_mfma_f32_16x16x32_bf16 v[28:31], v[170:173], v[204:207], v[28:31]
	v_mfma_f32_16x16x32_bf16 v[24:27], v[178:181], v[204:207], v[24:27]
	v_mfma_f32_16x16x32_bf16 v[12:15], v[170:173], v[212:215], v[12:15]
	v_mfma_f32_16x16x32_bf16 v[8:11], v[178:181], v[212:215], v[8:11]
	v_mfma_f32_16x16x32_bf16 v[60:63], v[174:177], v[190:193], v[60:63]
	v_mfma_f32_16x16x32_bf16 v[56:59], v[182:185], v[190:193], v[56:59]
	v_mfma_f32_16x16x32_bf16 v[44:47], v[174:177], v[200:203], v[44:47]
	v_mfma_f32_16x16x32_bf16 v[40:43], v[182:185], v[200:203], v[40:43]
	v_mfma_f32_16x16x32_bf16 v[28:31], v[174:177], v[208:211], v[28:31]
	v_mfma_f32_16x16x32_bf16 v[24:27], v[182:185], v[208:211], v[24:27]
	v_mfma_f32_16x16x32_bf16 v[12:15], v[174:177], v[216:219], v[12:15]
	v_mfma_f32_16x16x32_bf16 v[8:11], v[182:185], v[216:219], v[8:11]
	s_setprio 0
	s_barrier
	s_add_i32 s60, 0, 0x18000
	v_add_u32_e32 v153, s60, v147
	s_add_i32 s61, 0, 0x1c000
	ds_read_b128 v[154:157], v153
	ds_read_b128 v[158:161], v153 offset:1024
	ds_read_b128 v[162:165], v153 offset:2048
	ds_read_b128 v[166:169], v153 offset:3072
	v_add_u32_e32 v153, s61, v147
	ds_read_b128 v[170:173], v153
	ds_read_b128 v[174:177], v153 offset:1024
	ds_read_b128 v[178:181], v153 offset:2048
	ds_read_b128 v[182:185], v153 offset:3072
	s_add_u32 s30, s30, 0x40000
	s_addc_u32 s31, s31, 0
	v_lshl_add_u64 v[226:227], s[30:31], 0, v[134:135]
	ds_read_b128 v[186:189], v151 offset:32768
	ds_read_b128 v[190:193], v151 offset:33792
	ds_read_b128 v[196:199], v151 offset:34816
	ds_read_b128 v[200:203], v151 offset:35840
	ds_read_b128 v[204:207], v151 offset:36864
	ds_read_b128 v[208:211], v151 offset:37888
	ds_read_b128 v[212:215], v151 offset:38912
	ds_read_b128 v[216:219], v151 offset:39936
	s_mov_b32 m0, s25
	s_nop 0
	global_load_lds_dwordx4 v[222:223], off
	s_mov_b32 m0, s41
	s_nop 0
	global_load_lds_dwordx4 v[224:225], off
	s_mov_b32 m0, s42
	s_nop 0
	global_load_lds_dwordx4 v[226:227], off
	v_lshl_add_u64 v[226:227], s[30:31], 0, v[130:131]
	s_mov_b32 m0, s43
	s_nop 0
	global_load_lds_dwordx4 v[226:227], off
	s_waitcnt vmcnt(8)
	s_waitcnt lgkmcnt(0)
	s_barrier
	s_setprio 1
	s_waitcnt lgkmcnt(0)
	v_mfma_f32_16x16x32_bf16 v[116:119], v[154:157], v[186:189], v[116:119]
	v_mfma_f32_16x16x32_bf16 v[112:115], v[162:165], v[186:189], v[112:115]
	v_mfma_f32_16x16x32_bf16 v[100:103], v[154:157], v[196:199], v[100:103]
	v_mfma_f32_16x16x32_bf16 v[96:99], v[162:165], v[196:199], v[96:99]
	v_mfma_f32_16x16x32_bf16 v[84:87], v[154:157], v[204:207], v[84:87]
	v_mfma_f32_16x16x32_bf16 v[80:83], v[162:165], v[204:207], v[80:83]
	v_mfma_f32_16x16x32_bf16 v[68:71], v[154:157], v[212:215], v[68:71]
	v_mfma_f32_16x16x32_bf16 v[64:67], v[162:165], v[212:215], v[64:67]
	v_mfma_f32_16x16x32_bf16 v[116:119], v[158:161], v[190:193], v[116:119]
	v_mfma_f32_16x16x32_bf16 v[112:115], v[166:169], v[190:193], v[112:115]
	v_mfma_f32_16x16x32_bf16 v[100:103], v[158:161], v[200:203], v[100:103]
	v_mfma_f32_16x16x32_bf16 v[96:99], v[166:169], v[200:203], v[96:99]
	v_mfma_f32_16x16x32_bf16 v[84:87], v[158:161], v[208:211], v[84:87]
	v_mfma_f32_16x16x32_bf16 v[80:83], v[166:169], v[208:211], v[80:83]
	v_mfma_f32_16x16x32_bf16 v[68:71], v[158:161], v[216:219], v[68:71]
	v_mfma_f32_16x16x32_bf16 v[64:67], v[166:169], v[216:219], v[64:67]
	s_setprio 0
	s_setprio 1
	v_mfma_f32_16x16x32_bf16 v[124:127], v[170:173], v[186:189], v[124:127]
	v_mfma_f32_16x16x32_bf16 v[120:123], v[178:181], v[186:189], v[120:123]
	v_mfma_f32_16x16x32_bf16 v[108:111], v[170:173], v[196:199], v[108:111]
	v_mfma_f32_16x16x32_bf16 v[104:107], v[178:181], v[196:199], v[104:107]
	v_mfma_f32_16x16x32_bf16 v[92:95], v[170:173], v[204:207], v[92:95]
	v_mfma_f32_16x16x32_bf16 v[88:91], v[178:181], v[204:207], v[88:91]
	v_mfma_f32_16x16x32_bf16 v[76:79], v[170:173], v[212:215], v[76:79]
	v_mfma_f32_16x16x32_bf16 v[72:75], v[178:181], v[212:215], v[72:75]
	v_mfma_f32_16x16x32_bf16 v[124:127], v[174:177], v[190:193], v[124:127]
	v_mfma_f32_16x16x32_bf16 v[120:123], v[182:185], v[190:193], v[120:123]
	v_mfma_f32_16x16x32_bf16 v[108:111], v[174:177], v[200:203], v[108:111]
	v_mfma_f32_16x16x32_bf16 v[104:107], v[182:185], v[200:203], v[104:107]
	v_mfma_f32_16x16x32_bf16 v[92:95], v[174:177], v[208:211], v[92:95]
	v_mfma_f32_16x16x32_bf16 v[88:91], v[182:185], v[208:211], v[88:91]
	v_mfma_f32_16x16x32_bf16 v[76:79], v[174:177], v[216:219], v[76:79]
	v_mfma_f32_16x16x32_bf16 v[72:75], v[182:185], v[216:219], v[72:75]
	s_setprio 0
	s_barrier
	s_add_i32 s30, s60, s39
	v_lshl_add_u64 v[144:145], v[144:145], 0, s[12:13]
	s_mov_b32 m0, s30
	ds_read_b128 v[186:189], v151 offset:49152
	ds_read_b128 v[190:193], v151 offset:50176
	ds_read_b128 v[196:199], v151 offset:51200
	ds_read_b128 v[200:203], v151 offset:52224
	ds_read_b128 v[204:207], v151 offset:53248
	ds_read_b128 v[208:211], v151 offset:54272
	ds_read_b128 v[212:215], v151 offset:55296
	ds_read_b128 v[216:219], v151 offset:56320
	global_load_lds_dwordx4 v[144:145], off
	s_add_i32 m0, s30, 0x2000
	s_add_u32 s28, s28, 0x40080
	v_lshl_add_u64 v[144:145], v[220:221], 0, s[12:13]
	s_addc_u32 s29, s29, 0
	s_add_i32 s30, s61, s39
	global_load_lds_dwordx4 v[144:145], off
	v_lshl_add_u64 v[144:145], s[28:29], 0, v[132:133]
	s_mov_b32 m0, s30
	s_nop 0
	global_load_lds_dwordx4 v[144:145], off
	v_lshl_add_u64 v[144:145], s[28:29], 0, v[128:129]
	s_add_i32 m0, s30, 0x2000
	s_nop 0
	global_load_lds_dwordx4 v[144:145], off
	s_waitcnt vmcnt(6)
	s_waitcnt lgkmcnt(0)
	s_barrier
	s_setprio 1
	s_waitcnt lgkmcnt(0)
	v_mfma_f32_16x16x32_bf16 v[52:55], v[154:157], v[186:189], v[52:55]
	v_mfma_f32_16x16x32_bf16 v[48:51], v[162:165], v[186:189], v[48:51]
	v_mfma_f32_16x16x32_bf16 v[36:39], v[154:157], v[196:199], v[36:39]
	v_mfma_f32_16x16x32_bf16 v[32:35], v[162:165], v[196:199], v[32:35]
	v_mfma_f32_16x16x32_bf16 v[20:23], v[154:157], v[204:207], v[20:23]
	v_mfma_f32_16x16x32_bf16 v[16:19], v[162:165], v[204:207], v[16:19]
	v_mfma_f32_16x16x32_bf16 v[4:7], v[154:157], v[212:215], v[4:7]
	v_mfma_f32_16x16x32_bf16 v[0:3], v[162:165], v[212:215], v[0:3]
	v_mfma_f32_16x16x32_bf16 v[52:55], v[158:161], v[190:193], v[52:55]
	v_mfma_f32_16x16x32_bf16 v[48:51], v[166:169], v[190:193], v[48:51]
	v_mfma_f32_16x16x32_bf16 v[36:39], v[158:161], v[200:203], v[36:39]
	v_mfma_f32_16x16x32_bf16 v[32:35], v[166:169], v[200:203], v[32:35]
	v_mfma_f32_16x16x32_bf16 v[20:23], v[158:161], v[208:211], v[20:23]
	v_mfma_f32_16x16x32_bf16 v[16:19], v[166:169], v[208:211], v[16:19]
	v_mfma_f32_16x16x32_bf16 v[4:7], v[158:161], v[216:219], v[4:7]
	v_mfma_f32_16x16x32_bf16 v[0:3], v[166:169], v[216:219], v[0:3]
	s_setprio 0
	s_setprio 1
	v_mfma_f32_16x16x32_bf16 v[60:63], v[170:173], v[186:189], v[60:63]
	v_mfma_f32_16x16x32_bf16 v[56:59], v[178:181], v[186:189], v[56:59]
	v_mfma_f32_16x16x32_bf16 v[44:47], v[170:173], v[196:199], v[44:47]
	v_mfma_f32_16x16x32_bf16 v[40:43], v[178:181], v[196:199], v[40:43]
	v_mfma_f32_16x16x32_bf16 v[28:31], v[170:173], v[204:207], v[28:31]
	v_mfma_f32_16x16x32_bf16 v[24:27], v[178:181], v[204:207], v[24:27]
	v_mfma_f32_16x16x32_bf16 v[12:15], v[170:173], v[212:215], v[12:15]
	v_mfma_f32_16x16x32_bf16 v[8:11], v[178:181], v[212:215], v[8:11]
	v_mfma_f32_16x16x32_bf16 v[60:63], v[174:177], v[190:193], v[60:63]
	v_mfma_f32_16x16x32_bf16 v[56:59], v[182:185], v[190:193], v[56:59]
	v_mfma_f32_16x16x32_bf16 v[44:47], v[174:177], v[200:203], v[44:47]
	v_mfma_f32_16x16x32_bf16 v[40:43], v[182:185], v[200:203], v[40:43]
	v_mfma_f32_16x16x32_bf16 v[28:31], v[174:177], v[208:211], v[28:31]
	v_mfma_f32_16x16x32_bf16 v[24:27], v[182:185], v[208:211], v[24:27]
	v_mfma_f32_16x16x32_bf16 v[12:15], v[174:177], v[216:219], v[12:15]
	v_mfma_f32_16x16x32_bf16 v[8:11], v[182:185], v[216:219], v[8:11]
	s_setprio 0
	s_barrier
	v_lshl_add_u64 v[222:223], v[222:223], 0, s[12:13]
	s_mov_b32 m0, s45
	s_nop 0
	global_load_lds_dwordx4 v[222:223], off
	v_lshl_add_u64 v[224:225], v[224:225], 0, s[12:13]
	s_mov_b32 m0, s48
	s_nop 0
	global_load_lds_dwordx4 v[224:225], off
	s_add_i32 s59, s59, 2
	s_add_u32 s26, s26, 0x100
	s_addc_u32 s27, s27, 0
	s_add_u32 s57, s57, 0x100
	s_addc_u32 s58, s58, 0
	s_cmp_gt_u32 s59, 13
	s_cbranch_scc0 .LBB0_3319
	s_and_b64 vcc, exec, s[14:15]
	s_cbranch_vccz .LBB0_3322
	s_barrier

.LBB0_3401:
	ds_read_b128 v[144:147], v151
	ds_read_b128 v[156:159], v151 offset:1024
	ds_read_b128 v[160:163], v151 offset:2048
	ds_read_b128 v[164:167], v151 offset:3072
	ds_read_b128 v[168:171], v152
	ds_read_b128 v[172:175], v152 offset:1024
	ds_read_b128 v[176:179], v152 offset:2048
	ds_read_b128 v[180:183], v152 offset:3072
	s_add_u32 s24, s22, 0x100
	s_addc_u32 s25, s23, 0
	s_cmp_eq_u32 s56, 40
	s_cselect_b32 s29, s1, s25
	s_cselect_b32 s28, s0, s24
	s_cselect_b32 s27, s21, s55
	s_cselect_b32 s26, s20, s54
	v_lshl_add_u64 v[192:193], s[22:23], 0, v[136:137]
	s_add_i32 m0, s38, 0xc000
	ds_read_b128 v[184:187], v153
	ds_read_b128 v[188:191], v153 offset:1024
	ds_read_b128 v[196:199], v153 offset:2048
	ds_read_b128 v[200:203], v153 offset:3072
	ds_read_b128 v[204:207], v153 offset:4096
	ds_read_b128 v[208:211], v153 offset:5120
	ds_read_b128 v[212:215], v153 offset:6144
	ds_read_b128 v[216:219], v153 offset:7168
	global_load_lds_dwordx4 v[192:193], off
	v_lshl_add_u64 v[192:193], s[22:23], 0, v[138:139]
	s_add_i32 m0, s38, 0xe000
	s_nop 0
	global_load_lds_dwordx4 v[192:193], off
	s_waitcnt vmcnt(8)
	s_waitcnt lgkmcnt(0)
	s_barrier
	s_setprio 1
	s_waitcnt lgkmcnt(0)
	v_mfma_f32_16x16x32_bf16 v[124:127], v[144:147], v[184:187], v[124:127]
	v_mfma_f32_16x16x32_bf16 v[120:123], v[160:163], v[184:187], v[120:123]
	v_mfma_f32_16x16x32_bf16 v[108:111], v[144:147], v[196:199], v[108:111]
	v_mfma_f32_16x16x32_bf16 v[104:107], v[160:163], v[196:199], v[104:107]
	v_mfma_f32_16x16x32_bf16 v[92:95], v[144:147], v[204:207], v[92:95]
	v_mfma_f32_16x16x32_bf16 v[88:91], v[160:163], v[204:207], v[88:91]
	v_mfma_f32_16x16x32_bf16 v[76:79], v[144:147], v[212:215], v[76:79]
	v_mfma_f32_16x16x32_bf16 v[72:75], v[160:163], v[212:215], v[72:75]
	v_mfma_f32_16x16x32_bf16 v[124:127], v[156:159], v[188:191], v[124:127]
	v_mfma_f32_16x16x32_bf16 v[120:123], v[164:167], v[188:191], v[120:123]
	v_mfma_f32_16x16x32_bf16 v[108:111], v[156:159], v[200:203], v[108:111]
	v_mfma_f32_16x16x32_bf16 v[104:107], v[164:167], v[200:203], v[104:107]
	v_mfma_f32_16x16x32_bf16 v[92:95], v[156:159], v[208:211], v[92:95]
	v_mfma_f32_16x16x32_bf16 v[88:91], v[164:167], v[208:211], v[88:91]
	v_mfma_f32_16x16x32_bf16 v[76:79], v[156:159], v[216:219], v[76:79]
	v_mfma_f32_16x16x32_bf16 v[72:75], v[164:167], v[216:219], v[72:75]
	s_setprio 0
	s_setprio 1
	v_mfma_f32_16x16x32_bf16 v[116:119], v[168:171], v[184:187], v[116:119]
	v_mfma_f32_16x16x32_bf16 v[112:115], v[176:179], v[184:187], v[112:115]
	v_mfma_f32_16x16x32_bf16 v[100:103], v[168:171], v[196:199], v[100:103]
	v_mfma_f32_16x16x32_bf16 v[96:99], v[176:179], v[196:199], v[96:99]
	v_mfma_f32_16x16x32_bf16 v[84:87], v[168:171], v[204:207], v[84:87]
	v_mfma_f32_16x16x32_bf16 v[80:83], v[176:179], v[204:207], v[80:83]
	v_mfma_f32_16x16x32_bf16 v[68:71], v[168:171], v[212:215], v[68:71]
	v_mfma_f32_16x16x32_bf16 v[64:67], v[176:179], v[212:215], v[64:67]
	v_mfma_f32_16x16x32_bf16 v[116:119], v[172:175], v[188:191], v[116:119]
	v_mfma_f32_16x16x32_bf16 v[112:115], v[180:183], v[188:191], v[112:115]
	v_mfma_f32_16x16x32_bf16 v[100:103], v[172:175], v[200:203], v[100:103]
	v_mfma_f32_16x16x32_bf16 v[96:99], v[180:183], v[200:203], v[96:99]
	v_mfma_f32_16x16x32_bf16 v[84:87], v[172:175], v[208:211], v[84:87]
	v_mfma_f32_16x16x32_bf16 v[80:83], v[180:183], v[208:211], v[80:83]
	v_mfma_f32_16x16x32_bf16 v[68:71], v[172:175], v[216:219], v[68:71]
	v_mfma_f32_16x16x32_bf16 v[64:67], v[180:183], v[216:219], v[64:67]
	s_setprio 0
	s_barrier
	s_add_i32 s22, s48, s37
	v_lshl_add_u64 v[192:193], s[26:27], 0, v[130:131]
	s_mov_b32 m0, s22
	ds_read_b128 v[184:187], v153 offset:16384
	ds_read_b128 v[188:191], v153 offset:17408
	ds_read_b128 v[196:199], v153 offset:18432
	ds_read_b128 v[200:203], v153 offset:19456
	ds_read_b128 v[204:207], v153 offset:20480
	ds_read_b128 v[208:211], v153 offset:21504
	ds_read_b128 v[212:215], v153 offset:22528
	ds_read_b128 v[216:219], v153 offset:23552
	global_load_lds_dwordx4 v[192:193], off
	s_add_i32 m0, s22, 0x2000
	s_add_u32 s22, s26, 0xb0000
	v_lshl_add_u64 v[220:221], s[26:27], 0, v[134:135]
	s_addc_u32 s23, s27, 0
	s_add_i32 s57, s49, s37
	global_load_lds_dwordx4 v[220:221], off
	v_lshl_add_u64 v[222:223], s[22:23], 0, v[130:131]
	s_mov_b32 m0, s57
	v_lshl_add_u64 v[224:225], s[28:29], 0, v[132:133]
	global_load_lds_dwordx4 v[222:223], off
	v_lshl_add_u64 v[222:223], s[22:23], 0, v[134:135]
	s_add_i32 m0, s57, 0x2000
	s_nop 0
	global_load_lds_dwordx4 v[222:223], off
	v_lshl_add_u64 v[222:223], s[28:29], 0, v[128:129]
	s_waitcnt vmcnt(6)
	s_waitcnt lgkmcnt(0)
	s_barrier
	s_setprio 1
	s_waitcnt lgkmcnt(0)
	v_mfma_f32_16x16x32_bf16 v[60:63], v[144:147], v[184:187], v[60:63]
	v_mfma_f32_16x16x32_bf16 v[56:59], v[160:163], v[184:187], v[56:59]
	v_mfma_f32_16x16x32_bf16 v[44:47], v[144:147], v[196:199], v[44:47]
	v_mfma_f32_16x16x32_bf16 v[40:43], v[160:163], v[196:199], v[40:43]
	v_mfma_f32_16x16x32_bf16 v[28:31], v[144:147], v[204:207], v[28:31]
	v_mfma_f32_16x16x32_bf16 v[24:27], v[160:163], v[204:207], v[24:27]
	v_mfma_f32_16x16x32_bf16 v[12:15], v[144:147], v[212:215], v[12:15]
	v_mfma_f32_16x16x32_bf16 v[8:11], v[160:163], v[212:215], v[8:11]
	v_mfma_f32_16x16x32_bf16 v[60:63], v[156:159], v[188:191], v[60:63]
	v_mfma_f32_16x16x32_bf16 v[56:59], v[164:167], v[188:191], v[56:59]
	v_mfma_f32_16x16x32_bf16 v[44:47], v[156:159], v[200:203], v[44:47]
	v_mfma_f32_16x16x32_bf16 v[40:43], v[164:167], v[200:203], v[40:43]
	v_mfma_f32_16x16x32_bf16 v[28:31], v[156:159], v[208:211], v[28:31]
	v_mfma_f32_16x16x32_bf16 v[24:27], v[164:167], v[208:211], v[24:27]
	v_mfma_f32_16x16x32_bf16 v[12:15], v[156:159], v[216:219], v[12:15]
	v_mfma_f32_16x16x32_bf16 v[8:11], v[164:167], v[216:219], v[8:11]
	s_setprio 0
	s_setprio 1
	v_mfma_f32_16x16x32_bf16 v[52:55], v[168:171], v[184:187], v[52:55]
	v_mfma_f32_16x16x32_bf16 v[48:51], v[176:179], v[184:187], v[48:51]
	v_mfma_f32_16x16x32_bf16 v[36:39], v[168:171], v[196:199], v[36:39]
	v_mfma_f32_16x16x32_bf16 v[32:35], v[176:179], v[196:199], v[32:35]
	v_mfma_f32_16x16x32_bf16 v[20:23], v[168:171], v[204:207], v[20:23]
	v_mfma_f32_16x16x32_bf16 v[16:19], v[176:179], v[204:207], v[16:19]
	v_mfma_f32_16x16x32_bf16 v[4:7], v[168:171], v[212:215], v[4:7]
	v_mfma_f32_16x16x32_bf16 v[0:3], v[176:179], v[212:215], v[0:3]
	v_mfma_f32_16x16x32_bf16 v[52:55], v[172:175], v[188:191], v[52:55]
	v_mfma_f32_16x16x32_bf16 v[48:51], v[180:183], v[188:191], v[48:51]
	v_mfma_f32_16x16x32_bf16 v[36:39], v[172:175], v[200:203], v[36:39]
	v_mfma_f32_16x16x32_bf16 v[32:35], v[180:183], v[200:203], v[32:35]
	v_mfma_f32_16x16x32_bf16 v[20:23], v[172:175], v[208:211], v[20:23]
	v_mfma_f32_16x16x32_bf16 v[16:19], v[180:183], v[208:211], v[16:19]
	v_mfma_f32_16x16x32_bf16 v[4:7], v[172:175], v[216:219], v[4:7]
	v_mfma_f32_16x16x32_bf16 v[0:3], v[180:183], v[216:219], v[0:3]
	s_setprio 0
	s_barrier
	s_add_i32 s57, 0, 0x18000
	v_add_u32_e32 v155, s57, v149
	s_add_i32 s58, 0, 0x1c000
	ds_read_b128 v[144:147], v155
	ds_read_b128 v[156:159], v155 offset:1024
	ds_read_b128 v[160:163], v155 offset:2048
	ds_read_b128 v[164:167], v155 offset:3072
	v_add_u32_e32 v155, s58, v149
	ds_read_b128 v[168:171], v155
	ds_read_b128 v[172:175], v155 offset:1024
	ds_read_b128 v[176:179], v155 offset:2048
	ds_read_b128 v[180:183], v155 offset:3072
	s_add_u32 s22, s28, 0xb0000
	s_addc_u32 s23, s29, 0
	v_lshl_add_u64 v[226:227], s[22:23], 0, v[128:129]
	ds_read_b128 v[184:187], v153 offset:32768
	ds_read_b128 v[188:191], v153 offset:33792
	ds_read_b128 v[196:199], v153 offset:34816
	ds_read_b128 v[200:203], v153 offset:35840
	ds_read_b128 v[204:207], v153 offset:36864
	ds_read_b128 v[208:211], v153 offset:37888
	ds_read_b128 v[212:215], v153 offset:38912
	ds_read_b128 v[216:219], v153 offset:39936
	s_mov_b32 m0, s38
	s_nop 0
	global_load_lds_dwordx4 v[222:223], off
	s_mov_b32 m0, s39
	s_nop 0
	global_load_lds_dwordx4 v[224:225], off
	s_mov_b32 m0, s40
	s_nop 0
	global_load_lds_dwordx4 v[226:227], off
	v_lshl_add_u64 v[226:227], s[22:23], 0, v[132:133]
	s_mov_b32 m0, s41
	s_nop 0
	global_load_lds_dwordx4 v[226:227], off
	s_waitcnt vmcnt(8)
	s_waitcnt lgkmcnt(0)
	s_barrier
	s_setprio 1
	s_waitcnt lgkmcnt(0)
	v_mfma_f32_16x16x32_bf16 v[124:127], v[144:147], v[184:187], v[124:127]
	v_mfma_f32_16x16x32_bf16 v[120:123], v[160:163], v[184:187], v[120:123]
	v_mfma_f32_16x16x32_bf16 v[108:111], v[144:147], v[196:199], v[108:111]
	v_mfma_f32_16x16x32_bf16 v[104:107], v[160:163], v[196:199], v[104:107]
	v_mfma_f32_16x16x32_bf16 v[92:95], v[144:147], v[204:207], v[92:95]
	v_mfma_f32_16x16x32_bf16 v[88:91], v[160:163], v[204:207], v[88:91]
	v_mfma_f32_16x16x32_bf16 v[76:79], v[144:147], v[212:215], v[76:79]
	v_mfma_f32_16x16x32_bf16 v[72:75], v[160:163], v[212:215], v[72:75]
	v_mfma_f32_16x16x32_bf16 v[124:127], v[156:159], v[188:191], v[124:127]
	v_mfma_f32_16x16x32_bf16 v[120:123], v[164:167], v[188:191], v[120:123]
	v_mfma_f32_16x16x32_bf16 v[108:111], v[156:159], v[200:203], v[108:111]
	v_mfma_f32_16x16x32_bf16 v[104:107], v[164:167], v[200:203], v[104:107]
	v_mfma_f32_16x16x32_bf16 v[92:95], v[156:159], v[208:211], v[92:95]
	v_mfma_f32_16x16x32_bf16 v[88:91], v[164:167], v[208:211], v[88:91]
	v_mfma_f32_16x16x32_bf16 v[76:79], v[156:159], v[216:219], v[76:79]
	v_mfma_f32_16x16x32_bf16 v[72:75], v[164:167], v[216:219], v[72:75]
	s_setprio 0
	s_setprio 1
	v_mfma_f32_16x16x32_bf16 v[116:119], v[168:171], v[184:187], v[116:119]
	v_mfma_f32_16x16x32_bf16 v[112:115], v[176:179], v[184:187], v[112:115]
	v_mfma_f32_16x16x32_bf16 v[100:103], v[168:171], v[196:199], v[100:103]
	v_mfma_f32_16x16x32_bf16 v[96:99], v[176:179], v[196:199], v[96:99]
	v_mfma_f32_16x16x32_bf16 v[84:87], v[168:171], v[204:207], v[84:87]
	v_mfma_f32_16x16x32_bf16 v[80:83], v[176:179], v[204:207], v[80:83]
	v_mfma_f32_16x16x32_bf16 v[68:71], v[168:171], v[212:215], v[68:71]
	v_mfma_f32_16x16x32_bf16 v[64:67], v[176:179], v[212:215], v[64:67]
	v_mfma_f32_16x16x32_bf16 v[116:119], v[172:175], v[188:191], v[116:119]
	v_mfma_f32_16x16x32_bf16 v[112:115], v[180:183], v[188:191], v[112:115]
	v_mfma_f32_16x16x32_bf16 v[100:103], v[172:175], v[200:203], v[100:103]
	v_mfma_f32_16x16x32_bf16 v[96:99], v[180:183], v[200:203], v[96:99]
	v_mfma_f32_16x16x32_bf16 v[84:87], v[172:175], v[208:211], v[84:87]
	v_mfma_f32_16x16x32_bf16 v[80:83], v[180:183], v[208:211], v[80:83]
	v_mfma_f32_16x16x32_bf16 v[68:71], v[172:175], v[216:219], v[68:71]
	v_mfma_f32_16x16x32_bf16 v[64:67], v[180:183], v[216:219], v[64:67]
	s_setprio 0
	s_barrier
	s_add_i32 s22, s57, s37
	v_lshl_add_u64 v[192:193], v[192:193], 0, s[16:17]
	s_mov_b32 m0, s22
	ds_read_b128 v[184:187], v153 offset:49152
	ds_read_b128 v[188:191], v153 offset:50176
	ds_read_b128 v[196:199], v153 offset:51200
	ds_read_b128 v[200:203], v153 offset:52224
	ds_read_b128 v[204:207], v153 offset:53248
	ds_read_b128 v[208:211], v153 offset:54272
	ds_read_b128 v[212:215], v153 offset:55296
	ds_read_b128 v[216:219], v153 offset:56320
	global_load_lds_dwordx4 v[192:193], off
	s_add_i32 m0, s22, 0x2000
	s_add_u32 s22, s26, 0xb0080
	v_lshl_add_u64 v[192:193], v[220:221], 0, s[16:17]
	s_addc_u32 s23, s27, 0
	s_add_i32 s26, s58, s37
	global_load_lds_dwordx4 v[192:193], off
	v_lshl_add_u64 v[192:193], s[22:23], 0, v[130:131]
	s_mov_b32 m0, s26
	s_nop 0
	global_load_lds_dwordx4 v[192:193], off
	v_lshl_add_u64 v[192:193], s[22:23], 0, v[134:135]
	s_add_i32 m0, s26, 0x2000
	s_nop 0
	global_load_lds_dwordx4 v[192:193], off
	s_waitcnt vmcnt(6)
	s_waitcnt lgkmcnt(0)
	s_barrier
	s_setprio 1
	s_waitcnt lgkmcnt(0)
	v_mfma_f32_16x16x32_bf16 v[60:63], v[144:147], v[184:187], v[60:63]
	v_mfma_f32_16x16x32_bf16 v[56:59], v[160:163], v[184:187], v[56:59]
	v_mfma_f32_16x16x32_bf16 v[44:47], v[144:147], v[196:199], v[44:47]
	v_mfma_f32_16x16x32_bf16 v[40:43], v[160:163], v[196:199], v[40:43]
	v_mfma_f32_16x16x32_bf16 v[28:31], v[144:147], v[204:207], v[28:31]
	v_mfma_f32_16x16x32_bf16 v[24:27], v[160:163], v[204:207], v[24:27]
	v_mfma_f32_16x16x32_bf16 v[12:15], v[144:147], v[212:215], v[12:15]
	v_mfma_f32_16x16x32_bf16 v[8:11], v[160:163], v[212:215], v[8:11]
	v_mfma_f32_16x16x32_bf16 v[60:63], v[156:159], v[188:191], v[60:63]
	v_mfma_f32_16x16x32_bf16 v[56:59], v[164:167], v[188:191], v[56:59]
	v_mfma_f32_16x16x32_bf16 v[44:47], v[156:159], v[200:203], v[44:47]
	v_mfma_f32_16x16x32_bf16 v[40:43], v[164:167], v[200:203], v[40:43]
	v_mfma_f32_16x16x32_bf16 v[28:31], v[156:159], v[208:211], v[28:31]
	v_mfma_f32_16x16x32_bf16 v[24:27], v[164:167], v[208:211], v[24:27]
	v_mfma_f32_16x16x32_bf16 v[12:15], v[156:159], v[216:219], v[12:15]
	v_mfma_f32_16x16x32_bf16 v[8:11], v[164:167], v[216:219], v[8:11]
	s_setprio 0
	s_setprio 1
	v_mfma_f32_16x16x32_bf16 v[52:55], v[168:171], v[184:187], v[52:55]
	v_mfma_f32_16x16x32_bf16 v[48:51], v[176:179], v[184:187], v[48:51]
	v_mfma_f32_16x16x32_bf16 v[36:39], v[168:171], v[196:199], v[36:39]
	v_mfma_f32_16x16x32_bf16 v[32:35], v[176:179], v[196:199], v[32:35]
	v_mfma_f32_16x16x32_bf16 v[20:23], v[168:171], v[204:207], v[20:23]
	v_mfma_f32_16x16x32_bf16 v[16:19], v[176:179], v[204:207], v[16:19]
	v_mfma_f32_16x16x32_bf16 v[4:7], v[168:171], v[212:215], v[4:7]
	v_mfma_f32_16x16x32_bf16 v[0:3], v[176:179], v[212:215], v[0:3]
	v_mfma_f32_16x16x32_bf16 v[52:55], v[172:175], v[188:191], v[52:55]
	v_mfma_f32_16x16x32_bf16 v[48:51], v[180:183], v[188:191], v[48:51]
	v_mfma_f32_16x16x32_bf16 v[36:39], v[172:175], v[200:203], v[36:39]
	v_mfma_f32_16x16x32_bf16 v[32:35], v[180:183], v[200:203], v[32:35]
	v_mfma_f32_16x16x32_bf16 v[20:23], v[172:175], v[208:211], v[20:23]
	v_mfma_f32_16x16x32_bf16 v[16:19], v[180:183], v[208:211], v[16:19]
	v_mfma_f32_16x16x32_bf16 v[4:7], v[172:175], v[216:219], v[4:7]
	v_mfma_f32_16x16x32_bf16 v[0:3], v[180:183], v[216:219], v[0:3]
	s_setprio 0
	s_barrier
	v_lshl_add_u64 v[222:223], v[222:223], 0, s[16:17]
	s_mov_b32 m0, s43
	s_nop 0
	global_load_lds_dwordx4 v[222:223], off
	v_lshl_add_u64 v[224:225], v[224:225], 0, s[16:17]
	s_mov_b32 m0, s44
	s_nop 0
	global_load_lds_dwordx4 v[224:225], off
	s_add_i32 s56, s56, 2
	s_add_u32 s54, s54, 0x100
	s_addc_u32 s55, s55, 0
	s_cmp_gt_u32 s56, 41
	s_mov_b64 s[22:23], s[24:25]
	s_cbranch_scc0 .LBB0_3401
	s_and_b64 vcc, exec, s[18:19]
	s_cbranch_vccz .LBB0_3404
	s_barrier
